# GEMM epilogue 16-byte stores made write-through (sc1) so the grid barrier's L2 writeback has little left to flush
# baseline (speedup 1.0000x reference)
; __device__ __forceinline__ v4u pack8(const float (&f)[8]) { v4u w; w.x = cvt_pk_bf16(f[0], f[1]); w.y = cvt_pk_bf16(f[2], f[3]); w.z = cvt_pk_bf16(f[4], f[5]); w.w = cvt_pk_bf16(f[6], f[7]); return w; }
;     __device__ __forceinline__ void operator()(const f32x4 (&acc)[2][2][4][2], const Unit& u, int wr, int wc, int fr, int fq) const {
;     ...
;                     for (int m = 0; m < 4; ++m) if (rrow[ai][m] >= 0) {
;                         bf16* rp = dst + (size_t)rrow[ai][m] * D;
; #pragma unroll
;                         for (int bj = 0; bj < 2; ++bj) { float o[8];
; #pragma unroll
;                             for (int n = 0; n < 2; ++n)
; #pragma unroll
;                                 for (int j = 0; j < 4; ++j) o[n * 4 + j] = acc[ai][bj][m][n][j];
;                             *(v4u*)(rp + bj * 128) = pack8(o); }
.LBB0_693:
	s_or_b64 exec, exec, s[44:45]
	v_mad_u64_u32 v[152:153], s[18:19], v144, s83, v[146:147]
	v_cvt_pk_bf16_f32 v148, v0, v133
	v_cvt_pk_bf16_f32 v149, v135, v137
	v_cvt_pk_bf16_f32 v150, v139, v141
	v_cvt_pk_bf16_f32 v151, v143, v145
	global_store_dwordx4 v[152:153], v[148:151], off sc1
	s_or_b64 exec, exec, s[10:11]
	v_cmp_lt_i32_e32 vcc, -1, v142
	s_and_saveexec_b64 s[10:11], vcc
	s_cbranch_execnz .LBB0_888

; __device__ __forceinline__ v4u pack8(const float (&f)[8]) { v4u w; w.x = cvt_pk_bf16(f[0], f[1]); w.y = cvt_pk_bf16(f[2], f[3]); w.z = cvt_pk_bf16(f[4], f[5]); w.w = cvt_pk_bf16(f[6], f[7]); return w; }
;     __device__ __forceinline__ void operator()(const f32x4 (&acc)[2][2][4][2], const Unit& u, int wr, int wc, int fr, int fq) const {
;     ...
;                     for (int m = 0; m < 4; ++m) if (rrow[ai][m] >= 0) {
;                         bf16* rp = dst + (size_t)rrow[ai][m] * D;
; #pragma unroll
;                         for (int bj = 0; bj < 2; ++bj) { float o[8];
; #pragma unroll
;                             for (int n = 0; n < 2; ++n)
; #pragma unroll
;                                 for (int j = 0; j < 4; ++j) o[n * 4 + j] = acc[ai][bj][m][n][j];
;                             *(v4u*)(rp + bj * 128) = pack8(o); }
.LBB0_743:
	s_or_b64 exec, exec, s[44:45]
	v_mad_u64_u32 v[152:153], s[18:19], v140, s83, v[146:147]
	v_cvt_pk_bf16_f32 v148, v0, v133
	v_cvt_pk_bf16_f32 v149, v135, v137
	v_cvt_pk_bf16_f32 v150, v139, v141
	v_cvt_pk_bf16_f32 v151, v143, v145
	global_store_dwordx4 v[152:153], v[148:151], off sc1
	s_or_b64 exec, exec, s[10:11]
	v_cmp_lt_i32_e32 vcc, -1, v138
	s_and_saveexec_b64 s[10:11], vcc
	s_cbranch_execnz .LBB0_938

; __device__ __forceinline__ v4u pack8(const float (&f)[8]) { v4u w; w.x = cvt_pk_bf16(f[0], f[1]); w.y = cvt_pk_bf16(f[2], f[3]); w.z = cvt_pk_bf16(f[4], f[5]); w.w = cvt_pk_bf16(f[6], f[7]); return w; }
;     __device__ __forceinline__ void operator()(const f32x4 (&acc)[2][2][4][2], const Unit& u, int wr, int wc, int fr, int fq) const {
;     ...
;                     for (int m = 0; m < 4; ++m) if (rrow[ai][m] >= 0) {
;                         bf16* rp = dst + (size_t)rrow[ai][m] * D;
; #pragma unroll
;                         for (int bj = 0; bj < 2; ++bj) { float o[8];
; #pragma unroll
;                             for (int n = 0; n < 2; ++n)
; #pragma unroll
;                                 for (int j = 0; j < 4; ++j) o[n * 4 + j] = acc[ai][bj][m][n][j];
;                             *(v4u*)(rp + bj * 128) = pack8(o); }
.LBB0_793:
	s_or_b64 exec, exec, s[44:45]
	v_mad_u64_u32 v[152:153], s[18:19], v136, s83, v[146:147]
	v_cvt_pk_bf16_f32 v148, v0, v133
	v_cvt_pk_bf16_f32 v149, v135, v137
	v_cvt_pk_bf16_f32 v150, v139, v141
	v_cvt_pk_bf16_f32 v151, v143, v145
	global_store_dwordx4 v[152:153], v[148:151], off sc1
	s_or_b64 exec, exec, s[10:11]
	v_cmp_lt_i32_e32 vcc, -1, v134
	s_and_saveexec_b64 s[10:11], vcc
	s_cbranch_execnz .LBB0_988

; __device__ __forceinline__ v4u pack8(const float (&f)[8]) { v4u w; w.x = cvt_pk_bf16(f[0], f[1]); w.y = cvt_pk_bf16(f[2], f[3]); w.z = cvt_pk_bf16(f[4], f[5]); w.w = cvt_pk_bf16(f[6], f[7]); return w; }
;     __device__ __forceinline__ void operator()(const f32x4 (&acc)[2][2][4][2], const Unit& u, int wr, int wc, int fr, int fq) const {
;     ...
;                     for (int m = 0; m < 4; ++m) if (rrow[ai][m] >= 0) {
;                         bf16* rp = dst + (size_t)rrow[ai][m] * D;
; #pragma unroll
;                         for (int bj = 0; bj < 2; ++bj) { float o[8];
; #pragma unroll
;                             for (int n = 0; n < 2; ++n)
; #pragma unroll
;                                 for (int j = 0; j < 4; ++j) o[n * 4 + j] = acc[ai][bj][m][n][j];
;                             *(v4u*)(rp + bj * 128) = pack8(o); }
.LBB0_843:
	s_or_b64 exec, exec, s[44:45]
	v_mad_u64_u32 v[152:153], s[18:19], v132, s83, v[146:147]
	v_cvt_pk_bf16_f32 v148, v0, v133
	v_cvt_pk_bf16_f32 v149, v135, v137
	v_cvt_pk_bf16_f32 v150, v139, v141
	v_cvt_pk_bf16_f32 v151, v143, v145
	global_store_dwordx4 v[152:153], v[148:151], off sc1
	s_or_b64 exec, exec, s[10:11]
	s_waitcnt lgkmcnt(0)
	v_cmp_lt_i32_e32 vcc, -1, v130
	s_and_b64 exec, exec, vcc
	s_cbranch_execz .LBB0_1087
	s_branch .LBB0_1038

; __device__ __forceinline__ unsigned cvt_pk_bf16(float lo, float hi) { unsigned r; asm("v_cvt_pk_bf16_f32 %0, %1, %2" : "=v"(r) : "v"(lo), "v"(hi)); return r; }
;     __device__ __forceinline__ void operator()(const f32x4 (&acc)[2][2][4][2], const Unit& u, int wr, int wc, int fr, int fq) const {
;     ...
;             for (int am = 0; am < 4; ++am) { const int ai = am >> 1, mb = (am & 1) * 2;
;                 v4u xv[2][2];
; #pragma unroll
;                 for (int mm = 0; mm < 2; ++mm) { const int m = mb + mm; const bf16* rp = (const bf16*)(ws + WS_XB) + (size_t)(row0 + ai * 128 + m * 16) * D + colw;
; #pragma unroll
;                     for (int bj = 0; bj < 2; ++bj) xv[mm][bj] = *(const v4u*)(rp + bj * 128); }
; #pragma unroll
;                 for (int mm = 0; mm < 2; ++mm) { const int m = mb + mm;
;                     const int row = row0 + ai * 128 + m * 16;
;                     bf16* xb = (bf16*)(ws + WS_XB) + (size_t)row * D + colw;
;                     float ssq = 0.f;
; #pragma unroll
;                     for (int bj = 0; bj < 2; ++bj) {
;                         const auto s0 = __builtin_amdgcn_permlane16_swap(xv[mm][bj].x, xv[mm][bj].z, false, false), s1 = __builtin_amdgcn_permlane16_swap(xv[mm][bj].y, xv[mm][bj].w, false, false);
;                         const unsigned xn[2][2] = {{s0[0], s1[0]}, {s0[1], s1[1]}};
;                         unsigned wn[2][2];
; #pragma unroll
;                         for (int n = 0; n < 2; ++n) {
;                             const f32x4 v = (f32x4){bf_lo(xn[n][0]), bf_hi(xn[n][0]), bf_lo(xn[n][1]), bf_hi(xn[n][1])} + acc[ai][bj][m][n] * amul;
;                             wn[n][0] = cvt_pk_bf16(v.x, v.y); wn[n][1] = cvt_pk_bf16(v.z, v.w);
;                             if (slot >= 0) ssq += (v.x * v.x + v.y * v.y) + (v.z * v.z + v.w * v.w); }
;                         const auto t0 = __builtin_amdgcn_permlane16_swap(wn[0][0], wn[1][0], false, false), t1 = __builtin_amdgcn_permlane16_swap(wn[0][1], wn[1][1], false, false);
;                         *(v4u*)(xb + bj * 128) = (v4u){t0[0], t1[0], t0[1], t1[1]};
;                     }
;                     if (slot >= 0) { ssq += shfl_xor_l(ssq, 16, fq * 16 + fr); ssq += shfl_xor_l(ssq, 32, fq * 16 + fr); if (fq == 0) ((float*)(ws + WS_SS))[((size_t)slot * M + row) * 16 + u.pn * 4 + wc] = ssq; }
;                 }
;                 asm volatile("" ::: "memory");
.LBB0_851:
	v_lshl_or_b32 v138, s87, 8, v244
	v_ashrrev_i32_e32 v139, 31, v138
	v_lshlrev_b64 v[150:151], 1, v[138:139]
	v_ashrrev_i32_e32 v211, 31, v210
	v_lshl_add_u64 v[140:141], s[90:91], 0, v[150:151]
	v_lshlrev_b64 v[152:153], 11, v[210:211]
	s_waitcnt lgkmcnt(0)
	v_lshl_add_u64 v[130:131], v[140:141], 0, v[152:153]
	global_load_dwordx4 v[146:149], v[130:131], off
	global_load_dwordx4 v[154:157], v[130:131], off offset:256
	v_or_b32_e32 v142, 16, v210
	v_ashrrev_i32_e32 v143, 31, v142
	v_lshlrev_b64 v[144:145], 11, v[142:143]
	v_lshl_add_u64 v[130:131], v[140:141], 0, v[144:145]
	global_load_dwordx4 v[134:137], v[130:131], off
	s_nop 0
	global_load_dwordx4 v[130:133], v[130:131], off offset:256
	v_lshl_add_u64 v[152:153], s[90:91], 0, v[152:153]
	v_lshl_add_u64 v[166:167], v[152:153], 0, v[150:151]
	s_andn2_b64 vcc, exec, s[36:37]
	s_waitcnt vmcnt(0)
	v_mov_b32_e32 v0, v148
	s_nop 1
	v_permlane16_swap_b32_e32 v146, v0
	v_mov_b32_e32 v160, v149
	s_nop 1
	v_permlane16_swap_b32_e32 v147, v160
	v_lshlrev_b32_e32 v148, 16, v146
	v_and_b32_e32 v149, 0xffff0000, v146
	v_lshlrev_b32_e32 v146, 16, v147
	v_and_b32_e32 v147, 0xffff0000, v147
	v_pk_add_f32 v[150:151], v[122:123], v[148:149]
	v_lshlrev_b32_e32 v152, 16, v0
	v_and_b32_e32 v153, 0xffff0000, v0
	v_lshlrev_b32_e32 v148, 16, v160
	v_and_b32_e32 v149, 0xffff0000, v160
	v_mov_b32_e32 v0, v156
	v_pk_add_f32 v[146:147], v[124:125], v[146:147]
	v_cvt_pk_bf16_f32 v158, v150, v151
	v_pk_add_f32 v[148:149], v[116:117], v[148:149]
	v_cvt_pk_bf16_f32 v159, v146, v147
	v_pk_add_f32 v[152:153], v[114:115], v[152:153]
	v_cvt_pk_bf16_f32 v161, v148, v149
	v_permlane16_swap_b32_e32 v154, v0
	v_cvt_pk_bf16_f32 v160, v152, v153
	v_mov_b32_e32 v164, v157
	v_permlane16_swap_b32_e32 v158, v160
	v_permlane16_swap_b32_e32 v159, v161
	v_permlane16_swap_b32_e32 v155, v164
	v_lshlrev_b32_e32 v156, 16, v154
	v_and_b32_e32 v157, 0xffff0000, v154
	global_store_dwordx4 v[166:167], v[158:161], off sc1
	v_lshlrev_b32_e32 v154, 16, v155
	v_and_b32_e32 v155, 0xffff0000, v155
	v_pk_add_f32 v[158:159], v[126:127], v[156:157]
	v_lshlrev_b32_e32 v160, 16, v0
	v_and_b32_e32 v161, 0xffff0000, v0
	v_lshlrev_b32_e32 v156, 16, v164
	v_and_b32_e32 v157, 0xffff0000, v164
	v_pk_add_f32 v[154:155], v[128:129], v[154:155]
	v_cvt_pk_bf16_f32 v162, v158, v159
	v_pk_add_f32 v[156:157], v[120:121], v[156:157]
	v_cvt_pk_bf16_f32 v163, v154, v155
	v_pk_add_f32 v[160:161], v[118:119], v[160:161]
	v_cvt_pk_bf16_f32 v165, v156, v157
	v_cndmask_b32_e64 v0, 0, 1, s[36:37]
	v_cvt_pk_bf16_f32 v164, v160, v161
	v_permlane16_swap_b32_e32 v163, v165
	v_permlane16_swap_b32_e32 v162, v164
	v_cmp_ne_u32_e64 s[10:11], 1, v0
	global_store_dwordx4 v[166:167], v[162:165], off offset:256 sc1
	s_cbranch_vccnz .LBB0_855
	v_mul_f32_e32 v0, v151, v151
	v_mul_f32_e32 v147, v147, v147
	v_fmac_f32_e32 v0, v150, v150
	v_fmac_f32_e32 v147, v146, v146
	v_add_f32_e32 v0, v0, v147
	v_mul_f32_e32 v146, v153, v153
	v_mul_f32_e32 v147, v149, v149
	v_fmac_f32_e32 v146, v152, v152
	v_fmac_f32_e32 v147, v148, v148
	v_add_f32_e32 v146, v146, v147
	v_add_f32_e32 v0, v0, v146
	v_mul_f32_e32 v146, v159, v159
	v_mul_f32_e32 v147, v155, v155
	v_fmac_f32_e32 v146, v158, v158
	v_fmac_f32_e32 v147, v154, v154
	v_add_f32_e32 v146, v146, v147
	v_add_f32_e32 v0, v0, v146
	v_mul_f32_e32 v146, v161, v161
	v_mul_f32_e32 v147, v157, v157
	v_fmac_f32_e32 v146, v160, v160
	v_fmac_f32_e32 v147, v156, v156
	v_add_f32_e32 v146, v146, v147
	v_add_f32_e32 v0, v146, v0
	ds_bpermute_b32 v146, v241, v0
	s_waitcnt lgkmcnt(0)
	v_add_f32_e32 v0, v0, v146
	ds_bpermute_b32 v146, v242, v0
	s_and_saveexec_b64 s[0:1], s[6:7]
	s_cbranch_execz .LBB0_854
	s_waitcnt lgkmcnt(0)
	v_add_f32_e32 v0, v0, v146
	v_lshl_add_u64 v[146:147], s[38:39], 0, v[210:211]
	v_readlane_b32 s18, v252, 23
	s_lshl_b32 s2, s87, 2
	v_lshlrev_b64 v[146:147], 6, v[146:147]
	v_readlane_b32 s19, v252, 24
	s_ashr_i32 s3, s2, 31
	s_lshl_b32 s94, s65, 2
	v_lshl_add_u64 v[146:147], s[18:19], 0, v[146:147]
	v_lshl_add_u64 v[146:147], s[2:3], 2, v[146:147]
	v_lshl_add_u64 v[146:147], v[146:147], 0, s[94:95]
	global_store_dword v[146:147], v0, off

; __device__ __forceinline__ unsigned cvt_pk_bf16(float lo, float hi) { unsigned r; asm("v_cvt_pk_bf16_f32 %0, %1, %2" : "=v"(r) : "v"(lo), "v"(hi)); return r; }
;     __device__ __forceinline__ void operator()(const f32x4 (&acc)[2][2][4][2], const Unit& u, int wr, int wc, int fr, int fq) const {
;     ...
;             for (int am = 0; am < 4; ++am) { const int ai = am >> 1, mb = (am & 1) * 2;
;                 v4u xv[2][2];
; #pragma unroll
;                 for (int mm = 0; mm < 2; ++mm) { const int m = mb + mm; const bf16* rp = (const bf16*)(ws + WS_XB) + (size_t)(row0 + ai * 128 + m * 16) * D + colw;
; #pragma unroll
;                     for (int bj = 0; bj < 2; ++bj) xv[mm][bj] = *(const v4u*)(rp + bj * 128); }
; #pragma unroll
;                 for (int mm = 0; mm < 2; ++mm) { const int m = mb + mm;
;                     const int row = row0 + ai * 128 + m * 16;
;                     bf16* xb = (bf16*)(ws + WS_XB) + (size_t)row * D + colw;
;                     float ssq = 0.f;
; #pragma unroll
;                     for (int bj = 0; bj < 2; ++bj) {
;                         const auto s0 = __builtin_amdgcn_permlane16_swap(xv[mm][bj].x, xv[mm][bj].z, false, false), s1 = __builtin_amdgcn_permlane16_swap(xv[mm][bj].y, xv[mm][bj].w, false, false);
;                         const unsigned xn[2][2] = {{s0[0], s1[0]}, {s0[1], s1[1]}};
;                         unsigned wn[2][2];
; #pragma unroll
;                         for (int n = 0; n < 2; ++n) {
;                             const f32x4 v = (f32x4){bf_lo(xn[n][0]), bf_hi(xn[n][0]), bf_lo(xn[n][1]), bf_hi(xn[n][1])} + acc[ai][bj][m][n] * amul;
;                             wn[n][0] = cvt_pk_bf16(v.x, v.y); wn[n][1] = cvt_pk_bf16(v.z, v.w);
;                             if (slot >= 0) ssq += (v.x * v.x + v.y * v.y) + (v.z * v.z + v.w * v.w); }
;                         const auto t0 = __builtin_amdgcn_permlane16_swap(wn[0][0], wn[1][0], false, false), t1 = __builtin_amdgcn_permlane16_swap(wn[0][1], wn[1][1], false, false);
;                         *(v4u*)(xb + bj * 128) = (v4u){t0[0], t1[0], t0[1], t1[1]};
;                     }
;                     if (slot >= 0) { ssq += shfl_xor_l(ssq, 16, fq * 16 + fr); ssq += shfl_xor_l(ssq, 32, fq * 16 + fr); if (fq == 0) ((float*)(ws + WS_SS))[((size_t)slot * M + row) * 16 + u.pn * 4 + wc] = ssq; }
;                 }
;                 asm volatile("" ::: "memory");
.LBB0_855:
	v_lshl_add_u64 v[144:145], s[90:91], 0, v[144:145]
	v_lshl_add_u64 v[156:157], v[138:139], 1, v[144:145]
	v_mov_b32_e32 v0, v136
	v_mov_b32_e32 v145, v137
	s_nop 0
	v_permlane16_swap_b32_e32 v134, v0
	v_permlane16_swap_b32_e32 v135, v145
	v_lshlrev_b32_e32 v136, 16, v134
	v_and_b32_e32 v137, 0xffff0000, v134
	v_lshlrev_b32_e32 v134, 16, v135
	v_and_b32_e32 v135, 0xffff0000, v135
	s_waitcnt lgkmcnt(0)
	v_lshlrev_b32_e32 v146, 16, v0
	v_and_b32_e32 v147, 0xffff0000, v0
	v_lshlrev_b32_e32 v144, 16, v145
	v_and_b32_e32 v145, 0xffff0000, v145
	v_pk_add_f32 v[134:135], v[108:109], v[134:135]
	v_pk_add_f32 v[136:137], v[106:107], v[136:137]
	v_cvt_pk_bf16_f32 v149, v134, v135
	v_pk_add_f32 v[144:145], v[100:101], v[144:145]
	v_cvt_pk_bf16_f32 v148, v136, v137
	v_pk_add_f32 v[146:147], v[98:99], v[146:147]
	v_cvt_pk_bf16_f32 v151, v144, v145
	v_mov_b32_e32 v0, v132
	v_cvt_pk_bf16_f32 v150, v146, v147
	v_permlane16_swap_b32_e32 v149, v151
	v_permlane16_swap_b32_e32 v148, v150
	global_store_dwordx4 v[156:157], v[148:151], off sc1
	v_permlane16_swap_b32_e32 v130, v0
	s_nop 0
	v_mov_b32_e32 v149, v133
	s_nop 1
	v_permlane16_swap_b32_e32 v131, v149
	v_lshlrev_b32_e32 v132, 16, v130
	v_and_b32_e32 v133, 0xffff0000, v130
	v_lshlrev_b32_e32 v130, 16, v131
	v_and_b32_e32 v131, 0xffff0000, v131
	v_lshlrev_b32_e32 v150, 16, v0
	v_and_b32_e32 v151, 0xffff0000, v0
	v_lshlrev_b32_e32 v148, 16, v149
	v_and_b32_e32 v149, 0xffff0000, v149
	v_pk_add_f32 v[130:131], v[112:113], v[130:131]
	v_pk_add_f32 v[132:133], v[110:111], v[132:133]
	v_cvt_pk_bf16_f32 v153, v130, v131
	v_pk_add_f32 v[148:149], v[104:105], v[148:149]
	v_cvt_pk_bf16_f32 v152, v132, v133
	v_pk_add_f32 v[150:151], v[102:103], v[150:151]
	v_cvt_pk_bf16_f32 v155, v148, v149
	s_and_b64 vcc, exec, s[10:11]
	v_cvt_pk_bf16_f32 v154, v150, v151
	v_permlane16_swap_b32_e32 v153, v155
	v_permlane16_swap_b32_e32 v152, v154
	global_store_dwordx4 v[156:157], v[152:155], off offset:256 sc1
	s_cbranch_vccnz .LBB0_859
	v_mul_f32_e32 v0, v137, v137
	v_mul_f32_e32 v135, v135, v135
	v_fmac_f32_e32 v0, v136, v136
	v_fmac_f32_e32 v135, v134, v134
	v_add_f32_e32 v0, v0, v135
	v_mul_f32_e32 v134, v147, v147
	v_mul_f32_e32 v135, v145, v145
	v_fmac_f32_e32 v134, v146, v146
	v_fmac_f32_e32 v135, v144, v144
	v_mul_f32_e32 v133, v133, v133
	v_mul_f32_e32 v131, v131, v131
	v_add_f32_e32 v134, v134, v135
	v_fmac_f32_e32 v133, v132, v132
	v_fmac_f32_e32 v131, v130, v130
	v_add_f32_e32 v0, v0, v134
	v_add_f32_e32 v130, v133, v131
	v_add_f32_e32 v0, v0, v130
	v_mul_f32_e32 v130, v151, v151
	v_mul_f32_e32 v131, v149, v149
	v_fmac_f32_e32 v130, v150, v150
	v_fmac_f32_e32 v131, v148, v148
	v_add_f32_e32 v130, v130, v131
	v_add_f32_e32 v0, v130, v0
	ds_bpermute_b32 v130, v241, v0
	s_waitcnt lgkmcnt(0)
	v_add_f32_e32 v0, v0, v130
	ds_bpermute_b32 v130, v242, v0
	s_and_saveexec_b64 s[0:1], s[6:7]
	s_cbranch_execz .LBB0_858
	s_waitcnt lgkmcnt(0)
	v_add_f32_e32 v0, v0, v130
	v_lshl_add_u64 v[130:131], s[38:39], 0, v[142:143]
	v_readlane_b32 s18, v252, 23
	s_lshl_b32 s2, s87, 2
	v_lshlrev_b64 v[130:131], 6, v[130:131]
	v_readlane_b32 s19, v252, 24
	s_ashr_i32 s3, s2, 31
	s_lshl_b32 s94, s65, 2
	v_lshl_add_u64 v[130:131], s[18:19], 0, v[130:131]
	v_lshl_add_u64 v[130:131], s[2:3], 2, v[130:131]
	v_lshl_add_u64 v[130:131], v[130:131], 0, s[94:95]
	global_store_dword v[130:131], v0, off

; __device__ __forceinline__ unsigned cvt_pk_bf16(float lo, float hi) { unsigned r; asm("v_cvt_pk_bf16_f32 %0, %1, %2" : "=v"(r) : "v"(lo), "v"(hi)); return r; }
;     __device__ __forceinline__ void operator()(const f32x4 (&acc)[2][2][4][2], const Unit& u, int wr, int wc, int fr, int fq) const {
;     ...
;             for (int am = 0; am < 4; ++am) { const int ai = am >> 1, mb = (am & 1) * 2;
;                 v4u xv[2][2];
; #pragma unroll
;                 for (int mm = 0; mm < 2; ++mm) { const int m = mb + mm; const bf16* rp = (const bf16*)(ws + WS_XB) + (size_t)(row0 + ai * 128 + m * 16) * D + colw;
; #pragma unroll
;                     for (int bj = 0; bj < 2; ++bj) xv[mm][bj] = *(const v4u*)(rp + bj * 128); }
; #pragma unroll
;                 for (int mm = 0; mm < 2; ++mm) { const int m = mb + mm;
;                     const int row = row0 + ai * 128 + m * 16;
;                     bf16* xb = (bf16*)(ws + WS_XB) + (size_t)row * D + colw;
;                     float ssq = 0.f;
; #pragma unroll
;                     for (int bj = 0; bj < 2; ++bj) {
;                         const auto s0 = __builtin_amdgcn_permlane16_swap(xv[mm][bj].x, xv[mm][bj].z, false, false), s1 = __builtin_amdgcn_permlane16_swap(xv[mm][bj].y, xv[mm][bj].w, false, false);
;                         const unsigned xn[2][2] = {{s0[0], s1[0]}, {s0[1], s1[1]}};
;                         unsigned wn[2][2];
; #pragma unroll
;                         for (int n = 0; n < 2; ++n) {
;                             const f32x4 v = (f32x4){bf_lo(xn[n][0]), bf_hi(xn[n][0]), bf_lo(xn[n][1]), bf_hi(xn[n][1])} + acc[ai][bj][m][n] * amul;
;                             wn[n][0] = cvt_pk_bf16(v.x, v.y); wn[n][1] = cvt_pk_bf16(v.z, v.w);
;                             if (slot >= 0) ssq += (v.x * v.x + v.y * v.y) + (v.z * v.z + v.w * v.w); }
;                         const auto t0 = __builtin_amdgcn_permlane16_swap(wn[0][0], wn[1][0], false, false), t1 = __builtin_amdgcn_permlane16_swap(wn[0][1], wn[1][1], false, false);
;                         *(v4u*)(xb + bj * 128) = (v4u){t0[0], t1[0], t0[1], t1[1]};
;                     }
;                     if (slot >= 0) { ssq += shfl_xor_l(ssq, 16, fq * 16 + fr); ssq += shfl_xor_l(ssq, 32, fq * 16 + fr); if (fq == 0) ((float*)(ws + WS_SS))[((size_t)slot * M + row) * 16 + u.pn * 4 + wc] = ssq; }
;                 }
;                 asm volatile("" ::: "memory");
.LBB0_859:
	v_or_b32_e32 v146, 32, v210
	v_ashrrev_i32_e32 v147, 31, v146
	v_lshlrev_b64 v[152:153], 11, v[146:147]
	s_waitcnt lgkmcnt(0)
	v_lshl_add_u64 v[130:131], v[140:141], 0, v[152:153]
	global_load_dwordx4 v[148:151], v[130:131], off
	global_load_dwordx4 v[156:159], v[130:131], off offset:256
	v_or_b32_e32 v142, 48, v210
	v_ashrrev_i32_e32 v143, 31, v142
	v_lshlrev_b64 v[144:145], 11, v[142:143]
	v_lshl_add_u64 v[130:131], v[140:141], 0, v[144:145]
	global_load_dwordx4 v[134:137], v[130:131], off
	s_nop 0
	global_load_dwordx4 v[130:133], v[130:131], off offset:256
	v_lshl_add_u64 v[152:153], s[90:91], 0, v[152:153]
	v_lshl_add_u64 v[168:169], v[138:139], 1, v[152:153]
	s_and_b64 vcc, exec, s[10:11]
	s_waitcnt vmcnt(3)
	v_mov_b32_e32 v0, v150
	s_nop 1
	v_permlane16_swap_b32_e32 v148, v0
	v_mov_b32_e32 v162, v151
	s_nop 1
	v_permlane16_swap_b32_e32 v149, v162
	v_lshlrev_b32_e32 v150, 16, v148
	v_and_b32_e32 v151, 0xffff0000, v148
	v_lshlrev_b32_e32 v148, 16, v149
	v_and_b32_e32 v149, 0xffff0000, v149
	v_pk_add_f32 v[152:153], v[90:91], v[150:151]
	v_lshlrev_b32_e32 v154, 16, v0
	v_and_b32_e32 v155, 0xffff0000, v0
	v_lshlrev_b32_e32 v150, 16, v162
	v_and_b32_e32 v151, 0xffff0000, v162
	s_waitcnt vmcnt(2)
	v_mov_b32_e32 v0, v158
	v_pk_add_f32 v[148:149], v[92:93], v[148:149]
	v_cvt_pk_bf16_f32 v160, v152, v153
	v_pk_add_f32 v[150:151], v[84:85], v[150:151]
	v_cvt_pk_bf16_f32 v161, v148, v149
	v_pk_add_f32 v[154:155], v[82:83], v[154:155]
	v_cvt_pk_bf16_f32 v163, v150, v151
	v_permlane16_swap_b32_e32 v156, v0
	v_cvt_pk_bf16_f32 v162, v154, v155
	v_mov_b32_e32 v166, v159
	v_permlane16_swap_b32_e32 v160, v162
	v_permlane16_swap_b32_e32 v161, v163
	v_permlane16_swap_b32_e32 v157, v166
	v_lshlrev_b32_e32 v158, 16, v156
	v_and_b32_e32 v159, 0xffff0000, v156
	global_store_dwordx4 v[168:169], v[160:163], off sc1
	v_lshlrev_b32_e32 v156, 16, v157
	v_and_b32_e32 v157, 0xffff0000, v157
	v_pk_add_f32 v[160:161], v[94:95], v[158:159]
	v_lshlrev_b32_e32 v162, 16, v0
	v_and_b32_e32 v163, 0xffff0000, v0
	v_lshlrev_b32_e32 v158, 16, v166
	v_and_b32_e32 v159, 0xffff0000, v166
	v_pk_add_f32 v[156:157], v[96:97], v[156:157]
	v_cvt_pk_bf16_f32 v164, v160, v161
	v_pk_add_f32 v[158:159], v[88:89], v[158:159]
	v_cvt_pk_bf16_f32 v165, v156, v157
	v_pk_add_f32 v[162:163], v[86:87], v[162:163]
	v_cvt_pk_bf16_f32 v167, v158, v159
	s_nop 0
	v_cvt_pk_bf16_f32 v166, v162, v163
	v_permlane16_swap_b32_e32 v165, v167
	v_permlane16_swap_b32_e32 v164, v166
	global_store_dwordx4 v[168:169], v[164:167], off offset:256 sc1
	s_cbranch_vccnz .LBB0_863
	v_mul_f32_e32 v0, v153, v153
	v_mul_f32_e32 v149, v149, v149
	v_fmac_f32_e32 v0, v152, v152
	v_fmac_f32_e32 v149, v148, v148
	v_add_f32_e32 v0, v0, v149
	v_mul_f32_e32 v148, v155, v155
	v_mul_f32_e32 v149, v151, v151
	v_fmac_f32_e32 v148, v154, v154
	v_fmac_f32_e32 v149, v150, v150
	v_add_f32_e32 v148, v148, v149
	v_add_f32_e32 v0, v0, v148
	v_mul_f32_e32 v148, v161, v161
	v_mul_f32_e32 v149, v157, v157
	v_fmac_f32_e32 v148, v160, v160
	v_fmac_f32_e32 v149, v156, v156
	v_add_f32_e32 v148, v148, v149
	v_add_f32_e32 v0, v0, v148
	v_mul_f32_e32 v148, v163, v163
	v_mul_f32_e32 v149, v159, v159
	v_fmac_f32_e32 v148, v162, v162
	v_fmac_f32_e32 v149, v158, v158
	v_add_f32_e32 v148, v148, v149
	v_add_f32_e32 v0, v148, v0
	ds_bpermute_b32 v148, v241, v0
	s_waitcnt lgkmcnt(0)
	v_add_f32_e32 v0, v0, v148
	ds_bpermute_b32 v148, v242, v0
	s_and_saveexec_b64 s[0:1], s[6:7]
	s_cbranch_execz .LBB0_862
	v_lshl_add_u64 v[146:147], s[38:39], 0, v[146:147]
	v_readlane_b32 s18, v252, 23
	s_lshl_b32 s2, s87, 2
	v_lshlrev_b64 v[146:147], 6, v[146:147]
	v_readlane_b32 s19, v252, 24
	s_ashr_i32 s3, s2, 31
	s_lshl_b32 s94, s65, 2
	v_lshl_add_u64 v[146:147], s[18:19], 0, v[146:147]
	v_lshl_add_u64 v[146:147], s[2:3], 2, v[146:147]
	s_waitcnt lgkmcnt(0)
	v_add_f32_e32 v0, v0, v148
	v_lshl_add_u64 v[146:147], v[146:147], 0, s[94:95]
	global_store_dword v[146:147], v0, off

; __device__ __forceinline__ unsigned cvt_pk_bf16(float lo, float hi) { unsigned r; asm("v_cvt_pk_bf16_f32 %0, %1, %2" : "=v"(r) : "v"(lo), "v"(hi)); return r; }
;     __device__ __forceinline__ void operator()(const f32x4 (&acc)[2][2][4][2], const Unit& u, int wr, int wc, int fr, int fq) const {
;     ...
;             for (int am = 0; am < 4; ++am) { const int ai = am >> 1, mb = (am & 1) * 2;
;                 v4u xv[2][2];
; #pragma unroll
;                 for (int mm = 0; mm < 2; ++mm) { const int m = mb + mm; const bf16* rp = (const bf16*)(ws + WS_XB) + (size_t)(row0 + ai * 128 + m * 16) * D + colw;
; #pragma unroll
;                     for (int bj = 0; bj < 2; ++bj) xv[mm][bj] = *(const v4u*)(rp + bj * 128); }
; #pragma unroll
;                 for (int mm = 0; mm < 2; ++mm) { const int m = mb + mm;
;                     const int row = row0 + ai * 128 + m * 16;
;                     bf16* xb = (bf16*)(ws + WS_XB) + (size_t)row * D + colw;
;                     float ssq = 0.f;
; #pragma unroll
;                     for (int bj = 0; bj < 2; ++bj) {
;                         const auto s0 = __builtin_amdgcn_permlane16_swap(xv[mm][bj].x, xv[mm][bj].z, false, false), s1 = __builtin_amdgcn_permlane16_swap(xv[mm][bj].y, xv[mm][bj].w, false, false);
;                         const unsigned xn[2][2] = {{s0[0], s1[0]}, {s0[1], s1[1]}};
;                         unsigned wn[2][2];
; #pragma unroll
;                         for (int n = 0; n < 2; ++n) {
;                             const f32x4 v = (f32x4){bf_lo(xn[n][0]), bf_hi(xn[n][0]), bf_lo(xn[n][1]), bf_hi(xn[n][1])} + acc[ai][bj][m][n] * amul;
;                             wn[n][0] = cvt_pk_bf16(v.x, v.y); wn[n][1] = cvt_pk_bf16(v.z, v.w);
;                             if (slot >= 0) ssq += (v.x * v.x + v.y * v.y) + (v.z * v.z + v.w * v.w); }
;                         const auto t0 = __builtin_amdgcn_permlane16_swap(wn[0][0], wn[1][0], false, false), t1 = __builtin_amdgcn_permlane16_swap(wn[0][1], wn[1][1], false, false);
;                         *(v4u*)(xb + bj * 128) = (v4u){t0[0], t1[0], t0[1], t1[1]};
;                     }
;                     if (slot >= 0) { ssq += shfl_xor_l(ssq, 16, fq * 16 + fr); ssq += shfl_xor_l(ssq, 32, fq * 16 + fr); if (fq == 0) ((float*)(ws + WS_SS))[((size_t)slot * M + row) * 16 + u.pn * 4 + wc] = ssq; }
;                 }
;                 asm volatile("" ::: "memory");
.LBB0_863:
	v_lshl_add_u64 v[144:145], s[90:91], 0, v[144:145]
	v_lshl_add_u64 v[156:157], v[138:139], 1, v[144:145]
	s_waitcnt vmcnt(3)
	v_mov_b32_e32 v0, v136
	v_mov_b32_e32 v145, v137
	s_nop 0
	v_permlane16_swap_b32_e32 v134, v0
	v_permlane16_swap_b32_e32 v135, v145
	v_lshlrev_b32_e32 v136, 16, v134
	v_and_b32_e32 v137, 0xffff0000, v134
	v_lshlrev_b32_e32 v134, 16, v135
	v_and_b32_e32 v135, 0xffff0000, v135
	v_lshlrev_b32_e32 v146, 16, v0
	v_and_b32_e32 v147, 0xffff0000, v0
	v_lshlrev_b32_e32 v144, 16, v145
	v_and_b32_e32 v145, 0xffff0000, v145
	v_pk_add_f32 v[134:135], v[76:77], v[134:135]
	v_pk_add_f32 v[136:137], v[74:75], v[136:137]
	v_cvt_pk_bf16_f32 v149, v134, v135
	v_pk_add_f32 v[144:145], v[68:69], v[144:145]
	s_waitcnt lgkmcnt(0)
	v_cvt_pk_bf16_f32 v148, v136, v137
	v_pk_add_f32 v[146:147], v[66:67], v[146:147]
	v_cvt_pk_bf16_f32 v151, v144, v145
	s_waitcnt vmcnt(2)
	v_mov_b32_e32 v0, v132
	v_cvt_pk_bf16_f32 v150, v146, v147
	v_permlane16_swap_b32_e32 v149, v151
	v_permlane16_swap_b32_e32 v148, v150
	global_store_dwordx4 v[156:157], v[148:151], off sc1
	v_permlane16_swap_b32_e32 v130, v0
	s_nop 0
	v_mov_b32_e32 v149, v133
	s_nop 1
	v_permlane16_swap_b32_e32 v131, v149
	v_lshlrev_b32_e32 v132, 16, v130
	v_and_b32_e32 v133, 0xffff0000, v130
	v_lshlrev_b32_e32 v130, 16, v131
	v_and_b32_e32 v131, 0xffff0000, v131
	v_lshlrev_b32_e32 v150, 16, v0
	v_and_b32_e32 v151, 0xffff0000, v0
	v_lshlrev_b32_e32 v148, 16, v149
	v_and_b32_e32 v149, 0xffff0000, v149
	v_pk_add_f32 v[130:131], v[80:81], v[130:131]
	v_pk_add_f32 v[132:133], v[78:79], v[132:133]
	v_cvt_pk_bf16_f32 v153, v130, v131
	v_pk_add_f32 v[148:149], v[72:73], v[148:149]
	v_cvt_pk_bf16_f32 v152, v132, v133
	v_pk_add_f32 v[150:151], v[70:71], v[150:151]
	v_cvt_pk_bf16_f32 v155, v148, v149
	s_and_b64 vcc, exec, s[10:11]
	v_cvt_pk_bf16_f32 v154, v150, v151
	v_permlane16_swap_b32_e32 v153, v155
	v_permlane16_swap_b32_e32 v152, v154
	global_store_dwordx4 v[156:157], v[152:155], off offset:256 sc1
	s_cbranch_vccnz .LBB0_867
	v_mul_f32_e32 v0, v137, v137
	v_mul_f32_e32 v135, v135, v135
	v_fmac_f32_e32 v0, v136, v136
	v_fmac_f32_e32 v135, v134, v134
	v_add_f32_e32 v0, v0, v135
	v_mul_f32_e32 v134, v147, v147
	v_mul_f32_e32 v135, v145, v145
	v_fmac_f32_e32 v134, v146, v146
	v_fmac_f32_e32 v135, v144, v144
	v_mul_f32_e32 v133, v133, v133
	v_mul_f32_e32 v131, v131, v131
	v_add_f32_e32 v134, v134, v135
	v_fmac_f32_e32 v133, v132, v132
	v_fmac_f32_e32 v131, v130, v130
	v_add_f32_e32 v0, v0, v134
	v_add_f32_e32 v130, v133, v131
	v_add_f32_e32 v0, v0, v130
	v_mul_f32_e32 v130, v151, v151
	v_mul_f32_e32 v131, v149, v149
	v_fmac_f32_e32 v130, v150, v150
	v_fmac_f32_e32 v131, v148, v148
	v_add_f32_e32 v130, v130, v131
	v_add_f32_e32 v0, v130, v0
	ds_bpermute_b32 v130, v241, v0
	s_waitcnt lgkmcnt(0)
	v_add_f32_e32 v0, v0, v130
	ds_bpermute_b32 v130, v242, v0
	s_and_saveexec_b64 s[0:1], s[6:7]
	s_cbranch_execz .LBB0_866
	s_waitcnt lgkmcnt(0)
	v_add_f32_e32 v0, v0, v130
	v_lshl_add_u64 v[130:131], s[38:39], 0, v[142:143]
	v_readlane_b32 s18, v252, 23
	s_lshl_b32 s2, s87, 2
	v_lshlrev_b64 v[130:131], 6, v[130:131]
	v_readlane_b32 s19, v252, 24
	s_ashr_i32 s3, s2, 31
	s_lshl_b32 s94, s65, 2
	v_lshl_add_u64 v[130:131], s[18:19], 0, v[130:131]
	v_lshl_add_u64 v[130:131], s[2:3], 2, v[130:131]
	v_lshl_add_u64 v[130:131], v[130:131], 0, s[94:95]
	global_store_dword v[130:131], v0, off

; __device__ __forceinline__ unsigned cvt_pk_bf16(float lo, float hi) { unsigned r; asm("v_cvt_pk_bf16_f32 %0, %1, %2" : "=v"(r) : "v"(lo), "v"(hi)); return r; }
;     __device__ __forceinline__ void operator()(const f32x4 (&acc)[2][2][4][2], const Unit& u, int wr, int wc, int fr, int fq) const {
;     ...
;             for (int am = 0; am < 4; ++am) { const int ai = am >> 1, mb = (am & 1) * 2;
;                 v4u xv[2][2];
; #pragma unroll
;                 for (int mm = 0; mm < 2; ++mm) { const int m = mb + mm; const bf16* rp = (const bf16*)(ws + WS_XB) + (size_t)(row0 + ai * 128 + m * 16) * D + colw;
; #pragma unroll
;                     for (int bj = 0; bj < 2; ++bj) xv[mm][bj] = *(const v4u*)(rp + bj * 128); }
; #pragma unroll
;                 for (int mm = 0; mm < 2; ++mm) { const int m = mb + mm;
;                     const int row = row0 + ai * 128 + m * 16;
;                     bf16* xb = (bf16*)(ws + WS_XB) + (size_t)row * D + colw;
;                     float ssq = 0.f;
; #pragma unroll
;                     for (int bj = 0; bj < 2; ++bj) {
;                         const auto s0 = __builtin_amdgcn_permlane16_swap(xv[mm][bj].x, xv[mm][bj].z, false, false), s1 = __builtin_amdgcn_permlane16_swap(xv[mm][bj].y, xv[mm][bj].w, false, false);
;                         const unsigned xn[2][2] = {{s0[0], s1[0]}, {s0[1], s1[1]}};
;                         unsigned wn[2][2];
; #pragma unroll
;                         for (int n = 0; n < 2; ++n) {
;                             const f32x4 v = (f32x4){bf_lo(xn[n][0]), bf_hi(xn[n][0]), bf_lo(xn[n][1]), bf_hi(xn[n][1])} + acc[ai][bj][m][n] * amul;
;                             wn[n][0] = cvt_pk_bf16(v.x, v.y); wn[n][1] = cvt_pk_bf16(v.z, v.w);
;                             if (slot >= 0) ssq += (v.x * v.x + v.y * v.y) + (v.z * v.z + v.w * v.w); }
;                         const auto t0 = __builtin_amdgcn_permlane16_swap(wn[0][0], wn[1][0], false, false), t1 = __builtin_amdgcn_permlane16_swap(wn[0][1], wn[1][1], false, false);
;                         *(v4u*)(xb + bj * 128) = (v4u){t0[0], t1[0], t0[1], t1[1]};
;                     }
;                     if (slot >= 0) { ssq += shfl_xor_l(ssq, 16, fq * 16 + fr); ssq += shfl_xor_l(ssq, 32, fq * 16 + fr); if (fq == 0) ((float*)(ws + WS_SS))[((size_t)slot * M + row) * 16 + u.pn * 4 + wc] = ssq; }
;                 }
;                 asm volatile("" ::: "memory");
.LBB0_867:
	v_add_u32_e32 v146, 0x80, v210
	v_ashrrev_i32_e32 v147, 31, v146
	v_lshlrev_b64 v[152:153], 11, v[146:147]
	s_waitcnt lgkmcnt(0)
	v_lshl_add_u64 v[130:131], v[140:141], 0, v[152:153]
	global_load_dwordx4 v[148:151], v[130:131], off
	global_load_dwordx4 v[156:159], v[130:131], off offset:256
	v_add_u32_e32 v142, 0x90, v210
	v_ashrrev_i32_e32 v143, 31, v142
	v_lshlrev_b64 v[144:145], 11, v[142:143]
	v_lshl_add_u64 v[130:131], v[140:141], 0, v[144:145]
	global_load_dwordx4 v[134:137], v[130:131], off
	s_nop 0
	global_load_dwordx4 v[130:133], v[130:131], off offset:256
	v_lshl_add_u64 v[152:153], s[90:91], 0, v[152:153]
	v_lshl_add_u64 v[168:169], v[138:139], 1, v[152:153]
	s_and_b64 vcc, exec, s[10:11]
	s_waitcnt vmcnt(3)
	v_mov_b32_e32 v0, v150
	s_nop 1
	v_permlane16_swap_b32_e32 v148, v0
	v_mov_b32_e32 v162, v151
	s_nop 1
	v_permlane16_swap_b32_e32 v149, v162
	v_lshlrev_b32_e32 v150, 16, v148
	v_and_b32_e32 v151, 0xffff0000, v148
	v_lshlrev_b32_e32 v148, 16, v149
	v_and_b32_e32 v149, 0xffff0000, v149
	v_pk_add_f32 v[152:153], v[58:59], v[150:151]
	v_lshlrev_b32_e32 v154, 16, v0
	v_and_b32_e32 v155, 0xffff0000, v0
	v_lshlrev_b32_e32 v150, 16, v162
	v_and_b32_e32 v151, 0xffff0000, v162
	s_waitcnt vmcnt(2)
	v_mov_b32_e32 v0, v158
	v_pk_add_f32 v[148:149], v[60:61], v[148:149]
	v_cvt_pk_bf16_f32 v160, v152, v153
	v_pk_add_f32 v[150:151], v[52:53], v[150:151]
	v_cvt_pk_bf16_f32 v161, v148, v149
	v_pk_add_f32 v[154:155], v[50:51], v[154:155]
	v_cvt_pk_bf16_f32 v163, v150, v151
	v_permlane16_swap_b32_e32 v156, v0
	v_cvt_pk_bf16_f32 v162, v154, v155
	v_mov_b32_e32 v166, v159
	v_permlane16_swap_b32_e32 v160, v162
	v_permlane16_swap_b32_e32 v161, v163
	v_permlane16_swap_b32_e32 v157, v166
	v_lshlrev_b32_e32 v158, 16, v156
	v_and_b32_e32 v159, 0xffff0000, v156
	global_store_dwordx4 v[168:169], v[160:163], off sc1
	v_lshlrev_b32_e32 v156, 16, v157
	v_and_b32_e32 v157, 0xffff0000, v157
	v_pk_add_f32 v[160:161], v[62:63], v[158:159]
	v_lshlrev_b32_e32 v162, 16, v0
	v_and_b32_e32 v163, 0xffff0000, v0
	v_lshlrev_b32_e32 v158, 16, v166
	v_and_b32_e32 v159, 0xffff0000, v166
	v_pk_add_f32 v[156:157], v[64:65], v[156:157]
	v_cvt_pk_bf16_f32 v164, v160, v161
	v_pk_add_f32 v[158:159], v[56:57], v[158:159]
	v_cvt_pk_bf16_f32 v165, v156, v157
	v_pk_add_f32 v[162:163], v[54:55], v[162:163]
	v_cvt_pk_bf16_f32 v167, v158, v159
	s_nop 0
	v_cvt_pk_bf16_f32 v166, v162, v163
	v_permlane16_swap_b32_e32 v165, v167
	v_permlane16_swap_b32_e32 v164, v166
	global_store_dwordx4 v[168:169], v[164:167], off offset:256 sc1
	s_cbranch_vccnz .LBB0_871
	v_mul_f32_e32 v0, v153, v153
	v_mul_f32_e32 v149, v149, v149
	v_fmac_f32_e32 v0, v152, v152
	v_fmac_f32_e32 v149, v148, v148
	v_add_f32_e32 v0, v0, v149
	v_mul_f32_e32 v148, v155, v155
	v_mul_f32_e32 v149, v151, v151
	v_fmac_f32_e32 v148, v154, v154
	v_fmac_f32_e32 v149, v150, v150
	v_add_f32_e32 v148, v148, v149
	v_add_f32_e32 v0, v0, v148
	v_mul_f32_e32 v148, v161, v161
	v_mul_f32_e32 v149, v157, v157
	v_fmac_f32_e32 v148, v160, v160
	v_fmac_f32_e32 v149, v156, v156
	v_add_f32_e32 v148, v148, v149
	v_add_f32_e32 v0, v0, v148
	v_mul_f32_e32 v148, v163, v163
	v_mul_f32_e32 v149, v159, v159
	v_fmac_f32_e32 v148, v162, v162
	v_fmac_f32_e32 v149, v158, v158
	v_add_f32_e32 v148, v148, v149
	v_add_f32_e32 v0, v148, v0
	ds_bpermute_b32 v148, v241, v0
	s_waitcnt lgkmcnt(0)
	v_add_f32_e32 v0, v0, v148
	ds_bpermute_b32 v148, v242, v0
	s_and_saveexec_b64 s[0:1], s[6:7]
	s_cbranch_execz .LBB0_870
	v_lshl_add_u64 v[146:147], s[38:39], 0, v[146:147]
	v_readlane_b32 s18, v252, 23
	s_lshl_b32 s2, s87, 2
	v_lshlrev_b64 v[146:147], 6, v[146:147]
	v_readlane_b32 s19, v252, 24
	s_ashr_i32 s3, s2, 31
	s_lshl_b32 s94, s65, 2
	v_lshl_add_u64 v[146:147], s[18:19], 0, v[146:147]
	v_lshl_add_u64 v[146:147], s[2:3], 2, v[146:147]
	s_waitcnt lgkmcnt(0)
	v_add_f32_e32 v0, v0, v148
	v_lshl_add_u64 v[146:147], v[146:147], 0, s[94:95]
	global_store_dword v[146:147], v0, off

; __device__ __forceinline__ unsigned cvt_pk_bf16(float lo, float hi) { unsigned r; asm("v_cvt_pk_bf16_f32 %0, %1, %2" : "=v"(r) : "v"(lo), "v"(hi)); return r; }
;     __device__ __forceinline__ void operator()(const f32x4 (&acc)[2][2][4][2], const Unit& u, int wr, int wc, int fr, int fq) const {
;     ...
;             for (int am = 0; am < 4; ++am) { const int ai = am >> 1, mb = (am & 1) * 2;
;                 v4u xv[2][2];
; #pragma unroll
;                 for (int mm = 0; mm < 2; ++mm) { const int m = mb + mm; const bf16* rp = (const bf16*)(ws + WS_XB) + (size_t)(row0 + ai * 128 + m * 16) * D + colw;
; #pragma unroll
;                     for (int bj = 0; bj < 2; ++bj) xv[mm][bj] = *(const v4u*)(rp + bj * 128); }
; #pragma unroll
;                 for (int mm = 0; mm < 2; ++mm) { const int m = mb + mm;
;                     const int row = row0 + ai * 128 + m * 16;
;                     bf16* xb = (bf16*)(ws + WS_XB) + (size_t)row * D + colw;
;                     float ssq = 0.f;
; #pragma unroll
;                     for (int bj = 0; bj < 2; ++bj) {
;                         const auto s0 = __builtin_amdgcn_permlane16_swap(xv[mm][bj].x, xv[mm][bj].z, false, false), s1 = __builtin_amdgcn_permlane16_swap(xv[mm][bj].y, xv[mm][bj].w, false, false);
;                         const unsigned xn[2][2] = {{s0[0], s1[0]}, {s0[1], s1[1]}};
;                         unsigned wn[2][2];
; #pragma unroll
;                         for (int n = 0; n < 2; ++n) {
;                             const f32x4 v = (f32x4){bf_lo(xn[n][0]), bf_hi(xn[n][0]), bf_lo(xn[n][1]), bf_hi(xn[n][1])} + acc[ai][bj][m][n] * amul;
;                             wn[n][0] = cvt_pk_bf16(v.x, v.y); wn[n][1] = cvt_pk_bf16(v.z, v.w);
;                             if (slot >= 0) ssq += (v.x * v.x + v.y * v.y) + (v.z * v.z + v.w * v.w); }
;                         const auto t0 = __builtin_amdgcn_permlane16_swap(wn[0][0], wn[1][0], false, false), t1 = __builtin_amdgcn_permlane16_swap(wn[0][1], wn[1][1], false, false);
;                         *(v4u*)(xb + bj * 128) = (v4u){t0[0], t1[0], t0[1], t1[1]};
;                     }
;                     if (slot >= 0) { ssq += shfl_xor_l(ssq, 16, fq * 16 + fr); ssq += shfl_xor_l(ssq, 32, fq * 16 + fr); if (fq == 0) ((float*)(ws + WS_SS))[((size_t)slot * M + row) * 16 + u.pn * 4 + wc] = ssq; }
;                 }
;                 asm volatile("" ::: "memory");
.LBB0_871:
	v_lshl_add_u64 v[144:145], s[90:91], 0, v[144:145]
	v_lshl_add_u64 v[156:157], v[138:139], 1, v[144:145]
	s_waitcnt vmcnt(3)
	v_mov_b32_e32 v0, v136
	v_mov_b32_e32 v145, v137
	s_nop 0
	v_permlane16_swap_b32_e32 v134, v0
	v_permlane16_swap_b32_e32 v135, v145
	v_lshlrev_b32_e32 v136, 16, v134
	v_and_b32_e32 v137, 0xffff0000, v134
	v_lshlrev_b32_e32 v134, 16, v135
	v_and_b32_e32 v135, 0xffff0000, v135
	v_lshlrev_b32_e32 v146, 16, v0
	v_and_b32_e32 v147, 0xffff0000, v0
	v_lshlrev_b32_e32 v144, 16, v145
	v_and_b32_e32 v145, 0xffff0000, v145
	v_pk_add_f32 v[134:135], v[44:45], v[134:135]
	v_pk_add_f32 v[136:137], v[42:43], v[136:137]
	v_cvt_pk_bf16_f32 v149, v134, v135
	v_pk_add_f32 v[144:145], v[36:37], v[144:145]
	s_waitcnt lgkmcnt(0)
	v_cvt_pk_bf16_f32 v148, v136, v137
	v_pk_add_f32 v[146:147], v[34:35], v[146:147]
	v_cvt_pk_bf16_f32 v151, v144, v145
	s_waitcnt vmcnt(2)
	v_mov_b32_e32 v0, v132
	v_cvt_pk_bf16_f32 v150, v146, v147
	v_permlane16_swap_b32_e32 v149, v151
	v_permlane16_swap_b32_e32 v148, v150
	global_store_dwordx4 v[156:157], v[148:151], off sc1
	v_permlane16_swap_b32_e32 v130, v0
	s_nop 0
	v_mov_b32_e32 v149, v133
	s_nop 1
	v_permlane16_swap_b32_e32 v131, v149
	v_lshlrev_b32_e32 v132, 16, v130
	v_and_b32_e32 v133, 0xffff0000, v130
	v_lshlrev_b32_e32 v130, 16, v131
	v_and_b32_e32 v131, 0xffff0000, v131
	v_lshlrev_b32_e32 v150, 16, v0
	v_and_b32_e32 v151, 0xffff0000, v0
	v_lshlrev_b32_e32 v148, 16, v149
	v_and_b32_e32 v149, 0xffff0000, v149
	v_pk_add_f32 v[130:131], v[48:49], v[130:131]
	v_pk_add_f32 v[132:133], v[46:47], v[132:133]
	v_cvt_pk_bf16_f32 v153, v130, v131
	v_pk_add_f32 v[148:149], v[40:41], v[148:149]
	v_cvt_pk_bf16_f32 v152, v132, v133
	v_pk_add_f32 v[150:151], v[38:39], v[150:151]
	v_cvt_pk_bf16_f32 v155, v148, v149
	s_and_b64 vcc, exec, s[10:11]
	v_cvt_pk_bf16_f32 v154, v150, v151
	v_permlane16_swap_b32_e32 v153, v155
	v_permlane16_swap_b32_e32 v152, v154
	global_store_dwordx4 v[156:157], v[152:155], off offset:256 sc1
	s_cbranch_vccnz .LBB0_875
	v_mul_f32_e32 v0, v137, v137
	v_mul_f32_e32 v135, v135, v135
	v_fmac_f32_e32 v0, v136, v136
	v_fmac_f32_e32 v135, v134, v134
	v_add_f32_e32 v0, v0, v135
	v_mul_f32_e32 v134, v147, v147
	v_mul_f32_e32 v135, v145, v145
	v_fmac_f32_e32 v134, v146, v146
	v_fmac_f32_e32 v135, v144, v144
	v_mul_f32_e32 v133, v133, v133
	v_mul_f32_e32 v131, v131, v131
	v_add_f32_e32 v134, v134, v135
	v_fmac_f32_e32 v133, v132, v132
	v_fmac_f32_e32 v131, v130, v130
	v_add_f32_e32 v0, v0, v134
	v_add_f32_e32 v130, v133, v131
	v_add_f32_e32 v0, v0, v130
	v_mul_f32_e32 v130, v151, v151
	v_mul_f32_e32 v131, v149, v149
	v_fmac_f32_e32 v130, v150, v150
	v_fmac_f32_e32 v131, v148, v148
	v_add_f32_e32 v130, v130, v131
	v_add_f32_e32 v0, v130, v0
	ds_bpermute_b32 v130, v241, v0
	s_waitcnt lgkmcnt(0)
	v_add_f32_e32 v0, v0, v130
	ds_bpermute_b32 v130, v242, v0
	s_and_saveexec_b64 s[0:1], s[6:7]
	s_cbranch_execz .LBB0_874
	s_waitcnt lgkmcnt(0)
	v_add_f32_e32 v0, v0, v130
	v_lshl_add_u64 v[130:131], s[38:39], 0, v[142:143]
	v_readlane_b32 s18, v252, 23
	s_lshl_b32 s2, s87, 2
	v_lshlrev_b64 v[130:131], 6, v[130:131]
	v_readlane_b32 s19, v252, 24
	s_ashr_i32 s3, s2, 31
	s_lshl_b32 s94, s65, 2
	v_lshl_add_u64 v[130:131], s[18:19], 0, v[130:131]
	v_lshl_add_u64 v[130:131], s[2:3], 2, v[130:131]
	v_lshl_add_u64 v[130:131], v[130:131], 0, s[94:95]
	global_store_dword v[130:131], v0, off

; __device__ __forceinline__ unsigned cvt_pk_bf16(float lo, float hi) { unsigned r; asm("v_cvt_pk_bf16_f32 %0, %1, %2" : "=v"(r) : "v"(lo), "v"(hi)); return r; }
; __device__ __forceinline__ float bf_lo(unsigned w) { return __uint_as_float(w << 16); }
; __device__ __forceinline__ float bf_hi(unsigned w) { return __uint_as_float(w & 0xffff0000u); }
;     __device__ __forceinline__ void operator()(const f32x4 (&acc)[2][2][4][2], const Unit& u, int wr, int wc, int fr, int fq) const {
;     ...
;                 for (int mm = 0; mm < 2; ++mm) { const int m = mb + mm; const bf16* rp = (const bf16*)(ws + WS_XB) + (size_t)(row0 + ai * 128 + m * 16) * D + colw;
; #pragma unroll
;                     for (int bj = 0; bj < 2; ++bj) xv[mm][bj] = *(const v4u*)(rp + bj * 128); }
; #pragma unroll
;                 for (int mm = 0; mm < 2; ++mm) { const int m = mb + mm;
;                     const int row = row0 + ai * 128 + m * 16;
;                     bf16* xb = (bf16*)(ws + WS_XB) + (size_t)row * D + colw;
;                     float ssq = 0.f;
; #pragma unroll
;                     for (int bj = 0; bj < 2; ++bj) {
;                         const auto s0 = __builtin_amdgcn_permlane16_swap(xv[mm][bj].x, xv[mm][bj].z, false, false), s1 = __builtin_amdgcn_permlane16_swap(xv[mm][bj].y, xv[mm][bj].w, false, false);
;                         const unsigned xn[2][2] = {{s0[0], s1[0]}, {s0[1], s1[1]}};
;                         unsigned wn[2][2];
; #pragma unroll
;                         for (int n = 0; n < 2; ++n) {
;                             const f32x4 v = (f32x4){bf_lo(xn[n][0]), bf_hi(xn[n][0]), bf_lo(xn[n][1]), bf_hi(xn[n][1])} + acc[ai][bj][m][n] * amul;
;                             wn[n][0] = cvt_pk_bf16(v.x, v.y); wn[n][1] = cvt_pk_bf16(v.z, v.w);
;                             if (slot >= 0) ssq += (v.x * v.x + v.y * v.y) + (v.z * v.z + v.w * v.w); }
;                         const auto t0 = __builtin_amdgcn_permlane16_swap(wn[0][0], wn[1][0], false, false), t1 = __builtin_amdgcn_permlane16_swap(wn[0][1], wn[1][1], false, false);
;                         *(v4u*)(xb + bj * 128) = (v4u){t0[0], t1[0], t0[1], t1[1]};
;                     }
;                     if (slot >= 0) { ssq += shfl_xor_l(ssq, 16, fq * 16 + fr); ssq += shfl_xor_l(ssq, 32, fq * 16 + fr); if (fq == 0) ((float*)(ws + WS_SS))[((size_t)slot * M + row) * 16 + u.pn * 4 + wc] = ssq; }
.LBB0_875:
	v_add_u32_e32 v146, 0xa0, v210
	v_ashrrev_i32_e32 v147, 31, v146
	v_lshlrev_b64 v[152:153], 11, v[146:147]
	s_waitcnt lgkmcnt(0)
	v_lshl_add_u64 v[130:131], v[140:141], 0, v[152:153]
	global_load_dwordx4 v[148:151], v[130:131], off
	global_load_dwordx4 v[154:157], v[130:131], off offset:256
	v_add_u32_e32 v142, 0xb0, v210
	v_ashrrev_i32_e32 v143, 31, v142
	v_lshlrev_b64 v[144:145], 11, v[142:143]
	v_lshl_add_u64 v[130:131], v[140:141], 0, v[144:145]
	global_load_dwordx4 v[134:137], v[130:131], off
	s_nop 0
	global_load_dwordx4 v[130:133], v[130:131], off offset:256
	v_lshl_add_u64 v[140:141], s[90:91], 0, v[152:153]
	v_lshl_add_u64 v[166:167], v[138:139], 1, v[140:141]
	s_and_b64 vcc, exec, s[10:11]
	s_waitcnt vmcnt(3)
	v_mov_b32_e32 v0, v150
	v_mov_b32_e32 v160, v151
	s_nop 0
	v_permlane16_swap_b32_e32 v148, v0
	v_permlane16_swap_b32_e32 v149, v160
	v_lshlrev_b32_e32 v150, 16, v148
	v_and_b32_e32 v151, 0xffff0000, v148
	v_lshlrev_b32_e32 v140, 16, v149
	v_and_b32_e32 v141, 0xffff0000, v149
	v_lshlrev_b32_e32 v152, 16, v0
	v_and_b32_e32 v153, 0xffff0000, v0
	v_lshlrev_b32_e32 v148, 16, v160
	v_and_b32_e32 v149, 0xffff0000, v160
	s_waitcnt vmcnt(2)
	v_mov_b32_e32 v0, v156
	v_pk_add_f32 v[140:141], v[28:29], v[140:141]
	v_pk_add_f32 v[150:151], v[26:27], v[150:151]
	v_cvt_pk_bf16_f32 v159, v140, v141
	v_pk_add_f32 v[148:149], v[20:21], v[148:149]
	v_cvt_pk_bf16_f32 v158, v150, v151
	v_pk_add_f32 v[152:153], v[18:19], v[152:153]
	v_cvt_pk_bf16_f32 v161, v148, v149
	v_permlane16_swap_b32_e32 v154, v0
	v_cvt_pk_bf16_f32 v160, v152, v153
	v_mov_b32_e32 v164, v157
	v_permlane16_swap_b32_e32 v158, v160
	v_permlane16_swap_b32_e32 v159, v161
	v_permlane16_swap_b32_e32 v155, v164
	v_lshlrev_b32_e32 v156, 16, v154
	v_and_b32_e32 v157, 0xffff0000, v154
	global_store_dwordx4 v[166:167], v[158:161], off sc1
	v_lshlrev_b32_e32 v154, 16, v155
	v_and_b32_e32 v155, 0xffff0000, v155
	v_pk_add_f32 v[158:159], v[30:31], v[156:157]
	v_lshlrev_b32_e32 v160, 16, v0
	v_and_b32_e32 v161, 0xffff0000, v0
	v_lshlrev_b32_e32 v156, 16, v164
	v_and_b32_e32 v157, 0xffff0000, v164
	v_pk_add_f32 v[154:155], v[32:33], v[154:155]
	v_cvt_pk_bf16_f32 v162, v158, v159
	v_pk_add_f32 v[156:157], v[24:25], v[156:157]
	v_cvt_pk_bf16_f32 v163, v154, v155
	v_pk_add_f32 v[160:161], v[22:23], v[160:161]
	v_cvt_pk_bf16_f32 v165, v156, v157
	s_nop 0
	v_cvt_pk_bf16_f32 v164, v160, v161
	v_permlane16_swap_b32_e32 v163, v165
	v_permlane16_swap_b32_e32 v162, v164
	global_store_dwordx4 v[166:167], v[162:165], off offset:256 sc1
	s_cbranch_vccnz .LBB0_879
	v_mul_f32_e32 v0, v151, v151
	v_mul_f32_e32 v141, v141, v141
	v_fmac_f32_e32 v0, v150, v150
	v_fmac_f32_e32 v141, v140, v140
	v_add_f32_e32 v0, v0, v141
	v_mul_f32_e32 v140, v153, v153
	v_mul_f32_e32 v141, v149, v149
	v_fmac_f32_e32 v140, v152, v152
	v_fmac_f32_e32 v141, v148, v148
	v_add_f32_e32 v140, v140, v141
	v_add_f32_e32 v0, v0, v140
	v_mul_f32_e32 v140, v159, v159
	v_mul_f32_e32 v141, v155, v155
	v_fmac_f32_e32 v140, v158, v158
	v_fmac_f32_e32 v141, v154, v154
	v_add_f32_e32 v140, v140, v141
	v_add_f32_e32 v0, v0, v140
	v_mul_f32_e32 v140, v161, v161
	v_mul_f32_e32 v141, v157, v157
	v_fmac_f32_e32 v140, v160, v160
	v_fmac_f32_e32 v141, v156, v156
	v_add_f32_e32 v140, v140, v141
	v_add_f32_e32 v0, v140, v0
	ds_bpermute_b32 v140, v241, v0
	s_waitcnt lgkmcnt(0)
	v_add_f32_e32 v0, v0, v140
	ds_bpermute_b32 v140, v242, v0
	s_and_saveexec_b64 s[0:1], s[6:7]
	s_cbranch_execz .LBB0_878
	s_waitcnt lgkmcnt(0)
	v_add_f32_e32 v0, v0, v140
	v_lshl_add_u64 v[140:141], s[38:39], 0, v[146:147]
	v_readlane_b32 s18, v252, 23
	s_lshl_b32 s2, s87, 2
	v_lshlrev_b64 v[140:141], 6, v[140:141]
	v_readlane_b32 s19, v252, 24
	s_ashr_i32 s3, s2, 31
	s_lshl_b32 s94, s65, 2
	v_lshl_add_u64 v[140:141], s[18:19], 0, v[140:141]
	v_lshl_add_u64 v[140:141], s[2:3], 2, v[140:141]
	v_lshl_add_u64 v[140:141], v[140:141], 0, s[94:95]
	global_store_dword v[140:141], v0, off

; __device__ __forceinline__ unsigned cvt_pk_bf16(float lo, float hi) { unsigned r; asm("v_cvt_pk_bf16_f32 %0, %1, %2" : "=v"(r) : "v"(lo), "v"(hi)); return r; }
; __device__ __forceinline__ float bf_lo(unsigned w) { return __uint_as_float(w << 16); }
; __device__ __forceinline__ float bf_hi(unsigned w) { return __uint_as_float(w & 0xffff0000u); }
; __device__ __forceinline__ float shfl_xor_l(float v, int m, int lane) { return __int_as_float(__builtin_amdgcn_ds_bpermute((lane ^ m) << 2, __float_as_int(v))); }
;     __device__ __forceinline__ void operator()(const f32x4 (&acc)[2][2][4][2], const Unit& u, int wr, int wc, int fr, int fq) const {
;     ...
;                 for (int mm = 0; mm < 2; ++mm) { const int m = mb + mm;
;                     const int row = row0 + ai * 128 + m * 16;
;                     bf16* xb = (bf16*)(ws + WS_XB) + (size_t)row * D + colw;
;                     float ssq = 0.f;
; #pragma unroll
;                     for (int bj = 0; bj < 2; ++bj) {
;                         const auto s0 = __builtin_amdgcn_permlane16_swap(xv[mm][bj].x, xv[mm][bj].z, false, false), s1 = __builtin_amdgcn_permlane16_swap(xv[mm][bj].y, xv[mm][bj].w, false, false);
;                         const unsigned xn[2][2] = {{s0[0], s1[0]}, {s0[1], s1[1]}};
;                         unsigned wn[2][2];
; #pragma unroll
;                         for (int n = 0; n < 2; ++n) {
;                             const f32x4 v = (f32x4){bf_lo(xn[n][0]), bf_hi(xn[n][0]), bf_lo(xn[n][1]), bf_hi(xn[n][1])} + acc[ai][bj][m][n] * amul;
;                             wn[n][0] = cvt_pk_bf16(v.x, v.y); wn[n][1] = cvt_pk_bf16(v.z, v.w);
;                             if (slot >= 0) ssq += (v.x * v.x + v.y * v.y) + (v.z * v.z + v.w * v.w); }
;                         const auto t0 = __builtin_amdgcn_permlane16_swap(wn[0][0], wn[1][0], false, false), t1 = __builtin_amdgcn_permlane16_swap(wn[0][1], wn[1][1], false, false);
;                         *(v4u*)(xb + bj * 128) = (v4u){t0[0], t1[0], t0[1], t1[1]};
;                     }
;                     if (slot >= 0) { ssq += shfl_xor_l(ssq, 16, fq * 16 + fr); ssq += shfl_xor_l(ssq, 32, fq * 16 + fr); if (fq == 0) ((float*)(ws + WS_SS))[((size_t)slot * M + row) * 16 + u.pn * 4 + wc] = ssq; }
.LBB0_879:
	s_waitcnt lgkmcnt(0)
	v_lshl_add_u64 v[140:141], s[90:91], 0, v[144:145]
	v_lshl_add_u64 v[152:153], v[138:139], 1, v[140:141]
	s_waitcnt vmcnt(3)
	v_mov_b32_e32 v0, v136
	v_mov_b32_e32 v139, v137
	s_nop 0
	v_permlane16_swap_b32_e32 v134, v0
	v_permlane16_swap_b32_e32 v135, v139
	v_lshlrev_b32_e32 v136, 16, v134
	v_and_b32_e32 v137, 0xffff0000, v134
	v_lshlrev_b32_e32 v134, 16, v135
	v_and_b32_e32 v135, 0xffff0000, v135
	v_lshlrev_b32_e32 v140, 16, v0
	v_and_b32_e32 v141, 0xffff0000, v0
	v_lshlrev_b32_e32 v138, 16, v139
	v_and_b32_e32 v139, 0xffff0000, v139
	v_pk_add_f32 v[134:135], v[12:13], v[134:135]
	v_pk_add_f32 v[136:137], v[10:11], v[136:137]
	v_cvt_pk_bf16_f32 v145, v134, v135
	v_pk_add_f32 v[138:139], v[8:9], v[138:139]
	v_cvt_pk_bf16_f32 v144, v136, v137
	v_pk_add_f32 v[140:141], v[6:7], v[140:141]
	v_cvt_pk_bf16_f32 v147, v138, v139
	s_waitcnt vmcnt(2)
	v_mov_b32_e32 v0, v132
	v_cvt_pk_bf16_f32 v146, v140, v141
	v_permlane16_swap_b32_e32 v145, v147
	v_permlane16_swap_b32_e32 v144, v146
	global_store_dwordx4 v[152:153], v[144:147], off sc1
	v_permlane16_swap_b32_e32 v130, v0
	s_nop 0
	v_mov_b32_e32 v145, v133
	s_nop 1
	v_permlane16_swap_b32_e32 v131, v145
	v_lshlrev_b32_e32 v132, 16, v130
	v_and_b32_e32 v133, 0xffff0000, v130
	v_lshlrev_b32_e32 v130, 16, v131
	v_and_b32_e32 v131, 0xffff0000, v131
	v_lshlrev_b32_e32 v146, 16, v0
	v_and_b32_e32 v147, 0xffff0000, v0
	v_lshlrev_b32_e32 v144, 16, v145
	v_and_b32_e32 v145, 0xffff0000, v145
	v_pk_add_f32 v[130:131], v[16:17], v[130:131]
	v_pk_add_f32 v[132:133], v[14:15], v[132:133]
	v_cvt_pk_bf16_f32 v149, v130, v131
	v_pk_add_f32 v[144:145], v[4:5], v[144:145]
	v_cvt_pk_bf16_f32 v148, v132, v133
	v_pk_add_f32 v[146:147], v[2:3], v[146:147]
	v_cvt_pk_bf16_f32 v151, v144, v145
	s_and_b64 vcc, exec, s[10:11]
	v_cvt_pk_bf16_f32 v150, v146, v147
	v_permlane16_swap_b32_e32 v149, v151
	v_permlane16_swap_b32_e32 v148, v150
	global_store_dwordx4 v[152:153], v[148:151], off offset:256 sc1
	s_cbranch_vccnz .LBB0_883
	v_mul_f32_e32 v0, v137, v137
	v_mul_f32_e32 v135, v135, v135
	v_fmac_f32_e32 v0, v136, v136
	v_fmac_f32_e32 v135, v134, v134
	v_add_f32_e32 v0, v0, v135
	v_mul_f32_e32 v134, v141, v141
	v_mul_f32_e32 v135, v139, v139
	v_fmac_f32_e32 v134, v140, v140
	v_fmac_f32_e32 v135, v138, v138
	v_mul_f32_e32 v133, v133, v133
	v_mul_f32_e32 v131, v131, v131
	v_add_f32_e32 v134, v134, v135
	v_fmac_f32_e32 v133, v132, v132
	v_fmac_f32_e32 v131, v130, v130
	v_add_f32_e32 v0, v0, v134
	v_add_f32_e32 v130, v133, v131
	v_add_f32_e32 v0, v0, v130
	v_mul_f32_e32 v130, v147, v147
	v_mul_f32_e32 v131, v145, v145
	v_fmac_f32_e32 v130, v146, v146
	v_fmac_f32_e32 v131, v144, v144
	v_add_f32_e32 v130, v130, v131
	v_add_f32_e32 v0, v130, v0
	ds_bpermute_b32 v130, v241, v0
	s_waitcnt lgkmcnt(0)
	v_add_f32_e32 v0, v0, v130
	ds_bpermute_b32 v130, v242, v0
	s_and_saveexec_b64 s[0:1], s[6:7]
	s_cbranch_execz .LBB0_882
	s_waitcnt lgkmcnt(0)
	v_add_f32_e32 v0, v0, v130
	v_lshl_add_u64 v[130:131], s[38:39], 0, v[142:143]
	v_readlane_b32 s10, v252, 23
	s_lshl_b32 s2, s87, 2
	v_lshlrev_b64 v[130:131], 6, v[130:131]
	v_readlane_b32 s11, v252, 24
	s_ashr_i32 s3, s2, 31
	s_lshl_b32 s94, s65, 2
	v_lshl_add_u64 v[130:131], s[10:11], 0, v[130:131]
	v_lshl_add_u64 v[130:131], s[2:3], 2, v[130:131]
	v_lshl_add_u64 v[130:131], v[130:131], 0, s[94:95]
	global_store_dword v[130:131], v0, off

; __device__ __forceinline__ v4u pack8(const float (&f)[8]) { v4u w; w.x = cvt_pk_bf16(f[0], f[1]); w.y = cvt_pk_bf16(f[2], f[3]); w.z = cvt_pk_bf16(f[4], f[5]); w.w = cvt_pk_bf16(f[6], f[7]); return w; }
; __device__ __forceinline__ float sigmoidf_(float x) { return rcpf_(1.f + __expf(-x)); }
; __device__ __forceinline__ float tanhf_(float x) { return 1.f - 2.f * rcpf_(1.f + __expf(2.f * x)); }
;     __device__ __forceinline__ void operator()(const f32x4 (&acc)[2][2][4][2], const Unit& u, int wr, int wc, int fr, int fq) const {
;     ...
;                             for (int m = 0; m < 4; ++m) if (rrow[ai][m] >= 0) { float o[8];
; #pragma unroll
;                                 for (int n = 0; n < 2; ++n)
; #pragma unroll
;                                     for (int j = 0; j < 4; ++j) { const float x = acc[ai][bj][m][n][j]; o[n * 4 + j] = kd == 1 ? tanhf_(x) : (kd == 2 ? sigmoidf_(x) : x); }
;                                 *(v4u*)(A2 + (size_t)rrow[ai][m] * KL2 + c) = pack8(o); }
.LBB0_936:
	s_or_b64 exec, exec, s[44:45]
	v_mad_u64_u32 v[152:153], s[18:19], v142, s83, v[146:147]
	v_cvt_pk_bf16_f32 v148, v0, v133
	v_cvt_pk_bf16_f32 v149, v135, v137
	v_cvt_pk_bf16_f32 v150, v139, v141
	v_cvt_pk_bf16_f32 v151, v143, v145
	global_store_dwordx4 v[152:153], v[148:151], off sc1
	s_or_b64 exec, exec, s[10:11]
	v_cmp_lt_i32_e32 vcc, -1, v140
	s_and_saveexec_b64 s[10:11], vcc
	s_cbranch_execnz .LBB0_695

; __device__ __forceinline__ v4u pack8(const float (&f)[8]) { v4u w; w.x = cvt_pk_bf16(f[0], f[1]); w.y = cvt_pk_bf16(f[2], f[3]); w.z = cvt_pk_bf16(f[4], f[5]); w.w = cvt_pk_bf16(f[6], f[7]); return w; }
; __device__ __forceinline__ float sigmoidf_(float x) { return rcpf_(1.f + __expf(-x)); }
; __device__ __forceinline__ float tanhf_(float x) { return 1.f - 2.f * rcpf_(1.f + __expf(2.f * x)); }
;     __device__ __forceinline__ void operator()(const f32x4 (&acc)[2][2][4][2], const Unit& u, int wr, int wc, int fr, int fq) const {
;     ...
;                             for (int m = 0; m < 4; ++m) if (rrow[ai][m] >= 0) { float o[8];
; #pragma unroll
;                                 for (int n = 0; n < 2; ++n)
; #pragma unroll
;                                     for (int j = 0; j < 4; ++j) { const float x = acc[ai][bj][m][n][j]; o[n * 4 + j] = kd == 1 ? tanhf_(x) : (kd == 2 ? sigmoidf_(x) : x); }
;                                 *(v4u*)(A2 + (size_t)rrow[ai][m] * KL2 + c) = pack8(o); }
.LBB0_986:
	s_or_b64 exec, exec, s[44:45]
	v_mad_u64_u32 v[152:153], s[18:19], v138, s83, v[146:147]
	v_cvt_pk_bf16_f32 v148, v0, v133
	v_cvt_pk_bf16_f32 v149, v135, v137
	v_cvt_pk_bf16_f32 v150, v139, v141
	v_cvt_pk_bf16_f32 v151, v143, v145
	global_store_dwordx4 v[152:153], v[148:151], off sc1
	s_or_b64 exec, exec, s[10:11]
	v_cmp_lt_i32_e32 vcc, -1, v136
	s_and_saveexec_b64 s[10:11], vcc
	s_cbranch_execnz .LBB0_745

; __device__ __forceinline__ v4u pack8(const float (&f)[8]) { v4u w; w.x = cvt_pk_bf16(f[0], f[1]); w.y = cvt_pk_bf16(f[2], f[3]); w.z = cvt_pk_bf16(f[4], f[5]); w.w = cvt_pk_bf16(f[6], f[7]); return w; }
; __device__ __forceinline__ float sigmoidf_(float x) { return rcpf_(1.f + __expf(-x)); }
; __device__ __forceinline__ float tanhf_(float x) { return 1.f - 2.f * rcpf_(1.f + __expf(2.f * x)); }
;     __device__ __forceinline__ void operator()(const f32x4 (&acc)[2][2][4][2], const Unit& u, int wr, int wc, int fr, int fq) const {
;     ...
;                             for (int m = 0; m < 4; ++m) if (rrow[ai][m] >= 0) { float o[8];
; #pragma unroll
;                                 for (int n = 0; n < 2; ++n)
; #pragma unroll
;                                     for (int j = 0; j < 4; ++j) { const float x = acc[ai][bj][m][n][j]; o[n * 4 + j] = kd == 1 ? tanhf_(x) : (kd == 2 ? sigmoidf_(x) : x); }
;                                 *(v4u*)(A2 + (size_t)rrow[ai][m] * KL2 + c) = pack8(o); }
.LBB0_1036:
	s_or_b64 exec, exec, s[44:45]
	v_mad_u64_u32 v[152:153], s[18:19], v134, s83, v[146:147]
	v_cvt_pk_bf16_f32 v148, v0, v133
	v_cvt_pk_bf16_f32 v149, v135, v137
	v_cvt_pk_bf16_f32 v150, v139, v141
	v_cvt_pk_bf16_f32 v151, v143, v145
	global_store_dwordx4 v[152:153], v[148:151], off sc1
	s_or_b64 exec, exec, s[10:11]
	v_cmp_lt_i32_e32 vcc, -1, v132
	s_and_saveexec_b64 s[10:11], vcc
	s_cbranch_execnz .LBB0_795

; __device__ __forceinline__ v4u pack8(const float (&f)[8]) { v4u w; w.x = cvt_pk_bf16(f[0], f[1]); w.y = cvt_pk_bf16(f[2], f[3]); w.z = cvt_pk_bf16(f[4], f[5]); w.w = cvt_pk_bf16(f[6], f[7]); return w; }
; __device__ __forceinline__ float sigmoidf_(float x) { return rcpf_(1.f + __expf(-x)); }
; __device__ __forceinline__ float tanhf_(float x) { return 1.f - 2.f * rcpf_(1.f + __expf(2.f * x)); }
;     __device__ __forceinline__ void operator()(const f32x4 (&acc)[2][2][4][2], const Unit& u, int wr, int wc, int fr, int fq) const {
;     ...
;                 for (int bj = 0; bj < 2; ++bj) {
;                     const int c = (u.pn - 12) * 256 + bj * 128 + cw;
;                     if (c < KL2) {
;                         const int kd = c < 64 ? 1 : ((c >= 128 && c < 288) ? 2 : 0);
; #pragma unroll
;                         for (int ai = 0; ai < 2; ++ai)
; #pragma unroll
;                             for (int m = 0; m < 4; ++m) if (rrow[ai][m] >= 0) { float o[8];
; #pragma unroll
;                                 for (int n = 0; n < 2; ++n)
; #pragma unroll
;                                     for (int j = 0; j < 4; ++j) { const float x = acc[ai][bj][m][n][j]; o[n * 4 + j] = kd == 1 ? tanhf_(x) : (kd == 2 ? sigmoidf_(x) : x); }
;                                 *(v4u*)(A2 + (size_t)rrow[ai][m] * KL2 + c) = pack8(o); }
.LBB0_1086:
	s_or_b64 exec, exec, s[10:11]
	v_mad_u64_u32 v[146:147], s[10:11], v130, s83, v[146:147]
	v_cvt_pk_bf16_f32 v148, v0, v133
	v_cvt_pk_bf16_f32 v149, v135, v137
	v_cvt_pk_bf16_f32 v150, v139, v141
	v_cvt_pk_bf16_f32 v151, v143, v145
	global_store_dwordx4 v[146:147], v[148:151], off sc1
.LBB0_1087:
	s_or_b64 exec, exec, s[0:1]
	v_add_u32_e32 v0, s13, v240
	s_movk_i32 s0, 0x180
	v_cmp_gt_i32_e32 vcc, s0, v0
	s_and_saveexec_b64 s[10:11], vcc
	s_cbranch_execz .LBB0_1104
	v_add_u32_e32 v131, 0xffffff80, v0
	s_movk_i32 s0, 0xa0
	v_cmp_gt_u32_e32 vcc, s0, v131
	v_readlane_b32 s0, v252, 16
	v_readlane_b32 s1, v252, 17
	s_nop 1
	v_lshl_add_u64 v[146:147], v[0:1], 1, s[0:1]
	v_cmp_lt_i32_e64 s[0:1], -1, v144
	s_and_saveexec_b64 s[44:45], s[0:1]
	s_cbranch_execz .LBB0_1096
	v_mul_f32_e32 v0, 0xbfb8aa3b, v126
	v_mul_f32_e32 v131, 0xbfb8aa3b, v127
	v_mul_f32_e32 v133, 0xbfb8aa3b, v128
	v_mul_f32_e32 v135, 0xbfb8aa3b, v129
	v_mul_f32_e32 v137, 0xbfb8aa3b, v118
	v_mul_f32_e32 v139, 0xbfb8aa3b, v119
	v_mul_f32_e32 v141, 0xbfb8aa3b, v120
	v_mul_f32_e32 v143, 0xbfb8aa3b, v121
	v_exp_f32_e32 v0, v0
	v_exp_f32_e32 v131, v131
	v_exp_f32_e32 v133, v133
	v_exp_f32_e32 v135, v135
	v_exp_f32_e32 v137, v137
	v_exp_f32_e32 v139, v139
	v_exp_f32_e32 v141, v141
	v_exp_f32_e32 v143, v143
	v_add_f32_e32 v0, 1.0, v0
	v_add_f32_e32 v131, 1.0, v131
	v_add_f32_e32 v133, 1.0, v133
	v_add_f32_e32 v135, 1.0, v135
	v_add_f32_e32 v137, 1.0, v137
	v_add_f32_e32 v139, 1.0, v139
	v_add_f32_e32 v141, 1.0, v141
	v_add_f32_e32 v143, 1.0, v143
	v_rcp_f32_e32 v0, v0
	v_rcp_f32_e32 v131, v131
	v_rcp_f32_e32 v133, v133
	v_rcp_f32_e32 v135, v135
	v_rcp_f32_e32 v137, v137
	v_rcp_f32_e32 v139, v139
	v_rcp_f32_e32 v141, v141
	v_rcp_f32_e32 v143, v143
	v_mad_u64_u32 v[152:153], s[0:1], v144, s83, v[146:147]
	v_cndmask_b32_e32 v0, v126, v0, vcc
	v_cndmask_b32_e32 v131, v127, v131, vcc
	v_cndmask_b32_e32 v133, v128, v133, vcc
	v_cndmask_b32_e32 v135, v129, v135, vcc
	v_cndmask_b32_e32 v137, v118, v137, vcc
	v_cndmask_b32_e32 v139, v119, v139, vcc
	v_cndmask_b32_e32 v141, v120, v141, vcc
	v_cndmask_b32_e32 v143, v121, v143, vcc
	v_cvt_pk_bf16_f32 v148, v0, v131
	v_cvt_pk_bf16_f32 v149, v133, v135
	v_cvt_pk_bf16_f32 v150, v137, v139
	v_cvt_pk_bf16_f32 v151, v141, v143
	global_store_dwordx4 v[152:153], v[148:151], off sc1
	s_or_b64 exec, exec, s[44:45]
	v_cmp_lt_i32_e64 s[0:1], -1, v142
	s_and_saveexec_b64 s[44:45], s[0:1]
	s_cbranch_execnz .LBB0_1097

; __device__ __forceinline__ v4u pack8(const float (&f)[8]) { v4u w; w.x = cvt_pk_bf16(f[0], f[1]); w.y = cvt_pk_bf16(f[2], f[3]); w.z = cvt_pk_bf16(f[4], f[5]); w.w = cvt_pk_bf16(f[6], f[7]); return w; }
; __device__ __forceinline__ float sigmoidf_(float x) { return rcpf_(1.f + __expf(-x)); }
; __device__ __forceinline__ float tanhf_(float x) { return 1.f - 2.f * rcpf_(1.f + __expf(2.f * x)); }
;     __device__ __forceinline__ void operator()(const f32x4 (&acc)[2][2][4][2], const Unit& u, int wr, int wc, int fr, int fq) const {
;     ...
;                             for (int m = 0; m < 4; ++m) if (rrow[ai][m] >= 0) { float o[8];
; #pragma unroll
;                                 for (int n = 0; n < 2; ++n)
; #pragma unroll
;                                     for (int j = 0; j < 4; ++j) { const float x = acc[ai][bj][m][n][j]; o[n * 4 + j] = kd == 1 ? tanhf_(x) : (kd == 2 ? sigmoidf_(x) : x); }
;                                 *(v4u*)(A2 + (size_t)rrow[ai][m] * KL2 + c) = pack8(o); }
.LBB0_1091:
	v_mul_f32_e32 v0, 0xbfb8aa3b, v94
	v_mul_f32_e32 v131, 0xbfb8aa3b, v95
	v_mul_f32_e32 v133, 0xbfb8aa3b, v96
	v_mul_f32_e32 v135, 0xbfb8aa3b, v97
	v_mul_f32_e32 v137, 0xbfb8aa3b, v86
	v_mul_f32_e32 v139, 0xbfb8aa3b, v87
	v_mul_f32_e32 v141, 0xbfb8aa3b, v88
	v_mul_f32_e32 v143, 0xbfb8aa3b, v89
	v_exp_f32_e32 v0, v0
	v_exp_f32_e32 v131, v131
	v_exp_f32_e32 v133, v133
	v_exp_f32_e32 v135, v135
	v_exp_f32_e32 v137, v137
	v_exp_f32_e32 v139, v139
	v_exp_f32_e32 v141, v141
	v_exp_f32_e32 v143, v143
	v_add_f32_e32 v0, 1.0, v0
	v_add_f32_e32 v131, 1.0, v131
	v_add_f32_e32 v133, 1.0, v133
	v_add_f32_e32 v135, 1.0, v135
	v_add_f32_e32 v137, 1.0, v137
	v_add_f32_e32 v139, 1.0, v139
	v_add_f32_e32 v141, 1.0, v141
	v_add_f32_e32 v143, 1.0, v143
	v_rcp_f32_e32 v0, v0
	v_rcp_f32_e32 v131, v131
	v_rcp_f32_e32 v133, v133
	v_rcp_f32_e32 v135, v135
	v_rcp_f32_e32 v137, v137
	v_rcp_f32_e32 v139, v139
	v_rcp_f32_e32 v141, v141
	v_rcp_f32_e32 v143, v143
	v_mad_u64_u32 v[152:153], s[0:1], v140, s83, v[146:147]
	v_cndmask_b32_e32 v0, v94, v0, vcc
	v_cndmask_b32_e32 v131, v95, v131, vcc
	v_cndmask_b32_e32 v133, v96, v133, vcc
	v_cndmask_b32_e32 v135, v97, v135, vcc
	v_cndmask_b32_e32 v137, v86, v137, vcc
	v_cndmask_b32_e32 v139, v87, v139, vcc
	v_cndmask_b32_e32 v141, v88, v141, vcc
	v_cndmask_b32_e32 v143, v89, v143, vcc
	v_cvt_pk_bf16_f32 v148, v0, v131
	v_cvt_pk_bf16_f32 v149, v133, v135
	v_cvt_pk_bf16_f32 v150, v137, v139
	v_cvt_pk_bf16_f32 v151, v141, v143
	global_store_dwordx4 v[152:153], v[148:151], off sc1
	s_or_b64 exec, exec, s[44:45]
	v_cmp_lt_i32_e64 s[0:1], -1, v138
	s_and_saveexec_b64 s[44:45], s[0:1]
	s_cbranch_execnz .LBB0_1099

; __device__ __forceinline__ v4u pack8(const float (&f)[8]) { v4u w; w.x = cvt_pk_bf16(f[0], f[1]); w.y = cvt_pk_bf16(f[2], f[3]); w.z = cvt_pk_bf16(f[4], f[5]); w.w = cvt_pk_bf16(f[6], f[7]); return w; }
; __device__ __forceinline__ float sigmoidf_(float x) { return rcpf_(1.f + __expf(-x)); }
; __device__ __forceinline__ float tanhf_(float x) { return 1.f - 2.f * rcpf_(1.f + __expf(2.f * x)); }
;     __device__ __forceinline__ void operator()(const f32x4 (&acc)[2][2][4][2], const Unit& u, int wr, int wc, int fr, int fq) const {
;     ...
;                             for (int m = 0; m < 4; ++m) if (rrow[ai][m] >= 0) { float o[8];
; #pragma unroll
;                                 for (int n = 0; n < 2; ++n)
; #pragma unroll
;                                     for (int j = 0; j < 4; ++j) { const float x = acc[ai][bj][m][n][j]; o[n * 4 + j] = kd == 1 ? tanhf_(x) : (kd == 2 ? sigmoidf_(x) : x); }
;                                 *(v4u*)(A2 + (size_t)rrow[ai][m] * KL2 + c) = pack8(o); }
.LBB0_1093:
	v_mul_f32_e32 v0, 0xbfb8aa3b, v62
	v_mul_f32_e32 v131, 0xbfb8aa3b, v63
	v_mul_f32_e32 v133, 0xbfb8aa3b, v64
	v_mul_f32_e32 v135, 0xbfb8aa3b, v65
	v_mul_f32_e32 v137, 0xbfb8aa3b, v54
	v_mul_f32_e32 v139, 0xbfb8aa3b, v55
	v_mul_f32_e32 v141, 0xbfb8aa3b, v56
	v_mul_f32_e32 v143, 0xbfb8aa3b, v57
	v_exp_f32_e32 v0, v0
	v_exp_f32_e32 v131, v131
	v_exp_f32_e32 v133, v133
	v_exp_f32_e32 v135, v135
	v_exp_f32_e32 v137, v137
	v_exp_f32_e32 v139, v139
	v_exp_f32_e32 v141, v141
	v_exp_f32_e32 v143, v143
	v_add_f32_e32 v0, 1.0, v0
	v_add_f32_e32 v131, 1.0, v131
	v_add_f32_e32 v133, 1.0, v133
	v_add_f32_e32 v135, 1.0, v135
	v_add_f32_e32 v137, 1.0, v137
	v_add_f32_e32 v139, 1.0, v139
	v_add_f32_e32 v141, 1.0, v141
	v_add_f32_e32 v143, 1.0, v143
	v_rcp_f32_e32 v0, v0
	v_rcp_f32_e32 v131, v131
	v_rcp_f32_e32 v133, v133
	v_rcp_f32_e32 v135, v135
	v_rcp_f32_e32 v137, v137
	v_rcp_f32_e32 v139, v139
	v_rcp_f32_e32 v141, v141
	v_rcp_f32_e32 v143, v143
	v_mad_u64_u32 v[152:153], s[0:1], v136, s83, v[146:147]
	v_cndmask_b32_e32 v0, v62, v0, vcc
	v_cndmask_b32_e32 v131, v63, v131, vcc
	v_cndmask_b32_e32 v133, v64, v133, vcc
	v_cndmask_b32_e32 v135, v65, v135, vcc
	v_cndmask_b32_e32 v137, v54, v137, vcc
	v_cndmask_b32_e32 v139, v55, v139, vcc
	v_cndmask_b32_e32 v141, v56, v141, vcc
	v_cndmask_b32_e32 v143, v57, v143, vcc
	v_cvt_pk_bf16_f32 v148, v0, v131
	v_cvt_pk_bf16_f32 v149, v133, v135
	v_cvt_pk_bf16_f32 v150, v137, v139
	v_cvt_pk_bf16_f32 v151, v141, v143
	global_store_dwordx4 v[152:153], v[148:151], off sc1
	s_or_b64 exec, exec, s[44:45]
	v_cmp_lt_i32_e64 s[0:1], -1, v134
	s_and_saveexec_b64 s[44:45], s[0:1]
	s_cbranch_execnz .LBB0_1101

; __device__ __forceinline__ v4u pack8(const float (&f)[8]) { v4u w; w.x = cvt_pk_bf16(f[0], f[1]); w.y = cvt_pk_bf16(f[2], f[3]); w.z = cvt_pk_bf16(f[4], f[5]); w.w = cvt_pk_bf16(f[6], f[7]); return w; }
; __device__ __forceinline__ float sigmoidf_(float x) { return rcpf_(1.f + __expf(-x)); }
; __device__ __forceinline__ float tanhf_(float x) { return 1.f - 2.f * rcpf_(1.f + __expf(2.f * x)); }
;     __device__ __forceinline__ void operator()(const f32x4 (&acc)[2][2][4][2], const Unit& u, int wr, int wc, int fr, int fq) const {
;     ...
;                             for (int m = 0; m < 4; ++m) if (rrow[ai][m] >= 0) { float o[8];
; #pragma unroll
;                                 for (int n = 0; n < 2; ++n)
; #pragma unroll
;                                     for (int j = 0; j < 4; ++j) { const float x = acc[ai][bj][m][n][j]; o[n * 4 + j] = kd == 1 ? tanhf_(x) : (kd == 2 ? sigmoidf_(x) : x); }
;                                 *(v4u*)(A2 + (size_t)rrow[ai][m] * KL2 + c) = pack8(o); }
.LBB0_1095:
	v_mul_f32_e32 v0, 0xbfb8aa3b, v30
	v_mul_f32_e32 v131, 0xbfb8aa3b, v31
	v_mul_f32_e32 v133, 0xbfb8aa3b, v32
	v_mul_f32_e32 v135, 0xbfb8aa3b, v33
	v_mul_f32_e32 v137, 0xbfb8aa3b, v22
	v_mul_f32_e32 v139, 0xbfb8aa3b, v23
	v_mul_f32_e32 v141, 0xbfb8aa3b, v24
	v_mul_f32_e32 v143, 0xbfb8aa3b, v25
	v_exp_f32_e32 v0, v0
	v_exp_f32_e32 v131, v131
	v_exp_f32_e32 v133, v133
	v_exp_f32_e32 v135, v135
	v_exp_f32_e32 v137, v137
	v_exp_f32_e32 v139, v139
	v_exp_f32_e32 v141, v141
	v_exp_f32_e32 v143, v143
	v_add_f32_e32 v0, 1.0, v0
	v_add_f32_e32 v131, 1.0, v131
	v_add_f32_e32 v133, 1.0, v133
	v_add_f32_e32 v135, 1.0, v135
	v_add_f32_e32 v137, 1.0, v137
	v_add_f32_e32 v139, 1.0, v139
	v_add_f32_e32 v141, 1.0, v141
	v_add_f32_e32 v143, 1.0, v143
	v_rcp_f32_e32 v0, v0
	v_rcp_f32_e32 v131, v131
	v_rcp_f32_e32 v133, v133
	v_rcp_f32_e32 v135, v135
	v_rcp_f32_e32 v137, v137
	v_rcp_f32_e32 v139, v139
	v_rcp_f32_e32 v141, v141
	v_rcp_f32_e32 v143, v143
	v_mad_u64_u32 v[152:153], s[0:1], v132, s83, v[146:147]
	v_cndmask_b32_e32 v0, v30, v0, vcc
	v_cndmask_b32_e32 v131, v31, v131, vcc
	v_cndmask_b32_e32 v133, v32, v133, vcc
	v_cndmask_b32_e32 v135, v33, v135, vcc
	v_cndmask_b32_e32 v137, v22, v137, vcc
	v_cndmask_b32_e32 v139, v23, v139, vcc
	v_cndmask_b32_e32 v141, v24, v141, vcc
	v_cndmask_b32_e32 v143, v25, v143, vcc
	v_cvt_pk_bf16_f32 v148, v0, v131
	v_cvt_pk_bf16_f32 v149, v133, v135
	v_cvt_pk_bf16_f32 v150, v137, v139
	v_cvt_pk_bf16_f32 v151, v141, v143
	global_store_dwordx4 v[152:153], v[148:151], off sc1
	s_or_b64 exec, exec, s[44:45]
	s_waitcnt lgkmcnt(0)
	v_cmp_lt_i32_e64 s[0:1], -1, v130
	s_and_b64 exec, exec, s[0:1]
	s_cbranch_execnz .LBB0_1103
	s_branch .LBB0_1104

; __device__ __forceinline__ v4u pack8(const float (&f)[8]) { v4u w; w.x = cvt_pk_bf16(f[0], f[1]); w.y = cvt_pk_bf16(f[2], f[3]); w.z = cvt_pk_bf16(f[4], f[5]); w.w = cvt_pk_bf16(f[6], f[7]); return w; }
; __device__ __forceinline__ float sigmoidf_(float x) { return rcpf_(1.f + __expf(-x)); }
; __device__ __forceinline__ float tanhf_(float x) { return 1.f - 2.f * rcpf_(1.f + __expf(2.f * x)); }
;     __device__ __forceinline__ void operator()(const f32x4 (&acc)[2][2][4][2], const Unit& u, int wr, int wc, int fr, int fq) const {
;     ...
;                             for (int m = 0; m < 4; ++m) if (rrow[ai][m] >= 0) { float o[8];
; #pragma unroll
;                                 for (int n = 0; n < 2; ++n)
; #pragma unroll
;                                     for (int j = 0; j < 4; ++j) { const float x = acc[ai][bj][m][n][j]; o[n * 4 + j] = kd == 1 ? tanhf_(x) : (kd == 2 ? sigmoidf_(x) : x); }
;                                 *(v4u*)(A2 + (size_t)rrow[ai][m] * KL2 + c) = pack8(o); }
.LBB0_1097:
	v_mul_f32_e32 v0, 0xbfb8aa3b, v110
	v_mul_f32_e32 v131, 0xbfb8aa3b, v111
	v_mul_f32_e32 v133, 0xbfb8aa3b, v112
	v_mul_f32_e32 v135, 0xbfb8aa3b, v113
	v_mul_f32_e32 v137, 0xbfb8aa3b, v102
	v_mul_f32_e32 v139, 0xbfb8aa3b, v103
	v_mul_f32_e32 v141, 0xbfb8aa3b, v104
	v_mul_f32_e32 v143, 0xbfb8aa3b, v105
	v_exp_f32_e32 v0, v0
	v_exp_f32_e32 v131, v131
	v_exp_f32_e32 v133, v133
	v_exp_f32_e32 v135, v135
	v_exp_f32_e32 v137, v137
	v_exp_f32_e32 v139, v139
	v_exp_f32_e32 v141, v141
	v_exp_f32_e32 v143, v143
	v_add_f32_e32 v0, 1.0, v0
	v_add_f32_e32 v131, 1.0, v131
	v_add_f32_e32 v133, 1.0, v133
	v_add_f32_e32 v135, 1.0, v135
	v_add_f32_e32 v137, 1.0, v137
	v_add_f32_e32 v139, 1.0, v139
	v_add_f32_e32 v141, 1.0, v141
	v_add_f32_e32 v143, 1.0, v143
	v_rcp_f32_e32 v0, v0
	v_rcp_f32_e32 v131, v131
	v_rcp_f32_e32 v133, v133
	v_rcp_f32_e32 v135, v135
	v_rcp_f32_e32 v137, v137
	v_rcp_f32_e32 v139, v139
	v_rcp_f32_e32 v141, v141
	v_rcp_f32_e32 v143, v143
	v_mad_u64_u32 v[152:153], s[0:1], v142, s83, v[146:147]
	v_cndmask_b32_e32 v0, v110, v0, vcc
	v_cndmask_b32_e32 v131, v111, v131, vcc
	v_cndmask_b32_e32 v133, v112, v133, vcc
	v_cndmask_b32_e32 v135, v113, v135, vcc
	v_cndmask_b32_e32 v137, v102, v137, vcc
	v_cndmask_b32_e32 v139, v103, v139, vcc
	v_cndmask_b32_e32 v141, v104, v141, vcc
	v_cndmask_b32_e32 v143, v105, v143, vcc
	v_cvt_pk_bf16_f32 v148, v0, v131
	v_cvt_pk_bf16_f32 v149, v133, v135
	v_cvt_pk_bf16_f32 v150, v137, v139
	v_cvt_pk_bf16_f32 v151, v141, v143
	global_store_dwordx4 v[152:153], v[148:151], off sc1
	s_or_b64 exec, exec, s[44:45]
	v_cmp_lt_i32_e64 s[0:1], -1, v140
	s_and_saveexec_b64 s[44:45], s[0:1]
	s_cbranch_execnz .LBB0_1091

; __device__ __forceinline__ v4u pack8(const float (&f)[8]) { v4u w; w.x = cvt_pk_bf16(f[0], f[1]); w.y = cvt_pk_bf16(f[2], f[3]); w.z = cvt_pk_bf16(f[4], f[5]); w.w = cvt_pk_bf16(f[6], f[7]); return w; }
; __device__ __forceinline__ float sigmoidf_(float x) { return rcpf_(1.f + __expf(-x)); }
; __device__ __forceinline__ float tanhf_(float x) { return 1.f - 2.f * rcpf_(1.f + __expf(2.f * x)); }
;     __device__ __forceinline__ void operator()(const f32x4 (&acc)[2][2][4][2], const Unit& u, int wr, int wc, int fr, int fq) const {
;     ...
;                             for (int m = 0; m < 4; ++m) if (rrow[ai][m] >= 0) { float o[8];
; #pragma unroll
;                                 for (int n = 0; n < 2; ++n)
; #pragma unroll
;                                     for (int j = 0; j < 4; ++j) { const float x = acc[ai][bj][m][n][j]; o[n * 4 + j] = kd == 1 ? tanhf_(x) : (kd == 2 ? sigmoidf_(x) : x); }
;                                 *(v4u*)(A2 + (size_t)rrow[ai][m] * KL2 + c) = pack8(o); }
.LBB0_1099:
	v_mul_f32_e32 v0, 0xbfb8aa3b, v78
	v_mul_f32_e32 v131, 0xbfb8aa3b, v79
	v_mul_f32_e32 v133, 0xbfb8aa3b, v80
	v_mul_f32_e32 v135, 0xbfb8aa3b, v81
	v_mul_f32_e32 v137, 0xbfb8aa3b, v70
	v_mul_f32_e32 v139, 0xbfb8aa3b, v71
	v_mul_f32_e32 v141, 0xbfb8aa3b, v72
	v_mul_f32_e32 v143, 0xbfb8aa3b, v73
	v_exp_f32_e32 v0, v0
	v_exp_f32_e32 v131, v131
	v_exp_f32_e32 v133, v133
	v_exp_f32_e32 v135, v135
	v_exp_f32_e32 v137, v137
	v_exp_f32_e32 v139, v139
	v_exp_f32_e32 v141, v141
	v_exp_f32_e32 v143, v143
	v_add_f32_e32 v0, 1.0, v0
	v_add_f32_e32 v131, 1.0, v131
	v_add_f32_e32 v133, 1.0, v133
	v_add_f32_e32 v135, 1.0, v135
	v_add_f32_e32 v137, 1.0, v137
	v_add_f32_e32 v139, 1.0, v139
	v_add_f32_e32 v141, 1.0, v141
	v_add_f32_e32 v143, 1.0, v143
	v_rcp_f32_e32 v0, v0
	v_rcp_f32_e32 v131, v131
	v_rcp_f32_e32 v133, v133
	v_rcp_f32_e32 v135, v135
	v_rcp_f32_e32 v137, v137
	v_rcp_f32_e32 v139, v139
	v_rcp_f32_e32 v141, v141
	v_rcp_f32_e32 v143, v143
	v_mad_u64_u32 v[152:153], s[0:1], v138, s83, v[146:147]
	v_cndmask_b32_e32 v0, v78, v0, vcc
	v_cndmask_b32_e32 v131, v79, v131, vcc
	v_cndmask_b32_e32 v133, v80, v133, vcc
	v_cndmask_b32_e32 v135, v81, v135, vcc
	v_cndmask_b32_e32 v137, v70, v137, vcc
	v_cndmask_b32_e32 v139, v71, v139, vcc
	v_cndmask_b32_e32 v141, v72, v141, vcc
	v_cndmask_b32_e32 v143, v73, v143, vcc
	v_cvt_pk_bf16_f32 v148, v0, v131
	v_cvt_pk_bf16_f32 v149, v133, v135
	v_cvt_pk_bf16_f32 v150, v137, v139
	v_cvt_pk_bf16_f32 v151, v141, v143
	global_store_dwordx4 v[152:153], v[148:151], off sc1
	s_or_b64 exec, exec, s[44:45]
	v_cmp_lt_i32_e64 s[0:1], -1, v136
	s_and_saveexec_b64 s[44:45], s[0:1]
	s_cbranch_execnz .LBB0_1093

; __device__ __forceinline__ v4u pack8(const float (&f)[8]) { v4u w; w.x = cvt_pk_bf16(f[0], f[1]); w.y = cvt_pk_bf16(f[2], f[3]); w.z = cvt_pk_bf16(f[4], f[5]); w.w = cvt_pk_bf16(f[6], f[7]); return w; }
; __device__ __forceinline__ float sigmoidf_(float x) { return rcpf_(1.f + __expf(-x)); }
; __device__ __forceinline__ float tanhf_(float x) { return 1.f - 2.f * rcpf_(1.f + __expf(2.f * x)); }
;     __device__ __forceinline__ void operator()(const f32x4 (&acc)[2][2][4][2], const Unit& u, int wr, int wc, int fr, int fq) const {
;     ...
;                             for (int m = 0; m < 4; ++m) if (rrow[ai][m] >= 0) { float o[8];
; #pragma unroll
;                                 for (int n = 0; n < 2; ++n)
; #pragma unroll
;                                     for (int j = 0; j < 4; ++j) { const float x = acc[ai][bj][m][n][j]; o[n * 4 + j] = kd == 1 ? tanhf_(x) : (kd == 2 ? sigmoidf_(x) : x); }
;                                 *(v4u*)(A2 + (size_t)rrow[ai][m] * KL2 + c) = pack8(o); }
.LBB0_1101:
	v_mul_f32_e32 v0, 0xbfb8aa3b, v46
	v_mul_f32_e32 v131, 0xbfb8aa3b, v47
	v_mul_f32_e32 v133, 0xbfb8aa3b, v48
	v_mul_f32_e32 v135, 0xbfb8aa3b, v49
	v_mul_f32_e32 v137, 0xbfb8aa3b, v38
	v_mul_f32_e32 v139, 0xbfb8aa3b, v39
	v_mul_f32_e32 v141, 0xbfb8aa3b, v40
	v_mul_f32_e32 v143, 0xbfb8aa3b, v41
	v_exp_f32_e32 v0, v0
	v_exp_f32_e32 v131, v131
	v_exp_f32_e32 v133, v133
	v_exp_f32_e32 v135, v135
	v_exp_f32_e32 v137, v137
	v_exp_f32_e32 v139, v139
	v_exp_f32_e32 v141, v141
	v_exp_f32_e32 v143, v143
	v_add_f32_e32 v0, 1.0, v0
	v_add_f32_e32 v131, 1.0, v131
	v_add_f32_e32 v133, 1.0, v133
	v_add_f32_e32 v135, 1.0, v135
	v_add_f32_e32 v137, 1.0, v137
	v_add_f32_e32 v139, 1.0, v139
	v_add_f32_e32 v141, 1.0, v141
	v_add_f32_e32 v143, 1.0, v143
	v_rcp_f32_e32 v0, v0
	v_rcp_f32_e32 v131, v131
	v_rcp_f32_e32 v133, v133
	v_rcp_f32_e32 v135, v135
	v_rcp_f32_e32 v137, v137
	v_rcp_f32_e32 v139, v139
	v_rcp_f32_e32 v141, v141
	v_rcp_f32_e32 v143, v143
	v_mad_u64_u32 v[152:153], s[0:1], v134, s83, v[146:147]
	v_cndmask_b32_e32 v0, v46, v0, vcc
	v_cndmask_b32_e32 v131, v47, v131, vcc
	v_cndmask_b32_e32 v133, v48, v133, vcc
	v_cndmask_b32_e32 v135, v49, v135, vcc
	v_cndmask_b32_e32 v137, v38, v137, vcc
	v_cndmask_b32_e32 v139, v39, v139, vcc
	v_cndmask_b32_e32 v141, v40, v141, vcc
	v_cndmask_b32_e32 v143, v41, v143, vcc
	v_cvt_pk_bf16_f32 v148, v0, v131
	v_cvt_pk_bf16_f32 v149, v133, v135
	v_cvt_pk_bf16_f32 v150, v137, v139
	v_cvt_pk_bf16_f32 v151, v141, v143
	global_store_dwordx4 v[152:153], v[148:151], off sc1
	s_or_b64 exec, exec, s[44:45]
	v_cmp_lt_i32_e64 s[0:1], -1, v132
	s_and_saveexec_b64 s[44:45], s[0:1]
	s_cbranch_execnz .LBB0_1095

; __device__ __forceinline__ v4u pack8(const float (&f)[8]) { v4u w; w.x = cvt_pk_bf16(f[0], f[1]); w.y = cvt_pk_bf16(f[2], f[3]); w.z = cvt_pk_bf16(f[4], f[5]); w.w = cvt_pk_bf16(f[6], f[7]); return w; }
; __device__ __forceinline__ float sigmoidf_(float x) { return rcpf_(1.f + __expf(-x)); }
; __device__ __forceinline__ float tanhf_(float x) { return 1.f - 2.f * rcpf_(1.f + __expf(2.f * x)); }
;     __device__ __forceinline__ void operator()(const f32x4 (&acc)[2][2][4][2], const Unit& u, int wr, int wc, int fr, int fq) const {
;     ...
;                             for (int m = 0; m < 4; ++m) if (rrow[ai][m] >= 0) { float o[8];
; #pragma unroll
;                                 for (int n = 0; n < 2; ++n)
; #pragma unroll
;                                     for (int j = 0; j < 4; ++j) { const float x = acc[ai][bj][m][n][j]; o[n * 4 + j] = kd == 1 ? tanhf_(x) : (kd == 2 ? sigmoidf_(x) : x); }
;                                 *(v4u*)(A2 + (size_t)rrow[ai][m] * KL2 + c) = pack8(o); }
.LBB0_1103:
	v_mul_f32_e32 v0, 0xbfb8aa3b, v14
	v_mul_f32_e32 v131, 0xbfb8aa3b, v15
	v_mul_f32_e32 v133, 0xbfb8aa3b, v16
	v_mul_f32_e32 v135, 0xbfb8aa3b, v17
	v_mul_f32_e32 v137, 0xbfb8aa3b, v2
	v_mul_f32_e32 v139, 0xbfb8aa3b, v3
	v_mul_f32_e32 v141, 0xbfb8aa3b, v4
	v_mul_f32_e32 v143, 0xbfb8aa3b, v5
	v_exp_f32_e32 v0, v0
	v_exp_f32_e32 v131, v131
	v_exp_f32_e32 v133, v133
	v_exp_f32_e32 v135, v135
	v_exp_f32_e32 v137, v137
	v_exp_f32_e32 v139, v139
	v_exp_f32_e32 v141, v141
	v_exp_f32_e32 v143, v143
	v_add_f32_e32 v0, 1.0, v0
	v_add_f32_e32 v131, 1.0, v131
	v_add_f32_e32 v133, 1.0, v133
	v_add_f32_e32 v135, 1.0, v135
	v_add_f32_e32 v137, 1.0, v137
	v_add_f32_e32 v139, 1.0, v139
	v_add_f32_e32 v141, 1.0, v141
	v_add_f32_e32 v143, 1.0, v143
	v_rcp_f32_e32 v0, v0
	v_rcp_f32_e32 v131, v131
	v_rcp_f32_e32 v133, v133
	v_rcp_f32_e32 v135, v135
	v_rcp_f32_e32 v137, v137
	v_rcp_f32_e32 v139, v139
	v_rcp_f32_e32 v141, v141
	v_rcp_f32_e32 v143, v143
	v_mad_u64_u32 v[146:147], s[0:1], v130, s83, v[146:147]
	v_cndmask_b32_e32 v0, v14, v0, vcc
	v_cndmask_b32_e32 v131, v15, v131, vcc
	v_cndmask_b32_e32 v133, v16, v133, vcc
	v_cndmask_b32_e32 v135, v17, v135, vcc
	v_cndmask_b32_e32 v137, v2, v137, vcc
	v_cndmask_b32_e32 v139, v3, v139, vcc
	v_cndmask_b32_e32 v141, v4, v141, vcc
	v_cndmask_b32_e32 v143, v5, v143, vcc
	v_cvt_pk_bf16_f32 v148, v0, v131
	v_cvt_pk_bf16_f32 v149, v133, v135
	v_cvt_pk_bf16_f32 v150, v137, v139
	v_cvt_pk_bf16_f32 v151, v141, v143
	global_store_dwordx4 v[146:147], v[148:151], off sc1

; __device__ __forceinline__ v4u pack8(const float (&f)[8]) { v4u w; w.x = cvt_pk_bf16(f[0], f[1]); w.y = cvt_pk_bf16(f[2], f[3]); w.z = cvt_pk_bf16(f[4], f[5]); w.w = cvt_pk_bf16(f[6], f[7]); return w; }
;     __device__ __forceinline__ void operator()(const f32x4 (&acc)[2][2][4][2], const Unit& u, int wr, int wc, int fr, int fq) const {
;     ...
;             if (u.pn < 12) {
;                 bf16* dst = (bf16*)(ws + (u.pn < 4 ? WS_R : (u.pn < 8 ? WS_K : (jl == 0 ? WS_VF : WS_VB)))) + (u.pn & 3) * 256 + cw;
; #pragma unroll
;                 for (int ai = 0; ai < 2; ++ai)
; #pragma unroll
;                     for (int m = 0; m < 4; ++m) if (rrow[ai][m] >= 0) {
;                         bf16* rp = dst + (size_t)rrow[ai][m] * D;
; #pragma unroll
;                         for (int bj = 0; bj < 2; ++bj) { float o[8];
; #pragma unroll
;                             for (int n = 0; n < 2; ++n)
; #pragma unroll
;                                 for (int j = 0; j < 4; ++j) o[n * 4 + j] = acc[ai][bj][m][n][j];
;                             *(v4u*)(rp + bj * 128) = pack8(o); }
.LBB0_1105:
	s_cmp_gt_u32 s87, 7
	s_cselect_b32 s0, s15, 0x19000000
	s_cselect_b32 s1, 0, 0
	s_cmp_gt_i32 s87, 3
	v_readlane_b32 s20, v254, 38
	s_cselect_b32 s0, s0, 0x14f00000
	v_readlane_b32 s22, v254, 40
	s_cselect_b32 s1, s1, 0
	v_readlane_b32 s23, v254, 41
	s_add_u32 s0, s22, s0
	s_addc_u32 s1, s23, s1
	s_lshl_b32 s10, s87, 9
	s_and_b32 s10, s10, 0x600
	s_add_u32 s0, s0, s10
	s_addc_u32 s1, s1, 0
	v_lshlrev_b32_e32 v0, 1, v204
	v_lshl_add_u64 v[146:147], s[0:1], 0, v[0:1]
	v_cmp_lt_i32_e32 vcc, -1, v144
	v_readlane_b32 s21, v254, 39
	s_and_saveexec_b64 s[0:1], vcc
	s_cbranch_execz .LBB0_1113
	v_mov_b32_e32 v145, v1
	v_lshlrev_b64 v[144:145], 11, v[144:145]
	v_lshl_add_u64 v[144:145], v[146:147], 0, v[144:145]
	v_cvt_pk_bf16_f32 v148, v122, v123
	v_cvt_pk_bf16_f32 v149, v124, v125
	v_cvt_pk_bf16_f32 v150, v114, v115
	v_cvt_pk_bf16_f32 v151, v116, v117
	global_store_dwordx4 v[144:145], v[148:151], off sc1
	s_nop 1
	v_cvt_pk_bf16_f32 v148, v126, v127
	v_cvt_pk_bf16_f32 v149, v128, v129
	v_cvt_pk_bf16_f32 v150, v118, v119
	v_cvt_pk_bf16_f32 v151, v120, v121
	global_store_dwordx4 v[144:145], v[148:151], off offset:256 sc1
	s_or_b64 exec, exec, s[0:1]
	v_cmp_lt_i32_e32 vcc, -1, v142
	s_and_saveexec_b64 s[0:1], vcc
	s_cbranch_execnz .LBB0_1114

; __device__ __forceinline__ v4u pack8(const float (&f)[8]) { v4u w; w.x = cvt_pk_bf16(f[0], f[1]); w.y = cvt_pk_bf16(f[2], f[3]); w.z = cvt_pk_bf16(f[4], f[5]); w.w = cvt_pk_bf16(f[6], f[7]); return w; }
;     __device__ __forceinline__ void operator()(const f32x4 (&acc)[2][2][4][2], const Unit& u, int wr, int wc, int fr, int fq) const {
;     ...
;                     for (int m = 0; m < 4; ++m) if (rrow[ai][m] >= 0) {
;                         bf16* rp = dst + (size_t)rrow[ai][m] * D;
; #pragma unroll
;                         for (int bj = 0; bj < 2; ++bj) { float o[8];
; #pragma unroll
;                             for (int n = 0; n < 2; ++n)
; #pragma unroll
;                                 for (int j = 0; j < 4; ++j) o[n * 4 + j] = acc[ai][bj][m][n][j];
;                             *(v4u*)(rp + bj * 128) = pack8(o); }
.LBB0_1108:
	v_mov_b32_e32 v141, v1
	v_lshlrev_b64 v[140:141], 11, v[140:141]
	v_lshl_add_u64 v[144:145], v[146:147], 0, v[140:141]
	v_cvt_pk_bf16_f32 v140, v90, v91
	v_cvt_pk_bf16_f32 v141, v92, v93
	v_cvt_pk_bf16_f32 v142, v82, v83
	v_cvt_pk_bf16_f32 v143, v84, v85
	global_store_dwordx4 v[144:145], v[140:143], off sc1
	s_nop 1
	v_cvt_pk_bf16_f32 v140, v94, v95
	v_cvt_pk_bf16_f32 v141, v96, v97
	v_cvt_pk_bf16_f32 v142, v86, v87
	v_cvt_pk_bf16_f32 v143, v88, v89
	global_store_dwordx4 v[144:145], v[140:143], off offset:256 sc1
	s_or_b64 exec, exec, s[0:1]
	v_cmp_lt_i32_e32 vcc, -1, v138
	s_and_saveexec_b64 s[0:1], vcc
	s_cbranch_execnz .LBB0_1116

; __device__ __forceinline__ v4u pack8(const float (&f)[8]) { v4u w; w.x = cvt_pk_bf16(f[0], f[1]); w.y = cvt_pk_bf16(f[2], f[3]); w.z = cvt_pk_bf16(f[4], f[5]); w.w = cvt_pk_bf16(f[6], f[7]); return w; }
;     __device__ __forceinline__ void operator()(const f32x4 (&acc)[2][2][4][2], const Unit& u, int wr, int wc, int fr, int fq) const {
;     ...
;                     for (int m = 0; m < 4; ++m) if (rrow[ai][m] >= 0) {
;                         bf16* rp = dst + (size_t)rrow[ai][m] * D;
; #pragma unroll
;                         for (int bj = 0; bj < 2; ++bj) { float o[8];
; #pragma unroll
;                             for (int n = 0; n < 2; ++n)
; #pragma unroll
;                                 for (int j = 0; j < 4; ++j) o[n * 4 + j] = acc[ai][bj][m][n][j];
;                             *(v4u*)(rp + bj * 128) = pack8(o); }
.LBB0_1110:
	v_mov_b32_e32 v137, v1
	v_lshlrev_b64 v[136:137], 11, v[136:137]
	v_lshl_add_u64 v[140:141], v[146:147], 0, v[136:137]
	v_cvt_pk_bf16_f32 v136, v58, v59
	v_cvt_pk_bf16_f32 v137, v60, v61
	v_cvt_pk_bf16_f32 v138, v50, v51
	v_cvt_pk_bf16_f32 v139, v52, v53
	global_store_dwordx4 v[140:141], v[136:139], off sc1
	s_nop 1
	v_cvt_pk_bf16_f32 v136, v62, v63
	v_cvt_pk_bf16_f32 v137, v64, v65
	v_cvt_pk_bf16_f32 v138, v54, v55
	v_cvt_pk_bf16_f32 v139, v56, v57
	global_store_dwordx4 v[140:141], v[136:139], off offset:256 sc1
	s_or_b64 exec, exec, s[0:1]
	v_cmp_lt_i32_e32 vcc, -1, v134
	s_and_saveexec_b64 s[0:1], vcc
	s_cbranch_execnz .LBB0_1118

; __device__ __forceinline__ v4u pack8(const float (&f)[8]) { v4u w; w.x = cvt_pk_bf16(f[0], f[1]); w.y = cvt_pk_bf16(f[2], f[3]); w.z = cvt_pk_bf16(f[4], f[5]); w.w = cvt_pk_bf16(f[6], f[7]); return w; }
;     __device__ __forceinline__ void operator()(const f32x4 (&acc)[2][2][4][2], const Unit& u, int wr, int wc, int fr, int fq) const {
;     ...
;                     for (int m = 0; m < 4; ++m) if (rrow[ai][m] >= 0) {
;                         bf16* rp = dst + (size_t)rrow[ai][m] * D;
; #pragma unroll
;                         for (int bj = 0; bj < 2; ++bj) { float o[8];
; #pragma unroll
;                             for (int n = 0; n < 2; ++n)
; #pragma unroll
;                                 for (int j = 0; j < 4; ++j) o[n * 4 + j] = acc[ai][bj][m][n][j];
;                             *(v4u*)(rp + bj * 128) = pack8(o); }
.LBB0_1112:
	v_mov_b32_e32 v133, v1
	v_lshlrev_b64 v[132:133], 11, v[132:133]
	v_lshl_add_u64 v[136:137], v[146:147], 0, v[132:133]
	v_cvt_pk_bf16_f32 v132, v26, v27
	v_cvt_pk_bf16_f32 v133, v28, v29
	v_cvt_pk_bf16_f32 v134, v18, v19
	v_cvt_pk_bf16_f32 v135, v20, v21
	global_store_dwordx4 v[136:137], v[132:135], off sc1
	s_nop 1
	v_cvt_pk_bf16_f32 v132, v30, v31
	v_cvt_pk_bf16_f32 v133, v32, v33
	v_cvt_pk_bf16_f32 v134, v22, v23
	v_cvt_pk_bf16_f32 v135, v24, v25
	global_store_dwordx4 v[136:137], v[132:135], off offset:256 sc1
	s_or_b64 exec, exec, s[0:1]
	s_waitcnt lgkmcnt(0)
	v_cmp_lt_i32_e32 vcc, -1, v130
	s_and_saveexec_b64 s[0:1], vcc
	s_cbranch_execnz .LBB0_1120
	s_branch .LBB0_1121

; __device__ __forceinline__ v4u pack8(const float (&f)[8]) { v4u w; w.x = cvt_pk_bf16(f[0], f[1]); w.y = cvt_pk_bf16(f[2], f[3]); w.z = cvt_pk_bf16(f[4], f[5]); w.w = cvt_pk_bf16(f[6], f[7]); return w; }
;     __device__ __forceinline__ void operator()(const f32x4 (&acc)[2][2][4][2], const Unit& u, int wr, int wc, int fr, int fq) const {
;     ...
;                     for (int m = 0; m < 4; ++m) if (rrow[ai][m] >= 0) {
;                         bf16* rp = dst + (size_t)rrow[ai][m] * D;
; #pragma unroll
;                         for (int bj = 0; bj < 2; ++bj) { float o[8];
; #pragma unroll
;                             for (int n = 0; n < 2; ++n)
; #pragma unroll
;                                 for (int j = 0; j < 4; ++j) o[n * 4 + j] = acc[ai][bj][m][n][j];
;                             *(v4u*)(rp + bj * 128) = pack8(o); }
.LBB0_1114:
	v_mov_b32_e32 v143, v1
	v_lshlrev_b64 v[142:143], 11, v[142:143]
	v_lshl_add_u64 v[148:149], v[146:147], 0, v[142:143]
	v_cvt_pk_bf16_f32 v142, v106, v107
	v_cvt_pk_bf16_f32 v143, v108, v109
	v_cvt_pk_bf16_f32 v144, v98, v99
	v_cvt_pk_bf16_f32 v145, v100, v101
	global_store_dwordx4 v[148:149], v[142:145], off sc1
	s_nop 1
	v_cvt_pk_bf16_f32 v142, v110, v111
	v_cvt_pk_bf16_f32 v143, v112, v113
	v_cvt_pk_bf16_f32 v144, v102, v103
	v_cvt_pk_bf16_f32 v145, v104, v105
	global_store_dwordx4 v[148:149], v[142:145], off offset:256 sc1
	s_or_b64 exec, exec, s[0:1]
	v_cmp_lt_i32_e32 vcc, -1, v140
	s_and_saveexec_b64 s[0:1], vcc
	s_cbranch_execnz .LBB0_1108

; __device__ __forceinline__ v4u pack8(const float (&f)[8]) { v4u w; w.x = cvt_pk_bf16(f[0], f[1]); w.y = cvt_pk_bf16(f[2], f[3]); w.z = cvt_pk_bf16(f[4], f[5]); w.w = cvt_pk_bf16(f[6], f[7]); return w; }
;     __device__ __forceinline__ void operator()(const f32x4 (&acc)[2][2][4][2], const Unit& u, int wr, int wc, int fr, int fq) const {
;     ...
;                     for (int m = 0; m < 4; ++m) if (rrow[ai][m] >= 0) {
;                         bf16* rp = dst + (size_t)rrow[ai][m] * D;
; #pragma unroll
;                         for (int bj = 0; bj < 2; ++bj) { float o[8];
; #pragma unroll
;                             for (int n = 0; n < 2; ++n)
; #pragma unroll
;                                 for (int j = 0; j < 4; ++j) o[n * 4 + j] = acc[ai][bj][m][n][j];
;                             *(v4u*)(rp + bj * 128) = pack8(o); }
.LBB0_1116:
	v_mov_b32_e32 v139, v1
	v_lshlrev_b64 v[138:139], 11, v[138:139]
	v_lshl_add_u64 v[142:143], v[146:147], 0, v[138:139]
	v_cvt_pk_bf16_f32 v138, v74, v75
	v_cvt_pk_bf16_f32 v139, v76, v77
	v_cvt_pk_bf16_f32 v140, v66, v67
	v_cvt_pk_bf16_f32 v141, v68, v69
	global_store_dwordx4 v[142:143], v[138:141], off sc1
	s_nop 1
	v_cvt_pk_bf16_f32 v138, v78, v79
	v_cvt_pk_bf16_f32 v139, v80, v81
	v_cvt_pk_bf16_f32 v140, v70, v71
	v_cvt_pk_bf16_f32 v141, v72, v73
	global_store_dwordx4 v[142:143], v[138:141], off offset:256 sc1
	s_or_b64 exec, exec, s[0:1]
	v_cmp_lt_i32_e32 vcc, -1, v136
	s_and_saveexec_b64 s[0:1], vcc
	s_cbranch_execnz .LBB0_1110

; __device__ __forceinline__ v4u pack8(const float (&f)[8]) { v4u w; w.x = cvt_pk_bf16(f[0], f[1]); w.y = cvt_pk_bf16(f[2], f[3]); w.z = cvt_pk_bf16(f[4], f[5]); w.w = cvt_pk_bf16(f[6], f[7]); return w; }
;     __device__ __forceinline__ void operator()(const f32x4 (&acc)[2][2][4][2], const Unit& u, int wr, int wc, int fr, int fq) const {
;     ...
;                     for (int m = 0; m < 4; ++m) if (rrow[ai][m] >= 0) {
;                         bf16* rp = dst + (size_t)rrow[ai][m] * D;
; #pragma unroll
;                         for (int bj = 0; bj < 2; ++bj) { float o[8];
; #pragma unroll
;                             for (int n = 0; n < 2; ++n)
; #pragma unroll
;                                 for (int j = 0; j < 4; ++j) o[n * 4 + j] = acc[ai][bj][m][n][j];
;                             *(v4u*)(rp + bj * 128) = pack8(o); }
.LBB0_1118:
	v_mov_b32_e32 v135, v1
	v_lshlrev_b64 v[134:135], 11, v[134:135]
	v_lshl_add_u64 v[138:139], v[146:147], 0, v[134:135]
	v_cvt_pk_bf16_f32 v134, v42, v43
	v_cvt_pk_bf16_f32 v135, v44, v45
	v_cvt_pk_bf16_f32 v136, v34, v35
	v_cvt_pk_bf16_f32 v137, v36, v37
	global_store_dwordx4 v[138:139], v[134:137], off sc1
	s_nop 1
	v_cvt_pk_bf16_f32 v134, v46, v47
	v_cvt_pk_bf16_f32 v135, v48, v49
	v_cvt_pk_bf16_f32 v136, v38, v39
	v_cvt_pk_bf16_f32 v137, v40, v41
	global_store_dwordx4 v[138:139], v[134:137], off offset:256 sc1
	s_or_b64 exec, exec, s[0:1]
	v_cmp_lt_i32_e32 vcc, -1, v132
	s_and_saveexec_b64 s[0:1], vcc
	s_cbranch_execnz .LBB0_1112

; __device__ __forceinline__ v4u pack8(const float (&f)[8]) { v4u w; w.x = cvt_pk_bf16(f[0], f[1]); w.y = cvt_pk_bf16(f[2], f[3]); w.z = cvt_pk_bf16(f[4], f[5]); w.w = cvt_pk_bf16(f[6], f[7]); return w; }
;     __device__ __forceinline__ void operator()(const f32x4 (&acc)[2][2][4][2], const Unit& u, int wr, int wc, int fr, int fq) const {
;     ...
;                     for (int m = 0; m < 4; ++m) if (rrow[ai][m] >= 0) {
;                         bf16* rp = dst + (size_t)rrow[ai][m] * D;
; #pragma unroll
;                         for (int bj = 0; bj < 2; ++bj) { float o[8];
; #pragma unroll
;                             for (int n = 0; n < 2; ++n)
; #pragma unroll
;                                 for (int j = 0; j < 4; ++j) o[n * 4 + j] = acc[ai][bj][m][n][j];
;                             *(v4u*)(rp + bj * 128) = pack8(o); }
.LBB0_1120:
	v_mov_b32_e32 v131, v1
	v_lshlrev_b64 v[130:131], 11, v[130:131]
	v_lshl_add_u64 v[134:135], v[146:147], 0, v[130:131]
	v_cvt_pk_bf16_f32 v130, v10, v11
	v_cvt_pk_bf16_f32 v131, v12, v13
	v_cvt_pk_bf16_f32 v132, v6, v7
	v_cvt_pk_bf16_f32 v133, v8, v9
	global_store_dwordx4 v[134:135], v[130:133], off sc1
	s_nop 1
	v_cvt_pk_bf16_f32 v130, v14, v15
	v_cvt_pk_bf16_f32 v131, v16, v17
	v_cvt_pk_bf16_f32 v132, v2, v3
	v_cvt_pk_bf16_f32 v133, v4, v5
	global_store_dwordx4 v[134:135], v[130:133], off offset:256 sc1

; __device__ __forceinline__ v4u pack8(const float (&f)[8]) { v4u w; w.x = cvt_pk_bf16(f[0], f[1]); w.y = cvt_pk_bf16(f[2], f[3]); w.z = cvt_pk_bf16(f[4], f[5]); w.w = cvt_pk_bf16(f[6], f[7]); return w; }
;     __device__ __forceinline__ void operator()(const f32x4 (&acc)[2][2][4][2], const Unit& u, int wr, int wc, int fr, int fq) const {
;     ...
;             bf16* C = (bf16*)(ws + WS_L2);
;             const int col0 = u.pn * 256 + wc * 32 + 8 * fq;
; #pragma unroll
;             for (int ai = 0; ai < 2; ++ai)
; #pragma unroll
;                 for (int m = 0; m < 4; ++m) {
;                     bf16* rp = C + (size_t)(row0 + ai * 128 + m * 16) * NL2 + col0;
; #pragma unroll
;                     for (int bj = 0; bj < 2; ++bj) { float o[8];
; #pragma unroll
;                         for (int n = 0; n < 2; ++n)
; #pragma unroll
;                             for (int j = 0; j < 4; ++j) o[n * 4 + j] = acc[ai][bj][m][n][j];
;                         *(v4u*)(rp + bj * 128) = pack8(o); }
;                 }
.LBB0_1125:
	s_waitcnt lgkmcnt(0)
	v_lshl_or_b32 v130, s87, 8, v204
	v_readlane_b32 s0, v252, 32
	v_ashrrev_i32_e32 v131, 31, v130
	v_readlane_b32 s1, v252, 33
	v_ashrrev_i32_e32 v211, 31, v210
	v_cvt_pk_bf16_f32 v132, v122, v123
	v_cvt_pk_bf16_f32 v133, v124, v125
	v_cvt_pk_bf16_f32 v134, v114, v115
	v_cvt_pk_bf16_f32 v135, v116, v117
	s_nop 0
	v_lshl_add_u64 v[136:137], v[130:131], 1, s[0:1]
	v_lshlrev_b64 v[130:131], 13, v[210:211]
	v_lshl_add_u64 v[130:131], v[136:137], 0, v[130:131]
	global_store_dwordx4 v[130:131], v[132:135], off sc1
	s_mov_b64 s[0:1], 0x100000
	s_nop 0
	v_cvt_pk_bf16_f32 v132, v126, v127
	v_cvt_pk_bf16_f32 v133, v128, v129
	v_cvt_pk_bf16_f32 v134, v118, v119
	v_cvt_pk_bf16_f32 v135, v120, v121
	global_store_dwordx4 v[130:131], v[132:135], off offset:256 sc1
	s_nop 1
	v_or_b32_e32 v132, 16, v210
	v_ashrrev_i32_e32 v133, 31, v132
	v_lshlrev_b64 v[132:133], 13, v[132:133]
	v_lshl_add_u64 v[138:139], v[136:137], 0, v[132:133]
	v_cvt_pk_bf16_f32 v132, v106, v107
	v_cvt_pk_bf16_f32 v133, v108, v109
	v_cvt_pk_bf16_f32 v134, v98, v99
	v_cvt_pk_bf16_f32 v135, v100, v101
	global_store_dwordx4 v[138:139], v[132:135], off sc1
	s_nop 1
	v_cvt_pk_bf16_f32 v132, v110, v111
	v_cvt_pk_bf16_f32 v133, v112, v113
	v_cvt_pk_bf16_f32 v134, v102, v103
	v_cvt_pk_bf16_f32 v135, v104, v105
	global_store_dwordx4 v[138:139], v[132:135], off offset:256 sc1
	s_nop 1
	v_or_b32_e32 v132, 32, v210
	v_ashrrev_i32_e32 v133, 31, v132
	v_lshlrev_b64 v[132:133], 13, v[132:133]
	v_lshl_add_u64 v[138:139], v[136:137], 0, v[132:133]
	v_cvt_pk_bf16_f32 v132, v90, v91
	v_cvt_pk_bf16_f32 v133, v92, v93
	v_cvt_pk_bf16_f32 v134, v82, v83
	v_cvt_pk_bf16_f32 v135, v84, v85
	global_store_dwordx4 v[138:139], v[132:135], off sc1
	s_nop 1
	v_cvt_pk_bf16_f32 v132, v94, v95
	v_cvt_pk_bf16_f32 v133, v96, v97
	v_cvt_pk_bf16_f32 v134, v86, v87
	v_cvt_pk_bf16_f32 v135, v88, v89
	global_store_dwordx4 v[138:139], v[132:135], off offset:256 sc1
	s_nop 1
	v_or_b32_e32 v132, 48, v210
	v_ashrrev_i32_e32 v133, 31, v132
	v_lshlrev_b64 v[132:133], 13, v[132:133]
	v_lshl_add_u64 v[136:137], v[136:137], 0, v[132:133]
	v_cvt_pk_bf16_f32 v132, v74, v75
	v_cvt_pk_bf16_f32 v133, v76, v77
	v_cvt_pk_bf16_f32 v134, v66, v67
	v_cvt_pk_bf16_f32 v135, v68, v69
	global_store_dwordx4 v[136:137], v[132:135], off sc1
	s_nop 1
	v_cvt_pk_bf16_f32 v132, v78, v79
	v_cvt_pk_bf16_f32 v133, v80, v81
	v_cvt_pk_bf16_f32 v134, v70, v71
	v_cvt_pk_bf16_f32 v135, v72, v73
	global_store_dwordx4 v[136:137], v[132:135], off offset:256 sc1
	v_lshl_add_u64 v[136:137], v[130:131], 0, s[0:1]
	s_mov_b32 s0, 0x100000
	v_add_co_u32_e32 v138, vcc, s0, v130
	v_cvt_pk_bf16_f32 v132, v58, v59
	v_cvt_pk_bf16_f32 v133, v60, v61
	v_cvt_pk_bf16_f32 v134, v50, v51
	v_cvt_pk_bf16_f32 v135, v52, v53
	s_nop 1
	v_addc_co_u32_e32 v139, vcc, 0, v131, vcc
	s_mov_b64 s[0:1], 0x120000
	global_store_dwordx4 v[138:139], v[132:135], off sc1
	s_nop 1
	v_cvt_pk_bf16_f32 v132, v62, v63
	v_cvt_pk_bf16_f32 v133, v64, v65
	v_cvt_pk_bf16_f32 v134, v54, v55
	v_cvt_pk_bf16_f32 v135, v56, v57
	global_store_dwordx4 v[136:137], v[132:135], off offset:256 sc1
	v_lshl_add_u64 v[136:137], v[130:131], 0, s[0:1]
	s_mov_b32 s0, 0x120000
	v_add_co_u32_e32 v138, vcc, s0, v130
	v_cvt_pk_bf16_f32 v132, v42, v43
	v_cvt_pk_bf16_f32 v133, v44, v45
	v_cvt_pk_bf16_f32 v134, v34, v35
	v_cvt_pk_bf16_f32 v135, v36, v37
	s_nop 1
	v_addc_co_u32_e32 v139, vcc, 0, v131, vcc
	s_mov_b64 s[0:1], 0x140000
	global_store_dwordx4 v[138:139], v[132:135], off sc1
	s_nop 1
	v_cvt_pk_bf16_f32 v132, v46, v47
	v_cvt_pk_bf16_f32 v133, v48, v49
	v_cvt_pk_bf16_f32 v134, v38, v39
	v_cvt_pk_bf16_f32 v135, v40, v41
	global_store_dwordx4 v[136:137], v[132:135], off offset:256 sc1
	v_lshl_add_u64 v[136:137], v[130:131], 0, s[0:1]
	s_mov_b32 s0, 0x140000
	v_add_co_u32_e32 v138, vcc, s0, v130
	v_cvt_pk_bf16_f32 v132, v26, v27
	v_cvt_pk_bf16_f32 v133, v28, v29
	v_cvt_pk_bf16_f32 v134, v18, v19
	v_cvt_pk_bf16_f32 v135, v20, v21
	s_nop 1
	v_addc_co_u32_e32 v139, vcc, 0, v131, vcc
	s_mov_b64 s[0:1], 0x160000
	global_store_dwordx4 v[138:139], v[132:135], off sc1
	s_nop 1
	v_cvt_pk_bf16_f32 v132, v30, v31
	v_cvt_pk_bf16_f32 v133, v32, v33
	v_cvt_pk_bf16_f32 v134, v22, v23
	v_cvt_pk_bf16_f32 v135, v24, v25
	global_store_dwordx4 v[136:137], v[132:135], off offset:256 sc1
	v_lshl_add_u64 v[136:137], v[130:131], 0, s[0:1]
	s_mov_b32 s0, 0x160000
	v_add_co_u32_e32 v130, vcc, s0, v130
	v_cvt_pk_bf16_f32 v132, v10, v11
	v_cvt_pk_bf16_f32 v133, v12, v13
	v_cvt_pk_bf16_f32 v134, v6, v7
	v_cvt_pk_bf16_f32 v135, v8, v9
	s_nop 1
	v_addc_co_u32_e32 v131, vcc, 0, v131, vcc
	global_store_dwordx4 v[130:131], v[132:135], off sc1
	v_cvt_pk_bf16_f32 v130, v14, v15
	v_cvt_pk_bf16_f32 v131, v16, v17
	s_nop 1
	v_cvt_pk_bf16_f32 v132, v2, v3
	v_cvt_pk_bf16_f32 v133, v4, v5
	global_store_dwordx4 v[136:137], v[130:133], off offset:256 sc1
	s_cbranch_execz .LBB0_851

; __device__ __forceinline__ v4u pack8(const float (&f)[8]) { v4u w; w.x = cvt_pk_bf16(f[0], f[1]); w.y = cvt_pk_bf16(f[2], f[3]); w.z = cvt_pk_bf16(f[4], f[5]); w.w = cvt_pk_bf16(f[6], f[7]); return w; }
; __device__ __forceinline__ float siluf_(float x) { return x * rcpf_(1.f + __expf(-x)); }
;     __device__ __forceinline__ void operator()(const f32x4 (&acc)[2][2][4][2], const Unit& u, int wr, int wc, int fr, int fq) const {
;     ...
;                 const bool isg = u.pn >= 16;
;                 bf16* base = (isg ? SG : V) + ((u.pn - (isg ? 16 : 8)) * 256) + cw;
; #pragma unroll
;                 for (int ai = 0; ai < 2; ++ai)
; #pragma unroll
;                     for (int m = 0; m < 4; ++m) {
;                         bf16* rp = base + (size_t)(row0 + ai * 128 + m * 16) * 2048;
;                         const float rs = rtab[u.ord * 256 + (wr * 64 + fr + ai * 128 + m * 16)];
; #pragma unroll
;                         for (int bj = 0; bj < 2; ++bj) {
;                             float o[8];
; #pragma unroll
;                             for (int n = 0; n < 2; ++n)
; #pragma unroll
;                                 for (int j = 0; j < 4; ++j) { const float x = acc[ai][bj][m][n][j] * rs; o[n * 4 + j] = isg ? siluf_(x) : x; }
;                             *(v4u*)(rp + bj * 128) = pack8(o);
;                         }
;                     }
.LBB0_1127:
	v_or_b32_e32 v216, 16, v210
	v_or_b32_e32 v214, 32, v210
	v_or_b32_e32 v212, 48, v210
	s_mov_b64 s[0:1], -1
	s_cmp_gt_i32 s87, 7
	v_ashrrev_i32_e32 v211, 31, v210
	v_lshlrev_b32_e32 v0, 1, v204
	v_ashrrev_i32_e32 v217, 31, v216
	v_ashrrev_i32_e32 v215, 31, v214
	v_ashrrev_i32_e32 v213, 31, v212
	s_cbranch_scc0 .LBB0_1129
	v_lshl_add_u32 v138, s88, 10, v243
	ds_read2_b32 v[134:135], v138 offset1:16
	s_cmp_gt_u32 s87, 15
	s_cselect_b64 vcc, -1, 0
	s_and_b64 s[0:1], vcc, exec
	s_mov_b32 s0, 0x19000000
	s_waitcnt lgkmcnt(0)
	v_mul_f32_e32 v136, v122, v134
	v_mul_f32_e32 v137, 0xbfb8aa3b, v136
	v_exp_f32_e32 v137, v137
	v_readlane_b32 s20, v254, 38
	s_cselect_b32 s0, 0x1d100000, s0
	v_readlane_b32 s22, v254, 40
	v_add_f32_e32 v137, 1.0, v137
	v_rcp_f32_e32 v137, v137
	v_readlane_b32 s23, v254, 41
	s_add_u32 s2, s22, s0
	s_addc_u32 s3, s23, 0
	v_mul_f32_e32 v137, v136, v137
	v_cndmask_b32_e32 v136, v136, v137, vcc
	v_mul_f32_e32 v137, v123, v134
	v_mul_f32_e32 v139, 0xbfb8aa3b, v137
	v_exp_f32_e32 v139, v139
	s_and_b64 s[0:1], vcc, exec
	s_cselect_b32 s0, -16, -8
	s_add_i32 s0, s0, s87
	v_add_f32_e32 v139, 1.0, v139
	v_rcp_f32_e32 v139, v139
	s_lshl_b32 s0, s0, 8
	s_ashr_i32 s1, s0, 31
	s_lshl_b64 s[0:1], s[0:1], 1
	v_mul_f32_e32 v139, v137, v139
	v_cndmask_b32_e32 v137, v137, v139, vcc
	v_mul_f32_e32 v139, v124, v134
	v_mul_f32_e32 v140, 0xbfb8aa3b, v139
	v_exp_f32_e32 v140, v140
	s_add_u32 s0, s2, s0
	s_addc_u32 s1, s3, s1
	v_lshl_add_u64 v[132:133], s[0:1], 0, v[0:1]
	v_add_f32_e32 v140, 1.0, v140
	v_rcp_f32_e32 v140, v140
	v_lshlrev_b64 v[130:131], 12, v[210:211]
	v_lshl_add_u64 v[130:131], v[132:133], 0, v[130:131]
	s_mov_b64 s[0:1], 0x80000
	v_mul_f32_e32 v140, v139, v140
	v_cndmask_b32_e32 v139, v139, v140, vcc
	v_mul_f32_e32 v140, v125, v134
	v_mul_f32_e32 v141, 0xbfb8aa3b, v140
	v_exp_f32_e32 v141, v141
	v_readlane_b32 s21, v254, 39
	v_add_f32_e32 v141, 1.0, v141
	v_rcp_f32_e32 v141, v141
	s_nop 0
	v_mul_f32_e32 v141, v140, v141
	v_cndmask_b32_e32 v141, v140, v141, vcc
	v_mul_f32_e32 v140, v114, v134
	v_mul_f32_e32 v142, 0xbfb8aa3b, v140
	v_exp_f32_e32 v142, v142
	v_cvt_pk_bf16_f32 v141, v139, v141
	s_nop 0
	v_add_f32_e32 v142, 1.0, v142
	v_rcp_f32_e32 v142, v142
	s_nop 0
	v_mul_f32_e32 v142, v140, v142
	v_cndmask_b32_e32 v142, v140, v142, vcc
	v_mul_f32_e32 v140, v115, v134
	v_mul_f32_e32 v143, 0xbfb8aa3b, v140
	v_exp_f32_e32 v143, v143
	s_nop 0
	v_add_f32_e32 v143, 1.0, v143
	v_rcp_f32_e32 v143, v143
	s_nop 0
	v_mul_f32_e32 v143, v140, v143
	v_cndmask_b32_e32 v143, v140, v143, vcc
	v_mul_f32_e32 v140, v116, v134
	v_mul_f32_e32 v144, 0xbfb8aa3b, v140
	v_exp_f32_e32 v144, v144
	v_cvt_pk_bf16_f32 v142, v142, v143
	s_nop 0
	v_add_f32_e32 v144, 1.0, v144
	v_rcp_f32_e32 v144, v144
	s_nop 0
	v_mul_f32_e32 v144, v140, v144
	v_cndmask_b32_e32 v144, v140, v144, vcc
	v_mul_f32_e32 v140, v117, v134
	v_mul_f32_e32 v145, 0xbfb8aa3b, v140
	v_exp_f32_e32 v145, v145
	s_nop 0
	v_add_f32_e32 v145, 1.0, v145
	v_rcp_f32_e32 v145, v145
	s_nop 0
	v_mul_f32_e32 v145, v140, v145
	v_cndmask_b32_e32 v145, v140, v145, vcc
	v_cvt_pk_bf16_f32 v140, v136, v137
	v_mul_f32_e32 v136, v126, v134
	v_mul_f32_e32 v137, 0xbfb8aa3b, v136
	v_exp_f32_e32 v137, v137
	v_cvt_pk_bf16_f32 v143, v144, v145
	global_store_dwordx4 v[130:131], v[140:143], off sc1
	v_add_f32_e32 v137, 1.0, v137
	v_rcp_f32_e32 v137, v137
	s_nop 0
	v_mul_f32_e32 v137, v136, v137
	v_cndmask_b32_e32 v136, v136, v137, vcc
	v_mul_f32_e32 v137, v127, v134
	v_mul_f32_e32 v139, 0xbfb8aa3b, v137
	v_exp_f32_e32 v139, v139
	s_nop 0
	v_add_f32_e32 v139, 1.0, v139
	v_rcp_f32_e32 v139, v139
	s_nop 0
	v_mul_f32_e32 v139, v137, v139
	v_cndmask_b32_e32 v137, v137, v139, vcc
	v_mul_f32_e32 v139, v128, v134
	v_mul_f32_e32 v140, 0xbfb8aa3b, v139
	v_exp_f32_e32 v140, v140
	s_nop 0
	v_add_f32_e32 v140, 1.0, v140
	v_rcp_f32_e32 v140, v140
	s_nop 0
	v_mul_f32_e32 v140, v139, v140
	v_cndmask_b32_e32 v139, v139, v140, vcc
	v_mul_f32_e32 v140, v129, v134
	v_mul_f32_e32 v141, 0xbfb8aa3b, v140
	v_exp_f32_e32 v141, v141
	s_nop 0
	v_add_f32_e32 v141, 1.0, v141
	v_rcp_f32_e32 v141, v141
	s_nop 0
	v_mul_f32_e32 v141, v140, v141
	v_cndmask_b32_e32 v141, v140, v141, vcc
	v_mul_f32_e32 v140, v118, v134
	v_mul_f32_e32 v142, 0xbfb8aa3b, v140
	v_exp_f32_e32 v142, v142
	v_cvt_pk_bf16_f32 v141, v139, v141
	s_nop 0
	v_add_f32_e32 v142, 1.0, v142
	v_rcp_f32_e32 v142, v142
	s_nop 0
	v_mul_f32_e32 v142, v140, v142
	v_cndmask_b32_e32 v142, v140, v142, vcc
	v_mul_f32_e32 v140, v119, v134
	v_mul_f32_e32 v143, 0xbfb8aa3b, v140
	v_exp_f32_e32 v143, v143
	s_nop 0
	v_add_f32_e32 v143, 1.0, v143
	v_rcp_f32_e32 v143, v143
	s_nop 0
	v_mul_f32_e32 v143, v140, v143
	v_cndmask_b32_e32 v143, v140, v143, vcc
	v_mul_f32_e32 v140, v120, v134
	v_mul_f32_e32 v144, 0xbfb8aa3b, v140
	v_exp_f32_e32 v144, v144
	v_mul_f32_e32 v134, v121, v134
	v_cvt_pk_bf16_f32 v142, v142, v143
	v_add_f32_e32 v144, 1.0, v144
	v_rcp_f32_e32 v144, v144
	s_nop 0
	v_mul_f32_e32 v144, v140, v144
	v_cndmask_b32_e32 v144, v140, v144, vcc
	v_mul_f32_e32 v140, 0xbfb8aa3b, v134
	v_exp_f32_e32 v140, v140
	s_nop 0
	v_add_f32_e32 v140, 1.0, v140
	v_rcp_f32_e32 v140, v140
	s_nop 0
	v_mul_f32_e32 v140, v134, v140
	v_cndmask_b32_e32 v134, v134, v140, vcc
	v_cvt_pk_bf16_f32 v143, v144, v134
	v_mul_f32_e32 v134, v106, v135
	v_mul_f32_e32 v139, 0xbfb8aa3b, v134
	v_exp_f32_e32 v139, v139
	v_cvt_pk_bf16_f32 v140, v136, v137
	global_store_dwordx4 v[130:131], v[140:143], off offset:256 sc1
	v_lshlrev_b64 v[136:137], 12, v[216:217]
	v_add_f32_e32 v139, 1.0, v139
	v_rcp_f32_e32 v139, v139
	v_lshl_add_u64 v[136:137], v[132:133], 0, v[136:137]
	v_mul_f32_e32 v139, v134, v139
	v_cndmask_b32_e32 v134, v134, v139, vcc
; __device__ __forceinline__ v4u pack8(const float (&f)[8]) { v4u w; w.x = cvt_pk_bf16(f[0], f[1]); w.y = cvt_pk_bf16(f[2], f[3]); w.z = cvt_pk_bf16(f[4], f[5]); w.w = cvt_pk_bf16(f[6], f[7]); return w; }
; __device__ __forceinline__ float siluf_(float x) { return x * rcpf_(1.f + __expf(-x)); }
;     __device__ __forceinline__ void operator()(const f32x4 (&acc)[2][2][4][2], const Unit& u, int wr, int wc, int fr, int fq) const {
;     ...
;                 const bool isg = u.pn >= 16;
;                 bf16* base = (isg ? SG : V) + ((u.pn - (isg ? 16 : 8)) * 256) + cw;
; #pragma unroll
;                 for (int ai = 0; ai < 2; ++ai)
; #pragma unroll
;                     for (int m = 0; m < 4; ++m) {
;                         bf16* rp = base + (size_t)(row0 + ai * 128 + m * 16) * 2048;
;                         const float rs = rtab[u.ord * 256 + (wr * 64 + fr + ai * 128 + m * 16)];
; #pragma unroll
;                         for (int bj = 0; bj < 2; ++bj) {
;                             float o[8];
; #pragma unroll
;                             for (int n = 0; n < 2; ++n)
; #pragma unroll
;                                 for (int j = 0; j < 4; ++j) { const float x = acc[ai][bj][m][n][j] * rs; o[n * 4 + j] = isg ? siluf_(x) : x; }
;                             *(v4u*)(rp + bj * 128) = pack8(o);
;                         }
;                     }
	v_mul_f32_e32 v139, v107, v135
	v_mul_f32_e32 v140, 0xbfb8aa3b, v139
	v_exp_f32_e32 v140, v140
	s_nop 0
	v_add_f32_e32 v140, 1.0, v140
	v_rcp_f32_e32 v140, v140
	s_nop 0
	v_mul_f32_e32 v140, v139, v140
	v_cndmask_b32_e32 v139, v139, v140, vcc
	v_mul_f32_e32 v140, v108, v135
	v_mul_f32_e32 v141, 0xbfb8aa3b, v140
	v_exp_f32_e32 v141, v141
	s_nop 0
	v_add_f32_e32 v141, 1.0, v141
	v_rcp_f32_e32 v141, v141
	s_nop 0
	v_mul_f32_e32 v141, v140, v141
	v_cndmask_b32_e32 v141, v140, v141, vcc
	v_mul_f32_e32 v140, v109, v135
	v_mul_f32_e32 v142, 0xbfb8aa3b, v140
	v_exp_f32_e32 v142, v142
	s_nop 0
	v_add_f32_e32 v142, 1.0, v142
	v_rcp_f32_e32 v142, v142
	s_nop 0
	v_mul_f32_e32 v142, v140, v142
	v_cndmask_b32_e32 v142, v140, v142, vcc
	v_mul_f32_e32 v140, v98, v135
	v_mul_f32_e32 v143, 0xbfb8aa3b, v140
	v_exp_f32_e32 v143, v143
	v_cvt_pk_bf16_f32 v141, v141, v142
	s_nop 0
	v_add_f32_e32 v143, 1.0, v143
	v_rcp_f32_e32 v143, v143
	s_nop 0
	v_mul_f32_e32 v143, v140, v143
	v_cndmask_b32_e32 v143, v140, v143, vcc
	v_mul_f32_e32 v140, v99, v135
	v_mul_f32_e32 v144, 0xbfb8aa3b, v140
	v_exp_f32_e32 v144, v144
	s_nop 0
	v_add_f32_e32 v144, 1.0, v144
	v_rcp_f32_e32 v144, v144
	s_nop 0
	v_mul_f32_e32 v144, v140, v144
	v_cndmask_b32_e32 v144, v140, v144, vcc
	v_mul_f32_e32 v140, v100, v135
	v_mul_f32_e32 v145, 0xbfb8aa3b, v140
	v_exp_f32_e32 v145, v145
	v_cvt_pk_bf16_f32 v142, v143, v144
	s_nop 0
	v_add_f32_e32 v145, 1.0, v145
	v_rcp_f32_e32 v145, v145
	s_nop 0
	v_mul_f32_e32 v145, v140, v145
	v_cndmask_b32_e32 v145, v140, v145, vcc
	v_mul_f32_e32 v140, v101, v135
	v_mul_f32_e32 v146, 0xbfb8aa3b, v140
	v_exp_f32_e32 v146, v146
	s_nop 0
	v_add_f32_e32 v146, 1.0, v146
	v_rcp_f32_e32 v146, v146
	s_nop 0
	v_mul_f32_e32 v146, v140, v146
	v_cndmask_b32_e32 v146, v140, v146, vcc
	v_cvt_pk_bf16_f32 v140, v134, v139
	v_mul_f32_e32 v134, v110, v135
	v_mul_f32_e32 v139, 0xbfb8aa3b, v134
	v_exp_f32_e32 v139, v139
	v_cvt_pk_bf16_f32 v143, v145, v146
	global_store_dwordx4 v[136:137], v[140:143], off sc1
	v_add_f32_e32 v139, 1.0, v139
	v_rcp_f32_e32 v139, v139
	s_nop 0
	v_mul_f32_e32 v139, v134, v139
	v_cndmask_b32_e32 v134, v134, v139, vcc
	v_mul_f32_e32 v139, v111, v135
	v_mul_f32_e32 v140, 0xbfb8aa3b, v139
	v_exp_f32_e32 v140, v140
	s_nop 0
	v_add_f32_e32 v140, 1.0, v140
	v_rcp_f32_e32 v140, v140
	s_nop 0
	v_mul_f32_e32 v140, v139, v140
	v_cndmask_b32_e32 v139, v139, v140, vcc
	v_mul_f32_e32 v140, v112, v135
	v_mul_f32_e32 v141, 0xbfb8aa3b, v140
	v_exp_f32_e32 v141, v141
	s_nop 0
	v_add_f32_e32 v141, 1.0, v141
	v_rcp_f32_e32 v141, v141
	s_nop 0
	v_mul_f32_e32 v141, v140, v141
	v_cndmask_b32_e32 v141, v140, v141, vcc
	v_mul_f32_e32 v140, v113, v135
	v_mul_f32_e32 v142, 0xbfb8aa3b, v140
	v_exp_f32_e32 v142, v142
	s_nop 0
	v_add_f32_e32 v142, 1.0, v142
	v_rcp_f32_e32 v142, v142
	s_nop 0
	v_mul_f32_e32 v142, v140, v142
	v_cndmask_b32_e32 v142, v140, v142, vcc
	v_mul_f32_e32 v140, v102, v135
	v_mul_f32_e32 v143, 0xbfb8aa3b, v140
	v_exp_f32_e32 v143, v143
	v_cvt_pk_bf16_f32 v141, v141, v142
	s_nop 0
	v_add_f32_e32 v143, 1.0, v143
	v_rcp_f32_e32 v143, v143
	s_nop 0
	v_mul_f32_e32 v143, v140, v143
	v_cndmask_b32_e32 v143, v140, v143, vcc
	v_mul_f32_e32 v140, v103, v135
	v_mul_f32_e32 v144, 0xbfb8aa3b, v140
	v_exp_f32_e32 v144, v144
	s_nop 0
	v_add_f32_e32 v144, 1.0, v144
	v_rcp_f32_e32 v144, v144
	s_nop 0
	v_mul_f32_e32 v144, v140, v144
	v_cndmask_b32_e32 v144, v140, v144, vcc
	v_mul_f32_e32 v140, v104, v135
	v_mul_f32_e32 v145, 0xbfb8aa3b, v140
	v_exp_f32_e32 v145, v145
	v_mul_f32_e32 v135, v105, v135
	v_cvt_pk_bf16_f32 v142, v143, v144
	v_add_f32_e32 v145, 1.0, v145
	v_rcp_f32_e32 v145, v145
	s_nop 0
	v_mul_f32_e32 v145, v140, v145
	v_cndmask_b32_e32 v145, v140, v145, vcc
	v_mul_f32_e32 v140, 0xbfb8aa3b, v135
	v_exp_f32_e32 v140, v140
	s_nop 0
	v_add_f32_e32 v140, 1.0, v140
	v_rcp_f32_e32 v140, v140
	s_nop 0
	v_mul_f32_e32 v140, v135, v140
	v_cndmask_b32_e32 v135, v135, v140, vcc
	v_cvt_pk_bf16_f32 v140, v134, v139
	v_cvt_pk_bf16_f32 v143, v145, v135
	v_lshlrev_b64 v[134:135], 12, v[214:215]
	global_store_dwordx4 v[136:137], v[140:143], off offset:256 sc1
	v_lshl_add_u64 v[136:137], v[132:133], 0, v[134:135]
	ds_read2_b32 v[134:135], v138 offset0:32 offset1:48
	s_waitcnt lgkmcnt(0)
	v_mul_f32_e32 v139, v90, v134
	v_mul_f32_e32 v140, 0xbfb8aa3b, v139
	v_exp_f32_e32 v140, v140
	s_nop 0
	v_add_f32_e32 v140, 1.0, v140
	v_rcp_f32_e32 v140, v140
	s_nop 0
	v_mul_f32_e32 v140, v139, v140
	v_cndmask_b32_e32 v139, v139, v140, vcc
	v_mul_f32_e32 v140, v91, v134
	v_mul_f32_e32 v141, 0xbfb8aa3b, v140
	v_exp_f32_e32 v141, v141
	s_nop 0
	v_add_f32_e32 v141, 1.0, v141
	v_rcp_f32_e32 v141, v141
	s_nop 0
	v_mul_f32_e32 v141, v140, v141
	v_cndmask_b32_e32 v140, v140, v141, vcc
	v_mul_f32_e32 v141, v92, v134
	v_mul_f32_e32 v142, 0xbfb8aa3b, v141
	v_exp_f32_e32 v142, v142
	v_cvt_pk_bf16_f32 v140, v139, v140
	v_mul_f32_e32 v139, v94, v134
	v_add_f32_e32 v142, 1.0, v142
	v_rcp_f32_e32 v142, v142
	s_nop 0
	v_mul_f32_e32 v142, v141, v142
	v_cndmask_b32_e32 v141, v141, v142, vcc
	v_mul_f32_e32 v142, v93, v134
	v_mul_f32_e32 v143, 0xbfb8aa3b, v142
	v_exp_f32_e32 v143, v143
	s_nop 0
	v_add_f32_e32 v143, 1.0, v143
	v_rcp_f32_e32 v143, v143
	s_nop 0
	v_mul_f32_e32 v143, v142, v143
	v_cndmask_b32_e32 v142, v142, v143, vcc
	v_mul_f32_e32 v143, v82, v134
	v_mul_f32_e32 v144, 0xbfb8aa3b, v143
	v_exp_f32_e32 v144, v144
	v_cvt_pk_bf16_f32 v141, v141, v142
	s_nop 0
	v_add_f32_e32 v144, 1.0, v144
	v_rcp_f32_e32 v144, v144
	s_nop 0
	v_mul_f32_e32 v144, v143, v144
	v_cndmask_b32_e32 v143, v143, v144, vcc
	v_mul_f32_e32 v144, v83, v134
	v_mul_f32_e32 v145, 0xbfb8aa3b, v144
	v_exp_f32_e32 v145, v145
	s_nop 0
; __device__ __forceinline__ v4u pack8(const float (&f)[8]) { v4u w; w.x = cvt_pk_bf16(f[0], f[1]); w.y = cvt_pk_bf16(f[2], f[3]); w.z = cvt_pk_bf16(f[4], f[5]); w.w = cvt_pk_bf16(f[6], f[7]); return w; }
; __device__ __forceinline__ float siluf_(float x) { return x * rcpf_(1.f + __expf(-x)); }
;     __device__ __forceinline__ void operator()(const f32x4 (&acc)[2][2][4][2], const Unit& u, int wr, int wc, int fr, int fq) const {
;     ...
;                 const bool isg = u.pn >= 16;
;                 bf16* base = (isg ? SG : V) + ((u.pn - (isg ? 16 : 8)) * 256) + cw;
; #pragma unroll
;                 for (int ai = 0; ai < 2; ++ai)
; #pragma unroll
;                     for (int m = 0; m < 4; ++m) {
;                         bf16* rp = base + (size_t)(row0 + ai * 128 + m * 16) * 2048;
;                         const float rs = rtab[u.ord * 256 + (wr * 64 + fr + ai * 128 + m * 16)];
; #pragma unroll
;                         for (int bj = 0; bj < 2; ++bj) {
;                             float o[8];
; #pragma unroll
;                             for (int n = 0; n < 2; ++n)
; #pragma unroll
;                                 for (int j = 0; j < 4; ++j) { const float x = acc[ai][bj][m][n][j] * rs; o[n * 4 + j] = isg ? siluf_(x) : x; }
;                             *(v4u*)(rp + bj * 128) = pack8(o);
;                         }
;                     }
	v_add_f32_e32 v145, 1.0, v145
	v_rcp_f32_e32 v145, v145
	s_nop 0
	v_mul_f32_e32 v145, v144, v145
	v_cndmask_b32_e32 v144, v144, v145, vcc
	v_mul_f32_e32 v145, v84, v134
	v_mul_f32_e32 v146, 0xbfb8aa3b, v145
	v_exp_f32_e32 v146, v146
	v_cvt_pk_bf16_f32 v142, v143, v144
	s_nop 0
	v_add_f32_e32 v146, 1.0, v146
	v_rcp_f32_e32 v146, v146
	s_nop 0
	v_mul_f32_e32 v146, v145, v146
	v_cndmask_b32_e32 v145, v145, v146, vcc
	v_mul_f32_e32 v146, v85, v134
	v_mul_f32_e32 v147, 0xbfb8aa3b, v146
	v_exp_f32_e32 v147, v147
	s_nop 0
	v_add_f32_e32 v147, 1.0, v147
	v_rcp_f32_e32 v147, v147
	s_nop 0
	v_mul_f32_e32 v147, v146, v147
	v_cndmask_b32_e32 v146, v146, v147, vcc
	v_cvt_pk_bf16_f32 v143, v145, v146
	global_store_dwordx4 v[136:137], v[140:143], off sc1
	s_nop 1
	v_mul_f32_e32 v140, 0xbfb8aa3b, v139
	v_exp_f32_e32 v140, v140
	s_nop 0
	v_add_f32_e32 v140, 1.0, v140
	v_rcp_f32_e32 v140, v140
	s_nop 0
	v_mul_f32_e32 v140, v139, v140
	v_cndmask_b32_e32 v139, v139, v140, vcc
	v_mul_f32_e32 v140, v95, v134
	v_mul_f32_e32 v141, 0xbfb8aa3b, v140
	v_exp_f32_e32 v141, v141
	s_nop 0
	v_add_f32_e32 v141, 1.0, v141
	v_rcp_f32_e32 v141, v141
	s_nop 0
	v_mul_f32_e32 v141, v140, v141
	v_cndmask_b32_e32 v140, v140, v141, vcc
	v_mul_f32_e32 v141, v96, v134
	v_mul_f32_e32 v142, 0xbfb8aa3b, v141
	v_exp_f32_e32 v142, v142
	v_cvt_pk_bf16_f32 v140, v139, v140
	s_nop 0
	v_add_f32_e32 v142, 1.0, v142
	v_rcp_f32_e32 v142, v142
	s_nop 0
	v_mul_f32_e32 v142, v141, v142
	v_cndmask_b32_e32 v141, v141, v142, vcc
	v_mul_f32_e32 v142, v97, v134
	v_mul_f32_e32 v143, 0xbfb8aa3b, v142
	v_exp_f32_e32 v143, v143
	s_nop 0
	v_add_f32_e32 v143, 1.0, v143
	v_rcp_f32_e32 v143, v143
	s_nop 0
	v_mul_f32_e32 v143, v142, v143
	v_cndmask_b32_e32 v142, v142, v143, vcc
	v_mul_f32_e32 v143, v86, v134
	v_mul_f32_e32 v144, 0xbfb8aa3b, v143
	v_exp_f32_e32 v144, v144
	v_cvt_pk_bf16_f32 v141, v141, v142
	s_nop 0
	v_add_f32_e32 v144, 1.0, v144
	v_rcp_f32_e32 v144, v144
	s_nop 0
	v_mul_f32_e32 v144, v143, v144
	v_cndmask_b32_e32 v143, v143, v144, vcc
	v_mul_f32_e32 v144, v87, v134
	v_mul_f32_e32 v145, 0xbfb8aa3b, v144
	v_exp_f32_e32 v145, v145
	s_nop 0
	v_add_f32_e32 v145, 1.0, v145
	v_rcp_f32_e32 v145, v145
	s_nop 0
	v_mul_f32_e32 v145, v144, v145
	v_cndmask_b32_e32 v144, v144, v145, vcc
	v_mul_f32_e32 v145, v88, v134
	v_mul_f32_e32 v146, 0xbfb8aa3b, v145
	v_exp_f32_e32 v146, v146
	v_mul_f32_e32 v134, v89, v134
	v_cvt_pk_bf16_f32 v142, v143, v144
	v_add_f32_e32 v146, 1.0, v146
	v_rcp_f32_e32 v146, v146
	s_nop 0
	v_mul_f32_e32 v146, v145, v146
	v_cndmask_b32_e32 v145, v145, v146, vcc
	v_mul_f32_e32 v146, 0xbfb8aa3b, v134
	v_exp_f32_e32 v146, v146
	s_nop 0
	v_add_f32_e32 v146, 1.0, v146
	v_rcp_f32_e32 v146, v146
	s_nop 0
	v_mul_f32_e32 v146, v134, v146
	v_cndmask_b32_e32 v134, v134, v146, vcc
	v_cvt_pk_bf16_f32 v143, v145, v134
	global_store_dwordx4 v[136:137], v[140:143], off offset:256 sc1
	v_lshlrev_b64 v[136:137], 12, v[212:213]
	v_mul_f32_e32 v134, v74, v135
	v_lshl_add_u64 v[132:133], v[132:133], 0, v[136:137]
	v_mul_f32_e32 v136, 0xbfb8aa3b, v134
	v_exp_f32_e32 v136, v136
	s_nop 0
	v_add_f32_e32 v136, 1.0, v136
	v_rcp_f32_e32 v136, v136
	s_nop 0
	v_mul_f32_e32 v136, v134, v136
	v_cndmask_b32_e32 v134, v134, v136, vcc
	v_mul_f32_e32 v136, v75, v135
	v_mul_f32_e32 v137, 0xbfb8aa3b, v136
	v_exp_f32_e32 v137, v137
	s_nop 0
	v_add_f32_e32 v137, 1.0, v137
	v_rcp_f32_e32 v137, v137
	s_nop 0
	v_mul_f32_e32 v137, v136, v137
	v_cndmask_b32_e32 v136, v136, v137, vcc
	v_mul_f32_e32 v137, v76, v135
	v_mul_f32_e32 v139, 0xbfb8aa3b, v137
	v_exp_f32_e32 v139, v139
	s_nop 0
	v_add_f32_e32 v139, 1.0, v139
	v_rcp_f32_e32 v139, v139
	s_nop 0
	v_mul_f32_e32 v139, v137, v139
	v_cndmask_b32_e32 v137, v137, v139, vcc
	v_mul_f32_e32 v139, v77, v135
	v_mul_f32_e32 v140, 0xbfb8aa3b, v139
	v_exp_f32_e32 v140, v140
	s_nop 0
	v_add_f32_e32 v140, 1.0, v140
	v_rcp_f32_e32 v140, v140
	s_nop 0
	v_mul_f32_e32 v140, v139, v140
	v_cndmask_b32_e32 v139, v139, v140, vcc
	v_mul_f32_e32 v140, v66, v135
	v_mul_f32_e32 v141, 0xbfb8aa3b, v140
	v_exp_f32_e32 v141, v141
	s_nop 0
	v_add_f32_e32 v141, 1.0, v141
	v_rcp_f32_e32 v141, v141
	s_nop 0
	v_mul_f32_e32 v141, v140, v141
	v_cndmask_b32_e32 v142, v140, v141, vcc
	v_mul_f32_e32 v140, v67, v135
	v_mul_f32_e32 v141, 0xbfb8aa3b, v140
	v_exp_f32_e32 v141, v141
	s_nop 0
	v_add_f32_e32 v141, 1.0, v141
	v_rcp_f32_e32 v141, v141
	s_nop 0
	v_mul_f32_e32 v141, v140, v141
	v_cndmask_b32_e32 v143, v140, v141, vcc
	v_mul_f32_e32 v140, v68, v135
	v_mul_f32_e32 v141, 0xbfb8aa3b, v140
	v_exp_f32_e32 v141, v141
	v_cvt_pk_bf16_f32 v142, v142, v143
	s_nop 0
	v_add_f32_e32 v141, 1.0, v141
	v_rcp_f32_e32 v141, v141
	s_nop 0
	v_mul_f32_e32 v141, v140, v141
	v_cndmask_b32_e32 v144, v140, v141, vcc
	v_mul_f32_e32 v140, v69, v135
	v_mul_f32_e32 v141, 0xbfb8aa3b, v140
	v_exp_f32_e32 v141, v141
	s_nop 0
	v_add_f32_e32 v141, 1.0, v141
	v_rcp_f32_e32 v141, v141
	s_nop 0
	v_mul_f32_e32 v141, v140, v141
	v_cndmask_b32_e32 v145, v140, v141, vcc
	v_cvt_pk_bf16_f32 v140, v134, v136
	v_mul_f32_e32 v134, v78, v135
	v_mul_f32_e32 v136, 0xbfb8aa3b, v134
	v_exp_f32_e32 v136, v136
	v_cvt_pk_bf16_f32 v141, v137, v139
	v_cvt_pk_bf16_f32 v143, v144, v145
	global_store_dwordx4 v[132:133], v[140:143], off sc1
	v_add_f32_e32 v136, 1.0, v136
	v_rcp_f32_e32 v136, v136
	s_nop 0
	v_mul_f32_e32 v136, v134, v136
	v_cndmask_b32_e32 v134, v134, v136, vcc
	v_mul_f32_e32 v136, v79, v135
	v_mul_f32_e32 v137, 0xbfb8aa3b, v136
	v_exp_f32_e32 v137, v137
	s_nop 0
	v_add_f32_e32 v137, 1.0, v137
	v_rcp_f32_e32 v137, v137
	s_nop 0
	v_mul_f32_e32 v137, v136, v137
	v_cndmask_b32_e32 v136, v136, v137, vcc
	v_mul_f32_e32 v137, v80, v135
	v_mul_f32_e32 v139, 0xbfb8aa3b, v137
; __device__ __forceinline__ v4u pack8(const float (&f)[8]) { v4u w; w.x = cvt_pk_bf16(f[0], f[1]); w.y = cvt_pk_bf16(f[2], f[3]); w.z = cvt_pk_bf16(f[4], f[5]); w.w = cvt_pk_bf16(f[6], f[7]); return w; }
; __device__ __forceinline__ float siluf_(float x) { return x * rcpf_(1.f + __expf(-x)); }
;     __device__ __forceinline__ void operator()(const f32x4 (&acc)[2][2][4][2], const Unit& u, int wr, int wc, int fr, int fq) const {
;     ...
;                 const bool isg = u.pn >= 16;
;                 bf16* base = (isg ? SG : V) + ((u.pn - (isg ? 16 : 8)) * 256) + cw;
; #pragma unroll
;                 for (int ai = 0; ai < 2; ++ai)
; #pragma unroll
;                     for (int m = 0; m < 4; ++m) {
;                         bf16* rp = base + (size_t)(row0 + ai * 128 + m * 16) * 2048;
;                         const float rs = rtab[u.ord * 256 + (wr * 64 + fr + ai * 128 + m * 16)];
; #pragma unroll
;                         for (int bj = 0; bj < 2; ++bj) {
;                             float o[8];
; #pragma unroll
;                             for (int n = 0; n < 2; ++n)
; #pragma unroll
;                                 for (int j = 0; j < 4; ++j) { const float x = acc[ai][bj][m][n][j] * rs; o[n * 4 + j] = isg ? siluf_(x) : x; }
;                             *(v4u*)(rp + bj * 128) = pack8(o);
;                         }
;                     }
	v_exp_f32_e32 v139, v139
	v_cvt_pk_bf16_f32 v134, v134, v136
	s_nop 0
	v_add_f32_e32 v139, 1.0, v139
	v_rcp_f32_e32 v139, v139
	s_nop 0
	v_mul_f32_e32 v139, v137, v139
	v_cndmask_b32_e32 v137, v137, v139, vcc
	v_mul_f32_e32 v139, v81, v135
	v_mul_f32_e32 v140, 0xbfb8aa3b, v139
	v_exp_f32_e32 v140, v140
	s_nop 0
	v_add_f32_e32 v140, 1.0, v140
	v_rcp_f32_e32 v140, v140
	s_nop 0
	v_mul_f32_e32 v140, v139, v140
	v_cndmask_b32_e32 v139, v139, v140, vcc
	v_mul_f32_e32 v140, v70, v135
	v_mul_f32_e32 v141, 0xbfb8aa3b, v140
	v_exp_f32_e32 v141, v141
	s_nop 0
	v_add_f32_e32 v141, 1.0, v141
	v_rcp_f32_e32 v141, v141
	s_nop 0
	v_mul_f32_e32 v141, v140, v141
	v_cndmask_b32_e32 v140, v140, v141, vcc
	v_mul_f32_e32 v141, v71, v135
	v_mul_f32_e32 v142, 0xbfb8aa3b, v141
	v_exp_f32_e32 v142, v142
	s_nop 0
	v_add_f32_e32 v142, 1.0, v142
	v_rcp_f32_e32 v142, v142
	s_nop 0
	v_mul_f32_e32 v142, v141, v142
	v_cndmask_b32_e32 v141, v141, v142, vcc
	v_mul_f32_e32 v142, v72, v135
	v_mul_f32_e32 v143, 0xbfb8aa3b, v142
	v_exp_f32_e32 v143, v143
	v_mul_f32_e32 v135, v73, v135
	v_cvt_pk_bf16_f32 v136, v140, v141
	v_add_f32_e32 v143, 1.0, v143
	v_rcp_f32_e32 v143, v143
	s_nop 0
	v_mul_f32_e32 v143, v142, v143
	v_cndmask_b32_e32 v142, v142, v143, vcc
	v_mul_f32_e32 v143, 0xbfb8aa3b, v135
	v_exp_f32_e32 v143, v143
	s_nop 0
	v_add_f32_e32 v143, 1.0, v143
	v_rcp_f32_e32 v143, v143
	s_nop 0
	v_mul_f32_e32 v143, v135, v143
	v_cndmask_b32_e32 v143, v135, v143, vcc
	v_cvt_pk_bf16_f32 v135, v137, v139
	v_cvt_pk_bf16_f32 v137, v142, v143
	global_store_dwordx4 v[132:133], v[134:137], off offset:256 sc1
	ds_read2_b32 v[132:133], v138 offset0:128 offset1:144
	s_nop 0
	v_lshl_add_u64 v[134:135], v[130:131], 0, s[0:1]
	s_mov_b32 s0, 0x80000
	s_waitcnt lgkmcnt(0)
	v_mul_f32_e32 v136, v58, v132
	v_mul_f32_e32 v137, 0xbfb8aa3b, v136
	v_exp_f32_e32 v137, v137
	s_nop 0
	v_add_f32_e32 v137, 1.0, v137
	v_rcp_f32_e32 v137, v137
	s_nop 0
	v_mul_f32_e32 v137, v136, v137
	v_cndmask_b32_e32 v136, v136, v137, vcc
	v_mul_f32_e32 v137, v59, v132
	v_mul_f32_e32 v139, 0xbfb8aa3b, v137
	v_exp_f32_e32 v139, v139
	s_nop 0
	v_add_f32_e32 v139, 1.0, v139
	v_rcp_f32_e32 v139, v139
	s_nop 0
	v_mul_f32_e32 v139, v137, v139
	v_cndmask_b32_e32 v137, v137, v139, vcc
	v_mul_f32_e32 v139, v60, v132
	v_mul_f32_e32 v140, 0xbfb8aa3b, v139
	v_exp_f32_e32 v140, v140
	s_nop 0
	v_add_f32_e32 v140, 1.0, v140
	v_rcp_f32_e32 v140, v140
	s_nop 0
	v_mul_f32_e32 v140, v139, v140
	v_cndmask_b32_e32 v139, v139, v140, vcc
	v_mul_f32_e32 v140, v61, v132
	v_mul_f32_e32 v141, 0xbfb8aa3b, v140
	v_exp_f32_e32 v141, v141
	s_nop 0
	v_add_f32_e32 v141, 1.0, v141
	v_rcp_f32_e32 v141, v141
	s_nop 0
	v_mul_f32_e32 v141, v140, v141
	v_cndmask_b32_e32 v141, v140, v141, vcc
	v_mul_f32_e32 v140, v50, v132
	v_mul_f32_e32 v142, 0xbfb8aa3b, v140
	v_exp_f32_e32 v142, v142
	v_cvt_pk_bf16_f32 v141, v139, v141
	s_nop 0
	v_add_f32_e32 v142, 1.0, v142
	v_rcp_f32_e32 v142, v142
	s_nop 0
	v_mul_f32_e32 v142, v140, v142
	v_cndmask_b32_e32 v142, v140, v142, vcc
	v_mul_f32_e32 v140, v51, v132
	v_mul_f32_e32 v143, 0xbfb8aa3b, v140
	v_exp_f32_e32 v143, v143
	s_nop 0
	v_add_f32_e32 v143, 1.0, v143
	v_rcp_f32_e32 v143, v143
	s_nop 0
	v_mul_f32_e32 v143, v140, v143
	v_cndmask_b32_e32 v143, v140, v143, vcc
	v_mul_f32_e32 v140, v52, v132
	v_mul_f32_e32 v144, 0xbfb8aa3b, v140
	v_exp_f32_e32 v144, v144
	v_cvt_pk_bf16_f32 v142, v142, v143
	s_nop 0
	v_add_f32_e32 v144, 1.0, v144
	v_rcp_f32_e32 v144, v144
	s_nop 0
	v_mul_f32_e32 v144, v140, v144
	v_cndmask_b32_e32 v144, v140, v144, vcc
	v_mul_f32_e32 v140, v53, v132
	v_mul_f32_e32 v145, 0xbfb8aa3b, v140
	v_exp_f32_e32 v145, v145
	s_nop 0
	v_add_f32_e32 v145, 1.0, v145
	v_rcp_f32_e32 v145, v145
	s_nop 0
	v_mul_f32_e32 v145, v140, v145
	v_cndmask_b32_e32 v145, v140, v145, vcc
	v_cvt_pk_bf16_f32 v140, v136, v137
	v_add_co_u32_e64 v136, s[0:1], s0, v130
	v_cvt_pk_bf16_f32 v143, v144, v145
	s_nop 1
	v_addc_co_u32_e64 v137, s[0:1], 0, v131, s[0:1]
	global_store_dwordx4 v[136:137], v[140:143], off sc1
	v_mul_f32_e32 v136, v62, v132
	v_mul_f32_e32 v137, 0xbfb8aa3b, v136
	v_exp_f32_e32 v137, v137
	s_mov_b64 s[0:1], 0x90000
	v_add_f32_e32 v137, 1.0, v137
	v_rcp_f32_e32 v137, v137
	s_nop 0
	v_mul_f32_e32 v137, v136, v137
	v_cndmask_b32_e32 v136, v136, v137, vcc
	v_mul_f32_e32 v137, v63, v132
	v_mul_f32_e32 v139, 0xbfb8aa3b, v137
	v_exp_f32_e32 v139, v139
	s_nop 0
	v_add_f32_e32 v139, 1.0, v139
	v_rcp_f32_e32 v139, v139
	s_nop 0
	v_mul_f32_e32 v139, v137, v139
	v_cndmask_b32_e32 v137, v137, v139, vcc
	v_mul_f32_e32 v139, v64, v132
	v_mul_f32_e32 v140, 0xbfb8aa3b, v139
	v_exp_f32_e32 v140, v140
	s_nop 0
	v_add_f32_e32 v140, 1.0, v140
	v_rcp_f32_e32 v140, v140
	s_nop 0
	v_mul_f32_e32 v140, v139, v140
	v_cndmask_b32_e32 v139, v139, v140, vcc
	v_mul_f32_e32 v140, v65, v132
	v_mul_f32_e32 v141, 0xbfb8aa3b, v140
	v_exp_f32_e32 v141, v141
	s_nop 0
	v_add_f32_e32 v141, 1.0, v141
	v_rcp_f32_e32 v141, v141
	s_nop 0
	v_mul_f32_e32 v141, v140, v141
	v_cndmask_b32_e32 v141, v140, v141, vcc
	v_mul_f32_e32 v140, v54, v132
	v_mul_f32_e32 v142, 0xbfb8aa3b, v140
	v_exp_f32_e32 v142, v142
	v_cvt_pk_bf16_f32 v141, v139, v141
	s_nop 0
	v_add_f32_e32 v142, 1.0, v142
	v_rcp_f32_e32 v142, v142
	s_nop 0
	v_mul_f32_e32 v142, v140, v142
	v_cndmask_b32_e32 v142, v140, v142, vcc
	v_mul_f32_e32 v140, v55, v132
	v_mul_f32_e32 v143, 0xbfb8aa3b, v140
	v_exp_f32_e32 v143, v143
	s_nop 0
	v_add_f32_e32 v143, 1.0, v143
	v_rcp_f32_e32 v143, v143
	s_nop 0
	v_mul_f32_e32 v143, v140, v143
	v_cndmask_b32_e32 v143, v140, v143, vcc
	v_mul_f32_e32 v140, v56, v132
	v_mul_f32_e32 v144, 0xbfb8aa3b, v140
	v_exp_f32_e32 v144, v144
	v_mul_f32_e32 v132, v57, v132
; __device__ __forceinline__ v4u pack8(const float (&f)[8]) { v4u w; w.x = cvt_pk_bf16(f[0], f[1]); w.y = cvt_pk_bf16(f[2], f[3]); w.z = cvt_pk_bf16(f[4], f[5]); w.w = cvt_pk_bf16(f[6], f[7]); return w; }
; __device__ __forceinline__ float siluf_(float x) { return x * rcpf_(1.f + __expf(-x)); }
;     __device__ __forceinline__ void operator()(const f32x4 (&acc)[2][2][4][2], const Unit& u, int wr, int wc, int fr, int fq) const {
;     ...
;                 const bool isg = u.pn >= 16;
;                 bf16* base = (isg ? SG : V) + ((u.pn - (isg ? 16 : 8)) * 256) + cw;
; #pragma unroll
;                 for (int ai = 0; ai < 2; ++ai)
; #pragma unroll
;                     for (int m = 0; m < 4; ++m) {
;                         bf16* rp = base + (size_t)(row0 + ai * 128 + m * 16) * 2048;
;                         const float rs = rtab[u.ord * 256 + (wr * 64 + fr + ai * 128 + m * 16)];
; #pragma unroll
;                         for (int bj = 0; bj < 2; ++bj) {
;                             float o[8];
; #pragma unroll
;                             for (int n = 0; n < 2; ++n)
; #pragma unroll
;                                 for (int j = 0; j < 4; ++j) { const float x = acc[ai][bj][m][n][j] * rs; o[n * 4 + j] = isg ? siluf_(x) : x; }
;                             *(v4u*)(rp + bj * 128) = pack8(o);
;                         }
;                     }
	v_cvt_pk_bf16_f32 v142, v142, v143
	v_add_f32_e32 v144, 1.0, v144
	v_rcp_f32_e32 v144, v144
	s_nop 0
	v_mul_f32_e32 v144, v140, v144
	v_cndmask_b32_e32 v144, v140, v144, vcc
	v_mul_f32_e32 v140, 0xbfb8aa3b, v132
	v_exp_f32_e32 v140, v140
	s_nop 0
	v_add_f32_e32 v140, 1.0, v140
	v_rcp_f32_e32 v140, v140
	s_nop 0
	v_mul_f32_e32 v140, v132, v140
	v_cndmask_b32_e32 v132, v132, v140, vcc
	v_cvt_pk_bf16_f32 v143, v144, v132
	v_mul_f32_e32 v132, v42, v133
	v_cvt_pk_bf16_f32 v140, v136, v137
	v_mul_f32_e32 v136, 0xbfb8aa3b, v132
	v_exp_f32_e32 v136, v136
	global_store_dwordx4 v[134:135], v[140:143], off offset:256 sc1
	v_lshl_add_u64 v[134:135], v[130:131], 0, s[0:1]
	s_mov_b32 s0, 0x90000
	v_add_f32_e32 v136, 1.0, v136
	v_rcp_f32_e32 v136, v136
	s_nop 0
	v_mul_f32_e32 v136, v132, v136
	v_cndmask_b32_e32 v132, v132, v136, vcc
	v_mul_f32_e32 v136, v43, v133
	v_mul_f32_e32 v137, 0xbfb8aa3b, v136
	v_exp_f32_e32 v137, v137
	s_nop 0
	v_add_f32_e32 v137, 1.0, v137
	v_rcp_f32_e32 v137, v137
	s_nop 0
	v_mul_f32_e32 v137, v136, v137
	v_cndmask_b32_e32 v136, v136, v137, vcc
	v_mul_f32_e32 v137, v44, v133
	v_mul_f32_e32 v139, 0xbfb8aa3b, v137
	v_exp_f32_e32 v139, v139
	s_nop 0
	v_add_f32_e32 v139, 1.0, v139
	v_rcp_f32_e32 v139, v139
	s_nop 0
	v_mul_f32_e32 v139, v137, v139
	v_cndmask_b32_e32 v137, v137, v139, vcc
	v_mul_f32_e32 v139, v45, v133
	v_mul_f32_e32 v140, 0xbfb8aa3b, v139
	v_exp_f32_e32 v140, v140
	s_nop 0
	v_add_f32_e32 v140, 1.0, v140
	v_rcp_f32_e32 v140, v140
	s_nop 0
	v_mul_f32_e32 v140, v139, v140
	v_cndmask_b32_e32 v139, v139, v140, vcc
	v_mul_f32_e32 v140, v34, v133
	v_mul_f32_e32 v141, 0xbfb8aa3b, v140
	v_exp_f32_e32 v141, v141
	s_nop 0
	v_add_f32_e32 v141, 1.0, v141
	v_rcp_f32_e32 v141, v141
	s_nop 0
	v_mul_f32_e32 v141, v140, v141
	v_cndmask_b32_e32 v142, v140, v141, vcc
	v_mul_f32_e32 v140, v35, v133
	v_mul_f32_e32 v141, 0xbfb8aa3b, v140
	v_exp_f32_e32 v141, v141
	s_nop 0
	v_add_f32_e32 v141, 1.0, v141
	v_rcp_f32_e32 v141, v141
	s_nop 0
	v_mul_f32_e32 v141, v140, v141
	v_cndmask_b32_e32 v143, v140, v141, vcc
	v_mul_f32_e32 v140, v36, v133
	v_mul_f32_e32 v141, 0xbfb8aa3b, v140
	v_exp_f32_e32 v141, v141
	v_cvt_pk_bf16_f32 v142, v142, v143
	s_nop 0
	v_add_f32_e32 v141, 1.0, v141
	v_rcp_f32_e32 v141, v141
	s_nop 0
	v_mul_f32_e32 v141, v140, v141
	v_cndmask_b32_e32 v144, v140, v141, vcc
	v_mul_f32_e32 v140, v37, v133
	v_mul_f32_e32 v141, 0xbfb8aa3b, v140
	v_exp_f32_e32 v141, v141
	s_nop 0
	v_add_f32_e32 v141, 1.0, v141
	v_rcp_f32_e32 v141, v141
	s_nop 0
	v_mul_f32_e32 v141, v140, v141
	v_cndmask_b32_e32 v145, v140, v141, vcc
	v_cvt_pk_bf16_f32 v140, v132, v136
	v_add_co_u32_e64 v136, s[0:1], s0, v130
	v_cvt_pk_bf16_f32 v141, v137, v139
	v_mul_f32_e32 v132, v46, v133
	s_nop 0
	v_addc_co_u32_e64 v137, s[0:1], 0, v131, s[0:1]
	v_cvt_pk_bf16_f32 v143, v144, v145
	global_store_dwordx4 v[136:137], v[140:143], off sc1
	v_mul_f32_e32 v136, 0xbfb8aa3b, v132
	v_exp_f32_e32 v136, v136
	s_mov_b64 s[0:1], 0xa0000
	v_add_f32_e32 v136, 1.0, v136
	v_rcp_f32_e32 v136, v136
	s_nop 0
	v_mul_f32_e32 v136, v132, v136
	v_cndmask_b32_e32 v132, v132, v136, vcc
	v_mul_f32_e32 v136, v47, v133
	v_mul_f32_e32 v137, 0xbfb8aa3b, v136
	v_exp_f32_e32 v137, v137
	s_nop 0
	v_add_f32_e32 v137, 1.0, v137
	v_rcp_f32_e32 v137, v137
	s_nop 0
	v_mul_f32_e32 v137, v136, v137
	v_cndmask_b32_e32 v136, v136, v137, vcc
	v_mul_f32_e32 v137, v48, v133
	v_mul_f32_e32 v139, 0xbfb8aa3b, v137
	v_exp_f32_e32 v139, v139
	s_nop 0
	v_add_f32_e32 v139, 1.0, v139
	v_rcp_f32_e32 v139, v139
	s_nop 0
	v_mul_f32_e32 v139, v137, v139
	v_cndmask_b32_e32 v137, v137, v139, vcc
	v_mul_f32_e32 v139, v49, v133
	v_mul_f32_e32 v140, 0xbfb8aa3b, v139
	v_exp_f32_e32 v140, v140
	s_nop 0
	v_add_f32_e32 v140, 1.0, v140
	v_rcp_f32_e32 v140, v140
	s_nop 0
	v_mul_f32_e32 v140, v139, v140
	v_cndmask_b32_e32 v139, v139, v140, vcc
	v_mul_f32_e32 v140, v38, v133
	v_mul_f32_e32 v141, 0xbfb8aa3b, v140
	v_exp_f32_e32 v141, v141
	s_nop 0
	v_add_f32_e32 v141, 1.0, v141
	v_rcp_f32_e32 v141, v141
	s_nop 0
	v_mul_f32_e32 v141, v140, v141
	v_cndmask_b32_e32 v142, v140, v141, vcc
	v_mul_f32_e32 v140, v39, v133
	v_mul_f32_e32 v141, 0xbfb8aa3b, v140
	v_exp_f32_e32 v141, v141
	s_nop 0
	v_add_f32_e32 v141, 1.0, v141
	v_rcp_f32_e32 v141, v141
	s_nop 0
	v_mul_f32_e32 v141, v140, v141
	v_cndmask_b32_e32 v143, v140, v141, vcc
	v_mul_f32_e32 v140, v40, v133
	v_mul_f32_e32 v141, 0xbfb8aa3b, v140
	v_exp_f32_e32 v141, v141
	v_mul_f32_e32 v133, v41, v133
	v_cvt_pk_bf16_f32 v142, v142, v143
	v_add_f32_e32 v141, 1.0, v141
	v_rcp_f32_e32 v141, v141
	s_nop 0
	v_mul_f32_e32 v141, v140, v141
	v_cndmask_b32_e32 v144, v140, v141, vcc
	v_mul_f32_e32 v140, 0xbfb8aa3b, v133
	v_exp_f32_e32 v140, v140
	v_cvt_pk_bf16_f32 v141, v137, v139
	s_nop 0
	v_add_f32_e32 v140, 1.0, v140
	v_rcp_f32_e32 v140, v140
	s_nop 0
	v_mul_f32_e32 v140, v133, v140
	v_cndmask_b32_e32 v133, v133, v140, vcc
	v_cvt_pk_bf16_f32 v140, v132, v136
	v_cvt_pk_bf16_f32 v143, v144, v133
	ds_read2_b32 v[132:133], v138 offset0:160 offset1:176
	global_store_dwordx4 v[134:135], v[140:143], off offset:256 sc1
	v_lshl_add_u64 v[134:135], v[130:131], 0, s[0:1]
	s_mov_b32 s0, 0xa0000
	s_waitcnt lgkmcnt(0)
; __device__ __forceinline__ v4u pack8(const float (&f)[8]) { v4u w; w.x = cvt_pk_bf16(f[0], f[1]); w.y = cvt_pk_bf16(f[2], f[3]); w.z = cvt_pk_bf16(f[4], f[5]); w.w = cvt_pk_bf16(f[6], f[7]); return w; }
; __device__ __forceinline__ float siluf_(float x) { return x * rcpf_(1.f + __expf(-x)); }
;     __device__ __forceinline__ void operator()(const f32x4 (&acc)[2][2][4][2], const Unit& u, int wr, int wc, int fr, int fq) const {
;     ...
;                 const bool isg = u.pn >= 16;
;                 bf16* base = (isg ? SG : V) + ((u.pn - (isg ? 16 : 8)) * 256) + cw;
; #pragma unroll
;                 for (int ai = 0; ai < 2; ++ai)
; #pragma unroll
;                     for (int m = 0; m < 4; ++m) {
;                         bf16* rp = base + (size_t)(row0 + ai * 128 + m * 16) * 2048;
;                         const float rs = rtab[u.ord * 256 + (wr * 64 + fr + ai * 128 + m * 16)];
; #pragma unroll
;                         for (int bj = 0; bj < 2; ++bj) {
;                             float o[8];
; #pragma unroll
;                             for (int n = 0; n < 2; ++n)
; #pragma unroll
;                                 for (int j = 0; j < 4; ++j) { const float x = acc[ai][bj][m][n][j] * rs; o[n * 4 + j] = isg ? siluf_(x) : x; }
;                             *(v4u*)(rp + bj * 128) = pack8(o);
;                         }
;                     }
	v_mul_f32_e32 v136, v26, v132
	v_mul_f32_e32 v137, 0xbfb8aa3b, v136
	v_exp_f32_e32 v137, v137
	s_nop 0
	v_add_f32_e32 v137, 1.0, v137
	v_rcp_f32_e32 v137, v137
	s_nop 0
	v_mul_f32_e32 v137, v136, v137
	v_cndmask_b32_e32 v136, v136, v137, vcc
	v_mul_f32_e32 v137, v27, v132
	v_mul_f32_e32 v138, 0xbfb8aa3b, v137
	v_exp_f32_e32 v138, v138
	s_nop 0
	v_add_f32_e32 v138, 1.0, v138
	v_rcp_f32_e32 v138, v138
	s_nop 0
	v_mul_f32_e32 v138, v137, v138
	v_cndmask_b32_e32 v137, v137, v138, vcc
	v_mul_f32_e32 v138, v28, v132
	v_mul_f32_e32 v139, 0xbfb8aa3b, v138
	v_exp_f32_e32 v139, v139
	v_cvt_pk_bf16_f32 v136, v136, v137
	s_nop 0
	v_add_f32_e32 v139, 1.0, v139
	v_rcp_f32_e32 v139, v139
	s_nop 0
	v_mul_f32_e32 v139, v138, v139
	v_cndmask_b32_e32 v138, v138, v139, vcc
	v_mul_f32_e32 v139, v29, v132
	v_mul_f32_e32 v140, 0xbfb8aa3b, v139
	v_exp_f32_e32 v140, v140
	s_nop 0
	v_add_f32_e32 v140, 1.0, v140
	v_rcp_f32_e32 v140, v140
	s_nop 0
	v_mul_f32_e32 v140, v139, v140
	v_cndmask_b32_e32 v139, v139, v140, vcc
	v_mul_f32_e32 v140, v18, v132
	v_mul_f32_e32 v141, 0xbfb8aa3b, v140
	v_exp_f32_e32 v141, v141
	v_cvt_pk_bf16_f32 v137, v138, v139
	s_nop 0
	v_add_f32_e32 v141, 1.0, v141
	v_rcp_f32_e32 v141, v141
	s_nop 0
	v_mul_f32_e32 v141, v140, v141
	v_cndmask_b32_e32 v140, v140, v141, vcc
	v_mul_f32_e32 v141, v19, v132
	v_mul_f32_e32 v142, 0xbfb8aa3b, v141
	v_exp_f32_e32 v142, v142
	s_nop 0
	v_add_f32_e32 v142, 1.0, v142
	v_rcp_f32_e32 v142, v142
	s_nop 0
	v_mul_f32_e32 v142, v141, v142
	v_cndmask_b32_e32 v141, v141, v142, vcc
	v_mul_f32_e32 v142, v20, v132
	v_mul_f32_e32 v143, 0xbfb8aa3b, v142
	v_exp_f32_e32 v143, v143
	v_cvt_pk_bf16_f32 v138, v140, v141
	v_add_co_u32_e64 v140, s[0:1], s0, v130
	v_add_f32_e32 v143, 1.0, v143
	v_rcp_f32_e32 v143, v143
	v_addc_co_u32_e64 v141, s[0:1], 0, v131, s[0:1]
	s_mov_b64 s[0:1], 0xb0000
	v_mul_f32_e32 v143, v142, v143
	v_cndmask_b32_e32 v142, v142, v143, vcc
	v_mul_f32_e32 v143, v21, v132
	v_mul_f32_e32 v144, 0xbfb8aa3b, v143
	v_exp_f32_e32 v144, v144
	s_nop 0
	v_add_f32_e32 v144, 1.0, v144
	v_rcp_f32_e32 v144, v144
	s_nop 0
	v_mul_f32_e32 v144, v143, v144
	v_cndmask_b32_e32 v143, v143, v144, vcc
	v_cvt_pk_bf16_f32 v139, v142, v143
	global_store_dwordx4 v[140:141], v[136:139], off sc1
	s_nop 1
	v_mul_f32_e32 v136, v30, v132
	v_mul_f32_e32 v137, 0xbfb8aa3b, v136
	v_exp_f32_e32 v137, v137
	s_nop 0
	v_add_f32_e32 v137, 1.0, v137
	v_rcp_f32_e32 v137, v137
	s_nop 0
	v_mul_f32_e32 v137, v136, v137
	v_cndmask_b32_e32 v136, v136, v137, vcc
	v_mul_f32_e32 v137, v31, v132
	v_mul_f32_e32 v138, 0xbfb8aa3b, v137
	v_exp_f32_e32 v138, v138
	s_nop 0
	v_add_f32_e32 v138, 1.0, v138
	v_rcp_f32_e32 v138, v138
	s_nop 0
	v_mul_f32_e32 v138, v137, v138
	v_cndmask_b32_e32 v137, v137, v138, vcc
	v_mul_f32_e32 v138, v32, v132
	v_mul_f32_e32 v139, 0xbfb8aa3b, v138
	v_exp_f32_e32 v139, v139
	v_cvt_pk_bf16_f32 v136, v136, v137
	s_nop 0
	v_add_f32_e32 v139, 1.0, v139
	v_rcp_f32_e32 v139, v139
	s_nop 0
	v_mul_f32_e32 v139, v138, v139
	v_cndmask_b32_e32 v138, v138, v139, vcc
	v_mul_f32_e32 v139, v33, v132
	v_mul_f32_e32 v140, 0xbfb8aa3b, v139
	v_exp_f32_e32 v140, v140
	s_nop 0
	v_add_f32_e32 v140, 1.0, v140
	v_rcp_f32_e32 v140, v140
	s_nop 0
	v_mul_f32_e32 v140, v139, v140
	v_cndmask_b32_e32 v139, v139, v140, vcc
	v_mul_f32_e32 v140, v22, v132
	v_mul_f32_e32 v141, 0xbfb8aa3b, v140
	v_exp_f32_e32 v141, v141
	v_cvt_pk_bf16_f32 v137, v138, v139
	s_nop 0
	v_add_f32_e32 v141, 1.0, v141
	v_rcp_f32_e32 v141, v141
	s_nop 0
	v_mul_f32_e32 v141, v140, v141
	v_cndmask_b32_e32 v140, v140, v141, vcc
	v_mul_f32_e32 v141, v23, v132
	v_mul_f32_e32 v142, 0xbfb8aa3b, v141
	v_exp_f32_e32 v142, v142
	s_nop 0
	v_add_f32_e32 v142, 1.0, v142
	v_rcp_f32_e32 v142, v142
	s_nop 0
	v_mul_f32_e32 v142, v141, v142
	v_cndmask_b32_e32 v141, v141, v142, vcc
	v_mul_f32_e32 v142, v24, v132
	v_mul_f32_e32 v143, 0xbfb8aa3b, v142
	v_exp_f32_e32 v143, v143
	v_mul_f32_e32 v132, v25, v132
	v_cvt_pk_bf16_f32 v138, v140, v141
	v_add_f32_e32 v143, 1.0, v143
	v_rcp_f32_e32 v143, v143
	s_nop 0
	v_mul_f32_e32 v143, v142, v143
	v_cndmask_b32_e32 v142, v142, v143, vcc
	v_mul_f32_e32 v143, 0xbfb8aa3b, v132
	v_exp_f32_e32 v143, v143
	s_nop 0
	v_add_f32_e32 v143, 1.0, v143
	v_rcp_f32_e32 v143, v143
	s_nop 0
	v_mul_f32_e32 v143, v132, v143
	v_cndmask_b32_e32 v132, v132, v143, vcc
	v_cvt_pk_bf16_f32 v139, v142, v132
	v_mul_f32_e32 v132, v10, v133
	global_store_dwordx4 v[134:135], v[136:139], off offset:256 sc1
	v_lshl_add_u64 v[134:135], v[130:131], 0, s[0:1]
	s_mov_b32 s0, 0xb0000
	v_mul_f32_e32 v136, 0xbfb8aa3b, v132
	v_exp_f32_e32 v136, v136
	v_add_co_u32_e64 v130, s[0:1], s0, v130
	v_add_f32_e32 v136, 1.0, v136
	v_rcp_f32_e32 v136, v136
	v_addc_co_u32_e64 v131, s[0:1], 0, v131, s[0:1]
	s_mov_b64 s[0:1], 0
	v_mul_f32_e32 v136, v132, v136
	v_cndmask_b32_e32 v132, v132, v136, vcc
	v_mul_f32_e32 v136, v11, v133
	v_mul_f32_e32 v137, 0xbfb8aa3b, v136
	v_exp_f32_e32 v137, v137
	s_nop 0
	v_add_f32_e32 v137, 1.0, v137
	v_rcp_f32_e32 v137, v137
	s_nop 0
	v_mul_f32_e32 v137, v136, v137
	v_cndmask_b32_e32 v136, v136, v137, vcc
	v_mul_f32_e32 v137, v12, v133
	v_mul_f32_e32 v138, 0xbfb8aa3b, v137
	v_exp_f32_e32 v138, v138
	v_cvt_pk_bf16_f32 v136, v132, v136
	s_nop 0
	v_add_f32_e32 v138, 1.0, v138
	v_rcp_f32_e32 v138, v138
	s_nop 0
	v_mul_f32_e32 v138, v137, v138
	v_cndmask_b32_e32 v137, v137, v138, vcc
	v_mul_f32_e32 v138, v13, v133
	v_mul_f32_e32 v139, 0xbfb8aa3b, v138
	v_exp_f32_e32 v139, v139
	s_nop 0
	v_add_f32_e32 v139, 1.0, v139
	v_rcp_f32_e32 v139, v139
	s_nop 0
	v_mul_f32_e32 v139, v138, v139
	v_cndmask_b32_e32 v138, v138, v139, vcc
	v_mul_f32_e32 v139, v6, v133
	v_mul_f32_e32 v140, 0xbfb8aa3b, v139
; __device__ __forceinline__ v4u pack8(const float (&f)[8]) { v4u w; w.x = cvt_pk_bf16(f[0], f[1]); w.y = cvt_pk_bf16(f[2], f[3]); w.z = cvt_pk_bf16(f[4], f[5]); w.w = cvt_pk_bf16(f[6], f[7]); return w; }
; __device__ __forceinline__ float siluf_(float x) { return x * rcpf_(1.f + __expf(-x)); }
;     __device__ __forceinline__ void operator()(const f32x4 (&acc)[2][2][4][2], const Unit& u, int wr, int wc, int fr, int fq) const {
;     ...
;                     for (int m = 0; m < 4; ++m) { const int row = row0 + ai * 128 + m * 16; const int pi = row < MP ? row % TP : TP;
;                         const f32x4* cs = (const f32x4*)(CS + ((size_t)pi * 128 + cw) * 2);
; #pragma unroll
;                         for (int q4 = 0; q4 < 4; ++q4) tt[m][q4] = cs[q4]; }
;     ...
;                     for (int m = 0; m < 4; ++m) {
;                         bf16* rp = base + (size_t)(row0 + ai * 128 + m * 16) * 2048;
;                         const float rs = rtab[u.ord * 256 + (wr * 64 + fr + ai * 128 + m * 16)];
; #pragma unroll
;                         for (int bj = 0; bj < 2; ++bj) {
;                             float o[8];
; #pragma unroll
;                             for (int n = 0; n < 2; ++n)
; #pragma unroll
;                                 for (int j = 0; j < 4; ++j) { const float x = acc[ai][bj][m][n][j] * rs; o[n * 4 + j] = isg ? siluf_(x) : x; }
;                             *(v4u*)(rp + bj * 128) = pack8(o);
;                         }
;                     }
	v_exp_f32_e32 v140, v140
	v_cvt_pk_bf16_f32 v137, v137, v138
	s_nop 0
	v_add_f32_e32 v140, 1.0, v140
	v_rcp_f32_e32 v140, v140
	s_nop 0
	v_mul_f32_e32 v140, v139, v140
	v_cndmask_b32_e32 v139, v139, v140, vcc
	v_mul_f32_e32 v140, v7, v133
	v_mul_f32_e32 v141, 0xbfb8aa3b, v140
	v_exp_f32_e32 v141, v141
	s_nop 0
	v_add_f32_e32 v141, 1.0, v141
	v_rcp_f32_e32 v141, v141
	s_nop 0
	v_mul_f32_e32 v141, v140, v141
	v_cndmask_b32_e32 v140, v140, v141, vcc
	v_mul_f32_e32 v141, v8, v133
	v_mul_f32_e32 v142, 0xbfb8aa3b, v141
	v_exp_f32_e32 v142, v142
	v_cvt_pk_bf16_f32 v138, v139, v140
	s_nop 0
	v_add_f32_e32 v142, 1.0, v142
	v_rcp_f32_e32 v142, v142
	s_nop 0
	v_mul_f32_e32 v142, v141, v142
	v_cndmask_b32_e32 v141, v141, v142, vcc
	v_mul_f32_e32 v142, v9, v133
	v_mul_f32_e32 v143, 0xbfb8aa3b, v142
	v_exp_f32_e32 v143, v143
	s_nop 0
	v_add_f32_e32 v143, 1.0, v143
	v_rcp_f32_e32 v143, v143
	s_nop 0
	v_mul_f32_e32 v143, v142, v143
	v_cndmask_b32_e32 v142, v142, v143, vcc
	v_cvt_pk_bf16_f32 v139, v141, v142
	global_store_dwordx4 v[130:131], v[136:139], off sc1
	v_mul_f32_e32 v130, v14, v133
	v_mul_f32_e32 v131, 0xbfb8aa3b, v130
	v_exp_f32_e32 v131, v131
	s_nop 0
	v_add_f32_e32 v131, 1.0, v131
	v_rcp_f32_e32 v131, v131
	s_nop 0
	v_mul_f32_e32 v131, v130, v131
	v_cndmask_b32_e32 v130, v130, v131, vcc
	v_mul_f32_e32 v131, v15, v133
	v_mul_f32_e32 v132, 0xbfb8aa3b, v131
	v_exp_f32_e32 v132, v132
	s_nop 0
	v_add_f32_e32 v132, 1.0, v132
	v_rcp_f32_e32 v132, v132
	s_nop 0
	v_mul_f32_e32 v132, v131, v132
	v_cndmask_b32_e32 v131, v131, v132, vcc
	v_mul_f32_e32 v132, v16, v133
	v_mul_f32_e32 v136, 0xbfb8aa3b, v132
	v_exp_f32_e32 v136, v136
	v_cvt_pk_bf16_f32 v130, v130, v131
	s_nop 0
	v_add_f32_e32 v136, 1.0, v136
	v_rcp_f32_e32 v136, v136
	s_nop 0
	v_mul_f32_e32 v136, v132, v136
	v_cndmask_b32_e32 v132, v132, v136, vcc
	v_mul_f32_e32 v136, v17, v133
	v_mul_f32_e32 v137, 0xbfb8aa3b, v136
	v_exp_f32_e32 v137, v137
	s_nop 0
	v_add_f32_e32 v137, 1.0, v137
	v_rcp_f32_e32 v137, v137
	s_nop 0
	v_mul_f32_e32 v137, v136, v137
	v_cndmask_b32_e32 v136, v136, v137, vcc
	v_mul_f32_e32 v137, v2, v133
	v_mul_f32_e32 v138, 0xbfb8aa3b, v137
	v_exp_f32_e32 v138, v138
	v_cvt_pk_bf16_f32 v131, v132, v136
	s_nop 0
	v_add_f32_e32 v138, 1.0, v138
	v_rcp_f32_e32 v138, v138
	s_nop 0
	v_mul_f32_e32 v138, v137, v138
	v_cndmask_b32_e32 v137, v137, v138, vcc
	v_mul_f32_e32 v138, v3, v133
	v_mul_f32_e32 v139, 0xbfb8aa3b, v138
	v_exp_f32_e32 v139, v139
	s_nop 0
	v_add_f32_e32 v139, 1.0, v139
	v_rcp_f32_e32 v139, v139
	s_nop 0
	v_mul_f32_e32 v139, v138, v139
	v_cndmask_b32_e32 v138, v138, v139, vcc
	v_mul_f32_e32 v139, v4, v133
	v_mul_f32_e32 v140, 0xbfb8aa3b, v139
	v_exp_f32_e32 v140, v140
	v_mul_f32_e32 v133, v5, v133
	v_cvt_pk_bf16_f32 v132, v137, v138
	v_add_f32_e32 v140, 1.0, v140
	v_rcp_f32_e32 v140, v140
	s_nop 0
	v_mul_f32_e32 v140, v139, v140
	v_cndmask_b32_e32 v139, v139, v140, vcc
	v_mul_f32_e32 v140, 0xbfb8aa3b, v133
	v_exp_f32_e32 v140, v140
	s_nop 0
	v_add_f32_e32 v140, 1.0, v140
	v_rcp_f32_e32 v140, v140
	s_nop 0
	v_mul_f32_e32 v140, v133, v140
	v_cndmask_b32_e32 v133, v133, v140, vcc
	v_cvt_pk_bf16_f32 v133, v139, v133
	global_store_dwordx4 v[134:135], v[130:133], off offset:256 sc1
.LBB0_1129:
	s_andn2_b64 vcc, exec, s[0:1]
	s_cbranch_vccnz .LBB0_1147
	v_cmp_gt_i32_e32 vcc, s17, v210
	s_waitcnt lgkmcnt(0)
	v_mov_b64_e32 v[130:131], 0x40800
	v_mov_b64_e32 v[132:133], 0x40800
	s_and_saveexec_b64 s[0:1], vcc
	s_mov_b32 s2, 0xfe03f81
	v_mul_hi_i32 v132, v210, s2
	v_lshrrev_b32_e32 v133, 31, v132
	v_ashrrev_i32_e32 v132, 7, v132
	v_add_u32_e32 v132, v132, v133
	v_mul_lo_u32 v132, v132, s16
	v_sub_u32_e32 v132, v210, v132
	v_ashrrev_i32_e32 v133, 31, v132
	v_lshlrev_b64 v[132:133], 7, v[132:133]
	s_or_b64 exec, exec, s[0:1]
	v_readlane_b32 s0, v252, 28
	v_or_b32_e32 v132, v132, v204
	v_readlane_b32 s1, v252, 29
	v_cmp_gt_i32_e32 vcc, s17, v216
	s_nop 0
	v_lshl_add_u64 v[132:133], v[132:133], 3, s[0:1]
	global_load_dwordx4 v[178:181], v[132:133], off offset:48
	global_load_dwordx4 v[182:185], v[132:133], off offset:32
	global_load_dwordx4 v[186:189], v[132:133], off offset:16
	global_load_dwordx4 v[190:193], v[132:133], off
	s_and_saveexec_b64 s[0:1], vcc
	s_mov_b32 s2, 0xfe03f81
	v_mul_hi_i32 v130, v216, s2
	v_lshrrev_b32_e32 v131, 31, v130
	v_ashrrev_i32_e32 v130, 7, v130
	v_add_u32_e32 v130, v130, v131
	v_mul_lo_u32 v130, v130, s16
	v_sub_u32_e32 v130, v216, v130
	v_ashrrev_i32_e32 v131, 31, v130
	v_lshlrev_b64 v[130:131], 7, v[130:131]
	s_or_b64 exec, exec, s[0:1]
	v_readlane_b32 s0, v252, 28
	v_or_b32_e32 v130, v130, v204
	v_readlane_b32 s1, v252, 29
	v_cmp_gt_i32_e32 vcc, s17, v214
	v_mov_b64_e32 v[132:133], 0x40800
	v_lshl_add_u64 v[130:131], v[130:131], 3, s[0:1]
	global_load_dwordx4 v[162:165], v[130:131], off offset:48
	global_load_dwordx4 v[166:169], v[130:131], off offset:32
	global_load_dwordx4 v[170:173], v[130:131], off offset:16
	global_load_dwordx4 v[174:177], v[130:131], off
	v_mov_b64_e32 v[130:131], 0x40800
	s_and_saveexec_b64 s[0:1], vcc
	s_mov_b32 s2, 0xfe03f81
	v_mul_hi_i32 v132, v214, s2
	v_lshrrev_b32_e32 v133, 31, v132
	v_ashrrev_i32_e32 v132, 7, v132
	v_add_u32_e32 v132, v132, v133
	v_mul_lo_u32 v132, v132, s16
	v_sub_u32_e32 v132, v214, v132
	v_ashrrev_i32_e32 v133, 31, v132
	v_lshlrev_b64 v[132:133], 7, v[132:133]
	s_or_b64 exec, exec, s[0:1]
	v_readlane_b32 s0, v252, 28
	v_or_b32_e32 v132, v132, v204
	v_readlane_b32 s1, v252, 29
	v_cmp_gt_i32_e32 vcc, s17, v212
	s_nop 0
	v_lshl_add_u64 v[132:133], v[132:133], 3, s[0:1]
	global_load_dwordx4 v[138:141], v[132:133], off offset:48
	global_load_dwordx4 v[150:153], v[132:133], off offset:32
; __device__ __forceinline__ v4u pack8(const float (&f)[8]) { v4u w; w.x = cvt_pk_bf16(f[0], f[1]); w.y = cvt_pk_bf16(f[2], f[3]); w.z = cvt_pk_bf16(f[4], f[5]); w.w = cvt_pk_bf16(f[6], f[7]); return w; }
;     __device__ __forceinline__ void operator()(const f32x4 (&acc)[2][2][4][2], const Unit& u, int wr, int wc, int fr, int fq) const {
;     ...
;                     for (int m = 0; m < 4; ++m) { const int row = row0 + ai * 128 + m * 16; const int pi = row < MP ? row % TP : TP;
;                         const f32x4* cs = (const f32x4*)(CS + ((size_t)pi * 128 + cw) * 2);
; #pragma unroll
;                         for (int q4 = 0; q4 < 4; ++q4) tt[m][q4] = cs[q4]; }
; #pragma unroll
;                     for (int m = 0; m < 4; ++m) {
;                         const int row = row0 + ai * 128 + m * 16;
;                         const float rs = rtab[u.ord * 256 + (row - u.pm * 256)] * sc;
;                         const f32x4 t0 = tt[m][0], t1 = tt[m][1], t2 = tt[m][2], t3 = tt[m][3];
;                         const float c[8] = {t0.x, t0.z, t1.x, t1.z, t2.x, t2.z, t3.x, t3.z}, s[8] = {t0.y, t0.w, t1.y, t1.w, t2.y, t2.w, t3.y, t3.w};
;                         float o1[8], o2[8];
; #pragma unroll
;                         for (int n = 0; n < 2; ++n)
; #pragma unroll
;                             for (int j = 0; j < 4; ++j) {
;                                 const float x1 = acc[ai][0][m][n][j], x2 = acc[ai][1][m][n][j];
;                                 o1[n * 4 + j] = (x1 * c[n * 4 + j] - x2 * s[n * 4 + j]) * rs;
;                                 o2[n * 4 + j] = (x1 * s[n * 4 + j] + x2 * c[n * 4 + j]) * rs;
;                             }
;                         bf16* rp = base + (size_t)row * 2048;
;                         *(v4u*)rp = pack8(o1); *(v4u*)(rp + 128) = pack8(o2);
	global_load_dwordx4 v[154:157], v[132:133], off offset:16
	global_load_dwordx4 v[158:161], v[132:133], off
	s_and_saveexec_b64 s[0:1], vcc
	s_mov_b32 s2, 0xfe03f81
	v_mul_hi_i32 v130, v212, s2
	v_lshrrev_b32_e32 v131, 31, v130
	v_ashrrev_i32_e32 v130, 7, v130
	v_add_u32_e32 v130, v130, v131
	v_mul_lo_u32 v130, v130, s16
	v_sub_u32_e32 v130, v212, v130
	v_ashrrev_i32_e32 v131, 31, v130
	v_lshlrev_b64 v[130:131], 7, v[130:131]
	s_or_b64 exec, exec, s[0:1]
	s_cmp_gt_i32 s87, 3
	s_cselect_b64 vcc, -1, 0
	s_and_b64 s[0:1], vcc, exec
	s_cselect_b32 s0, 0x800, 0
	v_readlane_b32 s2, v252, 30
	v_readlane_b32 s3, v252, 31
	s_add_u32 s0, s2, s0
	s_addc_u32 s1, s3, 0
	s_lshl_b32 s2, s87, 9
	s_and_b32 s2, s2, 0x600
	s_add_u32 s0, s0, s2
	s_addc_u32 s1, s1, 0
	v_lshl_add_u64 v[218:219], s[0:1], 0, v[0:1]
	v_readlane_b32 s0, v252, 28
	v_or_b32_e32 v130, v130, v204
	v_readlane_b32 s1, v252, 29
	v_mov_b32_e32 v132, 0x3d800000
	v_cndmask_b32_e32 v221, 1.0, v132, vcc
	v_lshl_add_u64 v[146:147], v[130:131], 3, s[0:1]
	global_load_dwordx4 v[130:133], v[146:147], off offset:48
	global_load_dwordx4 v[134:137], v[146:147], off offset:32
	global_load_dwordx4 v[142:145], v[146:147], off offset:16
	s_nop 0
	global_load_dwordx4 v[146:149], v[146:147], off
	s_lshl_b32 s0, s88, 10
	v_add_u32_e32 v0, s0, v245
	ds_read2_b32 v[234:235], v0 offset1:16
	v_mov_b32_e32 v236, v122
	v_mov_b32_e32 v237, v126
	v_mov_b32_e32 v248, v126
	v_mov_b32_e32 v249, v122
	v_mov_b32_e32 v126, v123
	v_mov_b32_e32 v122, v127
	s_waitcnt vmcnt(0)
	v_pk_mul_f32 v[236:237], v[236:237], v[190:191]
	v_pk_mul_f32 v[190:191], v[248:249], v[190:191]
	v_pk_mul_f32 v[248:249], v[126:127], v[192:193]
	v_pk_mul_f32 v[122:123], v[122:123], v[192:193]
	v_mov_b32_e32 v126, v124
	v_mov_b32_e32 v127, v128
	v_mov_b32_e32 v192, v128
	v_mov_b32_e32 v193, v124
	v_mov_b32_e32 v128, v125
	v_mov_b32_e32 v124, v129
	v_pk_mul_f32 v[126:127], v[126:127], v[186:187]
	v_pk_mul_f32 v[186:187], v[192:193], v[186:187]
	v_pk_mul_f32 v[192:193], v[128:129], v[188:189]
	v_pk_mul_f32 v[124:125], v[124:125], v[188:189]
	v_mov_b32_e32 v128, v114
	v_mov_b32_e32 v129, v118
	v_mov_b32_e32 v188, v118
	v_mov_b32_e32 v189, v114
	v_mov_b32_e32 v118, v115
	v_mov_b32_e32 v114, v119
	v_pk_mul_f32 v[128:129], v[128:129], v[182:183]
	v_pk_mul_f32 v[182:183], v[188:189], v[182:183]
	v_pk_mul_f32 v[188:189], v[118:119], v[184:185]
	v_pk_mul_f32 v[114:115], v[114:115], v[184:185]
	v_mov_b32_e32 v220, v116
	v_mov_b32_e32 v118, v178
	s_waitcnt lgkmcnt(0)
	v_mov_b32_e32 v119, v234
	v_pk_mul_f32 v[118:119], v[220:221], v[118:119]
	v_add_f32_e32 v114, v115, v114
	v_add_f32_e32 v124, v125, v124
	v_sub_f32_e32 v125, v128, v129
	v_add_f32_e32 v128, v183, v182
	v_mul_f32_e32 v182, v114, v119
	v_fma_f32 v114, -v120, v179, v118
	v_mul_f32_e32 v183, v114, v119
	v_mov_b32_e32 v114, v120
	v_mov_b32_e32 v115, v116
	v_pk_mul_f32 v[114:115], v[114:115], v[178:179]
	v_mov_b32_e32 v120, v117
	v_add_f32_e32 v114, v115, v114
	v_mul_f32_e32 v178, v114, v119
	v_pk_mul_f32 v[114:115], v[120:121], v[180:181]
	v_mov_b32_e32 v116, v121
	v_sub_f32_e32 v114, v114, v115
	v_mul_f32_e32 v120, v114, v119
	v_pk_mul_f32 v[114:115], v[116:117], v[180:181]
	v_sub_f32_e32 v184, v236, v237
	v_add_f32_e32 v114, v115, v114
	v_add_f32_e32 v185, v191, v190
	v_sub_f32_e32 v190, v248, v249
	v_add_f32_e32 v122, v123, v122
	v_sub_f32_e32 v123, v126, v127
	v_add_f32_e32 v126, v187, v186
	v_sub_f32_e32 v127, v192, v193
	v_sub_f32_e32 v129, v188, v189
	v_mul_f32_e32 v121, v114, v119
	v_lshlrev_b64 v[114:115], 12, v[210:211]
	v_mul_f32_e32 v184, v184, v119
	v_mul_f32_e32 v185, v185, v119
	v_mul_f32_e32 v190, v190, v119
	v_mul_f32_e32 v122, v122, v119
	v_mul_f32_e32 v123, v123, v119
	v_mul_f32_e32 v126, v126, v119
	v_mul_f32_e32 v127, v127, v119
	v_mul_f32_e32 v124, v124, v119
	v_mul_f32_e32 v125, v125, v119
	v_mul_f32_e32 v128, v128, v119
	v_mul_f32_e32 v129, v129, v119
	v_lshl_add_u64 v[118:119], v[218:219], 0, v[114:115]
	v_cvt_pk_bf16_f32 v115, v123, v127
	v_cvt_pk_bf16_f32 v116, v125, v129
	v_cvt_pk_bf16_f32 v114, v184, v190
	v_cvt_pk_bf16_f32 v117, v183, v120
	global_store_dwordx4 v[118:119], v[114:117], off sc1
	v_mov_b32_e32 v120, v112
	v_mov_b32_e32 v125, v98
	v_cvt_pk_bf16_f32 v115, v126, v124
	v_cvt_pk_bf16_f32 v116, v128, v182
	v_cvt_pk_bf16_f32 v114, v185, v122
	v_cvt_pk_bf16_f32 v117, v178, v121
	global_store_dwordx4 v[118:119], v[114:117], off offset:256 sc1
	v_mov_b32_e32 v121, v108
	v_mov_b32_e32 v124, v102
	v_mov_b32_e32 v115, v110
	v_mov_b32_e32 v116, v110
	v_mov_b32_e32 v110, v107
	v_mov_b32_e32 v114, v106
	v_mov_b32_e32 v117, v106
	v_pk_mul_f32 v[118:119], v[110:111], v[176:177]
	v_mov_b32_e32 v106, v111
	v_mov_b32_e32 v111, v112
	v_mov_b32_e32 v112, v109
	v_pk_mul_f32 v[122:123], v[112:113], v[172:173]
	v_mov_b32_e32 v112, v98
	v_mov_b32_e32 v98, v103
	v_mov_b32_e32 v110, v108
	v_mov_b32_e32 v108, v113
	v_mov_b32_e32 v113, v102
	v_mov_b32_e32 v102, v99
	v_pk_mul_f32 v[98:99], v[98:99], v[168:169]
	v_mov_b32_e32 v220, v100
	v_mov_b32_e32 v234, v162
	v_pk_mul_f32 v[114:115], v[114:115], v[174:175]
	v_pk_mul_f32 v[116:117], v[116:117], v[174:175]
	v_pk_mul_f32 v[126:127], v[102:103], v[168:169]
	v_pk_mul_f32 v[102:103], v[220:221], v[234:235]
	v_add_f32_e32 v98, v99, v98
	v_sub_f32_e32 v114, v114, v115
	v_add_f32_e32 v115, v117, v116
	v_mul_f32_e32 v117, v98, v103
	v_fma_f32 v98, -v104, v163, v102
	v_sub_f32_e32 v116, v118, v119
	v_mul_f32_e32 v118, v98, v103
	v_mov_b32_e32 v98, v104
	v_mov_b32_e32 v99, v100
	v_pk_mul_f32 v[98:99], v[98:99], v[162:163]
	v_mov_b32_e32 v104, v101
	v_add_f32_e32 v98, v99, v98
	v_mul_f32_e32 v119, v98, v103
	v_pk_mul_f32 v[98:99], v[104:105], v[164:165]
; __device__ __forceinline__ v4u pack8(const float (&f)[8]) { v4u w; w.x = cvt_pk_bf16(f[0], f[1]); w.y = cvt_pk_bf16(f[2], f[3]); w.z = cvt_pk_bf16(f[4], f[5]); w.w = cvt_pk_bf16(f[6], f[7]); return w; }
;     __device__ __forceinline__ void operator()(const f32x4 (&acc)[2][2][4][2], const Unit& u, int wr, int wc, int fr, int fq) const {
;     ...
;                     for (int m = 0; m < 4; ++m) {
;                         const int row = row0 + ai * 128 + m * 16;
;                         const float rs = rtab[u.ord * 256 + (row - u.pm * 256)] * sc;
;                         const f32x4 t0 = tt[m][0], t1 = tt[m][1], t2 = tt[m][2], t3 = tt[m][3];
;                         const float c[8] = {t0.x, t0.z, t1.x, t1.z, t2.x, t2.z, t3.x, t3.z}, s[8] = {t0.y, t0.w, t1.y, t1.w, t2.y, t2.w, t3.y, t3.w};
;                         float o1[8], o2[8];
; #pragma unroll
;                         for (int n = 0; n < 2; ++n)
; #pragma unroll
;                             for (int j = 0; j < 4; ++j) {
;                                 const float x1 = acc[ai][0][m][n][j], x2 = acc[ai][1][m][n][j];
;                                 o1[n * 4 + j] = (x1 * c[n * 4 + j] - x2 * s[n * 4 + j]) * rs;
;                                 o2[n * 4 + j] = (x1 * s[n * 4 + j] + x2 * c[n * 4 + j]) * rs;
;                             }
;                         bf16* rp = base + (size_t)row * 2048;
;                         *(v4u*)rp = pack8(o1); *(v4u*)(rp + 128) = pack8(o2);
	v_mov_b32_e32 v100, v105
	v_sub_f32_e32 v98, v98, v99
	v_mul_f32_e32 v104, v98, v103
	v_pk_mul_f32 v[98:99], v[100:101], v[164:165]
	v_pk_mul_f32 v[106:107], v[106:107], v[176:177]
	v_pk_mul_f32 v[110:111], v[110:111], v[170:171]
	v_pk_mul_f32 v[120:121], v[120:121], v[170:171]
	v_pk_mul_f32 v[108:109], v[108:109], v[172:173]
	v_pk_mul_f32 v[112:113], v[112:113], v[166:167]
	v_pk_mul_f32 v[124:125], v[124:125], v[166:167]
	v_add_f32_e32 v98, v99, v98
	v_add_f32_e32 v106, v107, v106
	v_sub_f32_e32 v107, v110, v111
	v_add_f32_e32 v110, v121, v120
	v_sub_f32_e32 v111, v122, v123
	v_add_f32_e32 v108, v109, v108
	v_sub_f32_e32 v109, v112, v113
	v_add_f32_e32 v112, v125, v124
	v_sub_f32_e32 v113, v126, v127
	v_mul_f32_e32 v105, v98, v103
	v_lshlrev_b64 v[98:99], 12, v[216:217]
	v_mul_f32_e32 v114, v114, v103
	v_mul_f32_e32 v115, v115, v103
	v_mul_f32_e32 v116, v116, v103
	v_mul_f32_e32 v106, v106, v103
	v_mul_f32_e32 v107, v107, v103
	v_mul_f32_e32 v110, v110, v103
	v_mul_f32_e32 v111, v111, v103
	v_mul_f32_e32 v108, v108, v103
	v_mul_f32_e32 v109, v109, v103
	v_mul_f32_e32 v112, v112, v103
	v_mul_f32_e32 v113, v113, v103
	v_lshl_add_u64 v[102:103], v[218:219], 0, v[98:99]
	v_cvt_pk_bf16_f32 v98, v114, v116
	v_cvt_pk_bf16_f32 v99, v107, v111
	v_cvt_pk_bf16_f32 v100, v109, v113
	v_cvt_pk_bf16_f32 v101, v118, v104
	global_store_dwordx4 v[102:103], v[98:101], off sc1
	v_mov_b32_e32 v107, v92
	v_mov_b32_e32 v111, v82
	v_cvt_pk_bf16_f32 v98, v115, v106
	v_cvt_pk_bf16_f32 v99, v110, v108
	v_cvt_pk_bf16_f32 v100, v112, v117
	v_cvt_pk_bf16_f32 v101, v119, v105
	global_store_dwordx4 v[102:103], v[98:101], off offset:256 sc1
	ds_read2_b32 v[98:99], v0 offset0:32 offset1:48
	v_mov_b32_e32 v102, v94
	v_mov_b32_e32 v101, v94
	v_mov_b32_e32 v94, v91
	v_mov_b32_e32 v100, v90
	v_mov_b32_e32 v103, v90
	v_pk_mul_f32 v[104:105], v[94:95], v[160:161]
	v_mov_b32_e32 v90, v95
	v_mov_b32_e32 v95, v96
	v_mov_b32_e32 v106, v96
	v_mov_b32_e32 v96, v93
	v_mov_b32_e32 v94, v92
	v_pk_mul_f32 v[108:109], v[96:97], v[156:157]
	v_mov_b32_e32 v92, v97
	v_mov_b32_e32 v96, v82
	v_mov_b32_e32 v97, v86
	v_mov_b32_e32 v110, v86
	v_mov_b32_e32 v86, v83
	v_mov_b32_e32 v82, v87
	v_pk_mul_f32 v[112:113], v[86:87], v[152:153]
	v_pk_mul_f32 v[82:83], v[82:83], v[152:153]
	v_mov_b32_e32 v220, v84
	v_mov_b32_e32 v86, v138
	s_waitcnt lgkmcnt(0)
	v_mov_b32_e32 v87, v98
	v_pk_mul_f32 v[100:101], v[100:101], v[158:159]
	v_pk_mul_f32 v[102:103], v[102:103], v[158:159]
	v_pk_mul_f32 v[86:87], v[220:221], v[86:87]
	v_add_f32_e32 v82, v83, v82
	v_sub_f32_e32 v98, v100, v101
	v_add_f32_e32 v100, v103, v102
	v_mul_f32_e32 v102, v82, v87
	v_fma_f32 v82, -v88, v139, v86
	v_mul_f32_e32 v103, v82, v87
	v_mov_b32_e32 v82, v88
	v_mov_b32_e32 v83, v84
	v_pk_mul_f32 v[82:83], v[82:83], v[138:139]
	v_mov_b32_e32 v88, v85
	v_add_f32_e32 v82, v83, v82
	v_sub_f32_e32 v101, v104, v105
	v_mul_f32_e32 v104, v82, v87
	v_pk_mul_f32 v[82:83], v[88:89], v[140:141]
	v_mov_b32_e32 v84, v89
	v_sub_f32_e32 v82, v82, v83
	v_mul_f32_e32 v88, v82, v87
	v_pk_mul_f32 v[82:83], v[84:85], v[140:141]
	v_pk_mul_f32 v[90:91], v[90:91], v[160:161]
	v_pk_mul_f32 v[94:95], v[94:95], v[154:155]
	v_pk_mul_f32 v[106:107], v[106:107], v[154:155]
	v_pk_mul_f32 v[92:93], v[92:93], v[156:157]
	v_pk_mul_f32 v[96:97], v[96:97], v[150:151]
	v_pk_mul_f32 v[110:111], v[110:111], v[150:151]
	v_add_f32_e32 v82, v83, v82
	v_add_f32_e32 v90, v91, v90
	v_sub_f32_e32 v91, v94, v95
	v_add_f32_e32 v94, v107, v106
	v_sub_f32_e32 v95, v108, v109
	v_add_f32_e32 v92, v93, v92
	v_sub_f32_e32 v93, v96, v97
	v_add_f32_e32 v96, v111, v110
	v_sub_f32_e32 v97, v112, v113
	v_mul_f32_e32 v89, v82, v87
	v_lshlrev_b64 v[82:83], 12, v[214:215]
	v_mul_f32_e32 v98, v98, v87
	v_mul_f32_e32 v100, v100, v87
	v_mul_f32_e32 v101, v101, v87
	v_mul_f32_e32 v90, v90, v87
	v_mul_f32_e32 v91, v91, v87
	v_mul_f32_e32 v94, v94, v87
	v_mul_f32_e32 v95, v95, v87
	v_mul_f32_e32 v92, v92, v87
	v_mul_f32_e32 v93, v93, v87
	v_mul_f32_e32 v96, v96, v87
	v_mul_f32_e32 v97, v97, v87
	v_lshl_add_u64 v[86:87], v[218:219], 0, v[82:83]
	v_cvt_pk_bf16_f32 v83, v91, v95
	v_cvt_pk_bf16_f32 v84, v93, v97
	v_cvt_pk_bf16_f32 v82, v98, v101
	v_cvt_pk_bf16_f32 v85, v103, v88
	global_store_dwordx4 v[86:87], v[82:85], off sc1
	v_mov_b32_e32 v88, v80
	v_mov_b32_e32 v93, v66
	v_cvt_pk_bf16_f32 v83, v94, v92
	v_cvt_pk_bf16_f32 v84, v96, v102
	v_cvt_pk_bf16_f32 v82, v100, v90
	v_cvt_pk_bf16_f32 v85, v104, v89
	global_store_dwordx4 v[86:87], v[82:85], off offset:256 sc1
	v_mov_b32_e32 v89, v76
	v_mov_b32_e32 v92, v70
	v_mov_b32_e32 v83, v78
	v_mov_b32_e32 v84, v78
	v_mov_b32_e32 v78, v75
	v_mov_b32_e32 v82, v74
	v_mov_b32_e32 v85, v74
	v_pk_mul_f32 v[86:87], v[78:79], v[148:149]
	v_mov_b32_e32 v74, v79
	v_mov_b32_e32 v79, v80
	v_mov_b32_e32 v80, v77
	v_pk_mul_f32 v[90:91], v[80:81], v[144:145]
	v_mov_b32_e32 v80, v66
	v_mov_b32_e32 v66, v71
	v_mov_b32_e32 v78, v76
	v_mov_b32_e32 v76, v81
	v_mov_b32_e32 v81, v70
	v_mov_b32_e32 v70, v67
	v_pk_mul_f32 v[66:67], v[66:67], v[136:137]
	v_mov_b32_e32 v220, v68
	v_mov_b32_e32 v98, v130
	v_pk_mul_f32 v[82:83], v[82:83], v[146:147]
	v_pk_mul_f32 v[84:85], v[84:85], v[146:147]
	v_pk_mul_f32 v[94:95], v[70:71], v[136:137]
	v_pk_mul_f32 v[70:71], v[220:221], v[98:99]
	v_add_f32_e32 v66, v67, v66
	v_sub_f32_e32 v82, v82, v83
	v_add_f32_e32 v83, v85, v84
	v_mul_f32_e32 v85, v66, v71
	v_fma_f32 v66, -v72, v131, v70
	v_sub_f32_e32 v84, v86, v87
	v_mul_f32_e32 v86, v66, v71
	v_mov_b32_e32 v66, v72
	v_mov_b32_e32 v67, v68
	v_pk_mul_f32 v[66:67], v[66:67], v[130:131]
	v_mov_b32_e32 v72, v69
	v_add_f32_e32 v66, v67, v66
	v_mul_f32_e32 v87, v66, v71
	v_pk_mul_f32 v[66:67], v[72:73], v[132:133]
; __device__ __forceinline__ v4u pack8(const float (&f)[8]) { v4u w; w.x = cvt_pk_bf16(f[0], f[1]); w.y = cvt_pk_bf16(f[2], f[3]); w.z = cvt_pk_bf16(f[4], f[5]); w.w = cvt_pk_bf16(f[6], f[7]); return w; }
;     __device__ __forceinline__ void operator()(const f32x4 (&acc)[2][2][4][2], const Unit& u, int wr, int wc, int fr, int fq) const {
;     ...
;                     for (int m = 0; m < 4; ++m) { const int row = row0 + ai * 128 + m * 16; const int pi = row < MP ? row % TP : TP;
;                         const f32x4* cs = (const f32x4*)(CS + ((size_t)pi * 128 + cw) * 2);
; #pragma unroll
;                         for (int q4 = 0; q4 < 4; ++q4) tt[m][q4] = cs[q4]; }
; #pragma unroll
;                     for (int m = 0; m < 4; ++m) {
;                         const int row = row0 + ai * 128 + m * 16;
;                         const float rs = rtab[u.ord * 256 + (row - u.pm * 256)] * sc;
;                         const f32x4 t0 = tt[m][0], t1 = tt[m][1], t2 = tt[m][2], t3 = tt[m][3];
;                         const float c[8] = {t0.x, t0.z, t1.x, t1.z, t2.x, t2.z, t3.x, t3.z}, s[8] = {t0.y, t0.w, t1.y, t1.w, t2.y, t2.w, t3.y, t3.w};
;                         float o1[8], o2[8];
; #pragma unroll
;                         for (int n = 0; n < 2; ++n)
; #pragma unroll
;                             for (int j = 0; j < 4; ++j) {
;                                 const float x1 = acc[ai][0][m][n][j], x2 = acc[ai][1][m][n][j];
;                                 o1[n * 4 + j] = (x1 * c[n * 4 + j] - x2 * s[n * 4 + j]) * rs;
;                                 o2[n * 4 + j] = (x1 * s[n * 4 + j] + x2 * c[n * 4 + j]) * rs;
;                             }
;                         bf16* rp = base + (size_t)row * 2048;
;                         *(v4u*)rp = pack8(o1); *(v4u*)(rp + 128) = pack8(o2);
	v_mov_b32_e32 v68, v73
	v_sub_f32_e32 v66, v66, v67
	v_mul_f32_e32 v72, v66, v71
	v_pk_mul_f32 v[66:67], v[68:69], v[132:133]
	v_pk_mul_f32 v[74:75], v[74:75], v[148:149]
	v_pk_mul_f32 v[78:79], v[78:79], v[142:143]
	v_pk_mul_f32 v[88:89], v[88:89], v[142:143]
	v_pk_mul_f32 v[76:77], v[76:77], v[144:145]
	v_pk_mul_f32 v[80:81], v[80:81], v[134:135]
	v_pk_mul_f32 v[92:93], v[92:93], v[134:135]
	v_add_f32_e32 v66, v67, v66
	v_add_f32_e32 v74, v75, v74
	v_sub_f32_e32 v75, v78, v79
	v_add_f32_e32 v78, v89, v88
	v_sub_f32_e32 v79, v90, v91
	v_add_f32_e32 v76, v77, v76
	v_sub_f32_e32 v77, v80, v81
	v_add_f32_e32 v80, v93, v92
	v_sub_f32_e32 v81, v94, v95
	v_mul_f32_e32 v73, v66, v71
	v_lshlrev_b64 v[66:67], 12, v[212:213]
	v_mul_f32_e32 v82, v82, v71
	v_mul_f32_e32 v83, v83, v71
	v_mul_f32_e32 v84, v84, v71
	v_mul_f32_e32 v74, v74, v71
	v_mul_f32_e32 v75, v75, v71
	v_mul_f32_e32 v78, v78, v71
	v_mul_f32_e32 v79, v79, v71
	v_mul_f32_e32 v76, v76, v71
	v_mul_f32_e32 v77, v77, v71
	v_mul_f32_e32 v80, v80, v71
	v_mul_f32_e32 v81, v81, v71
	v_lshl_add_u64 v[70:71], v[218:219], 0, v[66:67]
	v_cvt_pk_bf16_f32 v66, v82, v84
	v_cvt_pk_bf16_f32 v67, v75, v79
	v_cvt_pk_bf16_f32 v68, v77, v81
	v_cvt_pk_bf16_f32 v69, v86, v72
	global_store_dwordx4 v[70:71], v[66:69], off sc1
	s_movk_i32 s0, 0x4000
	v_add_u32_e32 v136, 0x80, v210
	v_cvt_pk_bf16_f32 v66, v83, v74
	v_cvt_pk_bf16_f32 v67, v78, v76
	v_cvt_pk_bf16_f32 v68, v80, v85
	v_cvt_pk_bf16_f32 v69, v87, v73
	global_store_dwordx4 v[70:71], v[66:69], off offset:256 sc1
	v_cmp_gt_i32_e32 vcc, s0, v210
	s_nop 0
	v_mov_b64_e32 v[66:67], 0x40800
	v_mov_b64_e32 v[68:69], 0x40800
	s_and_saveexec_b64 s[0:1], vcc
	s_mov_b32 s2, 0xfe03f81
	v_mul_hi_i32 v68, v136, s2
	v_lshrrev_b32_e32 v69, 31, v68
	v_ashrrev_i32_e32 v68, 7, v68
	v_add_u32_e32 v68, v68, v69
	v_mul_lo_u32 v68, v68, s16
	v_sub_u32_e32 v68, v136, v68
	v_ashrrev_i32_e32 v69, 31, v68
	v_lshlrev_b64 v[68:69], 7, v[68:69]
	s_or_b64 exec, exec, s[0:1]
	v_readlane_b32 s0, v252, 28
	v_or_b32_e32 v68, v68, v204
	v_readlane_b32 s1, v252, 29
	v_add_u32_e32 v134, 0x90, v210
	s_nop 0
	v_lshl_add_u64 v[68:69], v[68:69], 3, s[0:1]
	global_load_dwordx4 v[110:113], v[68:69], off offset:48
	global_load_dwordx4 v[118:121], v[68:69], off offset:32
	global_load_dwordx4 v[122:125], v[68:69], off offset:16
	global_load_dwordx4 v[126:129], v[68:69], off
	s_movk_i32 s0, 0x3ff0
	v_cmp_gt_i32_e32 vcc, s0, v210
	s_and_saveexec_b64 s[0:1], vcc
	s_mov_b32 s2, 0xfe03f81
	v_mul_hi_i32 v66, v134, s2
	v_lshrrev_b32_e32 v67, 31, v66
	v_ashrrev_i32_e32 v66, 7, v66
	v_add_u32_e32 v66, v66, v67
	v_mul_lo_u32 v66, v66, s16
	v_sub_u32_e32 v66, v134, v66
	v_ashrrev_i32_e32 v67, 31, v66
	v_lshlrev_b64 v[66:67], 7, v[66:67]
	s_or_b64 exec, exec, s[0:1]
	v_readlane_b32 s0, v252, 28
	v_or_b32_e32 v66, v66, v204
	v_readlane_b32 s1, v252, 29
	v_add_u32_e32 v132, 0xa0, v210
	v_mov_b64_e32 v[68:69], 0x40800
	v_lshl_add_u64 v[66:67], v[66:67], 3, s[0:1]
	global_load_dwordx4 v[98:101], v[66:67], off offset:48
	global_load_dwordx4 v[102:105], v[66:67], off offset:32
	global_load_dwordx4 v[106:109], v[66:67], off offset:16
	global_load_dwordx4 v[114:117], v[66:67], off
	s_movk_i32 s0, 0x3fe0
	v_cmp_gt_i32_e32 vcc, s0, v210
	v_mov_b64_e32 v[66:67], 0x40800
	s_and_saveexec_b64 s[0:1], vcc
	s_mov_b32 s2, 0xfe03f81
	v_mul_hi_i32 v68, v132, s2
	v_lshrrev_b32_e32 v69, 31, v68
	v_ashrrev_i32_e32 v68, 7, v68
	v_add_u32_e32 v68, v68, v69
	v_mul_lo_u32 v68, v68, s16
	v_sub_u32_e32 v68, v132, v68
	v_ashrrev_i32_e32 v69, 31, v68
	v_lshlrev_b64 v[68:69], 7, v[68:69]
	s_or_b64 exec, exec, s[0:1]
	v_readlane_b32 s0, v252, 28
	v_or_b32_e32 v68, v68, v204
	v_readlane_b32 s1, v252, 29
	v_add_u32_e32 v130, 0xb0, v210
	s_nop 0
	v_lshl_add_u64 v[68:69], v[68:69], 3, s[0:1]
	global_load_dwordx4 v[78:81], v[68:69], off offset:48
	global_load_dwordx4 v[86:89], v[68:69], off offset:32
	global_load_dwordx4 v[90:93], v[68:69], off offset:16
	global_load_dwordx4 v[94:97], v[68:69], off
	s_movk_i32 s0, 0x3fd0
	v_cmp_gt_i32_e32 vcc, s0, v210
	s_and_saveexec_b64 s[0:1], vcc
	s_mov_b32 s2, 0xfe03f81
	v_mul_hi_i32 v66, v130, s2
	v_lshrrev_b32_e32 v67, 31, v66
	v_ashrrev_i32_e32 v66, 7, v66
	v_add_u32_e32 v66, v66, v67
	v_mul_lo_u32 v66, v66, s16
	v_sub_u32_e32 v66, v130, v66
	v_ashrrev_i32_e32 v67, 31, v66
	v_lshlrev_b64 v[66:67], 7, v[66:67]
	s_or_b64 exec, exec, s[0:1]
	v_readlane_b32 s0, v252, 28
	v_or_b32_e32 v66, v66, v204
	v_readlane_b32 s1, v252, 29
	v_mov_b32_e32 v140, v58
	v_mov_b32_e32 v141, v62
	v_lshl_add_u64 v[82:83], v[66:67], 3, s[0:1]
	global_load_dwordx4 v[66:69], v[82:83], off offset:48
	global_load_dwordx4 v[70:73], v[82:83], off offset:32
	global_load_dwordx4 v[74:77], v[82:83], off offset:16
	s_nop 0
	global_load_dwordx4 v[82:85], v[82:83], off
	ds_read2_b32 v[138:139], v0 offset0:128 offset1:144
	v_mov_b32_e32 v142, v62
	v_mov_b32_e32 v143, v58
	v_mov_b32_e32 v62, v59
	v_mov_b32_e32 v58, v63
	s_waitcnt vmcnt(12)
	v_pk_mul_f32 v[140:141], v[140:141], v[126:127]
	v_pk_mul_f32 v[126:127], v[142:143], v[126:127]
	v_pk_mul_f32 v[142:143], v[62:63], v[128:129]
	v_pk_mul_f32 v[58:59], v[58:59], v[128:129]
	v_mov_b32_e32 v62, v60
	v_mov_b32_e32 v63, v64
	v_mov_b32_e32 v128, v64
	v_mov_b32_e32 v129, v60
	v_mov_b32_e32 v64, v61
	v_mov_b32_e32 v60, v65
	v_pk_mul_f32 v[62:63], v[62:63], v[122:123]
	v_pk_mul_f32 v[122:123], v[128:129], v[122:123]
	v_pk_mul_f32 v[128:129], v[64:65], v[124:125]
	v_pk_mul_f32 v[60:61], v[60:61], v[124:125]
	v_mov_b32_e32 v64, v50
	v_mov_b32_e32 v65, v54
	v_mov_b32_e32 v124, v54
	v_mov_b32_e32 v125, v50
	v_mov_b32_e32 v54, v51
	v_mov_b32_e32 v50, v55
	v_pk_mul_f32 v[64:65], v[64:65], v[118:119]
	v_pk_mul_f32 v[118:119], v[124:125], v[118:119]
	v_pk_mul_f32 v[124:125], v[54:55], v[120:121]
	v_pk_mul_f32 v[50:51], v[50:51], v[120:121]
	v_mov_b32_e32 v220, v52
	v_mov_b32_e32 v54, v110
	s_waitcnt lgkmcnt(0)
; __device__ __forceinline__ v4u pack8(const float (&f)[8]) { v4u w; w.x = cvt_pk_bf16(f[0], f[1]); w.y = cvt_pk_bf16(f[2], f[3]); w.z = cvt_pk_bf16(f[4], f[5]); w.w = cvt_pk_bf16(f[6], f[7]); return w; }
;     __device__ __forceinline__ void operator()(const f32x4 (&acc)[2][2][4][2], const Unit& u, int wr, int wc, int fr, int fq) const {
;     ...
;                     for (int m = 0; m < 4; ++m) {
;                         const int row = row0 + ai * 128 + m * 16;
;                         const float rs = rtab[u.ord * 256 + (row - u.pm * 256)] * sc;
;                         const f32x4 t0 = tt[m][0], t1 = tt[m][1], t2 = tt[m][2], t3 = tt[m][3];
;                         const float c[8] = {t0.x, t0.z, t1.x, t1.z, t2.x, t2.z, t3.x, t3.z}, s[8] = {t0.y, t0.w, t1.y, t1.w, t2.y, t2.w, t3.y, t3.w};
;                         float o1[8], o2[8];
; #pragma unroll
;                         for (int n = 0; n < 2; ++n)
; #pragma unroll
;                             for (int j = 0; j < 4; ++j) {
;                                 const float x1 = acc[ai][0][m][n][j], x2 = acc[ai][1][m][n][j];
;                                 o1[n * 4 + j] = (x1 * c[n * 4 + j] - x2 * s[n * 4 + j]) * rs;
;                                 o2[n * 4 + j] = (x1 * s[n * 4 + j] + x2 * c[n * 4 + j]) * rs;
;                             }
;                         bf16* rp = base + (size_t)row * 2048;
;                         *(v4u*)rp = pack8(o1); *(v4u*)(rp + 128) = pack8(o2);
	v_mov_b32_e32 v55, v138
	v_pk_mul_f32 v[54:55], v[220:221], v[54:55]
	v_add_f32_e32 v50, v51, v50
	v_add_f32_e32 v60, v61, v60
	v_sub_f32_e32 v61, v64, v65
	v_add_f32_e32 v64, v119, v118
	v_mul_f32_e32 v118, v50, v55
	v_fma_f32 v50, -v56, v111, v54
	v_mul_f32_e32 v119, v50, v55
	v_mov_b32_e32 v50, v56
	v_mov_b32_e32 v51, v52
	v_pk_mul_f32 v[50:51], v[50:51], v[110:111]
	v_mov_b32_e32 v56, v53
	v_add_f32_e32 v50, v51, v50
	v_mul_f32_e32 v110, v50, v55
	v_pk_mul_f32 v[50:51], v[56:57], v[112:113]
	v_mov_b32_e32 v52, v57
	v_sub_f32_e32 v50, v50, v51
	v_mul_f32_e32 v56, v50, v55
	v_pk_mul_f32 v[50:51], v[52:53], v[112:113]
	v_ashrrev_i32_e32 v137, 31, v136
	v_add_f32_e32 v50, v51, v50
	v_sub_f32_e32 v120, v140, v141
	v_add_f32_e32 v121, v127, v126
	v_sub_f32_e32 v126, v142, v143
	v_add_f32_e32 v58, v59, v58
	v_sub_f32_e32 v59, v62, v63
	v_add_f32_e32 v62, v123, v122
	v_sub_f32_e32 v63, v128, v129
	v_sub_f32_e32 v65, v124, v125
	v_mul_f32_e32 v57, v50, v55
	v_lshlrev_b64 v[50:51], 12, v[136:137]
	v_mul_f32_e32 v120, v120, v55
	v_mul_f32_e32 v121, v121, v55
	v_mul_f32_e32 v126, v126, v55
	v_mul_f32_e32 v58, v58, v55
	v_mul_f32_e32 v59, v59, v55
	v_mul_f32_e32 v62, v62, v55
	v_mul_f32_e32 v63, v63, v55
	v_mul_f32_e32 v60, v60, v55
	v_mul_f32_e32 v61, v61, v55
	v_mul_f32_e32 v64, v64, v55
	v_mul_f32_e32 v65, v65, v55
	v_lshl_add_u64 v[54:55], v[218:219], 0, v[50:51]
	v_cvt_pk_bf16_f32 v51, v59, v63
	v_cvt_pk_bf16_f32 v52, v61, v65
	v_cvt_pk_bf16_f32 v50, v120, v126
	v_cvt_pk_bf16_f32 v53, v119, v56
	global_store_dwordx4 v[54:55], v[50:53], off sc1
	v_mov_b32_e32 v56, v48
	v_mov_b32_e32 v61, v34
	v_cvt_pk_bf16_f32 v51, v62, v60
	v_cvt_pk_bf16_f32 v52, v64, v118
	v_cvt_pk_bf16_f32 v50, v121, v58
	v_cvt_pk_bf16_f32 v53, v110, v57
	global_store_dwordx4 v[54:55], v[50:53], off offset:256 sc1
	v_mov_b32_e32 v57, v44
	v_mov_b32_e32 v60, v38
	v_mov_b32_e32 v51, v46
	v_mov_b32_e32 v52, v46
	v_mov_b32_e32 v46, v43
	v_mov_b32_e32 v50, v42
	v_mov_b32_e32 v53, v42
	s_waitcnt vmcnt(10)
	v_pk_mul_f32 v[54:55], v[46:47], v[116:117]
	v_mov_b32_e32 v42, v47
	v_mov_b32_e32 v47, v48
	v_mov_b32_e32 v48, v45
	v_pk_mul_f32 v[58:59], v[48:49], v[108:109]
	v_mov_b32_e32 v48, v34
	v_mov_b32_e32 v34, v39
	v_mov_b32_e32 v46, v44
	v_mov_b32_e32 v44, v49
	v_mov_b32_e32 v49, v38
	v_mov_b32_e32 v38, v35
	v_pk_mul_f32 v[34:35], v[34:35], v[104:105]
	v_mov_b32_e32 v220, v36
	v_mov_b32_e32 v138, v98
	v_pk_mul_f32 v[50:51], v[50:51], v[114:115]
	v_pk_mul_f32 v[52:53], v[52:53], v[114:115]
	v_pk_mul_f32 v[62:63], v[38:39], v[104:105]
	v_pk_mul_f32 v[38:39], v[220:221], v[138:139]
	v_add_f32_e32 v34, v35, v34
	v_sub_f32_e32 v50, v50, v51
	v_add_f32_e32 v51, v53, v52
	v_mul_f32_e32 v53, v34, v39
	v_fma_f32 v34, -v40, v99, v38
	v_sub_f32_e32 v52, v54, v55
	v_mul_f32_e32 v54, v34, v39
	v_mov_b32_e32 v34, v40
	v_mov_b32_e32 v35, v36
	v_pk_mul_f32 v[34:35], v[34:35], v[98:99]
	v_mov_b32_e32 v40, v37
	v_add_f32_e32 v34, v35, v34
	v_mul_f32_e32 v55, v34, v39
	v_pk_mul_f32 v[34:35], v[40:41], v[100:101]
	v_mov_b32_e32 v36, v41
	v_sub_f32_e32 v34, v34, v35
	v_mul_f32_e32 v40, v34, v39
	v_pk_mul_f32 v[34:35], v[36:37], v[100:101]
	v_pk_mul_f32 v[42:43], v[42:43], v[116:117]
	v_pk_mul_f32 v[46:47], v[46:47], v[106:107]
	v_pk_mul_f32 v[56:57], v[56:57], v[106:107]
	v_pk_mul_f32 v[44:45], v[44:45], v[108:109]
	v_pk_mul_f32 v[48:49], v[48:49], v[102:103]
	v_pk_mul_f32 v[60:61], v[60:61], v[102:103]
	v_add_f32_e32 v34, v35, v34
	v_ashrrev_i32_e32 v135, 31, v134
	v_add_f32_e32 v42, v43, v42
	v_sub_f32_e32 v43, v46, v47
	v_add_f32_e32 v46, v57, v56
	v_sub_f32_e32 v47, v58, v59
	v_add_f32_e32 v44, v45, v44
	v_sub_f32_e32 v45, v48, v49
	v_add_f32_e32 v48, v61, v60
	v_sub_f32_e32 v49, v62, v63
	v_mul_f32_e32 v41, v34, v39
	v_lshlrev_b64 v[34:35], 12, v[134:135]
	v_mul_f32_e32 v50, v50, v39
	v_mul_f32_e32 v51, v51, v39
	v_mul_f32_e32 v52, v52, v39
	v_mul_f32_e32 v42, v42, v39
	v_mul_f32_e32 v43, v43, v39
	v_mul_f32_e32 v46, v46, v39
	v_mul_f32_e32 v47, v47, v39
	v_mul_f32_e32 v44, v44, v39
	v_mul_f32_e32 v45, v45, v39
	v_mul_f32_e32 v48, v48, v39
	v_mul_f32_e32 v49, v49, v39
	v_lshl_add_u64 v[38:39], v[218:219], 0, v[34:35]
	v_cvt_pk_bf16_f32 v34, v50, v52
	v_cvt_pk_bf16_f32 v35, v43, v47
	v_cvt_pk_bf16_f32 v36, v45, v49
	v_cvt_pk_bf16_f32 v37, v54, v40
	global_store_dwordx4 v[38:39], v[34:37], off sc1
	v_mov_b32_e32 v43, v28
	v_mov_b32_e32 v47, v18
	v_cvt_pk_bf16_f32 v34, v51, v42
	v_cvt_pk_bf16_f32 v35, v46, v44
	v_cvt_pk_bf16_f32 v36, v48, v53
	v_cvt_pk_bf16_f32 v37, v55, v41
	global_store_dwordx4 v[38:39], v[34:37], off offset:256 sc1
	ds_read2_b32 v[34:35], v0 offset0:160 offset1:176
	v_mov_b32_e32 v38, v30
	v_mov_b32_e32 v37, v30
	v_mov_b32_e32 v30, v27
	v_mov_b32_e32 v36, v26
	v_mov_b32_e32 v39, v26
	s_waitcnt vmcnt(8)
; __device__ __forceinline__ v4u pack8(const float (&f)[8]) { v4u w; w.x = cvt_pk_bf16(f[0], f[1]); w.y = cvt_pk_bf16(f[2], f[3]); w.z = cvt_pk_bf16(f[4], f[5]); w.w = cvt_pk_bf16(f[6], f[7]); return w; }
;     __device__ __forceinline__ void operator()(const f32x4 (&acc)[2][2][4][2], const Unit& u, int wr, int wc, int fr, int fq) const {
;     ...
;                     for (int m = 0; m < 4; ++m) {
;                         const int row = row0 + ai * 128 + m * 16;
;                         const float rs = rtab[u.ord * 256 + (row - u.pm * 256)] * sc;
;                         const f32x4 t0 = tt[m][0], t1 = tt[m][1], t2 = tt[m][2], t3 = tt[m][3];
;                         const float c[8] = {t0.x, t0.z, t1.x, t1.z, t2.x, t2.z, t3.x, t3.z}, s[8] = {t0.y, t0.w, t1.y, t1.w, t2.y, t2.w, t3.y, t3.w};
;                         float o1[8], o2[8];
; #pragma unroll
;                         for (int n = 0; n < 2; ++n)
; #pragma unroll
;                             for (int j = 0; j < 4; ++j) {
;                                 const float x1 = acc[ai][0][m][n][j], x2 = acc[ai][1][m][n][j];
;                                 o1[n * 4 + j] = (x1 * c[n * 4 + j] - x2 * s[n * 4 + j]) * rs;
;                                 o2[n * 4 + j] = (x1 * s[n * 4 + j] + x2 * c[n * 4 + j]) * rs;
;                             }
;                         bf16* rp = base + (size_t)row * 2048;
;                         *(v4u*)rp = pack8(o1); *(v4u*)(rp + 128) = pack8(o2);
	v_pk_mul_f32 v[40:41], v[30:31], v[96:97]
	v_mov_b32_e32 v26, v31
	v_mov_b32_e32 v31, v32
	v_mov_b32_e32 v42, v32
	v_mov_b32_e32 v32, v29
	v_mov_b32_e32 v30, v28
	v_pk_mul_f32 v[44:45], v[32:33], v[92:93]
	v_mov_b32_e32 v28, v33
	v_mov_b32_e32 v32, v18
	v_mov_b32_e32 v33, v22
	v_mov_b32_e32 v46, v22
	v_mov_b32_e32 v22, v19
	v_mov_b32_e32 v18, v23
	v_pk_mul_f32 v[48:49], v[22:23], v[88:89]
	v_pk_mul_f32 v[18:19], v[18:19], v[88:89]
	v_mov_b32_e32 v220, v20
	v_mov_b32_e32 v22, v78
	s_waitcnt lgkmcnt(0)
	v_mov_b32_e32 v23, v34
	v_pk_mul_f32 v[36:37], v[36:37], v[94:95]
	v_pk_mul_f32 v[22:23], v[220:221], v[22:23]
	v_add_f32_e32 v18, v19, v18
	v_pk_mul_f32 v[38:39], v[38:39], v[94:95]
	v_sub_f32_e32 v0, v36, v37
	v_mul_f32_e32 v37, v18, v23
	v_fma_f32 v18, -v24, v79, v22
	v_add_f32_e32 v34, v39, v38
	v_mul_f32_e32 v38, v18, v23
	v_mov_b32_e32 v18, v24
	v_mov_b32_e32 v19, v20
	v_pk_mul_f32 v[18:19], v[18:19], v[78:79]
	v_mov_b32_e32 v24, v21
	v_add_f32_e32 v18, v19, v18
	v_mul_f32_e32 v39, v18, v23
	v_pk_mul_f32 v[18:19], v[24:25], v[80:81]
	v_mov_b32_e32 v20, v25
	v_sub_f32_e32 v18, v18, v19
	v_mul_f32_e32 v24, v18, v23
	v_pk_mul_f32 v[18:19], v[20:21], v[80:81]
	v_pk_mul_f32 v[26:27], v[26:27], v[96:97]
	v_pk_mul_f32 v[30:31], v[30:31], v[90:91]
	v_pk_mul_f32 v[42:43], v[42:43], v[90:91]
	v_pk_mul_f32 v[28:29], v[28:29], v[92:93]
	v_pk_mul_f32 v[32:33], v[32:33], v[86:87]
	v_pk_mul_f32 v[46:47], v[46:47], v[86:87]
	v_add_f32_e32 v18, v19, v18
	v_ashrrev_i32_e32 v133, 31, v132
	v_sub_f32_e32 v36, v40, v41
	v_add_f32_e32 v26, v27, v26
	v_sub_f32_e32 v27, v30, v31
	v_add_f32_e32 v30, v43, v42
	v_sub_f32_e32 v31, v44, v45
	v_add_f32_e32 v28, v29, v28
	v_sub_f32_e32 v29, v32, v33
	v_add_f32_e32 v32, v47, v46
	v_sub_f32_e32 v33, v48, v49
	v_mul_f32_e32 v25, v18, v23
	v_lshlrev_b64 v[18:19], 12, v[132:133]
	v_mul_f32_e32 v0, v0, v23
	v_mul_f32_e32 v34, v34, v23
	v_mul_f32_e32 v36, v36, v23
	v_mul_f32_e32 v26, v26, v23
	v_mul_f32_e32 v27, v27, v23
	v_mul_f32_e32 v30, v30, v23
	v_mul_f32_e32 v31, v31, v23
	v_mul_f32_e32 v28, v28, v23
	v_mul_f32_e32 v29, v29, v23
	v_mul_f32_e32 v32, v32, v23
	v_mul_f32_e32 v33, v33, v23
	v_lshl_add_u64 v[22:23], v[218:219], 0, v[18:19]
	v_cvt_pk_bf16_f32 v19, v27, v31
	v_cvt_pk_bf16_f32 v20, v29, v33
	v_cvt_pk_bf16_f32 v18, v0, v36
	v_cvt_pk_bf16_f32 v21, v38, v24
	global_store_dwordx4 v[22:23], v[18:21], off sc1
	v_mov_b32_e32 v24, v16
	v_mov_b32_e32 v29, v6
	v_cvt_pk_bf16_f32 v19, v30, v28
	v_cvt_pk_bf16_f32 v20, v32, v37
	v_cvt_pk_bf16_f32 v18, v34, v26
	v_cvt_pk_bf16_f32 v21, v39, v25
	global_store_dwordx4 v[22:23], v[18:21], off offset:256 sc1
	v_mov_b32_e32 v25, v12
	v_mov_b32_e32 v28, v2
	v_mov_b32_e32 v19, v14
	v_mov_b32_e32 v20, v14
	v_mov_b32_e32 v14, v11
	v_mov_b32_e32 v18, v10
	v_mov_b32_e32 v21, v10
	s_waitcnt vmcnt(6)
	v_pk_mul_f32 v[22:23], v[14:15], v[84:85]
	v_mov_b32_e32 v10, v15
	v_mov_b32_e32 v15, v16
	v_mov_b32_e32 v16, v13
	v_mov_b32_e32 v14, v12
	v_pk_mul_f32 v[26:27], v[16:17], v[76:77]
	v_mov_b32_e32 v12, v17
	v_mov_b32_e32 v16, v6
	v_mov_b32_e32 v17, v2
	v_mov_b32_e32 v2, v7
	v_mov_b32_e32 v6, v3
	v_pk_mul_f32 v[30:31], v[2:3], v[72:73]
	v_pk_mul_f32 v[2:3], v[6:7], v[72:73]
	v_mov_b32_e32 v220, v8
	v_mov_b32_e32 v34, v66
	v_pk_mul_f32 v[18:19], v[18:19], v[82:83]
	v_pk_mul_f32 v[20:21], v[20:21], v[82:83]
	v_pk_mul_f32 v[6:7], v[220:221], v[34:35]
	v_add_f32_e32 v2, v3, v2
	v_sub_f32_e32 v0, v18, v19
	v_add_f32_e32 v18, v21, v20
	v_mul_f32_e32 v20, v2, v7
	v_fma_f32 v2, -v4, v67, v6
	v_mul_f32_e32 v21, v2, v7
	v_mov_b32_e32 v2, v4
	v_mov_b32_e32 v3, v8
	v_pk_mul_f32 v[2:3], v[2:3], v[66:67]
	v_mov_b32_e32 v4, v9
	v_add_f32_e32 v2, v3, v2
	v_sub_f32_e32 v19, v22, v23
	v_mul_f32_e32 v22, v2, v7
	v_pk_mul_f32 v[2:3], v[4:5], v[68:69]
	v_mov_b32_e32 v8, v5
	v_sub_f32_e32 v2, v2, v3
	v_mul_f32_e32 v23, v2, v7
	v_pk_mul_f32 v[2:3], v[8:9], v[68:69]
	v_pk_mul_f32 v[10:11], v[10:11], v[84:85]
	v_pk_mul_f32 v[14:15], v[14:15], v[74:75]
	v_pk_mul_f32 v[24:25], v[24:25], v[74:75]
	v_pk_mul_f32 v[12:13], v[12:13], v[76:77]
	v_pk_mul_f32 v[16:17], v[16:17], v[70:71]
	v_pk_mul_f32 v[28:29], v[28:29], v[70:71]
	v_add_f32_e32 v2, v3, v2
	v_ashrrev_i32_e32 v131, 31, v130
	v_add_f32_e32 v10, v11, v10
	v_sub_f32_e32 v11, v14, v15
	v_add_f32_e32 v14, v25, v24
	v_sub_f32_e32 v15, v26, v27
	v_add_f32_e32 v12, v13, v12
	v_sub_f32_e32 v13, v16, v17
	v_add_f32_e32 v16, v29, v28
	v_sub_f32_e32 v17, v30, v31
	v_mul_f32_e32 v8, v2, v7
	v_lshlrev_b64 v[2:3], 12, v[130:131]
	v_mul_f32_e32 v0, v0, v7
	v_mul_f32_e32 v18, v18, v7
	v_mul_f32_e32 v19, v19, v7
	v_mul_f32_e32 v10, v10, v7
	v_mul_f32_e32 v11, v11, v7
	v_mul_f32_e32 v14, v14, v7
	v_mul_f32_e32 v15, v15, v7
	v_mul_f32_e32 v12, v12, v7
	v_mul_f32_e32 v13, v13, v7
	v_mul_f32_e32 v16, v16, v7
	v_mul_f32_e32 v17, v17, v7
	v_lshl_add_u64 v[6:7], v[218:219], 0, v[2:3]
	v_cvt_pk_bf16_f32 v2, v0, v19
	v_cvt_pk_bf16_f32 v3, v11, v15
	v_cvt_pk_bf16_f32 v4, v13, v17
	v_cvt_pk_bf16_f32 v5, v21, v23
	global_store_dwordx4 v[6:7], v[2:5], off sc1
	s_nop 1
	v_cvt_pk_bf16_f32 v2, v18, v10
	v_cvt_pk_bf16_f32 v3, v14, v12
	v_cvt_pk_bf16_f32 v4, v16, v20
	v_cvt_pk_bf16_f32 v5, v22, v8
	global_store_dwordx4 v[6:7], v[2:5], off offset:256 sc1

; #define LAS __attribute__((address_space(3)))
;     __device__ __forceinline__ void operator()(const f32x4 (&acc)[2][2][4][2], const Unit& u, int wr, int wc, int fr, int fq) const {
;     ...
;             for (int n = 0; n < 2; ++n) {
;                 const int f0 = u.pn * 128 + fl + 4 * n;
;                 const f32x4 w0 = *(const f32x4*)(cw + f0), w1 = *(const f32x4*)(cw + DFF + f0), w2 = *(const f32x4*)(cw + 2 * DFF + f0), bb = *(const f32x4*)(cb + f0);
;                 f32x4 prev = (f32x4){0.f, 0.f, 0.f, 0.f};
; #pragma unroll
;                 for (int ai = 0; ai < 2; ++ai)
; #pragma unroll
;                     for (int m = 0; m < 4; ++m) {
;                         const int l = 128 * ai + 64 * wr + 16 * m + frL, row = 254 * u.pm - 2 + l;
;                         const float rs = rt[l];
;                         const f32x4 cur = acc[ai][1][m][n] * rs, uu = acc[ai][0][m][n] * rs;
;                         if (m == 0) {
;                             const int B = 2 * ai + wr;
;                             prev = (f32x4){0.f, 0.f, 0.f, 0.f};
;                             if (B > 0 && frL >= 14) prev = *(const LAS f32x4*)(halo + ((B - 1) * 2 + (frL - 14)) * 128 + fl + 4 * n);
;                         }
;                         f32x4 g1, g2;
;                         {
;                             const float c1x = dpp_ror1(cur.x), c1y = dpp_ror1(cur.y), c1z = dpp_ror1(cur.z), c1w = dpp_ror1(cur.w);
;                             const float p1x = dpp_ror1(prev.x), p1y = dpp_ror1(prev.y), p1z = dpp_ror1(prev.z), p1w = dpp_ror1(prev.w);
;                             const float c2x = dpp_ror2(cur.x), c2y = dpp_ror2(cur.y), c2z = dpp_ror2(cur.z), c2w = dpp_ror2(cur.w);
;                             const float p2x = dpp_ror2(prev.x), p2y = dpp_ror2(prev.y), p2z = dpp_ror2(prev.z), p2w = dpp_ror2(prev.w);
;                             const bool s1 = frL >= 1, s2 = frL >= 2;
;                             g1.x = s1 ? c1x : p1x; g1.y = s1 ? c1y : p1y; g1.z = s1 ? c1z : p1z; g1.w = s1 ? c1w : p1w;
;                             g2.x = s2 ? c2x : p2x; g2.y = s2 ? c2y : p2y; g2.z = s2 ? c2z : p2z; g2.w = s2 ? c2w : p2w;
;                         }
;                         if (l >= 2 && row < M) {
;                             if (row < MP) {
;                                 const int b = row / TP, t = row - b * TP;
.LBB0_1185:
	s_or_b64 exec, exec, s[0:1]
	s_mul_i32 s21, s10, 0xfe
	s_mul_hi_i32 s0, s21, 0xfe03f81
	s_lshr_b32 s1, s0, 31
	s_ashr_i32 s0, s0, 7
	s_add_i32 s0, s0, s1
	s_mulk_i32 s0, 0x810
	s_sub_i32 s7, s21, s0
	s_cmpk_lt_i32 s21, 0x3f83
	s_cselect_b64 s[0:1], -1, 0
	s_cmp_gt_i32 s7, 1
	s_cselect_b64 s[8:9], -1, 0
	s_and_b64 s[0:1], s[0:1], s[8:9]
	s_cmpk_lt_u32 s7, 0x711
	s_waitcnt lgkmcnt(0)
	s_barrier
	s_cselect_b64 s[8:9], -1, 0
	s_and_b64 s[8:9], s[0:1], s[8:9]
	v_add_u32_e32 v211, s19, v212
	s_mov_b64 s[0:1], -1
	s_andn2_b64 vcc, exec, s[8:9]
	v_cmp_gt_i32_e64 s[10:11], 14, v212
	v_lshl_add_u32 v184, s52, 7, v0
	v_lshl_add_u32 v209, v211, 2, s6
	s_cbranch_vccz .LBB0_1388
	v_ashrrev_i32_e32 v185, 31, v184
	v_lshlrev_b64 v[2:3], 2, v[184:185]
	v_lshl_add_u64 v[198:199], s[34:35], 0, v[2:3]
	v_lshl_add_u64 v[132:133], s[44:45], 0, v[2:3]
	v_lshl_add_u64 v[134:135], s[46:47], 0, v[2:3]
	v_lshl_add_u64 v[200:201], s[36:37], 0, v[2:3]
	global_load_dwordx4 v[140:143], v[198:199], off
	global_load_dwordx4 v[136:139], v[132:133], off
	s_nop 0
	global_load_dwordx4 v[132:135], v[134:135], off
	ds_read_b32 v166, v209
	global_load_dwordx4 v[144:147], v[200:201], off
	v_lshl_add_u32 v190, v212, 9, s82
	s_movk_i32 s0, 0xe000
	v_add3_u32 v220, v190, v210, s0
	s_nor_b64 s[52:53], s[28:29], s[10:11]
	v_mov_b32_e32 v152, 0
	v_mov_b32_e32 v153, 0
	v_mov_b32_e32 v154, 0
	v_mov_b32_e32 v155, 0
	s_and_saveexec_b64 s[0:1], s[52:53]
	ds_read_b128 v[152:155], v220
	s_or_b64 exec, exec, s[0:1]
	v_readlane_b32 s0, v252, 8
	v_readlane_b32 s1, v252, 9
	s_waitcnt lgkmcnt(0)
	v_mov_b32_e32 v167, v166
	v_lshl_add_u64 v[164:165], s[38:39], 0, v[2:3]
	v_lshl_add_u64 v[202:203], v[184:185], 1, s[0:1]
	v_add3_u32 v185, s21, -2, v211
	s_movk_i32 s0, 0x4100
	v_lshl_add_u64 v[162:163], s[42:43], 0, v[2:3]
	v_lshl_add_u64 v[160:161], s[40:41], 0, v[2:3]
	v_pk_mul_f32 v[150:151], v[130:131], v[166:167] op_sel_hi:[1,0]
	v_pk_mul_f32 v[148:149], v[128:129], v[166:167] op_sel_hi:[1,0]
	v_mov_b32_e32 v0, v1
	v_mov_b32_e32 v2, v1
	v_mov_b32_e32 v3, v1
	v_mov_b32_e32 v168, v1
	v_mov_b32_e32 v169, v1
	v_mov_b32_e32 v170, v1
	v_mov_b32_e32 v171, v1
	v_mov_b32_e32 v187, v1
	v_mov_b32_e32 v186, v1
	v_mov_b32_e32 v188, v1
	v_mov_b32_e32 v189, v1
	v_mov_b32_e32 v191, v1
	v_mov_b32_e32 v192, v1
	v_mov_b32_e32 v193, v1
	v_mov_b32_e32 v196, v1
	v_mov_b32_e32 v197, v1
	v_cmp_lt_i32_e32 vcc, 1, v211
	v_cmp_gt_i32_e64 s[0:1], s0, v185
	v_cmp_lt_i32_e64 s[8:9], 0, v212
	v_cmp_lt_i32_e64 s[6:7], 1, v212
	v_mov_b32_dpp v0, v148 row_ror:1 row_mask:0xf bank_mask:0xf
	v_mov_b32_dpp v2, v149 row_ror:1 row_mask:0xf bank_mask:0xf
	v_mov_b32_dpp v3, v150 row_ror:1 row_mask:0xf bank_mask:0xf
	v_mov_b32_dpp v168, v151 row_ror:1 row_mask:0xf bank_mask:0xf
	v_mov_b32_dpp v169, v152 row_ror:1 row_mask:0xf bank_mask:0xf
	v_mov_b32_dpp v170, v153 row_ror:1 row_mask:0xf bank_mask:0xf
	v_mov_b32_dpp v171, v154 row_ror:1 row_mask:0xf bank_mask:0xf
	v_mov_b32_dpp v187, v155 row_ror:1 row_mask:0xf bank_mask:0xf
	v_mov_b32_dpp v186, v148 row_ror:2 row_mask:0xf bank_mask:0xf
	v_mov_b32_dpp v188, v149 row_ror:2 row_mask:0xf bank_mask:0xf
	v_mov_b32_dpp v189, v150 row_ror:2 row_mask:0xf bank_mask:0xf
	v_mov_b32_dpp v191, v151 row_ror:2 row_mask:0xf bank_mask:0xf
	v_mov_b32_dpp v192, v152 row_ror:2 row_mask:0xf bank_mask:0xf
	v_mov_b32_dpp v193, v153 row_ror:2 row_mask:0xf bank_mask:0xf
	v_mov_b32_dpp v196, v154 row_ror:2 row_mask:0xf bank_mask:0xf
	v_mov_b32_dpp v197, v155 row_ror:2 row_mask:0xf bank_mask:0xf
	s_and_b64 s[54:55], vcc, s[0:1]
	s_and_saveexec_b64 s[0:1], s[54:55]
	s_cbranch_execz .LBB0_1200
	s_movk_i32 s14, 0x407f
	v_cmp_lt_i32_e32 vcc, s14, v185
	s_and_saveexec_b64 s[56:57], vcc
	s_xor_b64 s[56:57], exec, s[56:57]
	s_cbranch_execz .LBB0_1191
	v_add_u32_e32 v0, 0xffffbf80, v185
	s_movk_i32 s14, 0x5800
	v_mad_u64_u32 v[2:3], s[58:59], v0, s14, v[164:165]
	v_add_co_u32_e32 v152, vcc, 0x2000, v2
	s_nop 1
	v_addc_co_u32_e32 v153, vcc, 0, v3, vcc
	global_load_dwordx4 v[152:155], v[152:153], off offset:3072
	s_nop 0
	global_load_dwordx4 v[156:159], v[2:3], off
	v_mad_u64_u32 v[2:3], s[58:59], v0, s14, v[162:163]
	v_add_co_u32_e32 v168, vcc, 0x2000, v2
	s_nop 1
	v_addc_co_u32_e32 v169, vcc, 0, v3, vcc
	s_waitcnt vmcnt(0)
	global_store_dwordx4 v[2:3], v[152:155], off sc1
	global_store_dwordx4 v[168:169], v[148:151], off offset:3072 sc1

;     __device__ __forceinline__ void operator()(const f32x4 (&acc)[2][2][4][2], const Unit& u, int wr, int wc, int fr, int fq) const {
;     ...
;                                 if (t >= TP - 2) *(f32x4*)(cvp + ((size_t)b * 2 + (t - (TP - 2))) * DFF + f0) = cur;
.LBB0_1196:
	s_or_b64 exec, exec, s[58:59]
	s_movk_i32 s14, 0x80d
	v_cmp_lt_i32_e32 vcc, s14, v170
	s_and_saveexec_b64 s[58:59], vcc
	s_cbranch_execz .LBB0_1198
	v_ashrrev_i32_e32 v169, 31, v168
	v_add_u32_e32 v0, 0xfffff7f2, v170
	v_lshl_add_u64 v[2:3], v[168:169], 1, v[0:1]
	s_movk_i32 s14, 0x2c00
	v_mad_u64_u32 v[168:169], s[60:61], v2, s14, v[160:161]
	v_mad_i32_i24 v169, v3, s14, v169
	global_store_dwordx4 v[168:169], v[148:151], off sc1

;     __device__ __forceinline__ void operator()(const f32x4 (&acc)[2][2][4][2], const Unit& u, int wr, int wc, int fr, int fq) const {
;     ...
;                     for (int m = 0; m < 4; ++m) {
;                         const int l = 128 * ai + 64 * wr + 16 * m + frL, row = 254 * u.pm - 2 + l;
;                         const float rs = rt[l];
;                         const f32x4 cur = acc[ai][1][m][n] * rs, uu = acc[ai][0][m][n] * rs;
;                         if (m == 0) {
;                             const int B = 2 * ai + wr;
;                             prev = (f32x4){0.f, 0.f, 0.f, 0.f};
;                             if (B > 0 && frL >= 14) prev = *(const LAS f32x4*)(halo + ((B - 1) * 2 + (frL - 14)) * 128 + fl + 4 * n);
;                         }
;                         f32x4 g1, g2;
;                         {
;                             const float c1x = dpp_ror1(cur.x), c1y = dpp_ror1(cur.y), c1z = dpp_ror1(cur.z), c1w = dpp_ror1(cur.w);
;                             const float p1x = dpp_ror1(prev.x), p1y = dpp_ror1(prev.y), p1z = dpp_ror1(prev.z), p1w = dpp_ror1(prev.w);
;                             const float c2x = dpp_ror2(cur.x), c2y = dpp_ror2(cur.y), c2z = dpp_ror2(cur.z), c2w = dpp_ror2(cur.w);
;                             const float p2x = dpp_ror2(prev.x), p2y = dpp_ror2(prev.y), p2z = dpp_ror2(prev.z), p2w = dpp_ror2(prev.w);
;                             const bool s1 = frL >= 1, s2 = frL >= 2;
;                             g1.x = s1 ? c1x : p1x; g1.y = s1 ? c1y : p1y; g1.z = s1 ? c1z : p1z; g1.w = s1 ? c1w : p1w;
;                             g2.x = s2 ? c2x : p2x; g2.y = s2 ? c2y : p2y; g2.z = s2 ? c2z : p2z; g2.w = s2 ? c2w : p2w;
;                         }
;                         if (l >= 2 && row < M) {
;                             if (row < MP) {
;                                 const int b = row / TP, t = row - b * TP;
;                                 if (t < 2) { g2 = (f32x4){0.f, 0.f, 0.f, 0.f}; if (t == 0) g1 = g2; }
;                                 if (t >= TP - 2) *(f32x4*)(cvp + ((size_t)b * 2 + (t - (TP - 2))) * DFF + f0) = cur;
;                             } else {
;                                 const int s = row - MP;
;                                 const float* c0 = cst + ((size_t)s * 2 + 0) * DFF + f0;
;                                 g2 = *(const f32x4*)c0; g1 = *(const f32x4*)(c0 + DFF);
.LBB0_1200:
	s_or_b64 exec, exec, s[0:1]
	ds_read_b32 v168, v209 offset:64
	v_add_u32_e32 v156, 16, v211
	v_add3_u32 v213, s21, 14, v211
	s_movk_i32 s0, 0x4100
	v_mov_b32_e32 v0, v1
	s_waitcnt lgkmcnt(0)
	v_mov_b32_e32 v169, v168
	v_pk_mul_f32 v[154:155], v[114:115], v[168:169] op_sel_hi:[1,0]
	v_pk_mul_f32 v[152:153], v[112:113], v[168:169] op_sel_hi:[1,0]
	v_mov_b32_e32 v2, v1
	v_mov_b32_e32 v3, v1
	v_mov_b32_e32 v170, v1
	v_mov_b32_e32 v171, v1
	v_mov_b32_e32 v186, v1
	v_mov_b32_e32 v187, v1
	v_mov_b32_e32 v189, v1
	v_mov_b32_e32 v188, v1
	v_mov_b32_e32 v191, v1
	v_mov_b32_e32 v192, v1
	v_mov_b32_e32 v193, v1
	v_mov_b32_e32 v196, v1
	v_mov_b32_e32 v197, v1
	v_mov_b32_e32 v204, v1
	v_mov_b32_e32 v205, v1
	v_cmp_lt_i32_e32 vcc, 1, v156
	v_cmp_gt_i32_e64 s[0:1], s0, v213
	v_mov_b32_dpp v0, v152 row_ror:1 row_mask:0xf bank_mask:0xf
	v_mov_b32_dpp v2, v153 row_ror:1 row_mask:0xf bank_mask:0xf
	v_mov_b32_dpp v3, v154 row_ror:1 row_mask:0xf bank_mask:0xf
	v_mov_b32_dpp v170, v155 row_ror:1 row_mask:0xf bank_mask:0xf
	v_mov_b32_dpp v171, v148 row_ror:1 row_mask:0xf bank_mask:0xf
	v_mov_b32_dpp v186, v149 row_ror:1 row_mask:0xf bank_mask:0xf
	v_mov_b32_dpp v187, v150 row_ror:1 row_mask:0xf bank_mask:0xf
	v_mov_b32_dpp v189, v151 row_ror:1 row_mask:0xf bank_mask:0xf
	v_mov_b32_dpp v188, v152 row_ror:2 row_mask:0xf bank_mask:0xf
	v_mov_b32_dpp v191, v153 row_ror:2 row_mask:0xf bank_mask:0xf
	v_mov_b32_dpp v192, v154 row_ror:2 row_mask:0xf bank_mask:0xf
	v_mov_b32_dpp v193, v155 row_ror:2 row_mask:0xf bank_mask:0xf
	v_mov_b32_dpp v196, v148 row_ror:2 row_mask:0xf bank_mask:0xf
	v_mov_b32_dpp v197, v149 row_ror:2 row_mask:0xf bank_mask:0xf
	v_mov_b32_dpp v204, v150 row_ror:2 row_mask:0xf bank_mask:0xf
	v_mov_b32_dpp v205, v151 row_ror:2 row_mask:0xf bank_mask:0xf
	s_and_b64 s[56:57], vcc, s[0:1]
	s_and_saveexec_b64 s[0:1], s[56:57]
	s_cbranch_execz .LBB0_1212
	s_movk_i32 s14, 0x407f
	v_cmp_lt_i32_e32 vcc, s14, v213
	s_and_saveexec_b64 s[58:59], vcc
	s_xor_b64 s[58:59], exec, s[58:59]
	s_cbranch_execz .LBB0_1203
	v_add_u32_e32 v0, 0xffffbf80, v213
	s_movk_i32 s14, 0x5800
	v_mad_u64_u32 v[2:3], s[60:61], v0, s14, v[164:165]
	v_add_co_u32_e32 v148, vcc, 0x2000, v2
	s_nop 1
	v_addc_co_u32_e32 v149, vcc, 0, v3, vcc
	global_load_dwordx4 v[148:151], v[148:149], off offset:3072
	s_nop 0
	global_load_dwordx4 v[156:159], v[2:3], off
	v_mad_u64_u32 v[2:3], s[60:61], v0, s14, v[162:163]
	v_add_co_u32_e32 v170, vcc, 0x2000, v2
	s_nop 1
	v_addc_co_u32_e32 v171, vcc, 0, v3, vcc
	s_waitcnt vmcnt(0)
	global_store_dwordx4 v[2:3], v[148:151], off sc1
	global_store_dwordx4 v[170:171], v[152:155], off offset:3072 sc1

;     __device__ __forceinline__ void operator()(const f32x4 (&acc)[2][2][4][2], const Unit& u, int wr, int wc, int fr, int fq) const {
;     ...
;                                 if (t >= TP - 2) *(f32x4*)(cvp + ((size_t)b * 2 + (t - (TP - 2))) * DFF + f0) = cur;
.LBB0_1208:
	s_or_b64 exec, exec, s[60:61]
	s_movk_i32 s14, 0x80d
	v_cmp_lt_i32_e32 vcc, s14, v186
	s_and_saveexec_b64 s[60:61], vcc
	s_cbranch_execz .LBB0_1210
	v_ashrrev_i32_e32 v171, 31, v170
	v_add_u32_e32 v0, 0xfffff7f2, v186
	v_lshl_add_u64 v[2:3], v[170:171], 1, v[0:1]
	s_movk_i32 s14, 0x2c00
	v_mad_u64_u32 v[170:171], s[62:63], v2, s14, v[160:161]
	v_mad_i32_i24 v171, v3, s14, v171
	global_store_dwordx4 v[170:171], v[152:155], off sc1

;     __device__ __forceinline__ void operator()(const f32x4 (&acc)[2][2][4][2], const Unit& u, int wr, int wc, int fr, int fq) const {
;     ...
;                     for (int m = 0; m < 4; ++m) {
;                         const int l = 128 * ai + 64 * wr + 16 * m + frL, row = 254 * u.pm - 2 + l;
;                         const float rs = rt[l];
;                         const f32x4 cur = acc[ai][1][m][n] * rs, uu = acc[ai][0][m][n] * rs;
;                         if (m == 0) {
;                             const int B = 2 * ai + wr;
;                             prev = (f32x4){0.f, 0.f, 0.f, 0.f};
;                             if (B > 0 && frL >= 14) prev = *(const LAS f32x4*)(halo + ((B - 1) * 2 + (frL - 14)) * 128 + fl + 4 * n);
;                         }
;                         f32x4 g1, g2;
;                         {
;                             const float c1x = dpp_ror1(cur.x), c1y = dpp_ror1(cur.y), c1z = dpp_ror1(cur.z), c1w = dpp_ror1(cur.w);
;                             const float p1x = dpp_ror1(prev.x), p1y = dpp_ror1(prev.y), p1z = dpp_ror1(prev.z), p1w = dpp_ror1(prev.w);
;                             const float c2x = dpp_ror2(cur.x), c2y = dpp_ror2(cur.y), c2z = dpp_ror2(cur.z), c2w = dpp_ror2(cur.w);
;                             const float p2x = dpp_ror2(prev.x), p2y = dpp_ror2(prev.y), p2z = dpp_ror2(prev.z), p2w = dpp_ror2(prev.w);
;                             const bool s1 = frL >= 1, s2 = frL >= 2;
;                             g1.x = s1 ? c1x : p1x; g1.y = s1 ? c1y : p1y; g1.z = s1 ? c1z : p1z; g1.w = s1 ? c1w : p1w;
;                             g2.x = s2 ? c2x : p2x; g2.y = s2 ? c2y : p2y; g2.z = s2 ? c2z : p2z; g2.w = s2 ? c2w : p2w;
;                         }
;                         if (l >= 2 && row < M) {
;                             if (row < MP) {
;                                 const int b = row / TP, t = row - b * TP;
;                                 if (t < 2) { g2 = (f32x4){0.f, 0.f, 0.f, 0.f}; if (t == 0) g1 = g2; }
;                                 if (t >= TP - 2) *(f32x4*)(cvp + ((size_t)b * 2 + (t - (TP - 2))) * DFF + f0) = cur;
;                             } else {
;                                 const int s = row - MP;
;                                 const float* c0 = cst + ((size_t)s * 2 + 0) * DFF + f0;
;                                 g2 = *(const f32x4*)c0; g1 = *(const f32x4*)(c0 + DFF);
.LBB0_1212:
	s_or_b64 exec, exec, s[0:1]
	ds_read_b32 v186, v209 offset:128
	v_add_u32_e32 v156, 32, v211
	v_add3_u32 v214, s21, 30, v211
	s_movk_i32 s0, 0x4100
	v_mov_b32_e32 v0, v1
	s_waitcnt lgkmcnt(0)
	v_mov_b32_e32 v187, v186
	v_pk_mul_f32 v[150:151], v[98:99], v[186:187] op_sel_hi:[1,0]
	v_pk_mul_f32 v[148:149], v[96:97], v[186:187] op_sel_hi:[1,0]
	v_mov_b32_e32 v2, v1
	v_mov_b32_e32 v3, v1
	v_mov_b32_e32 v170, v1
	v_mov_b32_e32 v171, v1
	v_mov_b32_e32 v188, v1
	v_mov_b32_e32 v189, v1
	v_mov_b32_e32 v192, v1
	v_mov_b32_e32 v191, v1
	v_mov_b32_e32 v193, v1
	v_mov_b32_e32 v196, v1
	v_mov_b32_e32 v197, v1
	v_mov_b32_e32 v204, v1
	v_mov_b32_e32 v205, v1
	v_mov_b32_e32 v215, v1
	v_mov_b32_e32 v216, v1
	v_cmp_lt_i32_e32 vcc, 1, v156
	v_cmp_gt_i32_e64 s[0:1], s0, v214
	v_mov_b32_dpp v0, v148 row_ror:1 row_mask:0xf bank_mask:0xf
	v_mov_b32_dpp v2, v149 row_ror:1 row_mask:0xf bank_mask:0xf
	v_mov_b32_dpp v3, v150 row_ror:1 row_mask:0xf bank_mask:0xf
	v_mov_b32_dpp v170, v151 row_ror:1 row_mask:0xf bank_mask:0xf
	v_mov_b32_dpp v171, v152 row_ror:1 row_mask:0xf bank_mask:0xf
	v_mov_b32_dpp v188, v153 row_ror:1 row_mask:0xf bank_mask:0xf
	v_mov_b32_dpp v189, v154 row_ror:1 row_mask:0xf bank_mask:0xf
	v_mov_b32_dpp v192, v155 row_ror:1 row_mask:0xf bank_mask:0xf
	v_mov_b32_dpp v191, v148 row_ror:2 row_mask:0xf bank_mask:0xf
	v_mov_b32_dpp v193, v149 row_ror:2 row_mask:0xf bank_mask:0xf
	v_mov_b32_dpp v196, v150 row_ror:2 row_mask:0xf bank_mask:0xf
	v_mov_b32_dpp v197, v151 row_ror:2 row_mask:0xf bank_mask:0xf
	v_mov_b32_dpp v204, v152 row_ror:2 row_mask:0xf bank_mask:0xf
	v_mov_b32_dpp v205, v153 row_ror:2 row_mask:0xf bank_mask:0xf
	v_mov_b32_dpp v215, v154 row_ror:2 row_mask:0xf bank_mask:0xf
	v_mov_b32_dpp v216, v155 row_ror:2 row_mask:0xf bank_mask:0xf
	s_and_b64 s[58:59], vcc, s[0:1]
	s_and_saveexec_b64 s[0:1], s[58:59]
	s_cbranch_execz .LBB0_1224
	s_movk_i32 s14, 0x407f
	v_cmp_lt_i32_e32 vcc, s14, v214
	s_and_saveexec_b64 s[60:61], vcc
	s_xor_b64 s[60:61], exec, s[60:61]
	s_cbranch_execz .LBB0_1215
	v_add_u32_e32 v0, 0xffffbf80, v214
	s_movk_i32 s14, 0x5800
	v_mad_u64_u32 v[2:3], s[62:63], v0, s14, v[164:165]
	v_add_co_u32_e32 v152, vcc, 0x2000, v2
	s_nop 1
	v_addc_co_u32_e32 v153, vcc, 0, v3, vcc
	global_load_dwordx4 v[152:155], v[152:153], off offset:3072
	s_nop 0
	global_load_dwordx4 v[156:159], v[2:3], off
	v_mad_u64_u32 v[2:3], s[62:63], v0, s14, v[162:163]
	v_add_co_u32_e32 v170, vcc, 0x2000, v2
	s_nop 1
	v_addc_co_u32_e32 v171, vcc, 0, v3, vcc
	s_waitcnt vmcnt(0)
	global_store_dwordx4 v[2:3], v[152:155], off sc1
	global_store_dwordx4 v[170:171], v[148:151], off offset:3072 sc1

;     __device__ __forceinline__ void operator()(const f32x4 (&acc)[2][2][4][2], const Unit& u, int wr, int wc, int fr, int fq) const {
;     ...
;                                 if (t >= TP - 2) *(f32x4*)(cvp + ((size_t)b * 2 + (t - (TP - 2))) * DFF + f0) = cur;
.LBB0_1220:
	s_or_b64 exec, exec, s[62:63]
	s_movk_i32 s14, 0x80d
	v_cmp_lt_i32_e32 vcc, s14, v188
	s_and_saveexec_b64 s[62:63], vcc
	s_cbranch_execz .LBB0_1222
	v_ashrrev_i32_e32 v171, 31, v170
	v_add_u32_e32 v0, 0xfffff7f2, v188
	v_lshl_add_u64 v[2:3], v[170:171], 1, v[0:1]
	s_movk_i32 s14, 0x2c00
	v_mad_u64_u32 v[170:171], s[64:65], v2, s14, v[160:161]
	v_mad_i32_i24 v171, v3, s14, v171
	global_store_dwordx4 v[170:171], v[148:151], off sc1

;     __device__ __forceinline__ void operator()(const f32x4 (&acc)[2][2][4][2], const Unit& u, int wr, int wc, int fr, int fq) const {
;     ...
;                     for (int m = 0; m < 4; ++m) {
;                         const int l = 128 * ai + 64 * wr + 16 * m + frL, row = 254 * u.pm - 2 + l;
;                         const float rs = rt[l];
;                         const f32x4 cur = acc[ai][1][m][n] * rs, uu = acc[ai][0][m][n] * rs;
;                         if (m == 0) {
;                             const int B = 2 * ai + wr;
;                             prev = (f32x4){0.f, 0.f, 0.f, 0.f};
;                             if (B > 0 && frL >= 14) prev = *(const LAS f32x4*)(halo + ((B - 1) * 2 + (frL - 14)) * 128 + fl + 4 * n);
;                         }
;                         f32x4 g1, g2;
;                         {
;                             const float c1x = dpp_ror1(cur.x), c1y = dpp_ror1(cur.y), c1z = dpp_ror1(cur.z), c1w = dpp_ror1(cur.w);
;                             const float p1x = dpp_ror1(prev.x), p1y = dpp_ror1(prev.y), p1z = dpp_ror1(prev.z), p1w = dpp_ror1(prev.w);
;                             const float c2x = dpp_ror2(cur.x), c2y = dpp_ror2(cur.y), c2z = dpp_ror2(cur.z), c2w = dpp_ror2(cur.w);
;                             const float p2x = dpp_ror2(prev.x), p2y = dpp_ror2(prev.y), p2z = dpp_ror2(prev.z), p2w = dpp_ror2(prev.w);
;                             const bool s1 = frL >= 1, s2 = frL >= 2;
;                             g1.x = s1 ? c1x : p1x; g1.y = s1 ? c1y : p1y; g1.z = s1 ? c1z : p1z; g1.w = s1 ? c1w : p1w;
;                             g2.x = s2 ? c2x : p2x; g2.y = s2 ? c2y : p2y; g2.z = s2 ? c2z : p2z; g2.w = s2 ? c2w : p2w;
;                         }
;                         if (l >= 2 && row < M) {
;                             if (row < MP) {
;                                 const int b = row / TP, t = row - b * TP;
;                                 if (t < 2) { g2 = (f32x4){0.f, 0.f, 0.f, 0.f}; if (t == 0) g1 = g2; }
;                                 if (t >= TP - 2) *(f32x4*)(cvp + ((size_t)b * 2 + (t - (TP - 2))) * DFF + f0) = cur;
;                             } else {
;                                 const int s = row - MP;
;                                 const float* c0 = cst + ((size_t)s * 2 + 0) * DFF + f0;
;                                 g2 = *(const f32x4*)c0; g1 = *(const f32x4*)(c0 + DFF);
.LBB0_1224:
	s_or_b64 exec, exec, s[0:1]
	ds_read_b32 v188, v209 offset:192
	v_add_u32_e32 v156, 48, v211
	v_add3_u32 v215, s21, 46, v211
	s_movk_i32 s0, 0x4100
	v_mov_b32_e32 v0, v1
	s_waitcnt lgkmcnt(0)
	v_mov_b32_e32 v189, v188
	v_pk_mul_f32 v[154:155], v[82:83], v[188:189] op_sel_hi:[1,0]
	v_pk_mul_f32 v[152:153], v[80:81], v[188:189] op_sel_hi:[1,0]
	v_mov_b32_e32 v2, v1
	v_mov_b32_e32 v3, v1
	v_mov_b32_e32 v170, v1
	v_mov_b32_e32 v171, v1
	v_mov_b32_e32 v191, v1
	v_mov_b32_e32 v192, v1
	v_mov_b32_e32 v196, v1
	v_mov_b32_e32 v193, v1
	v_mov_b32_e32 v197, v1
	v_mov_b32_e32 v204, v1
	v_mov_b32_e32 v205, v1
	v_mov_b32_e32 v216, v1
	v_mov_b32_e32 v217, v1
	v_mov_b32_e32 v218, v1
	v_mov_b32_e32 v219, v1
	v_cmp_lt_i32_e32 vcc, 1, v156
	v_cmp_gt_i32_e64 s[0:1], s0, v215
	v_mov_b32_dpp v0, v152 row_ror:1 row_mask:0xf bank_mask:0xf
	v_mov_b32_dpp v2, v153 row_ror:1 row_mask:0xf bank_mask:0xf
	v_mov_b32_dpp v3, v154 row_ror:1 row_mask:0xf bank_mask:0xf
	v_mov_b32_dpp v170, v155 row_ror:1 row_mask:0xf bank_mask:0xf
	v_mov_b32_dpp v171, v148 row_ror:1 row_mask:0xf bank_mask:0xf
	v_mov_b32_dpp v191, v149 row_ror:1 row_mask:0xf bank_mask:0xf
	v_mov_b32_dpp v192, v150 row_ror:1 row_mask:0xf bank_mask:0xf
	v_mov_b32_dpp v196, v151 row_ror:1 row_mask:0xf bank_mask:0xf
	v_mov_b32_dpp v193, v152 row_ror:2 row_mask:0xf bank_mask:0xf
	v_mov_b32_dpp v197, v153 row_ror:2 row_mask:0xf bank_mask:0xf
	v_mov_b32_dpp v204, v154 row_ror:2 row_mask:0xf bank_mask:0xf
	v_mov_b32_dpp v205, v155 row_ror:2 row_mask:0xf bank_mask:0xf
	v_mov_b32_dpp v216, v148 row_ror:2 row_mask:0xf bank_mask:0xf
	v_mov_b32_dpp v217, v149 row_ror:2 row_mask:0xf bank_mask:0xf
	v_mov_b32_dpp v218, v150 row_ror:2 row_mask:0xf bank_mask:0xf
	v_mov_b32_dpp v219, v151 row_ror:2 row_mask:0xf bank_mask:0xf
	s_and_b64 s[60:61], vcc, s[0:1]
	s_and_saveexec_b64 s[0:1], s[60:61]
	s_cbranch_execz .LBB0_1236
	s_movk_i32 s14, 0x407f
	v_cmp_lt_i32_e32 vcc, s14, v215
	s_and_saveexec_b64 s[62:63], vcc
	s_xor_b64 s[62:63], exec, s[62:63]
	s_cbranch_execz .LBB0_1227
	v_add_u32_e32 v0, 0xffffbf80, v215
	s_movk_i32 s14, 0x5800
	v_mad_u64_u32 v[2:3], s[64:65], v0, s14, v[164:165]
	v_add_co_u32_e32 v148, vcc, 0x2000, v2
	s_nop 1
	v_addc_co_u32_e32 v149, vcc, 0, v3, vcc
	global_load_dwordx4 v[148:151], v[148:149], off offset:3072
	s_nop 0
	global_load_dwordx4 v[156:159], v[2:3], off
	v_mad_u64_u32 v[2:3], s[64:65], v0, s14, v[162:163]
	v_add_co_u32_e32 v170, vcc, 0x2000, v2
	s_nop 1
	v_addc_co_u32_e32 v171, vcc, 0, v3, vcc
	s_waitcnt vmcnt(0)
	global_store_dwordx4 v[2:3], v[148:151], off sc1
	global_store_dwordx4 v[170:171], v[152:155], off offset:3072 sc1

;     __device__ __forceinline__ void operator()(const f32x4 (&acc)[2][2][4][2], const Unit& u, int wr, int wc, int fr, int fq) const {
;     ...
;                                 if (t >= TP - 2) *(f32x4*)(cvp + ((size_t)b * 2 + (t - (TP - 2))) * DFF + f0) = cur;
.LBB0_1232:
	s_or_b64 exec, exec, s[64:65]
	s_movk_i32 s14, 0x80d
	v_cmp_lt_i32_e32 vcc, s14, v191
	s_and_saveexec_b64 s[64:65], vcc
	s_cbranch_execz .LBB0_1234
	v_ashrrev_i32_e32 v171, 31, v170
	v_add_u32_e32 v0, 0xfffff7f2, v191
	v_lshl_add_u64 v[2:3], v[170:171], 1, v[0:1]
	s_movk_i32 s14, 0x2c00
	v_mad_u64_u32 v[170:171], s[66:67], v2, s14, v[160:161]
	v_mad_i32_i24 v171, v3, s14, v171
	global_store_dwordx4 v[170:171], v[152:155], off sc1

;     __device__ __forceinline__ void operator()(const f32x4 (&acc)[2][2][4][2], const Unit& u, int wr, int wc, int fr, int fq) const {
;     ...
;                     for (int m = 0; m < 4; ++m) {
;                         const int l = 128 * ai + 64 * wr + 16 * m + frL, row = 254 * u.pm - 2 + l;
;                         const float rs = rt[l];
;                         const f32x4 cur = acc[ai][1][m][n] * rs, uu = acc[ai][0][m][n] * rs;
;                         if (m == 0) {
;                             const int B = 2 * ai + wr;
;                             prev = (f32x4){0.f, 0.f, 0.f, 0.f};
;                             if (B > 0 && frL >= 14) prev = *(const LAS f32x4*)(halo + ((B - 1) * 2 + (frL - 14)) * 128 + fl + 4 * n);
;                         }
;                         f32x4 g1, g2;
;                         {
;                             const float c1x = dpp_ror1(cur.x), c1y = dpp_ror1(cur.y), c1z = dpp_ror1(cur.z), c1w = dpp_ror1(cur.w);
;                             const float p1x = dpp_ror1(prev.x), p1y = dpp_ror1(prev.y), p1z = dpp_ror1(prev.z), p1w = dpp_ror1(prev.w);
;                             const float c2x = dpp_ror2(cur.x), c2y = dpp_ror2(cur.y), c2z = dpp_ror2(cur.z), c2w = dpp_ror2(cur.w);
;                             const float p2x = dpp_ror2(prev.x), p2y = dpp_ror2(prev.y), p2z = dpp_ror2(prev.z), p2w = dpp_ror2(prev.w);
;                             const bool s1 = frL >= 1, s2 = frL >= 2;
;                             g1.x = s1 ? c1x : p1x; g1.y = s1 ? c1y : p1y; g1.z = s1 ? c1z : p1z; g1.w = s1 ? c1w : p1w;
;                             g2.x = s2 ? c2x : p2x; g2.y = s2 ? c2y : p2y; g2.z = s2 ? c2z : p2z; g2.w = s2 ? c2w : p2w;
;                         }
;                         if (l >= 2 && row < M) {
;                             if (row < MP) {
;                                 const int b = row / TP, t = row - b * TP;
;                                 if (t < 2) { g2 = (f32x4){0.f, 0.f, 0.f, 0.f}; if (t == 0) g1 = g2; }
;                                 if (t >= TP - 2) *(f32x4*)(cvp + ((size_t)b * 2 + (t - (TP - 2))) * DFF + f0) = cur;
;                             } else {
;                                 const int s = row - MP;
;                                 const float* c0 = cst + ((size_t)s * 2 + 0) * DFF + f0;
;                                 g2 = *(const f32x4*)c0; g1 = *(const f32x4*)(c0 + DFF);
.LBB0_1236:
	s_or_b64 exec, exec, s[0:1]
	ds_read_b32 v170, v209 offset:512
	s_movk_i32 s0, 0xe800
	v_add3_u32 v221, v190, v210, s0
	s_nor_b64 s[10:11], s[30:31], s[10:11]
	v_mov_b32_e32 v152, 0
	v_mov_b32_e32 v153, 0
	v_mov_b32_e32 v154, 0
	v_mov_b32_e32 v155, 0
	s_and_saveexec_b64 s[0:1], s[10:11]
	ds_read_b128 v[152:155], v221
	s_or_b64 exec, exec, s[0:1]
	s_add_i32 s0, s21, 0x7e
	v_add_u32_e32 v156, 0x80, v211
	v_add_u32_e32 v216, s0, v211
	s_waitcnt lgkmcnt(0)
	v_mov_b32_e32 v171, v170
	s_movk_i32 s0, 0x4100
	v_pk_mul_f32 v[150:151], v[66:67], v[170:171] op_sel_hi:[1,0]
	v_pk_mul_f32 v[148:149], v[64:65], v[170:171] op_sel_hi:[1,0]
	v_mov_b32_e32 v0, v1
	v_mov_b32_e32 v2, v1
	v_mov_b32_e32 v3, v1
	v_mov_b32_e32 v190, v1
	v_mov_b32_e32 v191, v1
	v_mov_b32_e32 v192, v1
	v_mov_b32_e32 v193, v1
	v_mov_b32_e32 v197, v1
	v_mov_b32_e32 v196, v1
	v_mov_b32_e32 v204, v1
	v_mov_b32_e32 v205, v1
	v_mov_b32_e32 v217, v1
	v_mov_b32_e32 v218, v1
	v_mov_b32_e32 v219, v1
	v_mov_b32_e32 v239, v1
	v_mov_b32_e32 v240, v1
	v_cmp_lt_i32_e32 vcc, 1, v156
	v_cmp_gt_i32_e64 s[0:1], s0, v216
	v_mov_b32_dpp v0, v148 row_ror:1 row_mask:0xf bank_mask:0xf
	v_mov_b32_dpp v2, v149 row_ror:1 row_mask:0xf bank_mask:0xf
	v_mov_b32_dpp v3, v150 row_ror:1 row_mask:0xf bank_mask:0xf
	v_mov_b32_dpp v190, v151 row_ror:1 row_mask:0xf bank_mask:0xf
	v_mov_b32_dpp v191, v152 row_ror:1 row_mask:0xf bank_mask:0xf
	v_mov_b32_dpp v192, v153 row_ror:1 row_mask:0xf bank_mask:0xf
	v_mov_b32_dpp v193, v154 row_ror:1 row_mask:0xf bank_mask:0xf
	v_mov_b32_dpp v197, v155 row_ror:1 row_mask:0xf bank_mask:0xf
	v_mov_b32_dpp v196, v148 row_ror:2 row_mask:0xf bank_mask:0xf
	v_mov_b32_dpp v204, v149 row_ror:2 row_mask:0xf bank_mask:0xf
	v_mov_b32_dpp v205, v150 row_ror:2 row_mask:0xf bank_mask:0xf
	v_mov_b32_dpp v217, v151 row_ror:2 row_mask:0xf bank_mask:0xf
	v_mov_b32_dpp v218, v152 row_ror:2 row_mask:0xf bank_mask:0xf
	v_mov_b32_dpp v219, v153 row_ror:2 row_mask:0xf bank_mask:0xf
	v_mov_b32_dpp v239, v154 row_ror:2 row_mask:0xf bank_mask:0xf
	v_mov_b32_dpp v240, v155 row_ror:2 row_mask:0xf bank_mask:0xf
	s_and_b64 s[62:63], vcc, s[0:1]
	s_and_saveexec_b64 s[0:1], s[62:63]
	s_cbranch_execz .LBB0_1250
	s_movk_i32 s14, 0x407f
	v_cmp_lt_i32_e32 vcc, s14, v216
	s_and_saveexec_b64 s[64:65], vcc
	s_xor_b64 s[64:65], exec, s[64:65]
	s_cbranch_execz .LBB0_1241
	v_add_u32_e32 v0, 0xffffbf80, v216
	s_movk_i32 s14, 0x5800
	v_mad_u64_u32 v[2:3], s[66:67], v0, s14, v[164:165]
	v_add_co_u32_e32 v152, vcc, 0x2000, v2
	s_nop 1
	v_addc_co_u32_e32 v153, vcc, 0, v3, vcc
	global_load_dwordx4 v[152:155], v[152:153], off offset:3072
	s_nop 0
	global_load_dwordx4 v[156:159], v[2:3], off
	v_mad_u64_u32 v[2:3], s[66:67], v0, s14, v[162:163]
	v_add_co_u32_e32 v190, vcc, 0x2000, v2
	s_nop 1
	v_addc_co_u32_e32 v191, vcc, 0, v3, vcc
	s_waitcnt vmcnt(0)
	global_store_dwordx4 v[2:3], v[152:155], off sc1
	global_store_dwordx4 v[190:191], v[148:151], off offset:3072 sc1

;     __device__ __forceinline__ void operator()(const f32x4 (&acc)[2][2][4][2], const Unit& u, int wr, int wc, int fr, int fq) const {
;     ...
;                                 if (t >= TP - 2) *(f32x4*)(cvp + ((size_t)b * 2 + (t - (TP - 2))) * DFF + f0) = cur;
.LBB0_1246:
	s_or_b64 exec, exec, s[66:67]
	s_movk_i32 s14, 0x80d
	v_cmp_lt_i32_e32 vcc, s14, v192
	s_and_saveexec_b64 s[66:67], vcc
	s_cbranch_execz .LBB0_1248
	v_ashrrev_i32_e32 v191, 31, v190
	v_add_u32_e32 v0, 0xfffff7f2, v192
	v_lshl_add_u64 v[2:3], v[190:191], 1, v[0:1]
	s_movk_i32 s14, 0x2c00
	v_mad_u64_u32 v[190:191], s[68:69], v2, s14, v[160:161]
	v_mad_i32_i24 v191, v3, s14, v191
	global_store_dwordx4 v[190:191], v[148:151], off sc1

; #define LAS __attribute__((address_space(3)))
;     __device__ __forceinline__ void operator()(const f32x4 (&acc)[2][2][4][2], const Unit& u, int wr, int wc, int fr, int fq) const {
;     ...
;                         const int l = 128 * ai + 64 * wr + 16 * m + frL, row = 254 * u.pm - 2 + l;
;                         const float rs = rt[l];
;                         const f32x4 cur = acc[ai][1][m][n] * rs, uu = acc[ai][0][m][n] * rs;
;                         if (m == 0) {
;                             const int B = 2 * ai + wr;
;                             prev = (f32x4){0.f, 0.f, 0.f, 0.f};
;                             if (B > 0 && frL >= 14) prev = *(const LAS f32x4*)(halo + ((B - 1) * 2 + (frL - 14)) * 128 + fl + 4 * n);
;                         }
;                         f32x4 g1, g2;
;                         {
;                             const float c1x = dpp_ror1(cur.x), c1y = dpp_ror1(cur.y), c1z = dpp_ror1(cur.z), c1w = dpp_ror1(cur.w);
;                             const float p1x = dpp_ror1(prev.x), p1y = dpp_ror1(prev.y), p1z = dpp_ror1(prev.z), p1w = dpp_ror1(prev.w);
;                             const float c2x = dpp_ror2(cur.x), c2y = dpp_ror2(cur.y), c2z = dpp_ror2(cur.z), c2w = dpp_ror2(cur.w);
;                             const float p2x = dpp_ror2(prev.x), p2y = dpp_ror2(prev.y), p2z = dpp_ror2(prev.z), p2w = dpp_ror2(prev.w);
;                             const bool s1 = frL >= 1, s2 = frL >= 2;
;                             g1.x = s1 ? c1x : p1x; g1.y = s1 ? c1y : p1y; g1.z = s1 ? c1z : p1z; g1.w = s1 ? c1w : p1w;
;                             g2.x = s2 ? c2x : p2x; g2.y = s2 ? c2y : p2y; g2.z = s2 ? c2z : p2z; g2.w = s2 ? c2w : p2w;
;                         }
;                         if (l >= 2 && row < M) {
;                             if (row < MP) {
;                                 const int b = row / TP, t = row - b * TP;
;                                 if (t < 2) { g2 = (f32x4){0.f, 0.f, 0.f, 0.f}; if (t == 0) g1 = g2; }
;                                 if (t >= TP - 2) *(f32x4*)(cvp + ((size_t)b * 2 + (t - (TP - 2))) * DFF + f0) = cur;
;                             } else {
;                                 const int s = row - MP;
;                                 const float* c0 = cst + ((size_t)s * 2 + 0) * DFF + f0;
;                                 g2 = *(const f32x4*)c0; g1 = *(const f32x4*)(c0 + DFF);
.LBB0_1250:
	s_or_b64 exec, exec, s[0:1]
	ds_read_b32 v190, v209 offset:576
	s_add_i32 s0, s21, 0x8e
	v_add_u32_e32 v156, 0x90, v211
	v_add_u32_e32 v217, s0, v211
	s_movk_i32 s0, 0x4100
	s_waitcnt lgkmcnt(0)
	v_mov_b32_e32 v191, v190
	v_pk_mul_f32 v[154:155], v[50:51], v[190:191] op_sel_hi:[1,0]
	v_pk_mul_f32 v[152:153], v[48:49], v[190:191] op_sel_hi:[1,0]
	v_mov_b32_e32 v0, v1
	v_mov_b32_e32 v2, v1
	v_mov_b32_e32 v3, v1
	v_mov_b32_e32 v192, v1
	v_mov_b32_e32 v193, v1
	v_mov_b32_e32 v196, v1
	v_mov_b32_e32 v197, v1
	v_mov_b32_e32 v205, v1
	v_mov_b32_e32 v204, v1
	v_mov_b32_e32 v218, v1
	v_mov_b32_e32 v219, v1
	v_mov_b32_e32 v239, v1
	v_mov_b32_e32 v240, v1
	v_mov_b32_e32 v241, v1
	v_mov_b32_e32 v242, v1
	v_mov_b32_e32 v243, v1
	v_cmp_lt_i32_e32 vcc, 1, v156
	v_cmp_gt_i32_e64 s[0:1], s0, v217
	v_mov_b32_dpp v0, v152 row_ror:1 row_mask:0xf bank_mask:0xf
	v_mov_b32_dpp v2, v153 row_ror:1 row_mask:0xf bank_mask:0xf
	v_mov_b32_dpp v3, v154 row_ror:1 row_mask:0xf bank_mask:0xf
	v_mov_b32_dpp v192, v155 row_ror:1 row_mask:0xf bank_mask:0xf
	v_mov_b32_dpp v193, v148 row_ror:1 row_mask:0xf bank_mask:0xf
	v_mov_b32_dpp v196, v149 row_ror:1 row_mask:0xf bank_mask:0xf
	v_mov_b32_dpp v197, v150 row_ror:1 row_mask:0xf bank_mask:0xf
	v_mov_b32_dpp v205, v151 row_ror:1 row_mask:0xf bank_mask:0xf
	v_mov_b32_dpp v204, v152 row_ror:2 row_mask:0xf bank_mask:0xf
	v_mov_b32_dpp v218, v153 row_ror:2 row_mask:0xf bank_mask:0xf
	v_mov_b32_dpp v219, v154 row_ror:2 row_mask:0xf bank_mask:0xf
	v_mov_b32_dpp v239, v155 row_ror:2 row_mask:0xf bank_mask:0xf
	v_mov_b32_dpp v240, v148 row_ror:2 row_mask:0xf bank_mask:0xf
	v_mov_b32_dpp v241, v149 row_ror:2 row_mask:0xf bank_mask:0xf
	v_mov_b32_dpp v242, v150 row_ror:2 row_mask:0xf bank_mask:0xf
	v_mov_b32_dpp v243, v151 row_ror:2 row_mask:0xf bank_mask:0xf
	s_and_b64 s[64:65], vcc, s[0:1]
	s_and_saveexec_b64 s[0:1], s[64:65]
	s_cbranch_execz .LBB0_1262
	s_movk_i32 s14, 0x407f
	v_cmp_lt_i32_e32 vcc, s14, v217
	s_and_saveexec_b64 s[66:67], vcc
	s_xor_b64 s[66:67], exec, s[66:67]
	s_cbranch_execz .LBB0_1253
	v_add_u32_e32 v0, 0xffffbf80, v217
	s_movk_i32 s14, 0x5800
	v_mad_u64_u32 v[2:3], s[68:69], v0, s14, v[164:165]
	v_add_co_u32_e32 v148, vcc, 0x2000, v2
	s_nop 1
	v_addc_co_u32_e32 v149, vcc, 0, v3, vcc
	global_load_dwordx4 v[148:151], v[148:149], off offset:3072
	s_nop 0
	global_load_dwordx4 v[156:159], v[2:3], off
	v_mad_u64_u32 v[2:3], s[68:69], v0, s14, v[162:163]
	v_add_co_u32_e32 v192, vcc, 0x2000, v2
	s_nop 1
	v_addc_co_u32_e32 v193, vcc, 0, v3, vcc
	s_waitcnt vmcnt(0)
	global_store_dwordx4 v[2:3], v[148:151], off sc1
	global_store_dwordx4 v[192:193], v[152:155], off offset:3072 sc1

;     __device__ __forceinline__ void operator()(const f32x4 (&acc)[2][2][4][2], const Unit& u, int wr, int wc, int fr, int fq) const {
;     ...
;                         if (l >= 2 && row < M) {
;                             if (row < MP) {
;                                 const int b = row / TP, t = row - b * TP;
;                                 if (t < 2) { g2 = (f32x4){0.f, 0.f, 0.f, 0.f}; if (t == 0) g1 = g2; }
;                                 if (t >= TP - 2) *(f32x4*)(cvp + ((size_t)b * 2 + (t - (TP - 2))) * DFF + f0) = cur;
.LBB0_1258:
	s_or_b64 exec, exec, s[68:69]
	s_movk_i32 s14, 0x80d
	v_cmp_lt_i32_e32 vcc, s14, v196
	s_and_saveexec_b64 s[68:69], vcc
	s_cbranch_execz .LBB0_1260
	v_ashrrev_i32_e32 v193, 31, v192
	v_add_u32_e32 v0, 0xfffff7f2, v196
	v_lshl_add_u64 v[2:3], v[192:193], 1, v[0:1]
	s_movk_i32 s14, 0x2c00
	v_mad_u64_u32 v[192:193], s[70:71], v2, s14, v[160:161]
	v_mad_i32_i24 v193, v3, s14, v193
	global_store_dwordx4 v[192:193], v[152:155], off sc1

; #define LAS __attribute__((address_space(3)))
;     __device__ __forceinline__ void operator()(const f32x4 (&acc)[2][2][4][2], const Unit& u, int wr, int wc, int fr, int fq) const {
;     ...
;                         const int l = 128 * ai + 64 * wr + 16 * m + frL, row = 254 * u.pm - 2 + l;
;                         const float rs = rt[l];
;                         const f32x4 cur = acc[ai][1][m][n] * rs, uu = acc[ai][0][m][n] * rs;
;                         if (m == 0) {
;                             const int B = 2 * ai + wr;
;                             prev = (f32x4){0.f, 0.f, 0.f, 0.f};
;                             if (B > 0 && frL >= 14) prev = *(const LAS f32x4*)(halo + ((B - 1) * 2 + (frL - 14)) * 128 + fl + 4 * n);
;                         }
;                         f32x4 g1, g2;
;                         {
;                             const float c1x = dpp_ror1(cur.x), c1y = dpp_ror1(cur.y), c1z = dpp_ror1(cur.z), c1w = dpp_ror1(cur.w);
;                             const float p1x = dpp_ror1(prev.x), p1y = dpp_ror1(prev.y), p1z = dpp_ror1(prev.z), p1w = dpp_ror1(prev.w);
;                             const float c2x = dpp_ror2(cur.x), c2y = dpp_ror2(cur.y), c2z = dpp_ror2(cur.z), c2w = dpp_ror2(cur.w);
;                             const float p2x = dpp_ror2(prev.x), p2y = dpp_ror2(prev.y), p2z = dpp_ror2(prev.z), p2w = dpp_ror2(prev.w);
;                             const bool s1 = frL >= 1, s2 = frL >= 2;
;                             g1.x = s1 ? c1x : p1x; g1.y = s1 ? c1y : p1y; g1.z = s1 ? c1z : p1z; g1.w = s1 ? c1w : p1w;
;                             g2.x = s2 ? c2x : p2x; g2.y = s2 ? c2y : p2y; g2.z = s2 ? c2z : p2z; g2.w = s2 ? c2w : p2w;
;                         }
;                         if (l >= 2 && row < M) {
;                             if (row < MP) {
;                                 const int b = row / TP, t = row - b * TP;
;                                 if (t < 2) { g2 = (f32x4){0.f, 0.f, 0.f, 0.f}; if (t == 0) g1 = g2; }
;                                 if (t >= TP - 2) *(f32x4*)(cvp + ((size_t)b * 2 + (t - (TP - 2))) * DFF + f0) = cur;
;                             } else {
;                                 const int s = row - MP;
;                                 const float* c0 = cst + ((size_t)s * 2 + 0) * DFF + f0;
;                                 g2 = *(const f32x4*)c0; g1 = *(const f32x4*)(c0 + DFF);
.LBB0_1262:
	s_or_b64 exec, exec, s[0:1]
	ds_read_b32 v192, v209 offset:640
	s_add_i32 s0, s21, 0x9e
	v_add_u32_e32 v156, 0xa0, v211
	v_add_u32_e32 v218, s0, v211
	s_movk_i32 s0, 0x4100
	s_waitcnt lgkmcnt(0)
	v_mov_b32_e32 v193, v192
	v_pk_mul_f32 v[150:151], v[34:35], v[192:193] op_sel_hi:[1,0]
	v_pk_mul_f32 v[148:149], v[32:33], v[192:193] op_sel_hi:[1,0]
	v_mov_b32_e32 v0, v1
	v_mov_b32_e32 v2, v1
	v_mov_b32_e32 v3, v1
	v_mov_b32_e32 v196, v1
	v_mov_b32_e32 v197, v1
	v_mov_b32_e32 v204, v1
	v_mov_b32_e32 v205, v1
	v_mov_b32_e32 v239, v1
	v_mov_b32_e32 v219, v1
	v_mov_b32_e32 v240, v1
	v_mov_b32_e32 v241, v1
	v_mov_b32_e32 v242, v1
	v_mov_b32_e32 v243, v1
	v_mov_b32_e32 v244, v1
	v_mov_b32_e32 v245, v1
	v_mov_b32_e32 v246, v1
	v_cmp_lt_i32_e32 vcc, 1, v156
	v_cmp_gt_i32_e64 s[0:1], s0, v218
	v_mov_b32_dpp v0, v148 row_ror:1 row_mask:0xf bank_mask:0xf
	v_mov_b32_dpp v2, v149 row_ror:1 row_mask:0xf bank_mask:0xf
	v_mov_b32_dpp v3, v150 row_ror:1 row_mask:0xf bank_mask:0xf
	v_mov_b32_dpp v196, v151 row_ror:1 row_mask:0xf bank_mask:0xf
	v_mov_b32_dpp v197, v152 row_ror:1 row_mask:0xf bank_mask:0xf
	v_mov_b32_dpp v204, v153 row_ror:1 row_mask:0xf bank_mask:0xf
	v_mov_b32_dpp v205, v154 row_ror:1 row_mask:0xf bank_mask:0xf
	v_mov_b32_dpp v239, v155 row_ror:1 row_mask:0xf bank_mask:0xf
	v_mov_b32_dpp v219, v148 row_ror:2 row_mask:0xf bank_mask:0xf
	v_mov_b32_dpp v240, v149 row_ror:2 row_mask:0xf bank_mask:0xf
	v_mov_b32_dpp v241, v150 row_ror:2 row_mask:0xf bank_mask:0xf
	v_mov_b32_dpp v242, v151 row_ror:2 row_mask:0xf bank_mask:0xf
	v_mov_b32_dpp v243, v152 row_ror:2 row_mask:0xf bank_mask:0xf
	v_mov_b32_dpp v244, v153 row_ror:2 row_mask:0xf bank_mask:0xf
	v_mov_b32_dpp v245, v154 row_ror:2 row_mask:0xf bank_mask:0xf
	v_mov_b32_dpp v246, v155 row_ror:2 row_mask:0xf bank_mask:0xf
	s_and_b64 s[66:67], vcc, s[0:1]
	s_and_saveexec_b64 s[0:1], s[66:67]
	s_cbranch_execz .LBB0_1274
	s_movk_i32 s14, 0x407f
	v_cmp_lt_i32_e32 vcc, s14, v218
	s_and_saveexec_b64 s[68:69], vcc
	s_xor_b64 s[68:69], exec, s[68:69]
	s_cbranch_execz .LBB0_1265
	v_add_u32_e32 v0, 0xffffbf80, v218
	s_movk_i32 s14, 0x5800
	v_mad_u64_u32 v[2:3], s[70:71], v0, s14, v[164:165]
	v_add_co_u32_e32 v152, vcc, 0x2000, v2
	s_nop 1
	v_addc_co_u32_e32 v153, vcc, 0, v3, vcc
	global_load_dwordx4 v[152:155], v[152:153], off offset:3072
	s_nop 0
	global_load_dwordx4 v[156:159], v[2:3], off
	v_mad_u64_u32 v[2:3], s[70:71], v0, s14, v[162:163]
	v_add_co_u32_e32 v196, vcc, 0x2000, v2
	s_nop 1
	v_addc_co_u32_e32 v197, vcc, 0, v3, vcc
	s_waitcnt vmcnt(0)
	global_store_dwordx4 v[2:3], v[152:155], off sc1
	global_store_dwordx4 v[196:197], v[148:151], off offset:3072 sc1

;     __device__ __forceinline__ void operator()(const f32x4 (&acc)[2][2][4][2], const Unit& u, int wr, int wc, int fr, int fq) const {
;     ...
;                         if (l >= 2 && row < M) {
;                             if (row < MP) {
;                                 const int b = row / TP, t = row - b * TP;
;                                 if (t < 2) { g2 = (f32x4){0.f, 0.f, 0.f, 0.f}; if (t == 0) g1 = g2; }
;                                 if (t >= TP - 2) *(f32x4*)(cvp + ((size_t)b * 2 + (t - (TP - 2))) * DFF + f0) = cur;
.LBB0_1270:
	s_or_b64 exec, exec, s[70:71]
	s_movk_i32 s14, 0x80d
	v_cmp_lt_i32_e32 vcc, s14, v204
	s_and_saveexec_b64 s[70:71], vcc
	s_cbranch_execz .LBB0_1272
	v_ashrrev_i32_e32 v197, 31, v196
	v_add_u32_e32 v0, 0xfffff7f2, v204
	v_lshl_add_u64 v[2:3], v[196:197], 1, v[0:1]
	s_movk_i32 s14, 0x2c00
	v_mad_u64_u32 v[196:197], s[72:73], v2, s14, v[160:161]
	v_mad_i32_i24 v197, v3, s14, v197
	global_store_dwordx4 v[196:197], v[148:151], off sc1

; #define LAS __attribute__((address_space(3)))
;     __device__ __forceinline__ void operator()(const f32x4 (&acc)[2][2][4][2], const Unit& u, int wr, int wc, int fr, int fq) const {
;     ...
;                         const int l = 128 * ai + 64 * wr + 16 * m + frL, row = 254 * u.pm - 2 + l;
;                         const float rs = rt[l];
;                         const f32x4 cur = acc[ai][1][m][n] * rs, uu = acc[ai][0][m][n] * rs;
;                         if (m == 0) {
;                             const int B = 2 * ai + wr;
;                             prev = (f32x4){0.f, 0.f, 0.f, 0.f};
;                             if (B > 0 && frL >= 14) prev = *(const LAS f32x4*)(halo + ((B - 1) * 2 + (frL - 14)) * 128 + fl + 4 * n);
;                         }
;                         f32x4 g1, g2;
;                         {
;                             const float c1x = dpp_ror1(cur.x), c1y = dpp_ror1(cur.y), c1z = dpp_ror1(cur.z), c1w = dpp_ror1(cur.w);
;                             const float p1x = dpp_ror1(prev.x), p1y = dpp_ror1(prev.y), p1z = dpp_ror1(prev.z), p1w = dpp_ror1(prev.w);
;                             const float c2x = dpp_ror2(cur.x), c2y = dpp_ror2(cur.y), c2z = dpp_ror2(cur.z), c2w = dpp_ror2(cur.w);
;                             const float p2x = dpp_ror2(prev.x), p2y = dpp_ror2(prev.y), p2z = dpp_ror2(prev.z), p2w = dpp_ror2(prev.w);
;                             const bool s1 = frL >= 1, s2 = frL >= 2;
;                             g1.x = s1 ? c1x : p1x; g1.y = s1 ? c1y : p1y; g1.z = s1 ? c1z : p1z; g1.w = s1 ? c1w : p1w;
;                             g2.x = s2 ? c2x : p2x; g2.y = s2 ? c2y : p2y; g2.z = s2 ? c2z : p2z; g2.w = s2 ? c2w : p2w;
;                         }
;                         if (l >= 2 && row < M) {
;                             if (row < MP) {
;                                 const int b = row / TP, t = row - b * TP;
;                                 if (t < 2) { g2 = (f32x4){0.f, 0.f, 0.f, 0.f}; if (t == 0) g1 = g2; }
;                                 if (t >= TP - 2) *(f32x4*)(cvp + ((size_t)b * 2 + (t - (TP - 2))) * DFF + f0) = cur;
;                             } else {
;                                 const int s = row - MP;
;                                 const float* c0 = cst + ((size_t)s * 2 + 0) * DFF + f0;
;                                 g2 = *(const f32x4*)c0; g1 = *(const f32x4*)(c0 + DFF);
.LBB0_1274:
	s_or_b64 exec, exec, s[0:1]
	ds_read_b32 v196, v209 offset:704
	s_add_i32 s0, s21, 0xae
	v_add_u32_e32 v156, 0xb0, v211
	v_add_u32_e32 v219, s0, v211
	s_movk_i32 s0, 0x4100
	s_waitcnt lgkmcnt(0)
	v_mov_b32_e32 v197, v196
	v_pk_mul_f32 v[154:155], v[18:19], v[196:197] op_sel_hi:[1,0]
	v_pk_mul_f32 v[152:153], v[16:17], v[196:197] op_sel_hi:[1,0]
	v_mov_b32_e32 v0, v1
	v_mov_b32_e32 v2, v1
	v_mov_b32_e32 v3, v1
	v_mov_b32_e32 v204, v1
	v_mov_b32_e32 v205, v1
	v_mov_b32_e32 v239, v1
	v_mov_b32_e32 v240, v1
	v_mov_b32_e32 v242, v1
	v_mov_b32_e32 v241, v1
	v_mov_b32_e32 v243, v1
	v_mov_b32_e32 v244, v1
	v_mov_b32_e32 v245, v1
	v_mov_b32_e32 v246, v1
	v_mov_b32_e32 v247, v1
	v_mov_b32_e32 v248, v1
	v_mov_b32_e32 v249, v1
	v_cmp_lt_i32_e32 vcc, 1, v156
	v_cmp_gt_i32_e64 s[0:1], s0, v219
	v_mov_b32_dpp v0, v152 row_ror:1 row_mask:0xf bank_mask:0xf
	v_mov_b32_dpp v2, v153 row_ror:1 row_mask:0xf bank_mask:0xf
	v_mov_b32_dpp v3, v154 row_ror:1 row_mask:0xf bank_mask:0xf
	v_mov_b32_dpp v204, v155 row_ror:1 row_mask:0xf bank_mask:0xf
	v_mov_b32_dpp v205, v148 row_ror:1 row_mask:0xf bank_mask:0xf
	v_mov_b32_dpp v239, v149 row_ror:1 row_mask:0xf bank_mask:0xf
	v_mov_b32_dpp v240, v150 row_ror:1 row_mask:0xf bank_mask:0xf
	v_mov_b32_dpp v242, v151 row_ror:1 row_mask:0xf bank_mask:0xf
	v_mov_b32_dpp v241, v152 row_ror:2 row_mask:0xf bank_mask:0xf
	v_mov_b32_dpp v243, v153 row_ror:2 row_mask:0xf bank_mask:0xf
	v_mov_b32_dpp v244, v154 row_ror:2 row_mask:0xf bank_mask:0xf
	v_mov_b32_dpp v245, v155 row_ror:2 row_mask:0xf bank_mask:0xf
	v_mov_b32_dpp v246, v148 row_ror:2 row_mask:0xf bank_mask:0xf
	v_mov_b32_dpp v247, v149 row_ror:2 row_mask:0xf bank_mask:0xf
	v_mov_b32_dpp v248, v150 row_ror:2 row_mask:0xf bank_mask:0xf
	v_mov_b32_dpp v249, v151 row_ror:2 row_mask:0xf bank_mask:0xf
	s_and_b64 s[0:1], vcc, s[0:1]
	s_and_saveexec_b64 s[68:69], s[0:1]
	s_cbranch_execz .LBB0_1286
	s_movk_i32 s14, 0x407f
	v_cmp_lt_i32_e32 vcc, s14, v219
	s_and_saveexec_b64 s[70:71], vcc
	s_xor_b64 s[70:71], exec, s[70:71]
	s_cbranch_execz .LBB0_1277
	v_add_u32_e32 v0, 0xffffbf80, v219
	s_movk_i32 s14, 0x5800
	v_mad_u64_u32 v[2:3], s[72:73], v0, s14, v[164:165]
	v_add_co_u32_e32 v148, vcc, 0x2000, v2
	s_nop 1
	v_addc_co_u32_e32 v149, vcc, 0, v3, vcc
	global_load_dwordx4 v[148:151], v[148:149], off offset:3072
	s_nop 0
	global_load_dwordx4 v[156:159], v[2:3], off
	v_mad_u64_u32 v[2:3], s[72:73], v0, s14, v[162:163]
	v_add_co_u32_e32 v204, vcc, 0x2000, v2
	s_nop 1
	v_addc_co_u32_e32 v205, vcc, 0, v3, vcc
	s_waitcnt vmcnt(0)
	global_store_dwordx4 v[2:3], v[148:151], off sc1
	global_store_dwordx4 v[204:205], v[152:155], off offset:3072 sc1

;     __device__ __forceinline__ void operator()(const f32x4 (&acc)[2][2][4][2], const Unit& u, int wr, int wc, int fr, int fq) const {
;     ...
;                         if (l >= 2 && row < M) {
;                             if (row < MP) {
;                                 const int b = row / TP, t = row - b * TP;
;                                 if (t < 2) { g2 = (f32x4){0.f, 0.f, 0.f, 0.f}; if (t == 0) g1 = g2; }
;                                 if (t >= TP - 2) *(f32x4*)(cvp + ((size_t)b * 2 + (t - (TP - 2))) * DFF + f0) = cur;
.LBB0_1282:
	s_or_b64 exec, exec, s[72:73]
	s_movk_i32 s14, 0x80d
	v_cmp_lt_i32_e32 vcc, s14, v239
	s_and_saveexec_b64 s[72:73], vcc
	s_cbranch_execz .LBB0_1284
	v_ashrrev_i32_e32 v205, 31, v204
	v_add_u32_e32 v0, 0xfffff7f2, v239
	v_lshl_add_u64 v[2:3], v[204:205], 1, v[0:1]
	s_movk_i32 s14, 0x2c00
	v_mad_u64_u32 v[204:205], s[74:75], v2, s14, v[160:161]
	v_mad_i32_i24 v205, v3, s14, v205
	global_store_dwordx4 v[204:205], v[152:155], off sc1

; #define LAS __attribute__((address_space(3)))
;     __device__ __forceinline__ void operator()(const f32x4 (&acc)[2][2][4][2], const Unit& u, int wr, int wc, int fr, int fq) const {
;     ...
;             for (int n = 0; n < 2; ++n) {
;                 const int f0 = u.pn * 128 + fl + 4 * n;
;                 const f32x4 w0 = *(const f32x4*)(cw + f0), w1 = *(const f32x4*)(cw + DFF + f0), w2 = *(const f32x4*)(cw + 2 * DFF + f0), bb = *(const f32x4*)(cb + f0);
;                 f32x4 prev = (f32x4){0.f, 0.f, 0.f, 0.f};
; #pragma unroll
;                 for (int ai = 0; ai < 2; ++ai)
; #pragma unroll
;                     for (int m = 0; m < 4; ++m) {
;                         const int l = 128 * ai + 64 * wr + 16 * m + frL, row = 254 * u.pm - 2 + l;
;                         const float rs = rt[l];
;                         const f32x4 cur = acc[ai][1][m][n] * rs, uu = acc[ai][0][m][n] * rs;
;                         if (m == 0) {
;                             const int B = 2 * ai + wr;
;                             prev = (f32x4){0.f, 0.f, 0.f, 0.f};
;                             if (B > 0 && frL >= 14) prev = *(const LAS f32x4*)(halo + ((B - 1) * 2 + (frL - 14)) * 128 + fl + 4 * n);
;                         }
;                         f32x4 g1, g2;
;                         {
;                             const float c1x = dpp_ror1(cur.x), c1y = dpp_ror1(cur.y), c1z = dpp_ror1(cur.z), c1w = dpp_ror1(cur.w);
;                             const float p1x = dpp_ror1(prev.x), p1y = dpp_ror1(prev.y), p1z = dpp_ror1(prev.z), p1w = dpp_ror1(prev.w);
;                             const float c2x = dpp_ror2(cur.x), c2y = dpp_ror2(cur.y), c2z = dpp_ror2(cur.z), c2w = dpp_ror2(cur.w);
;                             const float p2x = dpp_ror2(prev.x), p2y = dpp_ror2(prev.y), p2z = dpp_ror2(prev.z), p2w = dpp_ror2(prev.w);
;                             const bool s1 = frL >= 1, s2 = frL >= 2;
;                             g1.x = s1 ? c1x : p1x; g1.y = s1 ? c1y : p1y; g1.z = s1 ? c1z : p1z; g1.w = s1 ? c1w : p1w;
;                             g2.x = s2 ? c2x : p2x; g2.y = s2 ? c2y : p2y; g2.z = s2 ? c2z : p2z; g2.w = s2 ? c2w : p2w;
;                         }
;                         if (l >= 2 && row < M) {
;                             if (row < MP) {
;                                 const int b = row / TP, t = row - b * TP;
.LBB0_1286:
	s_or_b64 exec, exec, s[68:69]
	v_or_b32_e32 v202, 4, v184
	v_ashrrev_i32_e32 v203, 31, v202
	v_lshlrev_b64 v[2:3], 2, v[202:203]
	s_waitcnt vmcnt(0)
	v_lshl_add_u64 v[132:133], s[44:45], 0, v[2:3]
	global_load_dwordx4 v[140:143], v[198:199], off offset:16
	v_lshl_add_u64 v[2:3], s[46:47], 0, v[2:3]
	global_load_dwordx4 v[136:139], v[132:133], off
	s_nop 0
	global_load_dwordx4 v[132:135], v[2:3], off
	global_load_dwordx4 v[144:147], v[200:201], off offset:16
	v_mov_b32_e32 v152, 0
	v_mov_b32_e32 v153, 0
	v_mov_b32_e32 v154, 0
	v_mov_b32_e32 v155, 0
	s_and_saveexec_b64 s[68:69], s[52:53]
	ds_read_b128 v[152:155], v220 offset:16
	s_or_b64 exec, exec, s[68:69]
	v_mov_b32_e32 v2, v166
	v_mov_b32_e32 v3, v166
	v_pk_mul_f32 v[150:151], v[122:123], v[2:3]
	v_pk_mul_f32 v[148:149], v[120:121], v[166:167]
	v_mov_b32_e32 v0, v1
	v_mov_b32_e32 v2, v1
	v_mov_b32_e32 v3, v1
	v_mov_b32_e32 v198, v1
	v_mov_b32_e32 v199, v1
	v_mov_b32_e32 v200, v1
	v_mov_b32_e32 v201, v1
	v_mov_b32_e32 v205, v1
	v_mov_b32_e32 v204, v1
	v_mov_b32_e32 v220, v1
	v_mov_b32_e32 v239, v1
	v_mov_b32_e32 v240, v1
	v_mov_b32_e32 v241, v1
	v_mov_b32_e32 v242, v1
	v_mov_b32_e32 v243, v1
	v_mov_b32_e32 v244, v1
	v_mov_b32_dpp v0, v148 row_ror:1 row_mask:0xf bank_mask:0xf
	v_mov_b32_dpp v2, v149 row_ror:1 row_mask:0xf bank_mask:0xf
	v_mov_b32_dpp v3, v150 row_ror:1 row_mask:0xf bank_mask:0xf
	v_mov_b32_dpp v198, v151 row_ror:1 row_mask:0xf bank_mask:0xf
	s_waitcnt lgkmcnt(0)
	v_mov_b32_dpp v199, v152 row_ror:1 row_mask:0xf bank_mask:0xf
	v_mov_b32_dpp v200, v153 row_ror:1 row_mask:0xf bank_mask:0xf
	v_mov_b32_dpp v201, v154 row_ror:1 row_mask:0xf bank_mask:0xf
	v_mov_b32_dpp v205, v155 row_ror:1 row_mask:0xf bank_mask:0xf
	v_mov_b32_dpp v204, v148 row_ror:2 row_mask:0xf bank_mask:0xf
	v_mov_b32_dpp v220, v149 row_ror:2 row_mask:0xf bank_mask:0xf
	v_mov_b32_dpp v239, v150 row_ror:2 row_mask:0xf bank_mask:0xf
	v_mov_b32_dpp v240, v151 row_ror:2 row_mask:0xf bank_mask:0xf
	v_mov_b32_dpp v241, v152 row_ror:2 row_mask:0xf bank_mask:0xf
	v_mov_b32_dpp v242, v153 row_ror:2 row_mask:0xf bank_mask:0xf
	v_mov_b32_dpp v243, v154 row_ror:2 row_mask:0xf bank_mask:0xf
	v_mov_b32_dpp v244, v155 row_ror:2 row_mask:0xf bank_mask:0xf
	s_and_saveexec_b64 s[52:53], s[54:55]
	s_cbranch_execz .LBB0_1300
	s_movk_i32 s14, 0x407f
	v_cmp_lt_i32_e32 vcc, s14, v185
	s_and_saveexec_b64 s[54:55], vcc
	s_xor_b64 s[54:55], exec, s[54:55]
	s_cbranch_execz .LBB0_1291
	v_add_u32_e32 v0, 0xffffbf80, v185
	s_movk_i32 s14, 0x5800
	v_mad_u64_u32 v[2:3], s[68:69], v0, s14, v[164:165]
	v_add_co_u32_e32 v152, vcc, 0x2000, v2
	s_nop 1
	v_addc_co_u32_e32 v153, vcc, 0, v3, vcc
	global_load_dwordx4 v[152:155], v[152:153], off offset:3088
	s_nop 0
	global_load_dwordx4 v[156:159], v[2:3], off offset:16
	v_mad_u64_u32 v[2:3], s[68:69], v0, s14, v[162:163]
	v_add_co_u32_e32 v198, vcc, 0x2000, v2
	s_nop 1
	v_addc_co_u32_e32 v199, vcc, 0, v3, vcc
	s_waitcnt vmcnt(1)
	global_store_dwordx4 v[2:3], v[152:155], off offset:16 sc1
	global_store_dwordx4 v[198:199], v[148:151], off offset:3088 sc1

;     __device__ __forceinline__ void operator()(const f32x4 (&acc)[2][2][4][2], const Unit& u, int wr, int wc, int fr, int fq) const {
;     ...
;                         if (l >= 2 && row < M) {
;                             if (row < MP) {
;                                 const int b = row / TP, t = row - b * TP;
;                                 if (t < 2) { g2 = (f32x4){0.f, 0.f, 0.f, 0.f}; if (t == 0) g1 = g2; }
;                                 if (t >= TP - 2) *(f32x4*)(cvp + ((size_t)b * 2 + (t - (TP - 2))) * DFF + f0) = cur;
.LBB0_1296:
	s_or_b64 exec, exec, s[68:69]
	s_movk_i32 s14, 0x80d
	v_cmp_lt_i32_e32 vcc, s14, v200
	s_and_saveexec_b64 s[68:69], vcc
	s_cbranch_execz .LBB0_1298
	v_ashrrev_i32_e32 v199, 31, v198
	v_add_u32_e32 v0, 0xfffff7f2, v200
	v_lshl_add_u64 v[2:3], v[198:199], 1, v[0:1]
	s_movk_i32 s14, 0x2c00
	v_mad_u64_u32 v[198:199], s[70:71], v2, s14, v[160:161]
	v_mad_i32_i24 v199, v3, s14, v199
	global_store_dwordx4 v[198:199], v[148:151], off offset:16 sc1

; #define LAS __attribute__((address_space(3)))
;     __device__ __forceinline__ void operator()(const f32x4 (&acc)[2][2][4][2], const Unit& u, int wr, int wc, int fr, int fq) const {
;     ...
;                         const int l = 128 * ai + 64 * wr + 16 * m + frL, row = 254 * u.pm - 2 + l;
;                         const float rs = rt[l];
;                         const f32x4 cur = acc[ai][1][m][n] * rs, uu = acc[ai][0][m][n] * rs;
;                         if (m == 0) {
;                             const int B = 2 * ai + wr;
;                             prev = (f32x4){0.f, 0.f, 0.f, 0.f};
;                             if (B > 0 && frL >= 14) prev = *(const LAS f32x4*)(halo + ((B - 1) * 2 + (frL - 14)) * 128 + fl + 4 * n);
;                         }
;                         f32x4 g1, g2;
;                         {
;                             const float c1x = dpp_ror1(cur.x), c1y = dpp_ror1(cur.y), c1z = dpp_ror1(cur.z), c1w = dpp_ror1(cur.w);
;                             const float p1x = dpp_ror1(prev.x), p1y = dpp_ror1(prev.y), p1z = dpp_ror1(prev.z), p1w = dpp_ror1(prev.w);
;                             const float c2x = dpp_ror2(cur.x), c2y = dpp_ror2(cur.y), c2z = dpp_ror2(cur.z), c2w = dpp_ror2(cur.w);
;                             const float p2x = dpp_ror2(prev.x), p2y = dpp_ror2(prev.y), p2z = dpp_ror2(prev.z), p2w = dpp_ror2(prev.w);
;                             const bool s1 = frL >= 1, s2 = frL >= 2;
;                             g1.x = s1 ? c1x : p1x; g1.y = s1 ? c1y : p1y; g1.z = s1 ? c1z : p1z; g1.w = s1 ? c1w : p1w;
;                             g2.x = s2 ? c2x : p2x; g2.y = s2 ? c2y : p2y; g2.z = s2 ? c2z : p2z; g2.w = s2 ? c2w : p2w;
;                         }
;                         if (l >= 2 && row < M) {
;                             if (row < MP) {
;                                 const int b = row / TP, t = row - b * TP;
;                                 if (t < 2) { g2 = (f32x4){0.f, 0.f, 0.f, 0.f}; if (t == 0) g1 = g2; }
;                                 if (t >= TP - 2) *(f32x4*)(cvp + ((size_t)b * 2 + (t - (TP - 2))) * DFF + f0) = cur;
;                             } else {
;                                 const int s = row - MP;
;                                 const float* c0 = cst + ((size_t)s * 2 + 0) * DFF + f0;
;                                 g2 = *(const f32x4*)c0; g1 = *(const f32x4*)(c0 + DFF);
.LBB0_1300:
	s_or_b64 exec, exec, s[52:53]
	v_mov_b32_e32 v2, v168
	v_mov_b32_e32 v3, v168
	v_pk_mul_f32 v[154:155], v[106:107], v[2:3]
	v_pk_mul_f32 v[152:153], v[104:105], v[168:169]
	v_mov_b32_e32 v0, v1
	v_mov_b32_e32 v2, v1
	v_mov_b32_e32 v3, v1
	v_mov_b32_e32 v166, v1
	v_mov_b32_e32 v167, v1
	v_mov_b32_e32 v185, v1
	v_mov_b32_e32 v198, v1
	v_mov_b32_e32 v200, v1
	v_mov_b32_e32 v199, v1
	v_mov_b32_e32 v201, v1
	v_mov_b32_e32 v204, v1
	v_mov_b32_e32 v205, v1
	v_mov_b32_e32 v220, v1
	v_mov_b32_e32 v239, v1
	v_mov_b32_e32 v240, v1
	v_mov_b32_e32 v241, v1
	v_mov_b32_dpp v0, v152 row_ror:1 row_mask:0xf bank_mask:0xf
	v_mov_b32_dpp v2, v153 row_ror:1 row_mask:0xf bank_mask:0xf
	v_mov_b32_dpp v3, v154 row_ror:1 row_mask:0xf bank_mask:0xf
	v_mov_b32_dpp v166, v155 row_ror:1 row_mask:0xf bank_mask:0xf
	v_mov_b32_dpp v167, v148 row_ror:1 row_mask:0xf bank_mask:0xf
	v_mov_b32_dpp v185, v149 row_ror:1 row_mask:0xf bank_mask:0xf
	v_mov_b32_dpp v198, v150 row_ror:1 row_mask:0xf bank_mask:0xf
	v_mov_b32_dpp v200, v151 row_ror:1 row_mask:0xf bank_mask:0xf
	v_mov_b32_dpp v199, v152 row_ror:2 row_mask:0xf bank_mask:0xf
	v_mov_b32_dpp v201, v153 row_ror:2 row_mask:0xf bank_mask:0xf
	v_mov_b32_dpp v204, v154 row_ror:2 row_mask:0xf bank_mask:0xf
	v_mov_b32_dpp v205, v155 row_ror:2 row_mask:0xf bank_mask:0xf
	v_mov_b32_dpp v220, v148 row_ror:2 row_mask:0xf bank_mask:0xf
	v_mov_b32_dpp v239, v149 row_ror:2 row_mask:0xf bank_mask:0xf
	v_mov_b32_dpp v240, v150 row_ror:2 row_mask:0xf bank_mask:0xf
	v_mov_b32_dpp v241, v151 row_ror:2 row_mask:0xf bank_mask:0xf
	s_and_saveexec_b64 s[52:53], s[56:57]
	s_cbranch_execz .LBB0_1312
	s_movk_i32 s14, 0x407f
	v_cmp_lt_i32_e32 vcc, s14, v213
	s_and_saveexec_b64 s[54:55], vcc
	s_xor_b64 s[54:55], exec, s[54:55]
	s_cbranch_execz .LBB0_1303
	v_add_u32_e32 v0, 0xffffbf80, v213
	s_movk_i32 s14, 0x5800
	v_mad_u64_u32 v[2:3], s[56:57], v0, s14, v[164:165]
	v_add_co_u32_e32 v148, vcc, 0x2000, v2
	s_nop 1
	v_addc_co_u32_e32 v149, vcc, 0, v3, vcc
	global_load_dwordx4 v[148:151], v[148:149], off offset:3088
	s_nop 0
	global_load_dwordx4 v[156:159], v[2:3], off offset:16
	v_mad_u64_u32 v[2:3], s[56:57], v0, s14, v[162:163]
	v_add_co_u32_e32 v166, vcc, 0x2000, v2
	s_nop 1
	v_addc_co_u32_e32 v167, vcc, 0, v3, vcc
	s_waitcnt vmcnt(1)
	global_store_dwordx4 v[2:3], v[148:151], off offset:16 sc1
	global_store_dwordx4 v[166:167], v[152:155], off offset:3088 sc1

;     __device__ __forceinline__ void operator()(const f32x4 (&acc)[2][2][4][2], const Unit& u, int wr, int wc, int fr, int fq) const {
;     ...
;                         if (l >= 2 && row < M) {
;                             if (row < MP) {
;                                 const int b = row / TP, t = row - b * TP;
;                                 if (t < 2) { g2 = (f32x4){0.f, 0.f, 0.f, 0.f}; if (t == 0) g1 = g2; }
;                                 if (t >= TP - 2) *(f32x4*)(cvp + ((size_t)b * 2 + (t - (TP - 2))) * DFF + f0) = cur;
.LBB0_1308:
	s_or_b64 exec, exec, s[56:57]
	s_movk_i32 s14, 0x80d
	v_cmp_lt_i32_e32 vcc, s14, v185
	s_and_saveexec_b64 s[56:57], vcc
	s_cbranch_execz .LBB0_1310
	v_ashrrev_i32_e32 v167, 31, v166
	v_add_u32_e32 v0, 0xfffff7f2, v185
	v_lshl_add_u64 v[2:3], v[166:167], 1, v[0:1]
	s_movk_i32 s14, 0x2c00
	v_mad_u64_u32 v[166:167], s[68:69], v2, s14, v[160:161]
	v_mad_i32_i24 v167, v3, s14, v167
	global_store_dwordx4 v[166:167], v[152:155], off offset:16 sc1

; #define LAS __attribute__((address_space(3)))
;     __device__ __forceinline__ void operator()(const f32x4 (&acc)[2][2][4][2], const Unit& u, int wr, int wc, int fr, int fq) const {
;     ...
;                         const int l = 128 * ai + 64 * wr + 16 * m + frL, row = 254 * u.pm - 2 + l;
;                         const float rs = rt[l];
;                         const f32x4 cur = acc[ai][1][m][n] * rs, uu = acc[ai][0][m][n] * rs;
;                         if (m == 0) {
;                             const int B = 2 * ai + wr;
;                             prev = (f32x4){0.f, 0.f, 0.f, 0.f};
;                             if (B > 0 && frL >= 14) prev = *(const LAS f32x4*)(halo + ((B - 1) * 2 + (frL - 14)) * 128 + fl + 4 * n);
;                         }
;                         f32x4 g1, g2;
;                         {
;                             const float c1x = dpp_ror1(cur.x), c1y = dpp_ror1(cur.y), c1z = dpp_ror1(cur.z), c1w = dpp_ror1(cur.w);
;                             const float p1x = dpp_ror1(prev.x), p1y = dpp_ror1(prev.y), p1z = dpp_ror1(prev.z), p1w = dpp_ror1(prev.w);
;                             const float c2x = dpp_ror2(cur.x), c2y = dpp_ror2(cur.y), c2z = dpp_ror2(cur.z), c2w = dpp_ror2(cur.w);
;                             const float p2x = dpp_ror2(prev.x), p2y = dpp_ror2(prev.y), p2z = dpp_ror2(prev.z), p2w = dpp_ror2(prev.w);
;                             const bool s1 = frL >= 1, s2 = frL >= 2;
;                             g1.x = s1 ? c1x : p1x; g1.y = s1 ? c1y : p1y; g1.z = s1 ? c1z : p1z; g1.w = s1 ? c1w : p1w;
;                             g2.x = s2 ? c2x : p2x; g2.y = s2 ? c2y : p2y; g2.z = s2 ? c2z : p2z; g2.w = s2 ? c2w : p2w;
;                         }
;                         if (l >= 2 && row < M) {
;                             if (row < MP) {
;                                 const int b = row / TP, t = row - b * TP;
;                                 if (t < 2) { g2 = (f32x4){0.f, 0.f, 0.f, 0.f}; if (t == 0) g1 = g2; }
;                                 if (t >= TP - 2) *(f32x4*)(cvp + ((size_t)b * 2 + (t - (TP - 2))) * DFF + f0) = cur;
;                             } else {
;                                 const int s = row - MP;
;                                 const float* c0 = cst + ((size_t)s * 2 + 0) * DFF + f0;
;                                 g2 = *(const f32x4*)c0; g1 = *(const f32x4*)(c0 + DFF);
.LBB0_1312:
	s_or_b64 exec, exec, s[52:53]
	v_mov_b32_e32 v2, v186
	v_mov_b32_e32 v3, v186
	v_pk_mul_f32 v[150:151], v[90:91], v[2:3]
	v_pk_mul_f32 v[148:149], v[88:89], v[186:187]
	v_mov_b32_e32 v0, v1
	v_mov_b32_e32 v2, v1
	v_mov_b32_e32 v3, v1
	v_mov_b32_e32 v166, v1
	v_mov_b32_e32 v167, v1
	v_mov_b32_e32 v168, v1
	v_mov_b32_e32 v169, v1
	v_mov_b32_e32 v198, v1
	v_mov_b32_e32 v185, v1
	v_mov_b32_e32 v199, v1
	v_mov_b32_e32 v200, v1
	v_mov_b32_e32 v201, v1
	v_mov_b32_e32 v204, v1
	v_mov_b32_e32 v205, v1
	v_mov_b32_e32 v213, v1
	v_mov_b32_e32 v220, v1
	v_mov_b32_dpp v0, v148 row_ror:1 row_mask:0xf bank_mask:0xf
	v_mov_b32_dpp v2, v149 row_ror:1 row_mask:0xf bank_mask:0xf
	v_mov_b32_dpp v3, v150 row_ror:1 row_mask:0xf bank_mask:0xf
	v_mov_b32_dpp v166, v151 row_ror:1 row_mask:0xf bank_mask:0xf
	v_mov_b32_dpp v167, v152 row_ror:1 row_mask:0xf bank_mask:0xf
	v_mov_b32_dpp v168, v153 row_ror:1 row_mask:0xf bank_mask:0xf
	v_mov_b32_dpp v169, v154 row_ror:1 row_mask:0xf bank_mask:0xf
	v_mov_b32_dpp v198, v155 row_ror:1 row_mask:0xf bank_mask:0xf
	v_mov_b32_dpp v185, v148 row_ror:2 row_mask:0xf bank_mask:0xf
	v_mov_b32_dpp v199, v149 row_ror:2 row_mask:0xf bank_mask:0xf
	v_mov_b32_dpp v200, v150 row_ror:2 row_mask:0xf bank_mask:0xf
	v_mov_b32_dpp v201, v151 row_ror:2 row_mask:0xf bank_mask:0xf
	v_mov_b32_dpp v204, v152 row_ror:2 row_mask:0xf bank_mask:0xf
	v_mov_b32_dpp v205, v153 row_ror:2 row_mask:0xf bank_mask:0xf
	v_mov_b32_dpp v213, v154 row_ror:2 row_mask:0xf bank_mask:0xf
	v_mov_b32_dpp v220, v155 row_ror:2 row_mask:0xf bank_mask:0xf
	s_and_saveexec_b64 s[52:53], s[58:59]
	s_cbranch_execz .LBB0_1324
	s_movk_i32 s14, 0x407f
	v_cmp_lt_i32_e32 vcc, s14, v214
	s_and_saveexec_b64 s[54:55], vcc
	s_xor_b64 s[54:55], exec, s[54:55]
	s_cbranch_execz .LBB0_1315
	v_add_u32_e32 v0, 0xffffbf80, v214
	s_movk_i32 s14, 0x5800
	v_mad_u64_u32 v[2:3], s[56:57], v0, s14, v[164:165]
	v_add_co_u32_e32 v152, vcc, 0x2000, v2
	s_nop 1
	v_addc_co_u32_e32 v153, vcc, 0, v3, vcc
	global_load_dwordx4 v[152:155], v[152:153], off offset:3088
	s_nop 0
	global_load_dwordx4 v[156:159], v[2:3], off offset:16
	v_mad_u64_u32 v[2:3], s[56:57], v0, s14, v[162:163]
	v_add_co_u32_e32 v166, vcc, 0x2000, v2
	s_nop 1
	v_addc_co_u32_e32 v167, vcc, 0, v3, vcc
	s_waitcnt vmcnt(1)
	global_store_dwordx4 v[2:3], v[152:155], off offset:16 sc1
	global_store_dwordx4 v[166:167], v[148:151], off offset:3088 sc1

;     __device__ __forceinline__ void operator()(const f32x4 (&acc)[2][2][4][2], const Unit& u, int wr, int wc, int fr, int fq) const {
;     ...
;                         if (l >= 2 && row < M) {
;                             if (row < MP) {
;                                 const int b = row / TP, t = row - b * TP;
;                                 if (t < 2) { g2 = (f32x4){0.f, 0.f, 0.f, 0.f}; if (t == 0) g1 = g2; }
;                                 if (t >= TP - 2) *(f32x4*)(cvp + ((size_t)b * 2 + (t - (TP - 2))) * DFF + f0) = cur;
.LBB0_1320:
	s_or_b64 exec, exec, s[56:57]
	s_movk_i32 s14, 0x80d
	v_cmp_lt_i32_e32 vcc, s14, v168
	s_and_saveexec_b64 s[56:57], vcc
	s_cbranch_execz .LBB0_1322
	v_ashrrev_i32_e32 v167, 31, v166
	v_add_u32_e32 v0, 0xfffff7f2, v168
	v_lshl_add_u64 v[2:3], v[166:167], 1, v[0:1]
	s_movk_i32 s14, 0x2c00
	v_mad_u64_u32 v[166:167], s[58:59], v2, s14, v[160:161]
	v_mad_i32_i24 v167, v3, s14, v167
	global_store_dwordx4 v[166:167], v[148:151], off offset:16 sc1

; #define LAS __attribute__((address_space(3)))
;     __device__ __forceinline__ void operator()(const f32x4 (&acc)[2][2][4][2], const Unit& u, int wr, int wc, int fr, int fq) const {
;     ...
;                         const int l = 128 * ai + 64 * wr + 16 * m + frL, row = 254 * u.pm - 2 + l;
;                         const float rs = rt[l];
;                         const f32x4 cur = acc[ai][1][m][n] * rs, uu = acc[ai][0][m][n] * rs;
;                         if (m == 0) {
;                             const int B = 2 * ai + wr;
;                             prev = (f32x4){0.f, 0.f, 0.f, 0.f};
;                             if (B > 0 && frL >= 14) prev = *(const LAS f32x4*)(halo + ((B - 1) * 2 + (frL - 14)) * 128 + fl + 4 * n);
;                         }
;                         f32x4 g1, g2;
;                         {
;                             const float c1x = dpp_ror1(cur.x), c1y = dpp_ror1(cur.y), c1z = dpp_ror1(cur.z), c1w = dpp_ror1(cur.w);
;                             const float p1x = dpp_ror1(prev.x), p1y = dpp_ror1(prev.y), p1z = dpp_ror1(prev.z), p1w = dpp_ror1(prev.w);
;                             const float c2x = dpp_ror2(cur.x), c2y = dpp_ror2(cur.y), c2z = dpp_ror2(cur.z), c2w = dpp_ror2(cur.w);
;                             const float p2x = dpp_ror2(prev.x), p2y = dpp_ror2(prev.y), p2z = dpp_ror2(prev.z), p2w = dpp_ror2(prev.w);
;                             const bool s1 = frL >= 1, s2 = frL >= 2;
;                             g1.x = s1 ? c1x : p1x; g1.y = s1 ? c1y : p1y; g1.z = s1 ? c1z : p1z; g1.w = s1 ? c1w : p1w;
;                             g2.x = s2 ? c2x : p2x; g2.y = s2 ? c2y : p2y; g2.z = s2 ? c2z : p2z; g2.w = s2 ? c2w : p2w;
;                         }
;                         if (l >= 2 && row < M) {
;                             if (row < MP) {
;                                 const int b = row / TP, t = row - b * TP;
;                                 if (t < 2) { g2 = (f32x4){0.f, 0.f, 0.f, 0.f}; if (t == 0) g1 = g2; }
;                                 if (t >= TP - 2) *(f32x4*)(cvp + ((size_t)b * 2 + (t - (TP - 2))) * DFF + f0) = cur;
;                             } else {
;                                 const int s = row - MP;
;                                 const float* c0 = cst + ((size_t)s * 2 + 0) * DFF + f0;
;                                 g2 = *(const f32x4*)c0; g1 = *(const f32x4*)(c0 + DFF);
.LBB0_1324:
	s_or_b64 exec, exec, s[52:53]
	v_mov_b32_e32 v2, v188
	v_mov_b32_e32 v3, v188
	v_pk_mul_f32 v[154:155], v[74:75], v[2:3]
	v_pk_mul_f32 v[152:153], v[72:73], v[188:189]
	v_mov_b32_e32 v0, v1
	v_mov_b32_e32 v2, v1
	v_mov_b32_e32 v3, v1
	v_mov_b32_e32 v166, v1
	v_mov_b32_e32 v167, v1
	v_mov_b32_e32 v168, v1
	v_mov_b32_e32 v169, v1
	v_mov_b32_e32 v186, v1
	v_mov_b32_e32 v185, v1
	v_mov_b32_e32 v187, v1
	v_mov_b32_e32 v198, v1
	v_mov_b32_e32 v199, v1
	v_mov_b32_e32 v200, v1
	v_mov_b32_e32 v201, v1
	v_mov_b32_e32 v204, v1
	v_mov_b32_e32 v205, v1
	v_mov_b32_dpp v0, v152 row_ror:1 row_mask:0xf bank_mask:0xf
	v_mov_b32_dpp v2, v153 row_ror:1 row_mask:0xf bank_mask:0xf
	v_mov_b32_dpp v3, v154 row_ror:1 row_mask:0xf bank_mask:0xf
	v_mov_b32_dpp v166, v155 row_ror:1 row_mask:0xf bank_mask:0xf
	v_mov_b32_dpp v167, v148 row_ror:1 row_mask:0xf bank_mask:0xf
	v_mov_b32_dpp v168, v149 row_ror:1 row_mask:0xf bank_mask:0xf
	v_mov_b32_dpp v169, v150 row_ror:1 row_mask:0xf bank_mask:0xf
	v_mov_b32_dpp v186, v151 row_ror:1 row_mask:0xf bank_mask:0xf
	v_mov_b32_dpp v185, v152 row_ror:2 row_mask:0xf bank_mask:0xf
	v_mov_b32_dpp v187, v153 row_ror:2 row_mask:0xf bank_mask:0xf
	v_mov_b32_dpp v198, v154 row_ror:2 row_mask:0xf bank_mask:0xf
	v_mov_b32_dpp v199, v155 row_ror:2 row_mask:0xf bank_mask:0xf
	v_mov_b32_dpp v200, v148 row_ror:2 row_mask:0xf bank_mask:0xf
	v_mov_b32_dpp v201, v149 row_ror:2 row_mask:0xf bank_mask:0xf
	v_mov_b32_dpp v204, v150 row_ror:2 row_mask:0xf bank_mask:0xf
	v_mov_b32_dpp v205, v151 row_ror:2 row_mask:0xf bank_mask:0xf
	s_and_saveexec_b64 s[52:53], s[60:61]
	s_cbranch_execz .LBB0_1336
	s_movk_i32 s14, 0x407f
	v_cmp_lt_i32_e32 vcc, s14, v215
	s_and_saveexec_b64 s[54:55], vcc
	s_xor_b64 s[54:55], exec, s[54:55]
	s_cbranch_execz .LBB0_1327
	v_add_u32_e32 v0, 0xffffbf80, v215
	s_movk_i32 s14, 0x5800
	v_mad_u64_u32 v[2:3], s[56:57], v0, s14, v[164:165]
	v_add_co_u32_e32 v148, vcc, 0x2000, v2
	s_nop 1
	v_addc_co_u32_e32 v149, vcc, 0, v3, vcc
	global_load_dwordx4 v[148:151], v[148:149], off offset:3088
	s_nop 0
	global_load_dwordx4 v[156:159], v[2:3], off offset:16
	v_mad_u64_u32 v[2:3], s[56:57], v0, s14, v[162:163]
	v_add_co_u32_e32 v166, vcc, 0x2000, v2
	s_nop 1
	v_addc_co_u32_e32 v167, vcc, 0, v3, vcc
	s_waitcnt vmcnt(1)
	global_store_dwordx4 v[2:3], v[148:151], off offset:16 sc1
	global_store_dwordx4 v[166:167], v[152:155], off offset:3088 sc1

;     __device__ __forceinline__ void operator()(const f32x4 (&acc)[2][2][4][2], const Unit& u, int wr, int wc, int fr, int fq) const {
;     ...
;                         if (l >= 2 && row < M) {
;                             if (row < MP) {
;                                 const int b = row / TP, t = row - b * TP;
;                                 if (t < 2) { g2 = (f32x4){0.f, 0.f, 0.f, 0.f}; if (t == 0) g1 = g2; }
;                                 if (t >= TP - 2) *(f32x4*)(cvp + ((size_t)b * 2 + (t - (TP - 2))) * DFF + f0) = cur;
.LBB0_1332:
	s_or_b64 exec, exec, s[56:57]
	s_movk_i32 s14, 0x80d
	v_cmp_lt_i32_e32 vcc, s14, v168
	s_and_saveexec_b64 s[56:57], vcc
	s_cbranch_execz .LBB0_1334
	v_ashrrev_i32_e32 v167, 31, v166
	v_add_u32_e32 v0, 0xfffff7f2, v168
	v_lshl_add_u64 v[2:3], v[166:167], 1, v[0:1]
	s_movk_i32 s14, 0x2c00
	v_mad_u64_u32 v[166:167], s[58:59], v2, s14, v[160:161]
	v_mad_i32_i24 v167, v3, s14, v167
	global_store_dwordx4 v[166:167], v[152:155], off offset:16 sc1

; #define LAS __attribute__((address_space(3)))
;     __device__ __forceinline__ void operator()(const f32x4 (&acc)[2][2][4][2], const Unit& u, int wr, int wc, int fr, int fq) const {
;     ...
;                         const int l = 128 * ai + 64 * wr + 16 * m + frL, row = 254 * u.pm - 2 + l;
;                         const float rs = rt[l];
;                         const f32x4 cur = acc[ai][1][m][n] * rs, uu = acc[ai][0][m][n] * rs;
;                         if (m == 0) {
;                             const int B = 2 * ai + wr;
;                             prev = (f32x4){0.f, 0.f, 0.f, 0.f};
;                             if (B > 0 && frL >= 14) prev = *(const LAS f32x4*)(halo + ((B - 1) * 2 + (frL - 14)) * 128 + fl + 4 * n);
;                         }
;                         f32x4 g1, g2;
;                         {
;                             const float c1x = dpp_ror1(cur.x), c1y = dpp_ror1(cur.y), c1z = dpp_ror1(cur.z), c1w = dpp_ror1(cur.w);
;                             const float p1x = dpp_ror1(prev.x), p1y = dpp_ror1(prev.y), p1z = dpp_ror1(prev.z), p1w = dpp_ror1(prev.w);
;                             const float c2x = dpp_ror2(cur.x), c2y = dpp_ror2(cur.y), c2z = dpp_ror2(cur.z), c2w = dpp_ror2(cur.w);
;                             const float p2x = dpp_ror2(prev.x), p2y = dpp_ror2(prev.y), p2z = dpp_ror2(prev.z), p2w = dpp_ror2(prev.w);
;                             const bool s1 = frL >= 1, s2 = frL >= 2;
;                             g1.x = s1 ? c1x : p1x; g1.y = s1 ? c1y : p1y; g1.z = s1 ? c1z : p1z; g1.w = s1 ? c1w : p1w;
;                             g2.x = s2 ? c2x : p2x; g2.y = s2 ? c2y : p2y; g2.z = s2 ? c2z : p2z; g2.w = s2 ? c2w : p2w;
;                         }
;                         if (l >= 2 && row < M) {
;                             if (row < MP) {
;                                 const int b = row / TP, t = row - b * TP;
;                                 if (t < 2) { g2 = (f32x4){0.f, 0.f, 0.f, 0.f}; if (t == 0) g1 = g2; }
;                                 if (t >= TP - 2) *(f32x4*)(cvp + ((size_t)b * 2 + (t - (TP - 2))) * DFF + f0) = cur;
;                             } else {
;                                 const int s = row - MP;
;                                 const float* c0 = cst + ((size_t)s * 2 + 0) * DFF + f0;
;                                 g2 = *(const f32x4*)c0; g1 = *(const f32x4*)(c0 + DFF);
.LBB0_1336:
	s_or_b64 exec, exec, s[52:53]
	v_mov_b32_e32 v152, 0
	v_mov_b32_e32 v153, 0
	v_mov_b32_e32 v154, 0
	v_mov_b32_e32 v155, 0
	s_and_saveexec_b64 s[52:53], s[10:11]
	ds_read_b128 v[152:155], v221 offset:16
	s_or_b64 exec, exec, s[52:53]
	v_mov_b32_e32 v2, v170
	v_mov_b32_e32 v3, v170
	v_pk_mul_f32 v[150:151], v[58:59], v[2:3]
	v_pk_mul_f32 v[148:149], v[56:57], v[170:171]
	v_mov_b32_e32 v0, v1
	v_mov_b32_e32 v2, v1
	v_mov_b32_e32 v3, v1
	v_mov_b32_e32 v166, v1
	v_mov_b32_e32 v167, v1
	v_mov_b32_e32 v168, v1
	v_mov_b32_e32 v169, v1
	v_mov_b32_e32 v186, v1
	v_mov_b32_e32 v185, v1
	v_mov_b32_e32 v187, v1
	v_mov_b32_e32 v188, v1
	v_mov_b32_e32 v189, v1
	v_mov_b32_e32 v198, v1
	v_mov_b32_e32 v199, v1
	v_mov_b32_e32 v200, v1
	v_mov_b32_e32 v201, v1
	v_mov_b32_dpp v0, v148 row_ror:1 row_mask:0xf bank_mask:0xf
	v_mov_b32_dpp v2, v149 row_ror:1 row_mask:0xf bank_mask:0xf
	v_mov_b32_dpp v3, v150 row_ror:1 row_mask:0xf bank_mask:0xf
	v_mov_b32_dpp v166, v151 row_ror:1 row_mask:0xf bank_mask:0xf
	s_waitcnt lgkmcnt(0)
	v_mov_b32_dpp v167, v152 row_ror:1 row_mask:0xf bank_mask:0xf
	v_mov_b32_dpp v168, v153 row_ror:1 row_mask:0xf bank_mask:0xf
	v_mov_b32_dpp v169, v154 row_ror:1 row_mask:0xf bank_mask:0xf
	v_mov_b32_dpp v186, v155 row_ror:1 row_mask:0xf bank_mask:0xf
	v_mov_b32_dpp v185, v148 row_ror:2 row_mask:0xf bank_mask:0xf
	v_mov_b32_dpp v187, v149 row_ror:2 row_mask:0xf bank_mask:0xf
	v_mov_b32_dpp v188, v150 row_ror:2 row_mask:0xf bank_mask:0xf
	v_mov_b32_dpp v189, v151 row_ror:2 row_mask:0xf bank_mask:0xf
	v_mov_b32_dpp v198, v152 row_ror:2 row_mask:0xf bank_mask:0xf
	v_mov_b32_dpp v199, v153 row_ror:2 row_mask:0xf bank_mask:0xf
	v_mov_b32_dpp v200, v154 row_ror:2 row_mask:0xf bank_mask:0xf
	v_mov_b32_dpp v201, v155 row_ror:2 row_mask:0xf bank_mask:0xf
	s_and_saveexec_b64 s[10:11], s[62:63]
	s_cbranch_execz .LBB0_1350
	s_movk_i32 s14, 0x407f
	v_cmp_lt_i32_e32 vcc, s14, v216
	s_and_saveexec_b64 s[52:53], vcc
	s_xor_b64 s[52:53], exec, s[52:53]
	s_cbranch_execz .LBB0_1341
	v_add_u32_e32 v0, 0xffffbf80, v216
	s_movk_i32 s14, 0x5800
	v_mad_u64_u32 v[2:3], s[54:55], v0, s14, v[164:165]
	v_add_co_u32_e32 v152, vcc, 0x2000, v2
	s_nop 1
	v_addc_co_u32_e32 v153, vcc, 0, v3, vcc
	global_load_dwordx4 v[152:155], v[152:153], off offset:3088
	s_nop 0
	global_load_dwordx4 v[156:159], v[2:3], off offset:16
	v_mad_u64_u32 v[2:3], s[54:55], v0, s14, v[162:163]
	v_add_co_u32_e32 v166, vcc, 0x2000, v2
	s_nop 1
	v_addc_co_u32_e32 v167, vcc, 0, v3, vcc
	s_waitcnt vmcnt(1)
	global_store_dwordx4 v[2:3], v[152:155], off offset:16 sc1
	global_store_dwordx4 v[166:167], v[148:151], off offset:3088 sc1

;     __device__ __forceinline__ void operator()(const f32x4 (&acc)[2][2][4][2], const Unit& u, int wr, int wc, int fr, int fq) const {
;     ...
;                         if (l >= 2 && row < M) {
;                             if (row < MP) {
;                                 const int b = row / TP, t = row - b * TP;
;                                 if (t < 2) { g2 = (f32x4){0.f, 0.f, 0.f, 0.f}; if (t == 0) g1 = g2; }
;                                 if (t >= TP - 2) *(f32x4*)(cvp + ((size_t)b * 2 + (t - (TP - 2))) * DFF + f0) = cur;
.LBB0_1346:
	s_or_b64 exec, exec, s[54:55]
	s_movk_i32 s14, 0x80d
	v_cmp_lt_i32_e32 vcc, s14, v168
	s_and_saveexec_b64 s[54:55], vcc
	s_cbranch_execz .LBB0_1348
	v_ashrrev_i32_e32 v167, 31, v166
	v_add_u32_e32 v0, 0xfffff7f2, v168
	v_lshl_add_u64 v[2:3], v[166:167], 1, v[0:1]
	s_movk_i32 s14, 0x2c00
	v_mad_u64_u32 v[166:167], s[56:57], v2, s14, v[160:161]
	v_mad_i32_i24 v167, v3, s14, v167
	global_store_dwordx4 v[166:167], v[148:151], off offset:16 sc1

; #define LAS __attribute__((address_space(3)))
;     __device__ __forceinline__ void operator()(const f32x4 (&acc)[2][2][4][2], const Unit& u, int wr, int wc, int fr, int fq) const {
;     ...
;                         const int l = 128 * ai + 64 * wr + 16 * m + frL, row = 254 * u.pm - 2 + l;
;                         const float rs = rt[l];
;                         const f32x4 cur = acc[ai][1][m][n] * rs, uu = acc[ai][0][m][n] * rs;
;                         if (m == 0) {
;                             const int B = 2 * ai + wr;
;                             prev = (f32x4){0.f, 0.f, 0.f, 0.f};
;                             if (B > 0 && frL >= 14) prev = *(const LAS f32x4*)(halo + ((B - 1) * 2 + (frL - 14)) * 128 + fl + 4 * n);
;                         }
;                         f32x4 g1, g2;
;                         {
;                             const float c1x = dpp_ror1(cur.x), c1y = dpp_ror1(cur.y), c1z = dpp_ror1(cur.z), c1w = dpp_ror1(cur.w);
;                             const float p1x = dpp_ror1(prev.x), p1y = dpp_ror1(prev.y), p1z = dpp_ror1(prev.z), p1w = dpp_ror1(prev.w);
;                             const float c2x = dpp_ror2(cur.x), c2y = dpp_ror2(cur.y), c2z = dpp_ror2(cur.z), c2w = dpp_ror2(cur.w);
;                             const float p2x = dpp_ror2(prev.x), p2y = dpp_ror2(prev.y), p2z = dpp_ror2(prev.z), p2w = dpp_ror2(prev.w);
;                             const bool s1 = frL >= 1, s2 = frL >= 2;
;                             g1.x = s1 ? c1x : p1x; g1.y = s1 ? c1y : p1y; g1.z = s1 ? c1z : p1z; g1.w = s1 ? c1w : p1w;
;                             g2.x = s2 ? c2x : p2x; g2.y = s2 ? c2y : p2y; g2.z = s2 ? c2z : p2z; g2.w = s2 ? c2w : p2w;
;                         }
;                         if (l >= 2 && row < M) {
;                             if (row < MP) {
;                                 const int b = row / TP, t = row - b * TP;
;                                 if (t < 2) { g2 = (f32x4){0.f, 0.f, 0.f, 0.f}; if (t == 0) g1 = g2; }
;                                 if (t >= TP - 2) *(f32x4*)(cvp + ((size_t)b * 2 + (t - (TP - 2))) * DFF + f0) = cur;
;                             } else {
;                                 const int s = row - MP;
;                                 const float* c0 = cst + ((size_t)s * 2 + 0) * DFF + f0;
;                                 g2 = *(const f32x4*)c0; g1 = *(const f32x4*)(c0 + DFF);
.LBB0_1350:
	s_or_b64 exec, exec, s[10:11]
	v_mov_b32_e32 v2, v190
	v_mov_b32_e32 v3, v190
	v_pk_mul_f32 v[154:155], v[42:43], v[2:3]
	v_pk_mul_f32 v[152:153], v[40:41], v[190:191]
	v_mov_b32_e32 v0, v1
	v_mov_b32_e32 v2, v1
	v_mov_b32_e32 v3, v1
	v_mov_b32_e32 v166, v1
	v_mov_b32_e32 v167, v1
	v_mov_b32_e32 v168, v1
	v_mov_b32_e32 v169, v1
	v_mov_b32_e32 v171, v1
	v_mov_b32_e32 v170, v1
	v_mov_b32_e32 v185, v1
	v_mov_b32_e32 v186, v1
	v_mov_b32_e32 v187, v1
	v_mov_b32_e32 v188, v1
	v_mov_b32_e32 v189, v1
	v_mov_b32_e32 v198, v1
	v_mov_b32_e32 v199, v1
	v_mov_b32_dpp v0, v152 row_ror:1 row_mask:0xf bank_mask:0xf
	v_mov_b32_dpp v2, v153 row_ror:1 row_mask:0xf bank_mask:0xf
	v_mov_b32_dpp v3, v154 row_ror:1 row_mask:0xf bank_mask:0xf
	v_mov_b32_dpp v166, v155 row_ror:1 row_mask:0xf bank_mask:0xf
	v_mov_b32_dpp v167, v148 row_ror:1 row_mask:0xf bank_mask:0xf
	v_mov_b32_dpp v168, v149 row_ror:1 row_mask:0xf bank_mask:0xf
	v_mov_b32_dpp v169, v150 row_ror:1 row_mask:0xf bank_mask:0xf
	v_mov_b32_dpp v171, v151 row_ror:1 row_mask:0xf bank_mask:0xf
	v_mov_b32_dpp v170, v152 row_ror:2 row_mask:0xf bank_mask:0xf
	v_mov_b32_dpp v185, v153 row_ror:2 row_mask:0xf bank_mask:0xf
	v_mov_b32_dpp v186, v154 row_ror:2 row_mask:0xf bank_mask:0xf
	v_mov_b32_dpp v187, v155 row_ror:2 row_mask:0xf bank_mask:0xf
	v_mov_b32_dpp v188, v148 row_ror:2 row_mask:0xf bank_mask:0xf
	v_mov_b32_dpp v189, v149 row_ror:2 row_mask:0xf bank_mask:0xf
	v_mov_b32_dpp v198, v150 row_ror:2 row_mask:0xf bank_mask:0xf
	v_mov_b32_dpp v199, v151 row_ror:2 row_mask:0xf bank_mask:0xf
	s_and_saveexec_b64 s[10:11], s[64:65]
	s_cbranch_execz .LBB0_1362
	s_movk_i32 s14, 0x407f
	v_cmp_lt_i32_e32 vcc, s14, v217
	s_and_saveexec_b64 s[52:53], vcc
	s_xor_b64 s[52:53], exec, s[52:53]
	s_cbranch_execz .LBB0_1353
	v_add_u32_e32 v0, 0xffffbf80, v217
	s_movk_i32 s14, 0x5800
	v_mad_u64_u32 v[2:3], s[54:55], v0, s14, v[164:165]
	v_add_co_u32_e32 v148, vcc, 0x2000, v2
	s_nop 1
	v_addc_co_u32_e32 v149, vcc, 0, v3, vcc
	global_load_dwordx4 v[148:151], v[148:149], off offset:3088
	s_nop 0
	global_load_dwordx4 v[156:159], v[2:3], off offset:16
	v_mad_u64_u32 v[2:3], s[54:55], v0, s14, v[162:163]
	v_add_co_u32_e32 v166, vcc, 0x2000, v2
	s_nop 1
	v_addc_co_u32_e32 v167, vcc, 0, v3, vcc
	s_waitcnt vmcnt(1)
	global_store_dwordx4 v[2:3], v[148:151], off offset:16 sc1
	global_store_dwordx4 v[166:167], v[152:155], off offset:3088 sc1

;     __device__ __forceinline__ void operator()(const f32x4 (&acc)[2][2][4][2], const Unit& u, int wr, int wc, int fr, int fq) const {
;     ...
;                         if (l >= 2 && row < M) {
;                             if (row < MP) {
;                                 const int b = row / TP, t = row - b * TP;
;                                 if (t < 2) { g2 = (f32x4){0.f, 0.f, 0.f, 0.f}; if (t == 0) g1 = g2; }
;                                 if (t >= TP - 2) *(f32x4*)(cvp + ((size_t)b * 2 + (t - (TP - 2))) * DFF + f0) = cur;
.LBB0_1358:
	s_or_b64 exec, exec, s[54:55]
	s_movk_i32 s14, 0x80d
	v_cmp_lt_i32_e32 vcc, s14, v168
	s_and_saveexec_b64 s[54:55], vcc
	s_cbranch_execz .LBB0_1360
	v_ashrrev_i32_e32 v167, 31, v166
	v_add_u32_e32 v0, 0xfffff7f2, v168
	v_lshl_add_u64 v[2:3], v[166:167], 1, v[0:1]
	s_movk_i32 s14, 0x2c00
	v_mad_u64_u32 v[166:167], s[56:57], v2, s14, v[160:161]
	v_mad_i32_i24 v167, v3, s14, v167
	global_store_dwordx4 v[166:167], v[152:155], off offset:16 sc1

; #define LAS __attribute__((address_space(3)))
;     __device__ __forceinline__ void operator()(const f32x4 (&acc)[2][2][4][2], const Unit& u, int wr, int wc, int fr, int fq) const {
;     ...
;                         const int l = 128 * ai + 64 * wr + 16 * m + frL, row = 254 * u.pm - 2 + l;
;                         const float rs = rt[l];
;                         const f32x4 cur = acc[ai][1][m][n] * rs, uu = acc[ai][0][m][n] * rs;
;                         if (m == 0) {
;                             const int B = 2 * ai + wr;
;                             prev = (f32x4){0.f, 0.f, 0.f, 0.f};
;                             if (B > 0 && frL >= 14) prev = *(const LAS f32x4*)(halo + ((B - 1) * 2 + (frL - 14)) * 128 + fl + 4 * n);
;                         }
;                         f32x4 g1, g2;
;                         {
;                             const float c1x = dpp_ror1(cur.x), c1y = dpp_ror1(cur.y), c1z = dpp_ror1(cur.z), c1w = dpp_ror1(cur.w);
;                             const float p1x = dpp_ror1(prev.x), p1y = dpp_ror1(prev.y), p1z = dpp_ror1(prev.z), p1w = dpp_ror1(prev.w);
;                             const float c2x = dpp_ror2(cur.x), c2y = dpp_ror2(cur.y), c2z = dpp_ror2(cur.z), c2w = dpp_ror2(cur.w);
;                             const float p2x = dpp_ror2(prev.x), p2y = dpp_ror2(prev.y), p2z = dpp_ror2(prev.z), p2w = dpp_ror2(prev.w);
;                             const bool s1 = frL >= 1, s2 = frL >= 2;
;                             g1.x = s1 ? c1x : p1x; g1.y = s1 ? c1y : p1y; g1.z = s1 ? c1z : p1z; g1.w = s1 ? c1w : p1w;
;                             g2.x = s2 ? c2x : p2x; g2.y = s2 ? c2y : p2y; g2.z = s2 ? c2z : p2z; g2.w = s2 ? c2w : p2w;
;                         }
;                         if (l >= 2 && row < M) {
;                             if (row < MP) {
;                                 const int b = row / TP, t = row - b * TP;
;                                 if (t < 2) { g2 = (f32x4){0.f, 0.f, 0.f, 0.f}; if (t == 0) g1 = g2; }
;                                 if (t >= TP - 2) *(f32x4*)(cvp + ((size_t)b * 2 + (t - (TP - 2))) * DFF + f0) = cur;
;                             } else {
;                                 const int s = row - MP;
;                                 const float* c0 = cst + ((size_t)s * 2 + 0) * DFF + f0;
;                                 g2 = *(const f32x4*)c0; g1 = *(const f32x4*)(c0 + DFF);
.LBB0_1362:
	s_or_b64 exec, exec, s[10:11]
	v_mov_b32_e32 v2, v192
	v_mov_b32_e32 v3, v192
	v_pk_mul_f32 v[150:151], v[26:27], v[2:3]
	v_pk_mul_f32 v[148:149], v[24:25], v[192:193]
	v_mov_b32_e32 v0, v1
	v_mov_b32_e32 v2, v1
	v_mov_b32_e32 v3, v1
	v_mov_b32_e32 v166, v1
	v_mov_b32_e32 v167, v1
	v_mov_b32_e32 v168, v1
	v_mov_b32_e32 v169, v1
	v_mov_b32_e32 v171, v1
	v_mov_b32_e32 v170, v1
	v_mov_b32_e32 v185, v1
	v_mov_b32_e32 v186, v1
	v_mov_b32_e32 v187, v1
	v_mov_b32_e32 v188, v1
	v_mov_b32_e32 v189, v1
	v_mov_b32_e32 v190, v1
	v_mov_b32_e32 v191, v1
	v_mov_b32_dpp v0, v148 row_ror:1 row_mask:0xf bank_mask:0xf
	v_mov_b32_dpp v2, v149 row_ror:1 row_mask:0xf bank_mask:0xf
	v_mov_b32_dpp v3, v150 row_ror:1 row_mask:0xf bank_mask:0xf
	v_mov_b32_dpp v166, v151 row_ror:1 row_mask:0xf bank_mask:0xf
	v_mov_b32_dpp v167, v152 row_ror:1 row_mask:0xf bank_mask:0xf
	v_mov_b32_dpp v168, v153 row_ror:1 row_mask:0xf bank_mask:0xf
	v_mov_b32_dpp v169, v154 row_ror:1 row_mask:0xf bank_mask:0xf
	v_mov_b32_dpp v171, v155 row_ror:1 row_mask:0xf bank_mask:0xf
	v_mov_b32_dpp v170, v148 row_ror:2 row_mask:0xf bank_mask:0xf
	v_mov_b32_dpp v185, v149 row_ror:2 row_mask:0xf bank_mask:0xf
	v_mov_b32_dpp v186, v150 row_ror:2 row_mask:0xf bank_mask:0xf
	v_mov_b32_dpp v187, v151 row_ror:2 row_mask:0xf bank_mask:0xf
	v_mov_b32_dpp v188, v152 row_ror:2 row_mask:0xf bank_mask:0xf
	v_mov_b32_dpp v189, v153 row_ror:2 row_mask:0xf bank_mask:0xf
	v_mov_b32_dpp v190, v154 row_ror:2 row_mask:0xf bank_mask:0xf
	v_mov_b32_dpp v191, v155 row_ror:2 row_mask:0xf bank_mask:0xf
	s_and_saveexec_b64 s[10:11], s[66:67]
	s_cbranch_execz .LBB0_1374
	s_movk_i32 s14, 0x407f
	v_cmp_lt_i32_e32 vcc, s14, v218
	s_and_saveexec_b64 s[52:53], vcc
	s_xor_b64 s[52:53], exec, s[52:53]
	s_cbranch_execz .LBB0_1365
	v_add_u32_e32 v0, 0xffffbf80, v218
	s_movk_i32 s14, 0x5800
	v_mad_u64_u32 v[2:3], s[54:55], v0, s14, v[164:165]
	v_add_co_u32_e32 v152, vcc, 0x2000, v2
	s_nop 1
	v_addc_co_u32_e32 v153, vcc, 0, v3, vcc
	global_load_dwordx4 v[152:155], v[152:153], off offset:3088
	s_nop 0
	global_load_dwordx4 v[156:159], v[2:3], off offset:16
	v_mad_u64_u32 v[2:3], s[54:55], v0, s14, v[162:163]
	v_add_co_u32_e32 v166, vcc, 0x2000, v2
	s_nop 1
	v_addc_co_u32_e32 v167, vcc, 0, v3, vcc
	s_waitcnt vmcnt(1)
	global_store_dwordx4 v[2:3], v[152:155], off offset:16 sc1
	global_store_dwordx4 v[166:167], v[148:151], off offset:3088 sc1

; #define LAS __attribute__((address_space(3)))
;     __device__ __forceinline__ void operator()(const f32x4 (&acc)[2][2][4][2], const Unit& u, int wr, int wc, int fr, int fq) const {
;     ...
;                         const int l = 128 * ai + 64 * wr + 16 * m + frL, row = 254 * u.pm - 2 + l;
;                         const float rs = rt[l];
;                         const f32x4 cur = acc[ai][1][m][n] * rs, uu = acc[ai][0][m][n] * rs;
;                         if (m == 0) {
;                             const int B = 2 * ai + wr;
;                             prev = (f32x4){0.f, 0.f, 0.f, 0.f};
;                             if (B > 0 && frL >= 14) prev = *(const LAS f32x4*)(halo + ((B - 1) * 2 + (frL - 14)) * 128 + fl + 4 * n);
;                         }
;                         f32x4 g1, g2;
;                         {
;                             const float c1x = dpp_ror1(cur.x), c1y = dpp_ror1(cur.y), c1z = dpp_ror1(cur.z), c1w = dpp_ror1(cur.w);
;                             const float p1x = dpp_ror1(prev.x), p1y = dpp_ror1(prev.y), p1z = dpp_ror1(prev.z), p1w = dpp_ror1(prev.w);
;                             const float c2x = dpp_ror2(cur.x), c2y = dpp_ror2(cur.y), c2z = dpp_ror2(cur.z), c2w = dpp_ror2(cur.w);
;                             const float p2x = dpp_ror2(prev.x), p2y = dpp_ror2(prev.y), p2z = dpp_ror2(prev.z), p2w = dpp_ror2(prev.w);
;                             const bool s1 = frL >= 1, s2 = frL >= 2;
;                             g1.x = s1 ? c1x : p1x; g1.y = s1 ? c1y : p1y; g1.z = s1 ? c1z : p1z; g1.w = s1 ? c1w : p1w;
;                             g2.x = s2 ? c2x : p2x; g2.y = s2 ? c2y : p2y; g2.z = s2 ? c2z : p2z; g2.w = s2 ? c2w : p2w;
;                         }
;                         if (l >= 2 && row < M) {
;                             if (row < MP) {
;                                 const int b = row / TP, t = row - b * TP;
;                                 if (t < 2) { g2 = (f32x4){0.f, 0.f, 0.f, 0.f}; if (t == 0) g1 = g2; }
;                                 if (t >= TP - 2) *(f32x4*)(cvp + ((size_t)b * 2 + (t - (TP - 2))) * DFF + f0) = cur;
;                             } else {
;                                 const int s = row - MP;
;                                 const float* c0 = cst + ((size_t)s * 2 + 0) * DFF + f0;
;                                 g2 = *(const f32x4*)c0; g1 = *(const f32x4*)(c0 + DFF);
.LBB0_1374:
	s_or_b64 exec, exec, s[10:11]
	v_mov_b32_e32 v2, v196
	v_mov_b32_e32 v3, v196
	v_pk_mul_f32 v[154:155], v[10:11], v[2:3]
	v_pk_mul_f32 v[152:153], v[8:9], v[196:197]
	v_mov_b32_e32 v0, v1
	v_mov_b32_e32 v2, v1
	v_mov_b32_e32 v3, v1
	v_mov_b32_e32 v166, v1
	v_mov_b32_e32 v167, v1
	v_mov_b32_e32 v168, v1
	v_mov_b32_e32 v169, v1
	v_mov_b32_e32 v171, v1
	v_mov_b32_e32 v170, v1
	v_mov_b32_e32 v185, v1
	v_mov_b32_e32 v186, v1
	v_mov_b32_e32 v187, v1
	v_mov_b32_e32 v188, v1
	v_mov_b32_e32 v189, v1
	v_mov_b32_e32 v190, v1
	v_mov_b32_e32 v191, v1
	v_mov_b32_dpp v0, v152 row_ror:1 row_mask:0xf bank_mask:0xf
	v_mov_b32_dpp v2, v153 row_ror:1 row_mask:0xf bank_mask:0xf
	v_mov_b32_dpp v3, v154 row_ror:1 row_mask:0xf bank_mask:0xf
	v_mov_b32_dpp v166, v155 row_ror:1 row_mask:0xf bank_mask:0xf
	v_mov_b32_dpp v167, v148 row_ror:1 row_mask:0xf bank_mask:0xf
	v_mov_b32_dpp v168, v149 row_ror:1 row_mask:0xf bank_mask:0xf
	v_mov_b32_dpp v169, v150 row_ror:1 row_mask:0xf bank_mask:0xf
	v_mov_b32_dpp v171, v151 row_ror:1 row_mask:0xf bank_mask:0xf
	v_mov_b32_dpp v170, v152 row_ror:2 row_mask:0xf bank_mask:0xf
	v_mov_b32_dpp v185, v153 row_ror:2 row_mask:0xf bank_mask:0xf
	v_mov_b32_dpp v186, v154 row_ror:2 row_mask:0xf bank_mask:0xf
	v_mov_b32_dpp v187, v155 row_ror:2 row_mask:0xf bank_mask:0xf
	v_mov_b32_dpp v188, v148 row_ror:2 row_mask:0xf bank_mask:0xf
	v_mov_b32_dpp v189, v149 row_ror:2 row_mask:0xf bank_mask:0xf
	v_mov_b32_dpp v190, v150 row_ror:2 row_mask:0xf bank_mask:0xf
	v_mov_b32_dpp v191, v151 row_ror:2 row_mask:0xf bank_mask:0xf
	s_and_saveexec_b64 s[10:11], s[0:1]
	s_cbranch_execz .LBB0_1386
	s_movk_i32 s0, 0x407f
	v_cmp_lt_i32_e32 vcc, s0, v219
	s_and_saveexec_b64 s[0:1], vcc
	s_xor_b64 s[0:1], exec, s[0:1]
	s_cbranch_execz .LBB0_1377
	v_add_u32_e32 v0, 0xffffbf80, v219
	s_movk_i32 s14, 0x5800
	v_mad_u64_u32 v[2:3], s[52:53], v0, s14, v[164:165]
	v_add_co_u32_e32 v148, vcc, 0x2000, v2
	s_nop 1
	v_addc_co_u32_e32 v149, vcc, 0, v3, vcc
	global_load_dwordx4 v[148:151], v[148:149], off offset:3088
	s_nop 0
	global_load_dwordx4 v[156:159], v[2:3], off offset:16
	v_mad_u64_u32 v[2:3], s[52:53], v0, s14, v[162:163]
	v_add_co_u32_e32 v160, vcc, 0x2000, v2
	s_nop 1
	v_addc_co_u32_e32 v161, vcc, 0, v3, vcc
	s_waitcnt vmcnt(1)
	global_store_dwordx4 v[2:3], v[148:151], off offset:16 sc1
	global_store_dwordx4 v[160:161], v[152:155], off offset:3088 sc1

;     __device__ __forceinline__ void operator()(const f32x4 (&acc)[2][2][4][2], const Unit& u, int wr, int wc, int fr, int fq) const {
;     ...
;                         if (l >= 2 && row < M) {
;                             if (row < MP) {
;                                 const int b = row / TP, t = row - b * TP;
;                                 if (t < 2) { g2 = (f32x4){0.f, 0.f, 0.f, 0.f}; if (t == 0) g1 = g2; }
;                                 if (t >= TP - 2) *(f32x4*)(cvp + ((size_t)b * 2 + (t - (TP - 2))) * DFF + f0) = cur;
.LBB0_1382:
	s_or_b64 exec, exec, s[6:7]
	s_movk_i32 s6, 0x80d
	v_cmp_lt_i32_e32 vcc, s6, v164
	s_and_saveexec_b64 s[6:7], vcc
	s_cbranch_execz .LBB0_1384
	v_ashrrev_i32_e32 v163, 31, v162
	v_add_u32_e32 v0, 0xfffff7f2, v164
	v_lshl_add_u64 v[2:3], v[162:163], 1, v[0:1]
	s_movk_i32 s14, 0x2c00
	v_mad_u64_u32 v[160:161], s[8:9], v2, s14, v[160:161]
	v_mad_i32_i24 v161, v3, s14, v161
	global_store_dwordx4 v[160:161], v[152:155], off offset:16 sc1

; #define LAS __attribute__((address_space(3)))
;     __device__ __forceinline__ void operator()(const f32x4 (&acc)[2][2][4][2], const Unit& u, int wr, int wc, int fr, int fq) const {
;     ...
;             if (plain) {
;                 const bool k15 = frL == 15, k14 = frL >= 14;
;                 const int f00 = u.pn * 128 + fl;
;                 const f32x4 Wa0 = *(const f32x4*)(cw + f00), Wa1 = *(const f32x4*)(cw + DFF + f00), Wa2 = *(const f32x4*)(cw + 2 * DFF + f00), Wab = *(const f32x4*)(cb + f00);
;                 const f32x4 Wb0 = *(const f32x4*)(cw + f00 + 4), Wb1 = *(const f32x4*)(cw + DFF + f00 + 4), Wb2 = *(const f32x4*)(cw + 2 * DFF + f00 + 4), Wbb = *(const f32x4*)(cb + f00 + 4);
;                 const unsigned ob = (unsigned)((R0 + 64 * wr + frL) * DFF + f00) * 2u;
;                 f32x4 prevA = (f32x4){0.f, 0.f, 0.f, 0.f}, prevB = prevA;
; #pragma unroll
;                 for (int ai = 0; ai < 2; ++ai)
; #pragma unroll
;                     for (int m = 0; m < 4; ++m) {
;                         const int l = 128 * ai + 64 * wr + 16 * m + frL;
;                         const float rs = rt[l];
;                         if (m == 0) {
;                             const int B = 2 * ai + wr;
;                             prevA = (f32x4){0.f, 0.f, 0.f, 0.f}; prevB = prevA;
;                             if (B > 0 && frL >= 14) { const LAS float* hp = halo + ((B - 1) * 2 + (frL - 14)) * 128 + fl; prevA = *(const LAS f32x4*)hp; prevB = *(const LAS f32x4*)(hp + 4); }
;                         }
;                         unsigned wv[4];
; #pragma unroll
;                         for (int n = 0; n < 2; ++n) {
;                             const f32x4 w0 = n ? Wb0 : Wa0, w1 = n ? Wb1 : Wa1, w2 = n ? Wb2 : Wa2, bb = n ? Wbb : Wab;
;                             const f32x4 cur = acc[ai][1][m][n] * rs, uu = acc[ai][0][m][n] * rs, prev = n ? prevB : prevA;
;                             float ov[4];
; #pragma unroll
;                             for (int e = 0; e < 4; ++e) {
;                                 const float ce = cur[e], pe = prev[e];
;                                 const float g1 = dpp_mv<0x121>(k15 ? pe : ce), g2 = dpp_mv<0x122>(k14 ? pe : ce);
;                                 const float cv = fmaf(w0[e], g2, fmaf(w1[e], g1, fmaf(w2[e], ce, bb[e])));
;                                 ov[e] = siluf_(cv) * uu[e];
;                             }
.LBB0_1391:
	s_or_b64 exec, exec, s[0:1]
	v_readlane_b32 s0, v255, 12
	s_add_i32 s0, s0, s21
	v_cmp_eq_u32_e64 s[6:7], 15, v212
	v_add_u32_e32 v2, s0, v212
	s_movk_i32 s0, 0xb00
	v_mul_lo_u32 v2, v2, s0
	s_waitcnt lgkmcnt(0)
	v_pk_mul_f32 v[128:129], v[128:129], v[0:1] op_sel_hi:[1,0]
	v_add_lshl_u32 v184, v184, v2, 1
	v_pk_mul_f32 v[2:3], v[130:131], v[0:1] op_sel_hi:[1,0]
	v_cndmask_b32_e64 v130, v128, v168, s[6:7]
	v_cndmask_b32_e32 v131, v168, v128, vcc
	s_waitcnt vmcnt(0)
	v_fma_f32 v168, v160, v128, v148
	v_mov_b32_dpp v130, v130 row_ror:1 row_mask:0xf bank_mask:0xf bound_ctrl:1
	v_mov_b32_dpp v131, v131 row_ror:2 row_mask:0xf bank_mask:0xf bound_ctrl:1
	v_fmac_f32_e32 v168, v156, v130
	v_fmac_f32_e32 v168, v152, v131
	v_mul_f32_e32 v130, 0xbfb8aa3b, v168
	v_exp_f32_e32 v130, v130
	v_mul_f32_e32 v124, v124, v0
	v_cndmask_b32_e32 v131, v169, v129, vcc
	v_mul_f32_e32 v125, v125, v0
	v_add_f32_e32 v130, 1.0, v130
	v_rcp_f32_e32 v130, v130
	v_mov_b32_dpp v131, v131 row_ror:2 row_mask:0xf bank_mask:0xf bound_ctrl:1
	v_mul_f32_e32 v126, v126, v0
	v_mul_f32_e32 v127, v127, v0
	v_mul_f32_e32 v130, v168, v130
	v_mul_f32_e32 v124, v124, v130
	v_cndmask_b32_e64 v130, v129, v169, s[6:7]
	v_fma_f32 v168, v161, v129, v149
	v_pk_mul_f32 v[120:121], v[120:121], v[0:1] op_sel_hi:[1,0]
	v_mov_b32_dpp v130, v130 row_ror:1 row_mask:0xf bank_mask:0xf bound_ctrl:1
	v_fmac_f32_e32 v168, v157, v130
	v_fmac_f32_e32 v168, v153, v131
	v_mul_f32_e32 v130, 0xbfb8aa3b, v168
	v_exp_f32_e32 v130, v130
	v_cndmask_b32_e32 v131, v170, v2, vcc
	v_mul_f32_e32 v116, v116, v0
	v_pk_mul_f32 v[122:123], v[122:123], v[0:1] op_sel_hi:[1,0]
	v_add_f32_e32 v130, 1.0, v130
	v_rcp_f32_e32 v130, v130
	v_mov_b32_dpp v131, v131 row_ror:2 row_mask:0xf bank_mask:0xf bound_ctrl:1
	v_mul_f32_e32 v117, v117, v0
	v_mul_f32_e32 v118, v118, v0
	v_mul_f32_e32 v130, v168, v130
	v_mul_f32_e32 v125, v125, v130
	v_cndmask_b32_e64 v130, v2, v170, s[6:7]
	v_fma_f32 v168, v162, v2, v150
	v_cvt_pk_bf16_f32 v124, v124, v125
	v_mul_f32_e32 v0, v119, v0
	v_mov_b32_dpp v130, v130 row_ror:1 row_mask:0xf bank_mask:0xf bound_ctrl:1
	v_fmac_f32_e32 v168, v158, v130
	v_fmac_f32_e32 v168, v154, v131
	v_mul_f32_e32 v130, 0xbfb8aa3b, v168
	v_exp_f32_e32 v130, v130
	v_cndmask_b32_e32 v131, v171, v3, vcc
	v_cmp_lt_i32_e64 s[0:1], 1, v211
	v_add_f32_e32 v130, 1.0, v130
	v_rcp_f32_e32 v130, v130
	v_mov_b32_dpp v131, v131 row_ror:2 row_mask:0xf bank_mask:0xf bound_ctrl:1
	v_mul_f32_e32 v130, v168, v130
	v_mul_f32_e32 v126, v126, v130
	v_cndmask_b32_e64 v130, v3, v171, s[6:7]
	v_fma_f32 v168, v163, v3, v151
	s_nop 0
	v_mov_b32_dpp v130, v130 row_ror:1 row_mask:0xf bank_mask:0xf bound_ctrl:1
	v_fmac_f32_e32 v168, v159, v130
	v_fmac_f32_e32 v168, v155, v131
	v_mul_f32_e32 v130, 0xbfb8aa3b, v168
	v_exp_f32_e32 v130, v130
	s_nop 0
	v_add_f32_e32 v130, 1.0, v130
	v_rcp_f32_e32 v130, v130
	s_nop 0
	v_mul_f32_e32 v130, v168, v130
	v_mul_f32_e32 v127, v127, v130
	v_cvt_pk_bf16_f32 v125, v126, v127
	v_cndmask_b32_e64 v126, v120, v164, s[6:7]
	v_cndmask_b32_e32 v127, v164, v120, vcc
	v_fma_f32 v130, v144, v120, v132
	v_mov_b32_dpp v126, v126 row_ror:1 row_mask:0xf bank_mask:0xf bound_ctrl:1
	v_mov_b32_dpp v127, v127 row_ror:2 row_mask:0xf bank_mask:0xf bound_ctrl:1
	v_fmac_f32_e32 v130, v140, v126
	v_fmac_f32_e32 v130, v136, v127
	v_mul_f32_e32 v126, 0xbfb8aa3b, v130
	v_exp_f32_e32 v126, v126
	v_cndmask_b32_e32 v127, v165, v121, vcc
	v_add_f32_e32 v126, 1.0, v126
	v_rcp_f32_e32 v126, v126
	v_mov_b32_dpp v127, v127 row_ror:2 row_mask:0xf bank_mask:0xf bound_ctrl:1
	v_mul_f32_e32 v126, v130, v126
	v_mul_f32_e32 v116, v116, v126
	v_cndmask_b32_e64 v126, v121, v165, s[6:7]
	v_fma_f32 v130, v145, v121, v133
	s_nop 0
	v_mov_b32_dpp v126, v126 row_ror:1 row_mask:0xf bank_mask:0xf bound_ctrl:1
	v_fmac_f32_e32 v130, v141, v126
	v_fmac_f32_e32 v130, v137, v127
	v_mul_f32_e32 v126, 0xbfb8aa3b, v130
	v_exp_f32_e32 v126, v126
	v_cndmask_b32_e32 v127, v166, v122, vcc
	v_add_f32_e32 v126, 1.0, v126
	v_rcp_f32_e32 v126, v126
	v_mov_b32_dpp v127, v127 row_ror:2 row_mask:0xf bank_mask:0xf bound_ctrl:1
	v_mul_f32_e32 v126, v130, v126
	v_mul_f32_e32 v117, v117, v126
	v_cndmask_b32_e64 v126, v122, v166, s[6:7]
	v_fma_f32 v130, v146, v122, v134
	s_nop 0
	v_mov_b32_dpp v126, v126 row_ror:1 row_mask:0xf bank_mask:0xf bound_ctrl:1
	v_fmac_f32_e32 v130, v142, v126
	v_fmac_f32_e32 v130, v138, v127
	v_mul_f32_e32 v126, 0xbfb8aa3b, v130
	v_exp_f32_e32 v126, v126
	v_cndmask_b32_e32 v127, v167, v123, vcc
	v_add_f32_e32 v126, 1.0, v126
	v_rcp_f32_e32 v126, v126
	v_mov_b32_dpp v127, v127 row_ror:2 row_mask:0xf bank_mask:0xf bound_ctrl:1
	v_mul_f32_e32 v126, v130, v126
	v_mul_f32_e32 v118, v118, v126
	v_cndmask_b32_e64 v126, v123, v167, s[6:7]
	v_fma_f32 v130, v147, v123, v135
	s_nop 0
	v_mov_b32_dpp v126, v126 row_ror:1 row_mask:0xf bank_mask:0xf bound_ctrl:1
	v_fmac_f32_e32 v130, v143, v126
	v_fmac_f32_e32 v130, v139, v127
	v_mul_f32_e32 v126, 0xbfb8aa3b, v130
	v_exp_f32_e32 v126, v126
	s_nop 0
	v_add_f32_e32 v126, 1.0, v126
	v_rcp_f32_e32 v126, v126
	s_nop 0
	v_mul_f32_e32 v126, v130, v126
	v_mul_f32_e32 v0, v0, v126
	v_cvt_pk_bf16_f32 v126, v116, v117
	v_cvt_pk_bf16_f32 v127, v118, v0
	s_and_saveexec_b64 s[8:9], s[0:1]
	s_cbranch_execz .LBB0_1393
	v_readlane_b32 s0, v252, 8
	v_readlane_b32 s1, v252, 9
	s_nop 4
	global_store_dwordx4 v184, v[124:127], s[0:1] sc1
; #define LAS __attribute__((address_space(3)))
; __device__ __forceinline__ unsigned cvt_pk_bf16(float lo, float hi) { unsigned r; asm("v_cvt_pk_bf16_f32 %0, %1, %2" : "=v"(r) : "v"(lo), "v"(hi)); return r; }
;     __device__ __forceinline__ void operator()(const f32x4 (&acc)[2][2][4][2], const Unit& u, int wr, int wc, int fr, int fq) const {
;     ...
;                 for (int ai = 0; ai < 2; ++ai)
; #pragma unroll
;                     for (int m = 0; m < 4; ++m) {
;                         const int l = 128 * ai + 64 * wr + 16 * m + frL;
;                         const float rs = rt[l];
;                         if (m == 0) {
;                             const int B = 2 * ai + wr;
;                             prevA = (f32x4){0.f, 0.f, 0.f, 0.f}; prevB = prevA;
;                             if (B > 0 && frL >= 14) { const LAS float* hp = halo + ((B - 1) * 2 + (frL - 14)) * 128 + fl; prevA = *(const LAS f32x4*)hp; prevB = *(const LAS f32x4*)(hp + 4); }
;                         }
;                         unsigned wv[4];
; #pragma unroll
;                         for (int n = 0; n < 2; ++n) {
;                             const f32x4 w0 = n ? Wb0 : Wa0, w1 = n ? Wb1 : Wa1, w2 = n ? Wb2 : Wa2, bb = n ? Wbb : Wab;
;                             const f32x4 cur = acc[ai][1][m][n] * rs, uu = acc[ai][0][m][n] * rs, prev = n ? prevB : prevA;
;                             float ov[4];
; #pragma unroll
;                             for (int e = 0; e < 4; ++e) {
;                                 const float ce = cur[e], pe = prev[e];
;                                 const float g1 = dpp_mv<0x121>(k15 ? pe : ce), g2 = dpp_mv<0x122>(k14 ? pe : ce);
;                                 const float cv = fmaf(w0[e], g2, fmaf(w1[e], g1, fmaf(w2[e], ce, bb[e])));
;                                 ov[e] = siluf_(cv) * uu[e];
;                             }
;                             wv[2 * n] = cvt_pk_bf16(ov[0], ov[1]); wv[2 * n + 1] = cvt_pk_bf16(ov[2], ov[3]);
;                             if (n) prevB = cur; else prevA = cur;
;                         }
;                         if (ai > 0 || m > 0 || l >= 2) *(v4u*)((unsigned char*)ACT + (ob + (unsigned)((128 * ai + 16 * m) * DFF * 2))) = (v4u){wv[0], wv[1], wv[2], wv[3]};
;                         __builtin_amdgcn_sched_barrier(0);
;                     }
.LBB0_1393:
	s_or_b64 exec, exec, s[8:9]
	ds_read_b32 v116, v209 offset:64
	v_mov_b32_e32 v118, v108
	v_readlane_b32 s0, v252, 8
	v_readlane_b32 s1, v252, 9
	s_waitcnt lgkmcnt(0)
	v_pk_mul_f32 v[112:113], v[112:113], v[116:117] op_sel_hi:[1,0]
	s_nop 0
	v_cndmask_b32_e64 v0, v112, v128, s[6:7]
	v_pk_mul_f32 v[114:115], v[114:115], v[116:117] op_sel_hi:[1,0]
	v_cndmask_b32_e32 v117, v128, v112, vcc
	v_mov_b32_dpp v0, v0 row_ror:1 row_mask:0xf bank_mask:0xf bound_ctrl:1
	v_fma_f32 v119, v160, v112, v148
	v_mov_b32_dpp v117, v117 row_ror:2 row_mask:0xf bank_mask:0xf bound_ctrl:1
	v_fmac_f32_e32 v119, v156, v0
	v_fmac_f32_e32 v119, v152, v117
	v_mul_f32_e32 v0, 0xbfb8aa3b, v119
	v_exp_f32_e32 v0, v0
	v_cndmask_b32_e64 v108, v113, v129, s[6:7]
	v_add_f32_e32 v0, 1.0, v0
	v_rcp_f32_e32 v117, v0
	v_mov_b32_dpp v108, v108 row_ror:1 row_mask:0xf bank_mask:0xf bound_ctrl:1
	v_pk_mul_f32 v[118:119], v[118:119], v[116:117]
	s_nop 0
	v_mul_f32_e32 v0, v118, v119
	v_cndmask_b32_e32 v117, v129, v113, vcc
	v_fma_f32 v119, v161, v113, v149
	v_fmac_f32_e32 v119, v157, v108
	v_mov_b32_dpp v117, v117 row_ror:2 row_mask:0xf bank_mask:0xf bound_ctrl:1
	v_fmac_f32_e32 v119, v153, v117
	v_mul_f32_e32 v108, 0xbfb8aa3b, v119
	v_exp_f32_e32 v108, v108
	v_mov_b32_e32 v118, v109
	v_add_f32_e32 v108, 1.0, v108
	v_rcp_f32_e32 v117, v108
	s_nop 0
	v_pk_mul_f32 v[108:109], v[118:119], v[116:117]
	s_nop 0
	v_mul_f32_e32 v118, v108, v109
	v_cndmask_b32_e64 v108, v114, v2, s[6:7]
	v_cndmask_b32_e32 v2, v2, v114, vcc
	v_fma_f32 v109, v162, v114, v150
	v_mov_b32_dpp v108, v108 row_ror:1 row_mask:0xf bank_mask:0xf bound_ctrl:1
	v_mov_b32_dpp v2, v2 row_ror:2 row_mask:0xf bank_mask:0xf bound_ctrl:1
	v_fmac_f32_e32 v109, v158, v108
	v_fmac_f32_e32 v109, v154, v2
	v_mul_f32_e32 v2, 0xbfb8aa3b, v109
	v_exp_f32_e32 v2, v2
	v_mov_b32_e32 v108, v110
	v_add_f32_e32 v2, 1.0, v2
	v_rcp_f32_e32 v117, v2
	v_cndmask_b32_e64 v2, v115, v3, s[6:7]
	v_cndmask_b32_e32 v3, v3, v115, vcc
	v_pk_mul_f32 v[108:109], v[108:109], v[116:117]
	s_nop 0
	v_mul_f32_e32 v109, v108, v109
	v_mov_b32_dpp v2, v2 row_ror:1 row_mask:0xf bank_mask:0xf bound_ctrl:1
	v_mov_b32_dpp v108, v3 row_ror:2 row_mask:0xf bank_mask:0xf bound_ctrl:1
	v_fma_f32 v3, v163, v115, v151
	v_fmac_f32_e32 v3, v159, v2
	v_fmac_f32_e32 v3, v155, v108
	v_mul_f32_e32 v2, 0xbfb8aa3b, v3
	v_exp_f32_e32 v2, v2
	v_cvt_pk_bf16_f32 v108, v0, v118
	s_nop 0
	v_add_f32_e32 v2, 1.0, v2
	v_rcp_f32_e32 v117, v2
	v_mov_b32_e32 v2, v111
	v_pk_mul_f32 v[2:3], v[2:3], v[116:117]
	v_pk_mul_f32 v[104:105], v[104:105], v[116:117] op_sel_hi:[1,0]
	v_mul_f32_e32 v2, v2, v3
	v_cndmask_b32_e64 v0, v104, v120, s[6:7]
	v_cvt_pk_bf16_f32 v109, v109, v2
	v_pk_mul_f32 v[2:3], v[106:107], v[116:117] op_sel_hi:[1,0]
	v_cndmask_b32_e32 v106, v120, v104, vcc
	v_mov_b32_dpp v0, v0 row_ror:1 row_mask:0xf bank_mask:0xf bound_ctrl:1
	v_fma_f32 v107, v144, v104, v132
	v_mov_b32_dpp v106, v106 row_ror:2 row_mask:0xf bank_mask:0xf bound_ctrl:1
	v_fmac_f32_e32 v107, v140, v0
	v_fmac_f32_e32 v107, v136, v106
	v_mul_f32_e32 v0, 0xbfb8aa3b, v107
	v_exp_f32_e32 v0, v0
	v_mov_b32_e32 v106, v100
	v_cndmask_b32_e64 v100, v105, v121, s[6:7]
	v_add_f32_e32 v0, 1.0, v0
	v_rcp_f32_e32 v117, v0
	v_mov_b32_dpp v100, v100 row_ror:1 row_mask:0xf bank_mask:0xf bound_ctrl:1
	v_pk_mul_f32 v[106:107], v[106:107], v[116:117]
	s_nop 0
	v_mul_f32_e32 v0, v106, v107
	v_cndmask_b32_e32 v106, v121, v105, vcc
	v_fma_f32 v107, v145, v105, v133
	v_fmac_f32_e32 v107, v141, v100
	v_mov_b32_dpp v106, v106 row_ror:2 row_mask:0xf bank_mask:0xf bound_ctrl:1
	v_fmac_f32_e32 v107, v137, v106
	v_mul_f32_e32 v100, 0xbfb8aa3b, v107
	v_exp_f32_e32 v100, v100
	v_mov_b32_e32 v106, v101
	v_add_f32_e32 v100, 1.0, v100
	v_rcp_f32_e32 v117, v100
	s_nop 0
	v_pk_mul_f32 v[100:101], v[106:107], v[116:117]
	s_nop 0
	v_mul_f32_e32 v106, v100, v101
	v_cndmask_b32_e64 v100, v2, v122, s[6:7]
	v_cndmask_b32_e32 v101, v122, v2, vcc
	v_cvt_pk_bf16_f32 v110, v0, v106
	v_add_u32_e32 v0, 0x16000, v184
	v_mov_b32_dpp v100, v100 row_ror:1 row_mask:0xf bank_mask:0xf bound_ctrl:1
	v_mov_b32_dpp v107, v101 row_ror:2 row_mask:0xf bank_mask:0xf bound_ctrl:1
	v_fma_f32 v101, v146, v2, v134
	v_fmac_f32_e32 v101, v142, v100
	v_fmac_f32_e32 v101, v138, v107
	v_mul_f32_e32 v100, 0xbfb8aa3b, v101
	v_exp_f32_e32 v100, v100
	s_nop 0
	v_add_f32_e32 v100, 1.0, v100
	v_rcp_f32_e32 v117, v100
	v_mov_b32_e32 v100, v102
	v_pk_mul_f32 v[100:101], v[100:101], v[116:117]
	s_nop 0
	v_mul_f32_e32 v102, v100, v101
	v_cndmask_b32_e64 v100, v3, v123, s[6:7]
	v_cndmask_b32_e32 v101, v123, v3, vcc
	s_nop 0
	v_mov_b32_dpp v100, v100 row_ror:1 row_mask:0xf bank_mask:0xf bound_ctrl:1
	v_mov_b32_dpp v107, v101 row_ror:2 row_mask:0xf bank_mask:0xf bound_ctrl:1
	v_fma_f32 v101, v147, v3, v135
	v_fmac_f32_e32 v101, v143, v100
	v_fmac_f32_e32 v101, v139, v107
	v_mul_f32_e32 v100, 0xbfb8aa3b, v101
	v_exp_f32_e32 v100, v100
	s_nop 0
	v_add_f32_e32 v100, 1.0, v100
	v_rcp_f32_e32 v117, v100
	v_mov_b32_e32 v100, v103
	v_pk_mul_f32 v[100:101], v[100:101], v[116:117]
	s_nop 0
	v_mul_f32_e32 v100, v100, v101
	v_cvt_pk_bf16_f32 v111, v102, v100
	global_store_dwordx4 v0, v[108:111], s[0:1] sc1
	ds_read_b32 v100, v209 offset:128
	v_mov_b32_e32 v102, v92
	s_waitcnt lgkmcnt(0)
; #define LAS __attribute__((address_space(3)))
; __device__ __forceinline__ unsigned cvt_pk_bf16(float lo, float hi) { unsigned r; asm("v_cvt_pk_bf16_f32 %0, %1, %2" : "=v"(r) : "v"(lo), "v"(hi)); return r; }
;     __device__ __forceinline__ void operator()(const f32x4 (&acc)[2][2][4][2], const Unit& u, int wr, int wc, int fr, int fq) const {
;     ...
;                 for (int ai = 0; ai < 2; ++ai)
; #pragma unroll
;                     for (int m = 0; m < 4; ++m) {
;                         const int l = 128 * ai + 64 * wr + 16 * m + frL;
;                         const float rs = rt[l];
;                         if (m == 0) {
;                             const int B = 2 * ai + wr;
;                             prevA = (f32x4){0.f, 0.f, 0.f, 0.f}; prevB = prevA;
;                             if (B > 0 && frL >= 14) { const LAS float* hp = halo + ((B - 1) * 2 + (frL - 14)) * 128 + fl; prevA = *(const LAS f32x4*)hp; prevB = *(const LAS f32x4*)(hp + 4); }
;                         }
;                         unsigned wv[4];
; #pragma unroll
;                         for (int n = 0; n < 2; ++n) {
;                             const f32x4 w0 = n ? Wb0 : Wa0, w1 = n ? Wb1 : Wa1, w2 = n ? Wb2 : Wa2, bb = n ? Wbb : Wab;
;                             const f32x4 cur = acc[ai][1][m][n] * rs, uu = acc[ai][0][m][n] * rs, prev = n ? prevB : prevA;
;                             float ov[4];
; #pragma unroll
;                             for (int e = 0; e < 4; ++e) {
;                                 const float ce = cur[e], pe = prev[e];
;                                 const float g1 = dpp_mv<0x121>(k15 ? pe : ce), g2 = dpp_mv<0x122>(k14 ? pe : ce);
;                                 const float cv = fmaf(w0[e], g2, fmaf(w1[e], g1, fmaf(w2[e], ce, bb[e])));
;                                 ov[e] = siluf_(cv) * uu[e];
;                             }
;                             wv[2 * n] = cvt_pk_bf16(ov[0], ov[1]); wv[2 * n + 1] = cvt_pk_bf16(ov[2], ov[3]);
;                             if (n) prevB = cur; else prevA = cur;
;                         }
;                         if (ai > 0 || m > 0 || l >= 2) *(v4u*)((unsigned char*)ACT + (ob + (unsigned)((128 * ai + 16 * m) * DFF * 2))) = (v4u){wv[0], wv[1], wv[2], wv[3]};
;                         __builtin_amdgcn_sched_barrier(0);
;                     }
	v_pk_mul_f32 v[96:97], v[96:97], v[100:101] op_sel_hi:[1,0]
	s_nop 0
	v_cndmask_b32_e64 v0, v96, v112, s[6:7]
	v_pk_mul_f32 v[98:99], v[98:99], v[100:101] op_sel_hi:[1,0]
	v_cndmask_b32_e32 v101, v112, v96, vcc
	v_mov_b32_dpp v0, v0 row_ror:1 row_mask:0xf bank_mask:0xf bound_ctrl:1
	v_fma_f32 v103, v160, v96, v148
	v_mov_b32_dpp v101, v101 row_ror:2 row_mask:0xf bank_mask:0xf bound_ctrl:1
	v_fmac_f32_e32 v103, v156, v0
	v_fmac_f32_e32 v103, v152, v101
	v_mul_f32_e32 v0, 0xbfb8aa3b, v103
	v_exp_f32_e32 v0, v0
	v_cndmask_b32_e64 v92, v97, v113, s[6:7]
	v_add_f32_e32 v0, 1.0, v0
	v_rcp_f32_e32 v101, v0
	v_mov_b32_dpp v92, v92 row_ror:1 row_mask:0xf bank_mask:0xf bound_ctrl:1
	v_pk_mul_f32 v[102:103], v[102:103], v[100:101]
	s_nop 0
	v_mul_f32_e32 v0, v102, v103
	v_cndmask_b32_e32 v101, v113, v97, vcc
	v_fma_f32 v103, v161, v97, v149
	v_fmac_f32_e32 v103, v157, v92
	v_mov_b32_dpp v101, v101 row_ror:2 row_mask:0xf bank_mask:0xf bound_ctrl:1
	v_fmac_f32_e32 v103, v153, v101
	v_mul_f32_e32 v92, 0xbfb8aa3b, v103
	v_exp_f32_e32 v92, v92
	v_mov_b32_e32 v102, v93
	v_add_f32_e32 v92, 1.0, v92
	v_rcp_f32_e32 v101, v92
	s_nop 0
	v_pk_mul_f32 v[92:93], v[102:103], v[100:101]
	s_nop 0
	v_mul_f32_e32 v102, v92, v93
	v_cndmask_b32_e64 v92, v98, v114, s[6:7]
	v_cndmask_b32_e32 v93, v114, v98, vcc
	s_nop 0
	v_mov_b32_dpp v92, v92 row_ror:1 row_mask:0xf bank_mask:0xf bound_ctrl:1
	v_mov_b32_dpp v101, v93 row_ror:2 row_mask:0xf bank_mask:0xf bound_ctrl:1
	v_fma_f32 v93, v162, v98, v150
	v_fmac_f32_e32 v93, v158, v92
	v_fmac_f32_e32 v93, v154, v101
	v_mul_f32_e32 v92, 0xbfb8aa3b, v93
	v_exp_f32_e32 v92, v92
	s_nop 0
	v_add_f32_e32 v92, 1.0, v92
	v_rcp_f32_e32 v101, v92
	v_mov_b32_e32 v92, v94
	v_pk_mul_f32 v[92:93], v[92:93], v[100:101]
	s_nop 0
	v_mul_f32_e32 v94, v92, v93
	v_cndmask_b32_e64 v92, v99, v115, s[6:7]
	v_cndmask_b32_e32 v93, v115, v99, vcc
	s_nop 0
	v_mov_b32_dpp v92, v92 row_ror:1 row_mask:0xf bank_mask:0xf bound_ctrl:1
	v_mov_b32_dpp v101, v93 row_ror:2 row_mask:0xf bank_mask:0xf bound_ctrl:1
	v_fma_f32 v93, v163, v99, v151
	v_fmac_f32_e32 v93, v159, v92
	v_fmac_f32_e32 v93, v155, v101
	v_mul_f32_e32 v92, 0xbfb8aa3b, v93
	v_exp_f32_e32 v92, v92
	s_nop 0
	v_add_f32_e32 v92, 1.0, v92
	v_rcp_f32_e32 v101, v92
	v_mov_b32_e32 v92, v95
	v_pk_mul_f32 v[92:93], v[92:93], v[100:101]
	v_pk_mul_f32 v[88:89], v[88:89], v[100:101] op_sel_hi:[1,0]
	v_mul_f32_e32 v93, v92, v93
	v_cvt_pk_bf16_f32 v92, v0, v102
	v_cndmask_b32_e64 v0, v88, v104, s[6:7]
	v_cvt_pk_bf16_f32 v93, v94, v93
	v_cndmask_b32_e32 v94, v104, v88, vcc
	v_fma_f32 v95, v144, v88, v132
	v_mov_b32_dpp v0, v0 row_ror:1 row_mask:0xf bank_mask:0xf bound_ctrl:1
	v_mov_b32_dpp v94, v94 row_ror:2 row_mask:0xf bank_mask:0xf bound_ctrl:1
	v_fmac_f32_e32 v95, v140, v0
	v_fmac_f32_e32 v95, v136, v94
	v_mul_f32_e32 v0, 0xbfb8aa3b, v95
	v_exp_f32_e32 v0, v0
	v_pk_mul_f32 v[90:91], v[90:91], v[100:101] op_sel_hi:[1,0]
	v_mov_b32_e32 v94, v84
	v_cndmask_b32_e64 v84, v89, v105, s[6:7]
	v_add_f32_e32 v0, 1.0, v0
	v_rcp_f32_e32 v101, v0
	v_mov_b32_dpp v84, v84 row_ror:1 row_mask:0xf bank_mask:0xf bound_ctrl:1
	v_pk_mul_f32 v[94:95], v[94:95], v[100:101]
	s_nop 0
	v_mul_f32_e32 v0, v94, v95
	v_cndmask_b32_e32 v94, v105, v89, vcc
	v_fma_f32 v95, v145, v89, v133
	v_fmac_f32_e32 v95, v141, v84
	v_mov_b32_dpp v94, v94 row_ror:2 row_mask:0xf bank_mask:0xf bound_ctrl:1
	v_fmac_f32_e32 v95, v137, v94
	v_mul_f32_e32 v84, 0xbfb8aa3b, v95
	v_exp_f32_e32 v84, v84
	v_mov_b32_e32 v94, v85
	v_add_f32_e32 v84, 1.0, v84
	v_rcp_f32_e32 v101, v84
	s_nop 0
	v_pk_mul_f32 v[84:85], v[94:95], v[100:101]
	s_nop 0
	v_mul_f32_e32 v94, v84, v85
	v_cndmask_b32_e64 v84, v90, v2, s[6:7]
	v_cndmask_b32_e32 v2, v2, v90, vcc
	v_fma_f32 v85, v146, v90, v134
	v_mov_b32_dpp v84, v84 row_ror:1 row_mask:0xf bank_mask:0xf bound_ctrl:1
	v_mov_b32_dpp v2, v2 row_ror:2 row_mask:0xf bank_mask:0xf bound_ctrl:1
	v_fmac_f32_e32 v85, v142, v84
	v_fmac_f32_e32 v85, v138, v2
	v_mul_f32_e32 v2, 0xbfb8aa3b, v85
	v_exp_f32_e32 v2, v2
	v_mov_b32_e32 v84, v86
	v_cvt_pk_bf16_f32 v94, v0, v94
	v_add_u32_e32 v0, 0x2c000, v184
	v_add_f32_e32 v2, 1.0, v2
	v_rcp_f32_e32 v101, v2
	v_cndmask_b32_e64 v2, v91, v3, s[6:7]
	v_cndmask_b32_e32 v3, v3, v91, vcc
	v_pk_mul_f32 v[84:85], v[84:85], v[100:101]
	s_nop 0
	v_mul_f32_e32 v84, v84, v85
	v_mov_b32_dpp v2, v2 row_ror:1 row_mask:0xf bank_mask:0xf bound_ctrl:1
	v_mov_b32_dpp v85, v3 row_ror:2 row_mask:0xf bank_mask:0xf bound_ctrl:1
	v_fma_f32 v3, v147, v91, v135
	v_fmac_f32_e32 v3, v143, v2
	v_fmac_f32_e32 v3, v139, v85
	v_mul_f32_e32 v2, 0xbfb8aa3b, v3
	v_exp_f32_e32 v2, v2
	s_nop 0
	v_add_f32_e32 v2, 1.0, v2
	v_rcp_f32_e32 v101, v2
	v_mov_b32_e32 v2, v87
	v_pk_mul_f32 v[2:3], v[2:3], v[100:101]
	s_nop 0
	v_mul_f32_e32 v2, v2, v3
	v_cvt_pk_bf16_f32 v95, v84, v2
	global_store_dwordx4 v0, v[92:95], s[0:1] sc1
	ds_read_b32 v2, v209 offset:192
	v_mov_b32_e32 v86, v78
	s_waitcnt lgkmcnt(0)
; #define LAS __attribute__((address_space(3)))
; __device__ __forceinline__ unsigned cvt_pk_bf16(float lo, float hi) { unsigned r; asm("v_cvt_pk_bf16_f32 %0, %1, %2" : "=v"(r) : "v"(lo), "v"(hi)); return r; }
;     __device__ __forceinline__ void operator()(const f32x4 (&acc)[2][2][4][2], const Unit& u, int wr, int wc, int fr, int fq) const {
;     ...
;                 for (int ai = 0; ai < 2; ++ai)
; #pragma unroll
;                     for (int m = 0; m < 4; ++m) {
;                         const int l = 128 * ai + 64 * wr + 16 * m + frL;
;                         const float rs = rt[l];
;                         if (m == 0) {
;                             const int B = 2 * ai + wr;
;                             prevA = (f32x4){0.f, 0.f, 0.f, 0.f}; prevB = prevA;
;                             if (B > 0 && frL >= 14) { const LAS float* hp = halo + ((B - 1) * 2 + (frL - 14)) * 128 + fl; prevA = *(const LAS f32x4*)hp; prevB = *(const LAS f32x4*)(hp + 4); }
;                         }
;                         unsigned wv[4];
; #pragma unroll
;                         for (int n = 0; n < 2; ++n) {
;                             const f32x4 w0 = n ? Wb0 : Wa0, w1 = n ? Wb1 : Wa1, w2 = n ? Wb2 : Wa2, bb = n ? Wbb : Wab;
;                             const f32x4 cur = acc[ai][1][m][n] * rs, uu = acc[ai][0][m][n] * rs, prev = n ? prevB : prevA;
;                             float ov[4];
; #pragma unroll
;                             for (int e = 0; e < 4; ++e) {
;                                 const float ce = cur[e], pe = prev[e];
;                                 const float g1 = dpp_mv<0x121>(k15 ? pe : ce), g2 = dpp_mv<0x122>(k14 ? pe : ce);
;                                 const float cv = fmaf(w0[e], g2, fmaf(w1[e], g1, fmaf(w2[e], ce, bb[e])));
;                                 ov[e] = siluf_(cv) * uu[e];
;                             }
;                             wv[2 * n] = cvt_pk_bf16(ov[0], ov[1]); wv[2 * n + 1] = cvt_pk_bf16(ov[2], ov[3]);
;                             if (n) prevB = cur; else prevA = cur;
;                         }
;                         if (ai > 0 || m > 0 || l >= 2) *(v4u*)((unsigned char*)ACT + (ob + (unsigned)((128 * ai + 16 * m) * DFF * 2))) = (v4u){wv[0], wv[1], wv[2], wv[3]};
;                         __builtin_amdgcn_sched_barrier(0);
;                     }
	v_pk_mul_f32 v[80:81], v[80:81], v[2:3] op_sel_hi:[1,0]
	s_nop 0
	v_cndmask_b32_e64 v0, v80, v96, s[6:7]
	v_pk_mul_f32 v[82:83], v[82:83], v[2:3] op_sel_hi:[1,0]
	v_cndmask_b32_e32 v3, v96, v80, vcc
	v_fma_f32 v85, v160, v80, v148
	v_mov_b32_dpp v0, v0 row_ror:1 row_mask:0xf bank_mask:0xf bound_ctrl:1
	v_mov_b32_dpp v3, v3 row_ror:2 row_mask:0xf bank_mask:0xf bound_ctrl:1
	v_fmac_f32_e32 v85, v156, v0
	v_fmac_f32_e32 v85, v152, v3
	v_mul_f32_e32 v0, 0xbfb8aa3b, v85
	v_exp_f32_e32 v0, v0
	v_cndmask_b32_e64 v3, v81, v97, s[6:7]
	v_cndmask_b32_e32 v80, v97, v81, vcc
	v_fma_f32 v81, v161, v81, v149
	v_mov_b32_dpp v84, v3 row_ror:1 row_mask:0xf bank_mask:0xf bound_ctrl:1
	v_add_f32_e32 v0, 1.0, v0
	v_rcp_f32_e32 v3, v0
	v_fmac_f32_e32 v81, v157, v84
	v_mov_b32_dpp v0, v80 row_ror:2 row_mask:0xf bank_mask:0xf bound_ctrl:1
	v_fmac_f32_e32 v81, v153, v0
	v_mul_f32_e32 v0, 0xbfb8aa3b, v81
	v_exp_f32_e32 v0, v0
	v_mov_b32_e32 v84, v76
	v_pk_mul_f32 v[84:85], v[84:85], v[2:3]
	v_cndmask_b32_e32 v76, v98, v82, vcc
	v_add_f32_e32 v0, 1.0, v0
	v_rcp_f32_e32 v3, v0
	v_cndmask_b32_e64 v0, v82, v98, s[6:7]
	v_fma_f32 v87, v162, v82, v150
	v_mov_b32_dpp v76, v76 row_ror:2 row_mask:0xf bank_mask:0xf bound_ctrl:1
	v_mov_b32_dpp v0, v0 row_ror:1 row_mask:0xf bank_mask:0xf bound_ctrl:1
	v_fmac_f32_e32 v87, v158, v0
	v_fmac_f32_e32 v87, v154, v76
	v_mul_f32_e32 v0, 0xbfb8aa3b, v87
	v_exp_f32_e32 v0, v0
	v_mov_b32_e32 v80, v77
	v_pk_mul_f32 v[76:77], v[80:81], v[2:3]
	v_cndmask_b32_e32 v80, v99, v83, vcc
	v_add_f32_e32 v0, 1.0, v0
	v_rcp_f32_e32 v3, v0
	v_cndmask_b32_e64 v0, v83, v99, s[6:7]
	v_fma_f32 v81, v163, v83, v151
	v_mov_b32_dpp v80, v80 row_ror:2 row_mask:0xf bank_mask:0xf bound_ctrl:1
	v_mov_b32_dpp v0, v0 row_ror:1 row_mask:0xf bank_mask:0xf bound_ctrl:1
	v_fmac_f32_e32 v81, v159, v0
	v_fmac_f32_e32 v81, v155, v80
	v_mul_f32_e32 v0, 0xbfb8aa3b, v81
	v_exp_f32_e32 v0, v0
	v_pk_mul_f32 v[82:83], v[86:87], v[2:3]
	v_mov_b32_e32 v80, v79
	v_mul_f32_e32 v84, v84, v85
	v_add_f32_e32 v0, 1.0, v0
	v_rcp_f32_e32 v3, v0
	v_mul_f32_e32 v0, v76, v77
	v_mul_f32_e32 v82, v82, v83
	v_pk_mul_f32 v[72:73], v[72:73], v[2:3] op_sel_hi:[1,0]
	s_nop 0
	v_cndmask_b32_e64 v76, v72, v88, s[6:7]
	v_cndmask_b32_e32 v77, v88, v72, vcc
	v_pk_mul_f32 v[74:75], v[74:75], v[2:3] op_sel_hi:[1,0]
	v_mov_b32_dpp v76, v76 row_ror:1 row_mask:0xf bank_mask:0xf bound_ctrl:1
	v_mov_b32_dpp v78, v77 row_ror:2 row_mask:0xf bank_mask:0xf bound_ctrl:1
	v_fma_f32 v77, v144, v72, v132
	v_fmac_f32_e32 v77, v140, v76
	v_fmac_f32_e32 v77, v136, v78
	v_mul_f32_e32 v72, 0xbfb8aa3b, v77
	v_exp_f32_e32 v72, v72
	v_pk_mul_f32 v[78:79], v[80:81], v[2:3]
	v_cndmask_b32_e32 v76, v89, v73, vcc
	v_mul_f32_e32 v78, v78, v79
	v_add_f32_e32 v3, 1.0, v72
	v_cndmask_b32_e64 v72, v73, v89, s[6:7]
	v_fma_f32 v79, v145, v73, v133
	v_mov_b32_dpp v76, v76 row_ror:2 row_mask:0xf bank_mask:0xf bound_ctrl:1
	v_mov_b32_dpp v72, v72 row_ror:1 row_mask:0xf bank_mask:0xf bound_ctrl:1
	v_fmac_f32_e32 v79, v141, v72
	v_fmac_f32_e32 v79, v137, v76
	v_mul_f32_e32 v72, 0xbfb8aa3b, v79
	v_exp_f32_e32 v73, v72
	v_rcp_f32_e32 v3, v3
	v_cvt_pk_bf16_f32 v72, v84, v0
	v_mov_b32_e32 v76, v68
	v_add_f32_e32 v0, 1.0, v73
	v_pk_mul_f32 v[76:77], v[76:77], v[2:3]
	v_rcp_f32_e32 v3, v0
	v_cndmask_b32_e64 v0, v74, v90, s[6:7]
	v_cndmask_b32_e32 v68, v90, v74, vcc
	v_fma_f32 v81, v146, v74, v134
	v_mov_b32_dpp v0, v0 row_ror:1 row_mask:0xf bank_mask:0xf bound_ctrl:1
	v_mov_b32_dpp v68, v68 row_ror:2 row_mask:0xf bank_mask:0xf bound_ctrl:1
	v_fmac_f32_e32 v81, v142, v0
	v_fmac_f32_e32 v81, v138, v68
	v_mul_f32_e32 v0, 0xbfb8aa3b, v81
	v_exp_f32_e32 v0, v0
	v_cvt_pk_bf16_f32 v73, v82, v78
	v_mov_b32_e32 v78, v69
	v_pk_mul_f32 v[68:69], v[78:79], v[2:3]
	v_add_f32_e32 v0, 1.0, v0
	v_rcp_f32_e32 v3, v0
	v_cndmask_b32_e64 v0, v75, v91, s[6:7]
	v_cndmask_b32_e32 v74, v91, v75, vcc
	v_fma_f32 v75, v147, v75, v135
	v_mov_b32_dpp v0, v0 row_ror:1 row_mask:0xf bank_mask:0xf bound_ctrl:1
	v_mov_b32_dpp v74, v74 row_ror:2 row_mask:0xf bank_mask:0xf bound_ctrl:1
	v_fmac_f32_e32 v75, v143, v0
	v_fmac_f32_e32 v75, v139, v74
	v_mul_f32_e32 v0, 0xbfb8aa3b, v75
	v_exp_f32_e32 v0, v0
	v_mov_b32_e32 v80, v70
	v_mul_f32_e32 v78, v76, v77
	v_pk_mul_f32 v[76:77], v[80:81], v[2:3]
	v_add_f32_e32 v0, 1.0, v0
	v_rcp_f32_e32 v3, v0
	v_mul_f32_e32 v0, v68, v69
	v_mov_b32_e32 v74, v71
	v_mul_f32_e32 v68, v76, v77
	v_pk_mul_f32 v[2:3], v[74:75], v[2:3]
	v_cvt_pk_bf16_f32 v74, v78, v0
	v_add_u32_e32 v0, 0x42000, v184
	v_mul_f32_e32 v2, v2, v3
	v_cvt_pk_bf16_f32 v75, v68, v2
	global_store_dwordx4 v0, v[72:75], s[0:1] sc1
	ds_read_b32 v76, v209 offset:512
	s_nor_b64 s[8:9], s[30:31], vcc
	v_mov_b32_e32 v68, 0
	v_mov_b32_e32 v69, 0
	v_mov_b32_e32 v70, 0
	v_mov_b32_e32 v71, 0
	v_mov_b32_e32 v72, 0
	v_mov_b32_e32 v73, 0
	v_mov_b32_e32 v74, 0
	v_mov_b32_e32 v75, 0
	s_and_saveexec_b64 s[0:1], s[8:9]
	s_cbranch_execz .LBB0_1395
	s_movk_i32 s8, 0xe800
	v_add3_u32 v0, v185, v210, s8
	ds_read_b128 v[72:75], v0
	ds_read_b128 v[68:71], v0 offset:16
; #define LAS __attribute__((address_space(3)))
; __device__ __forceinline__ unsigned cvt_pk_bf16(float lo, float hi) { unsigned r; asm("v_cvt_pk_bf16_f32 %0, %1, %2" : "=v"(r) : "v"(lo), "v"(hi)); return r; }
;     __device__ __forceinline__ void operator()(const f32x4 (&acc)[2][2][4][2], const Unit& u, int wr, int wc, int fr, int fq) const {
;     ...
;                 for (int ai = 0; ai < 2; ++ai)
; #pragma unroll
;                     for (int m = 0; m < 4; ++m) {
;                         const int l = 128 * ai + 64 * wr + 16 * m + frL;
;                         const float rs = rt[l];
;                         if (m == 0) {
;                             const int B = 2 * ai + wr;
;                             prevA = (f32x4){0.f, 0.f, 0.f, 0.f}; prevB = prevA;
;                             if (B > 0 && frL >= 14) { const LAS float* hp = halo + ((B - 1) * 2 + (frL - 14)) * 128 + fl; prevA = *(const LAS f32x4*)hp; prevB = *(const LAS f32x4*)(hp + 4); }
;                         }
;                         unsigned wv[4];
; #pragma unroll
;                         for (int n = 0; n < 2; ++n) {
;                             const f32x4 w0 = n ? Wb0 : Wa0, w1 = n ? Wb1 : Wa1, w2 = n ? Wb2 : Wa2, bb = n ? Wbb : Wab;
;                             const f32x4 cur = acc[ai][1][m][n] * rs, uu = acc[ai][0][m][n] * rs, prev = n ? prevB : prevA;
;                             float ov[4];
; #pragma unroll
;                             for (int e = 0; e < 4; ++e) {
;                                 const float ce = cur[e], pe = prev[e];
;                                 const float g1 = dpp_mv<0x121>(k15 ? pe : ce), g2 = dpp_mv<0x122>(k14 ? pe : ce);
;                                 const float cv = fmaf(w0[e], g2, fmaf(w1[e], g1, fmaf(w2[e], ce, bb[e])));
;                                 ov[e] = siluf_(cv) * uu[e];
;                             }
;                             wv[2 * n] = cvt_pk_bf16(ov[0], ov[1]); wv[2 * n + 1] = cvt_pk_bf16(ov[2], ov[3]);
;                             if (n) prevB = cur; else prevA = cur;
;                         }
;                         if (ai > 0 || m > 0 || l >= 2) *(v4u*)((unsigned char*)ACT + (ob + (unsigned)((128 * ai + 16 * m) * DFF * 2))) = (v4u){wv[0], wv[1], wv[2], wv[3]};
;                         __builtin_amdgcn_sched_barrier(0);
;                     }
.LBB0_1395:
	s_or_b64 exec, exec, s[0:1]
	s_waitcnt lgkmcnt(0)
	v_pk_mul_f32 v[64:65], v[64:65], v[76:77] op_sel_hi:[1,0]
	v_pk_mul_f32 v[66:67], v[66:67], v[76:77] op_sel_hi:[1,0]
	v_cndmask_b32_e64 v0, v64, v72, s[6:7]
	v_cndmask_b32_e32 v2, v72, v64, vcc
	v_fma_f32 v3, v160, v64, v148
	v_mov_b32_dpp v0, v0 row_ror:1 row_mask:0xf bank_mask:0xf bound_ctrl:1
	v_mov_b32_dpp v2, v2 row_ror:2 row_mask:0xf bank_mask:0xf bound_ctrl:1
	v_fmac_f32_e32 v3, v156, v0
	v_fmac_f32_e32 v3, v152, v2
	v_mul_f32_e32 v0, 0xbfb8aa3b, v3
	v_exp_f32_e32 v0, v0
	v_mov_b32_e32 v2, v60
	v_readlane_b32 s0, v252, 8
	v_readlane_b32 s1, v252, 9
	v_add_f32_e32 v0, 1.0, v0
	v_rcp_f32_e32 v77, v0
	s_nop 0
	v_pk_mul_f32 v[2:3], v[2:3], v[76:77]
	s_nop 0
	v_mul_f32_e32 v0, v2, v3
	v_cndmask_b32_e64 v2, v65, v73, s[6:7]
	v_cndmask_b32_e32 v3, v73, v65, vcc
	s_nop 0
	v_mov_b32_dpp v2, v2 row_ror:1 row_mask:0xf bank_mask:0xf bound_ctrl:1
	v_mov_b32_dpp v60, v3 row_ror:2 row_mask:0xf bank_mask:0xf bound_ctrl:1
	v_fma_f32 v3, v161, v65, v149
	v_fmac_f32_e32 v3, v157, v2
	v_fmac_f32_e32 v3, v153, v60
	v_mul_f32_e32 v2, 0xbfb8aa3b, v3
	v_exp_f32_e32 v2, v2
	s_nop 0
	v_add_f32_e32 v2, 1.0, v2
	v_rcp_f32_e32 v77, v2
	v_mov_b32_e32 v2, v61
	v_pk_mul_f32 v[2:3], v[2:3], v[76:77]
	s_nop 0
	v_mul_f32_e32 v60, v2, v3
	v_cndmask_b32_e64 v2, v66, v74, s[6:7]
	v_cndmask_b32_e32 v3, v74, v66, vcc
	v_cvt_pk_bf16_f32 v60, v0, v60
	s_nop 0
	v_mov_b32_dpp v2, v2 row_ror:1 row_mask:0xf bank_mask:0xf bound_ctrl:1
	v_mov_b32_dpp v61, v3 row_ror:2 row_mask:0xf bank_mask:0xf bound_ctrl:1
	v_fma_f32 v3, v162, v66, v150
	v_fmac_f32_e32 v3, v158, v2
	v_fmac_f32_e32 v3, v154, v61
	v_mul_f32_e32 v2, 0xbfb8aa3b, v3
	v_exp_f32_e32 v2, v2
	s_nop 0
	v_add_f32_e32 v2, 1.0, v2
	v_rcp_f32_e32 v77, v2
	v_mov_b32_e32 v2, v62
	v_pk_mul_f32 v[2:3], v[2:3], v[76:77]
	s_nop 0
	v_mul_f32_e32 v61, v2, v3
	v_cndmask_b32_e64 v2, v67, v75, s[6:7]
	v_cndmask_b32_e32 v3, v75, v67, vcc
	s_nop 0
	v_mov_b32_dpp v2, v2 row_ror:1 row_mask:0xf bank_mask:0xf bound_ctrl:1
	v_mov_b32_dpp v62, v3 row_ror:2 row_mask:0xf bank_mask:0xf bound_ctrl:1
	v_fma_f32 v3, v163, v67, v151
	v_fmac_f32_e32 v3, v159, v2
	v_fmac_f32_e32 v3, v155, v62
	v_mul_f32_e32 v2, 0xbfb8aa3b, v3
	v_exp_f32_e32 v2, v2
	s_nop 0
	v_add_f32_e32 v2, 1.0, v2
	v_rcp_f32_e32 v77, v2
	v_mov_b32_e32 v2, v63
	v_pk_mul_f32 v[2:3], v[2:3], v[76:77]
	v_pk_mul_f32 v[56:57], v[56:57], v[76:77] op_sel_hi:[1,0]
	v_mul_f32_e32 v2, v2, v3
	v_cndmask_b32_e64 v0, v56, v68, s[6:7]
	v_cvt_pk_bf16_f32 v61, v61, v2
	v_pk_mul_f32 v[2:3], v[58:59], v[76:77] op_sel_hi:[1,0]
	v_cndmask_b32_e32 v58, v68, v56, vcc
	v_mov_b32_dpp v0, v0 row_ror:1 row_mask:0xf bank_mask:0xf bound_ctrl:1
	v_fma_f32 v59, v144, v56, v132
	v_mov_b32_dpp v58, v58 row_ror:2 row_mask:0xf bank_mask:0xf bound_ctrl:1
	v_fmac_f32_e32 v59, v140, v0
	v_fmac_f32_e32 v59, v136, v58
	v_mul_f32_e32 v0, 0xbfb8aa3b, v59
	v_exp_f32_e32 v0, v0
	v_mov_b32_e32 v58, v52
	v_cndmask_b32_e64 v52, v57, v69, s[6:7]
	v_add_f32_e32 v0, 1.0, v0
	v_rcp_f32_e32 v77, v0
	v_mov_b32_dpp v52, v52 row_ror:1 row_mask:0xf bank_mask:0xf bound_ctrl:1
	v_pk_mul_f32 v[58:59], v[58:59], v[76:77]
	s_nop 0
	v_mul_f32_e32 v0, v58, v59
	v_cndmask_b32_e32 v58, v69, v57, vcc
	v_fma_f32 v59, v145, v57, v133
	v_fmac_f32_e32 v59, v141, v52
	v_mov_b32_dpp v58, v58 row_ror:2 row_mask:0xf bank_mask:0xf bound_ctrl:1
	v_fmac_f32_e32 v59, v137, v58
	v_mul_f32_e32 v52, 0xbfb8aa3b, v59
	v_exp_f32_e32 v52, v52
	v_mov_b32_e32 v58, v53
	v_add_f32_e32 v52, 1.0, v52
	v_rcp_f32_e32 v77, v52
	s_nop 0
	v_pk_mul_f32 v[52:53], v[58:59], v[76:77]
	s_nop 0
	v_mul_f32_e32 v58, v52, v53
	v_cndmask_b32_e64 v52, v2, v70, s[6:7]
	v_cndmask_b32_e32 v53, v70, v2, vcc
	v_cvt_pk_bf16_f32 v62, v0, v58
	v_add_u32_e32 v0, 0xb0000, v184
	v_mov_b32_dpp v52, v52 row_ror:1 row_mask:0xf bank_mask:0xf bound_ctrl:1
	v_mov_b32_dpp v59, v53 row_ror:2 row_mask:0xf bank_mask:0xf bound_ctrl:1
	v_fma_f32 v53, v146, v2, v134
	v_fmac_f32_e32 v53, v142, v52
	v_fmac_f32_e32 v53, v138, v59
	v_mul_f32_e32 v52, 0xbfb8aa3b, v53
	v_exp_f32_e32 v52, v52
	s_nop 0
	v_add_f32_e32 v52, 1.0, v52
	v_rcp_f32_e32 v77, v52
	v_mov_b32_e32 v52, v54
	v_pk_mul_f32 v[52:53], v[52:53], v[76:77]
	s_nop 0
	v_mul_f32_e32 v54, v52, v53
	v_cndmask_b32_e64 v52, v3, v71, s[6:7]
	v_cndmask_b32_e32 v53, v71, v3, vcc
	s_nop 0
	v_mov_b32_dpp v52, v52 row_ror:1 row_mask:0xf bank_mask:0xf bound_ctrl:1
	v_mov_b32_dpp v59, v53 row_ror:2 row_mask:0xf bank_mask:0xf bound_ctrl:1
	v_fma_f32 v53, v147, v3, v135
	v_fmac_f32_e32 v53, v143, v52
	v_fmac_f32_e32 v53, v139, v59
	v_mul_f32_e32 v52, 0xbfb8aa3b, v53
	v_exp_f32_e32 v52, v52
	s_nop 0
	v_add_f32_e32 v52, 1.0, v52
	v_rcp_f32_e32 v77, v52
	v_mov_b32_e32 v52, v55
	v_pk_mul_f32 v[52:53], v[52:53], v[76:77]
	s_nop 0
	v_mul_f32_e32 v52, v52, v53
	v_cvt_pk_bf16_f32 v63, v54, v52
	global_store_dwordx4 v0, v[60:63], s[0:1] sc1
	ds_read_b32 v52, v209 offset:576
	v_mov_b32_e32 v54, v44
	s_waitcnt lgkmcnt(0)
; #define LAS __attribute__((address_space(3)))
; __device__ __forceinline__ unsigned cvt_pk_bf16(float lo, float hi) { unsigned r; asm("v_cvt_pk_bf16_f32 %0, %1, %2" : "=v"(r) : "v"(lo), "v"(hi)); return r; }
;     __device__ __forceinline__ void operator()(const f32x4 (&acc)[2][2][4][2], const Unit& u, int wr, int wc, int fr, int fq) const {
;     ...
;                 for (int ai = 0; ai < 2; ++ai)
; #pragma unroll
;                     for (int m = 0; m < 4; ++m) {
;                         const int l = 128 * ai + 64 * wr + 16 * m + frL;
;                         const float rs = rt[l];
;                         if (m == 0) {
;                             const int B = 2 * ai + wr;
;                             prevA = (f32x4){0.f, 0.f, 0.f, 0.f}; prevB = prevA;
;                             if (B > 0 && frL >= 14) { const LAS float* hp = halo + ((B - 1) * 2 + (frL - 14)) * 128 + fl; prevA = *(const LAS f32x4*)hp; prevB = *(const LAS f32x4*)(hp + 4); }
;                         }
;                         unsigned wv[4];
; #pragma unroll
;                         for (int n = 0; n < 2; ++n) {
;                             const f32x4 w0 = n ? Wb0 : Wa0, w1 = n ? Wb1 : Wa1, w2 = n ? Wb2 : Wa2, bb = n ? Wbb : Wab;
;                             const f32x4 cur = acc[ai][1][m][n] * rs, uu = acc[ai][0][m][n] * rs, prev = n ? prevB : prevA;
;                             float ov[4];
; #pragma unroll
;                             for (int e = 0; e < 4; ++e) {
;                                 const float ce = cur[e], pe = prev[e];
;                                 const float g1 = dpp_mv<0x121>(k15 ? pe : ce), g2 = dpp_mv<0x122>(k14 ? pe : ce);
;                                 const float cv = fmaf(w0[e], g2, fmaf(w1[e], g1, fmaf(w2[e], ce, bb[e])));
;                                 ov[e] = siluf_(cv) * uu[e];
;                             }
;                             wv[2 * n] = cvt_pk_bf16(ov[0], ov[1]); wv[2 * n + 1] = cvt_pk_bf16(ov[2], ov[3]);
;                             if (n) prevB = cur; else prevA = cur;
;                         }
;                         if (ai > 0 || m > 0 || l >= 2) *(v4u*)((unsigned char*)ACT + (ob + (unsigned)((128 * ai + 16 * m) * DFF * 2))) = (v4u){wv[0], wv[1], wv[2], wv[3]};
;                         __builtin_amdgcn_sched_barrier(0);
;                     }
	v_pk_mul_f32 v[48:49], v[48:49], v[52:53] op_sel_hi:[1,0]
	s_nop 0
	v_cndmask_b32_e64 v0, v48, v64, s[6:7]
	v_pk_mul_f32 v[50:51], v[50:51], v[52:53] op_sel_hi:[1,0]
	v_cndmask_b32_e32 v53, v64, v48, vcc
	v_mov_b32_dpp v0, v0 row_ror:1 row_mask:0xf bank_mask:0xf bound_ctrl:1
	v_fma_f32 v55, v160, v48, v148
	v_mov_b32_dpp v53, v53 row_ror:2 row_mask:0xf bank_mask:0xf bound_ctrl:1
	v_fmac_f32_e32 v55, v156, v0
	v_fmac_f32_e32 v55, v152, v53
	v_mul_f32_e32 v0, 0xbfb8aa3b, v55
	v_exp_f32_e32 v0, v0
	v_cndmask_b32_e64 v44, v49, v65, s[6:7]
	v_add_f32_e32 v0, 1.0, v0
	v_rcp_f32_e32 v53, v0
	v_mov_b32_dpp v44, v44 row_ror:1 row_mask:0xf bank_mask:0xf bound_ctrl:1
	v_pk_mul_f32 v[54:55], v[54:55], v[52:53]
	s_nop 0
	v_mul_f32_e32 v0, v54, v55
	v_cndmask_b32_e32 v53, v65, v49, vcc
	v_fma_f32 v55, v161, v49, v149
	v_fmac_f32_e32 v55, v157, v44
	v_mov_b32_dpp v53, v53 row_ror:2 row_mask:0xf bank_mask:0xf bound_ctrl:1
	v_fmac_f32_e32 v55, v153, v53
	v_mul_f32_e32 v44, 0xbfb8aa3b, v55
	v_exp_f32_e32 v44, v44
	v_mov_b32_e32 v54, v45
	v_add_f32_e32 v44, 1.0, v44
	v_rcp_f32_e32 v53, v44
	s_nop 0
	v_pk_mul_f32 v[44:45], v[54:55], v[52:53]
	s_nop 0
	v_mul_f32_e32 v54, v44, v45
	v_cndmask_b32_e64 v44, v50, v66, s[6:7]
	v_cndmask_b32_e32 v45, v66, v50, vcc
	s_nop 0
	v_mov_b32_dpp v44, v44 row_ror:1 row_mask:0xf bank_mask:0xf bound_ctrl:1
	v_mov_b32_dpp v53, v45 row_ror:2 row_mask:0xf bank_mask:0xf bound_ctrl:1
	v_fma_f32 v45, v162, v50, v150
	v_fmac_f32_e32 v45, v158, v44
	v_fmac_f32_e32 v45, v154, v53
	v_mul_f32_e32 v44, 0xbfb8aa3b, v45
	v_exp_f32_e32 v44, v44
	s_nop 0
	v_add_f32_e32 v44, 1.0, v44
	v_rcp_f32_e32 v53, v44
	v_mov_b32_e32 v44, v46
	v_pk_mul_f32 v[44:45], v[44:45], v[52:53]
	s_nop 0
	v_mul_f32_e32 v46, v44, v45
	v_cndmask_b32_e64 v44, v51, v67, s[6:7]
	v_cndmask_b32_e32 v45, v67, v51, vcc
	s_nop 0
	v_mov_b32_dpp v44, v44 row_ror:1 row_mask:0xf bank_mask:0xf bound_ctrl:1
	v_mov_b32_dpp v53, v45 row_ror:2 row_mask:0xf bank_mask:0xf bound_ctrl:1
	v_fma_f32 v45, v163, v51, v151
	v_fmac_f32_e32 v45, v159, v44
	v_fmac_f32_e32 v45, v155, v53
	v_mul_f32_e32 v44, 0xbfb8aa3b, v45
	v_exp_f32_e32 v44, v44
	s_nop 0
	v_add_f32_e32 v44, 1.0, v44
	v_rcp_f32_e32 v53, v44
	v_mov_b32_e32 v44, v47
	v_pk_mul_f32 v[44:45], v[44:45], v[52:53]
	v_pk_mul_f32 v[40:41], v[40:41], v[52:53] op_sel_hi:[1,0]
	v_mul_f32_e32 v45, v44, v45
	v_cvt_pk_bf16_f32 v44, v0, v54
	v_cndmask_b32_e64 v0, v40, v56, s[6:7]
	v_cvt_pk_bf16_f32 v45, v46, v45
	v_cndmask_b32_e32 v46, v56, v40, vcc
	v_fma_f32 v47, v144, v40, v132
	v_mov_b32_dpp v0, v0 row_ror:1 row_mask:0xf bank_mask:0xf bound_ctrl:1
	v_mov_b32_dpp v46, v46 row_ror:2 row_mask:0xf bank_mask:0xf bound_ctrl:1
	v_fmac_f32_e32 v47, v140, v0
	v_fmac_f32_e32 v47, v136, v46
	v_mul_f32_e32 v0, 0xbfb8aa3b, v47
	v_exp_f32_e32 v0, v0
	v_pk_mul_f32 v[42:43], v[42:43], v[52:53] op_sel_hi:[1,0]
	v_mov_b32_e32 v46, v36
	v_cndmask_b32_e64 v36, v41, v57, s[6:7]
	v_add_f32_e32 v0, 1.0, v0
	v_rcp_f32_e32 v53, v0
	v_mov_b32_dpp v36, v36 row_ror:1 row_mask:0xf bank_mask:0xf bound_ctrl:1
	v_pk_mul_f32 v[46:47], v[46:47], v[52:53]
	s_nop 0
	v_mul_f32_e32 v0, v46, v47
	v_cndmask_b32_e32 v46, v57, v41, vcc
	v_fma_f32 v47, v145, v41, v133
	v_fmac_f32_e32 v47, v141, v36
	v_mov_b32_dpp v46, v46 row_ror:2 row_mask:0xf bank_mask:0xf bound_ctrl:1
	v_fmac_f32_e32 v47, v137, v46
	v_mul_f32_e32 v36, 0xbfb8aa3b, v47
	v_exp_f32_e32 v36, v36
	v_mov_b32_e32 v46, v37
	v_add_f32_e32 v36, 1.0, v36
	v_rcp_f32_e32 v53, v36
	s_nop 0
	v_pk_mul_f32 v[36:37], v[46:47], v[52:53]
	s_nop 0
	v_mul_f32_e32 v46, v36, v37
	v_cndmask_b32_e64 v36, v42, v2, s[6:7]
	v_cndmask_b32_e32 v2, v2, v42, vcc
	v_fma_f32 v37, v146, v42, v134
	v_mov_b32_dpp v36, v36 row_ror:1 row_mask:0xf bank_mask:0xf bound_ctrl:1
	v_mov_b32_dpp v2, v2 row_ror:2 row_mask:0xf bank_mask:0xf bound_ctrl:1
	v_fmac_f32_e32 v37, v142, v36
	v_fmac_f32_e32 v37, v138, v2
	v_mul_f32_e32 v2, 0xbfb8aa3b, v37
	v_exp_f32_e32 v2, v2
	v_mov_b32_e32 v36, v38
	v_cvt_pk_bf16_f32 v46, v0, v46
	v_add_u32_e32 v0, 0xc6000, v184
	v_add_f32_e32 v2, 1.0, v2
	v_rcp_f32_e32 v53, v2
	v_cndmask_b32_e64 v2, v43, v3, s[6:7]
	v_cndmask_b32_e32 v3, v3, v43, vcc
	v_pk_mul_f32 v[36:37], v[36:37], v[52:53]
	s_nop 0
	v_mul_f32_e32 v36, v36, v37
	v_mov_b32_dpp v2, v2 row_ror:1 row_mask:0xf bank_mask:0xf bound_ctrl:1
	v_mov_b32_dpp v37, v3 row_ror:2 row_mask:0xf bank_mask:0xf bound_ctrl:1
	v_fma_f32 v3, v147, v43, v135
	v_fmac_f32_e32 v3, v143, v2
	v_fmac_f32_e32 v3, v139, v37
	v_mul_f32_e32 v2, 0xbfb8aa3b, v3
	v_exp_f32_e32 v2, v2
	s_nop 0
	v_add_f32_e32 v2, 1.0, v2
	v_rcp_f32_e32 v53, v2
	v_mov_b32_e32 v2, v39
	v_pk_mul_f32 v[2:3], v[2:3], v[52:53]
	s_nop 0
	v_mul_f32_e32 v2, v2, v3
	v_cvt_pk_bf16_f32 v47, v36, v2
	global_store_dwordx4 v0, v[44:47], s[0:1] sc1
	ds_read_b32 v36, v209 offset:640
	s_waitcnt lgkmcnt(0)
; #define LAS __attribute__((address_space(3)))
; __device__ __forceinline__ unsigned cvt_pk_bf16(float lo, float hi) { unsigned r; asm("v_cvt_pk_bf16_f32 %0, %1, %2" : "=v"(r) : "v"(lo), "v"(hi)); return r; }
;     __device__ __forceinline__ void operator()(const f32x4 (&acc)[2][2][4][2], const Unit& u, int wr, int wc, int fr, int fq) const {
;     ...
;                 for (int ai = 0; ai < 2; ++ai)
; #pragma unroll
;                     for (int m = 0; m < 4; ++m) {
;                         const int l = 128 * ai + 64 * wr + 16 * m + frL;
;                         const float rs = rt[l];
;                         if (m == 0) {
;                             const int B = 2 * ai + wr;
;                             prevA = (f32x4){0.f, 0.f, 0.f, 0.f}; prevB = prevA;
;                             if (B > 0 && frL >= 14) { const LAS float* hp = halo + ((B - 1) * 2 + (frL - 14)) * 128 + fl; prevA = *(const LAS f32x4*)hp; prevB = *(const LAS f32x4*)(hp + 4); }
;                         }
;                         unsigned wv[4];
; #pragma unroll
;                         for (int n = 0; n < 2; ++n) {
;                             const f32x4 w0 = n ? Wb0 : Wa0, w1 = n ? Wb1 : Wa1, w2 = n ? Wb2 : Wa2, bb = n ? Wbb : Wab;
;                             const f32x4 cur = acc[ai][1][m][n] * rs, uu = acc[ai][0][m][n] * rs, prev = n ? prevB : prevA;
;                             float ov[4];
; #pragma unroll
;                             for (int e = 0; e < 4; ++e) {
;                                 const float ce = cur[e], pe = prev[e];
;                                 const float g1 = dpp_mv<0x121>(k15 ? pe : ce), g2 = dpp_mv<0x122>(k14 ? pe : ce);
;                                 const float cv = fmaf(w0[e], g2, fmaf(w1[e], g1, fmaf(w2[e], ce, bb[e])));
;                                 ov[e] = siluf_(cv) * uu[e];
;                             }
;                             wv[2 * n] = cvt_pk_bf16(ov[0], ov[1]); wv[2 * n + 1] = cvt_pk_bf16(ov[2], ov[3]);
;                             if (n) prevB = cur; else prevA = cur;
;                         }
;                         if (ai > 0 || m > 0 || l >= 2) *(v4u*)((unsigned char*)ACT + (ob + (unsigned)((128 * ai + 16 * m) * DFF * 2))) = (v4u){wv[0], wv[1], wv[2], wv[3]};
;                         __builtin_amdgcn_sched_barrier(0);
;                     }
	v_pk_mul_f32 v[32:33], v[32:33], v[36:37] op_sel_hi:[1,0]
	s_nop 0
	v_cndmask_b32_e64 v0, v32, v48, s[6:7]
	v_pk_mul_f32 v[2:3], v[34:35], v[36:37] op_sel_hi:[1,0]
	v_cndmask_b32_e32 v34, v48, v32, vcc
	v_mov_b32_dpp v0, v0 row_ror:1 row_mask:0xf bank_mask:0xf bound_ctrl:1
	v_fma_f32 v35, v160, v32, v148
	v_mov_b32_dpp v34, v34 row_ror:2 row_mask:0xf bank_mask:0xf bound_ctrl:1
	v_fmac_f32_e32 v35, v156, v0
	v_fmac_f32_e32 v35, v152, v34
	v_mul_f32_e32 v0, 0xbfb8aa3b, v35
	v_exp_f32_e32 v0, v0
	v_mov_b32_e32 v34, v28
	v_cndmask_b32_e64 v28, v33, v49, s[6:7]
	v_add_f32_e32 v0, 1.0, v0
	v_rcp_f32_e32 v37, v0
	v_mov_b32_dpp v28, v28 row_ror:1 row_mask:0xf bank_mask:0xf bound_ctrl:1
	v_pk_mul_f32 v[34:35], v[34:35], v[36:37]
	s_nop 0
	v_mul_f32_e32 v0, v34, v35
	v_cndmask_b32_e32 v34, v49, v33, vcc
	v_fma_f32 v35, v161, v33, v149
	v_fmac_f32_e32 v35, v157, v28
	v_mov_b32_dpp v34, v34 row_ror:2 row_mask:0xf bank_mask:0xf bound_ctrl:1
	v_fmac_f32_e32 v35, v153, v34
	v_mul_f32_e32 v28, 0xbfb8aa3b, v35
	v_exp_f32_e32 v28, v28
	v_mov_b32_e32 v34, v29
	v_add_f32_e32 v28, 1.0, v28
	v_rcp_f32_e32 v37, v28
	s_nop 0
	v_pk_mul_f32 v[28:29], v[34:35], v[36:37]
	s_nop 0
	v_mul_f32_e32 v34, v28, v29
	v_cndmask_b32_e64 v28, v2, v50, s[6:7]
	v_cndmask_b32_e32 v29, v50, v2, vcc
	s_nop 0
	v_mov_b32_dpp v28, v28 row_ror:1 row_mask:0xf bank_mask:0xf bound_ctrl:1
	v_mov_b32_dpp v35, v29 row_ror:2 row_mask:0xf bank_mask:0xf bound_ctrl:1
	v_fma_f32 v29, v162, v2, v150
	v_fmac_f32_e32 v29, v158, v28
	v_fmac_f32_e32 v29, v154, v35
	v_mul_f32_e32 v28, 0xbfb8aa3b, v29
	v_exp_f32_e32 v28, v28
	s_nop 0
	v_add_f32_e32 v28, 1.0, v28
	v_rcp_f32_e32 v37, v28
	v_mov_b32_e32 v28, v30
	v_pk_mul_f32 v[28:29], v[28:29], v[36:37]
	s_nop 0
	v_mul_f32_e32 v30, v28, v29
	v_cndmask_b32_e64 v28, v3, v51, s[6:7]
	v_cndmask_b32_e32 v29, v51, v3, vcc
	s_nop 0
	v_mov_b32_dpp v28, v28 row_ror:1 row_mask:0xf bank_mask:0xf bound_ctrl:1
	v_mov_b32_dpp v35, v29 row_ror:2 row_mask:0xf bank_mask:0xf bound_ctrl:1
	v_fma_f32 v29, v163, v3, v151
	v_fmac_f32_e32 v29, v159, v28
	v_fmac_f32_e32 v29, v155, v35
	v_mul_f32_e32 v28, 0xbfb8aa3b, v29
	v_exp_f32_e32 v28, v28
	s_nop 0
	v_add_f32_e32 v28, 1.0, v28
	v_rcp_f32_e32 v37, v28
	v_mov_b32_e32 v28, v31
	v_pk_mul_f32 v[28:29], v[28:29], v[36:37]
	v_pk_mul_f32 v[24:25], v[24:25], v[36:37] op_sel_hi:[1,0]
	v_mul_f32_e32 v29, v28, v29
	v_cvt_pk_bf16_f32 v28, v0, v34
	v_cndmask_b32_e64 v0, v24, v40, s[6:7]
	v_cvt_pk_bf16_f32 v29, v30, v29
	v_cndmask_b32_e32 v30, v40, v24, vcc
	v_fma_f32 v31, v144, v24, v132
	v_mov_b32_dpp v0, v0 row_ror:1 row_mask:0xf bank_mask:0xf bound_ctrl:1
	v_mov_b32_dpp v30, v30 row_ror:2 row_mask:0xf bank_mask:0xf bound_ctrl:1
	v_fmac_f32_e32 v31, v140, v0
	v_fmac_f32_e32 v31, v136, v30
	v_mul_f32_e32 v0, 0xbfb8aa3b, v31
	v_exp_f32_e32 v0, v0
	v_pk_mul_f32 v[26:27], v[26:27], v[36:37] op_sel_hi:[1,0]
	v_mov_b32_e32 v30, v20
	v_cndmask_b32_e64 v20, v25, v41, s[6:7]
	v_add_f32_e32 v0, 1.0, v0
	v_rcp_f32_e32 v37, v0
	v_mov_b32_dpp v20, v20 row_ror:1 row_mask:0xf bank_mask:0xf bound_ctrl:1
	v_pk_mul_f32 v[30:31], v[30:31], v[36:37]
	s_nop 0
	v_mul_f32_e32 v0, v30, v31
	v_cndmask_b32_e32 v30, v41, v25, vcc
	v_fma_f32 v31, v145, v25, v133
	v_fmac_f32_e32 v31, v141, v20
	v_mov_b32_dpp v30, v30 row_ror:2 row_mask:0xf bank_mask:0xf bound_ctrl:1
	v_fmac_f32_e32 v31, v137, v30
	v_mul_f32_e32 v20, 0xbfb8aa3b, v31
	v_exp_f32_e32 v20, v20
	v_mov_b32_e32 v30, v21
	v_add_f32_e32 v20, 1.0, v20
	v_rcp_f32_e32 v37, v20
	s_nop 0
	v_pk_mul_f32 v[20:21], v[30:31], v[36:37]
	s_nop 0
	v_mul_f32_e32 v30, v20, v21
	v_cndmask_b32_e64 v20, v26, v42, s[6:7]
	v_cndmask_b32_e32 v21, v42, v26, vcc
	v_cvt_pk_bf16_f32 v30, v0, v30
	v_add_u32_e32 v0, 0xdc000, v184
	v_mov_b32_dpp v20, v20 row_ror:1 row_mask:0xf bank_mask:0xf bound_ctrl:1
	v_mov_b32_dpp v31, v21 row_ror:2 row_mask:0xf bank_mask:0xf bound_ctrl:1
	v_fma_f32 v21, v146, v26, v134
	v_fmac_f32_e32 v21, v142, v20
	v_fmac_f32_e32 v21, v138, v31
	v_mul_f32_e32 v20, 0xbfb8aa3b, v21
	v_exp_f32_e32 v20, v20
	s_nop 0
	v_add_f32_e32 v20, 1.0, v20
	v_rcp_f32_e32 v37, v20
	v_mov_b32_e32 v20, v22
	v_pk_mul_f32 v[20:21], v[20:21], v[36:37]
	s_nop 0
	v_mul_f32_e32 v22, v20, v21
	v_cndmask_b32_e64 v20, v27, v43, s[6:7]
	v_cndmask_b32_e32 v21, v43, v27, vcc
	s_nop 0
	v_mov_b32_dpp v20, v20 row_ror:1 row_mask:0xf bank_mask:0xf bound_ctrl:1
	v_mov_b32_dpp v31, v21 row_ror:2 row_mask:0xf bank_mask:0xf bound_ctrl:1
	v_fma_f32 v21, v147, v27, v135
	v_fmac_f32_e32 v21, v143, v20
	v_fmac_f32_e32 v21, v139, v31
	v_mul_f32_e32 v20, 0xbfb8aa3b, v21
	v_exp_f32_e32 v20, v20
	s_nop 0
	v_add_f32_e32 v20, 1.0, v20
	v_rcp_f32_e32 v37, v20
	v_mov_b32_e32 v20, v23
	v_pk_mul_f32 v[20:21], v[20:21], v[36:37]
	s_nop 0
	v_mul_f32_e32 v20, v20, v21
	v_cvt_pk_bf16_f32 v31, v22, v20
	global_store_dwordx4 v0, v[28:31], s[0:1] sc1
	ds_read_b32 v20, v209 offset:704
	s_nop 0
	v_mov_b32_e32 v28, v14
	s_waitcnt lgkmcnt(0)
; #define LAS __attribute__((address_space(3)))
; __device__ __forceinline__ unsigned cvt_pk_bf16(float lo, float hi) { unsigned r; asm("v_cvt_pk_bf16_f32 %0, %1, %2" : "=v"(r) : "v"(lo), "v"(hi)); return r; }
;     __device__ __forceinline__ void operator()(const f32x4 (&acc)[2][2][4][2], const Unit& u, int wr, int wc, int fr, int fq) const {
;     ...
;                 for (int ai = 0; ai < 2; ++ai)
; #pragma unroll
;                     for (int m = 0; m < 4; ++m) {
;                         const int l = 128 * ai + 64 * wr + 16 * m + frL;
;                         const float rs = rt[l];
;                         if (m == 0) {
;                             const int B = 2 * ai + wr;
;                             prevA = (f32x4){0.f, 0.f, 0.f, 0.f}; prevB = prevA;
;                             if (B > 0 && frL >= 14) { const LAS float* hp = halo + ((B - 1) * 2 + (frL - 14)) * 128 + fl; prevA = *(const LAS f32x4*)hp; prevB = *(const LAS f32x4*)(hp + 4); }
;                         }
;                         unsigned wv[4];
; #pragma unroll
;                         for (int n = 0; n < 2; ++n) {
;                             const f32x4 w0 = n ? Wb0 : Wa0, w1 = n ? Wb1 : Wa1, w2 = n ? Wb2 : Wa2, bb = n ? Wbb : Wab;
;                             const f32x4 cur = acc[ai][1][m][n] * rs, uu = acc[ai][0][m][n] * rs, prev = n ? prevB : prevA;
;                             float ov[4];
; #pragma unroll
;                             for (int e = 0; e < 4; ++e) {
;                                 const float ce = cur[e], pe = prev[e];
;                                 const float g1 = dpp_mv<0x121>(k15 ? pe : ce), g2 = dpp_mv<0x122>(k14 ? pe : ce);
;                                 const float cv = fmaf(w0[e], g2, fmaf(w1[e], g1, fmaf(w2[e], ce, bb[e])));
;                                 ov[e] = siluf_(cv) * uu[e];
;                             }
;                             wv[2 * n] = cvt_pk_bf16(ov[0], ov[1]); wv[2 * n + 1] = cvt_pk_bf16(ov[2], ov[3]);
;                             if (n) prevB = cur; else prevA = cur;
;                         }
;                         if (ai > 0 || m > 0 || l >= 2) *(v4u*)((unsigned char*)ACT + (ob + (unsigned)((128 * ai + 16 * m) * DFF * 2))) = (v4u){wv[0], wv[1], wv[2], wv[3]};
;                         __builtin_amdgcn_sched_barrier(0);
;                     }
	v_pk_mul_f32 v[16:17], v[16:17], v[20:21] op_sel_hi:[1,0]
	s_nop 0
	v_cndmask_b32_e64 v0, v16, v32, s[6:7]
	v_pk_mul_f32 v[18:19], v[18:19], v[20:21] op_sel_hi:[1,0]
	v_cndmask_b32_e32 v21, v32, v16, vcc
	v_fma_f32 v23, v160, v16, v148
	v_mov_b32_dpp v0, v0 row_ror:1 row_mask:0xf bank_mask:0xf bound_ctrl:1
	v_mov_b32_dpp v16, v21 row_ror:2 row_mask:0xf bank_mask:0xf bound_ctrl:1
	v_fmac_f32_e32 v23, v156, v0
	v_fmac_f32_e32 v23, v152, v16
	v_mul_f32_e32 v0, 0xbfb8aa3b, v23
	v_exp_f32_e32 v0, v0
	v_cndmask_b32_e64 v16, v17, v33, s[6:7]
	v_cndmask_b32_e32 v22, v33, v17, vcc
	v_fma_f32 v17, v161, v17, v149
	v_mov_b32_dpp v16, v16 row_ror:1 row_mask:0xf bank_mask:0xf bound_ctrl:1
	v_add_f32_e32 v0, 1.0, v0
	v_rcp_f32_e32 v21, v0
	v_fmac_f32_e32 v17, v157, v16
	v_mov_b32_dpp v0, v22 row_ror:2 row_mask:0xf bank_mask:0xf bound_ctrl:1
	v_fmac_f32_e32 v17, v153, v0
	v_mul_f32_e32 v0, 0xbfb8aa3b, v17
	v_exp_f32_e32 v0, v0
	v_mov_b32_e32 v22, v12
	v_pk_mul_f32 v[22:23], v[22:23], v[20:21]
	v_fma_f32 v29, v162, v18, v150
	v_add_f32_e32 v0, 1.0, v0
	v_rcp_f32_e32 v21, v0
	v_cndmask_b32_e64 v0, v18, v2, s[6:7]
	v_cndmask_b32_e32 v2, v2, v18, vcc
	v_mov_b32_e32 v16, v13
	v_mov_b32_dpp v0, v0 row_ror:1 row_mask:0xf bank_mask:0xf bound_ctrl:1
	v_mov_b32_dpp v2, v2 row_ror:2 row_mask:0xf bank_mask:0xf bound_ctrl:1
	v_fmac_f32_e32 v29, v158, v0
	v_fmac_f32_e32 v29, v154, v2
	v_mul_f32_e32 v0, 0xbfb8aa3b, v29
	v_exp_f32_e32 v0, v0
	v_pk_mul_f32 v[12:13], v[16:17], v[20:21]
	v_cndmask_b32_e32 v2, v3, v19, vcc
	v_fmac_f32_e32 v151, v163, v19
	v_add_f32_e32 v0, 1.0, v0
	v_rcp_f32_e32 v21, v0
	v_cndmask_b32_e64 v0, v19, v3, s[6:7]
	v_mov_b32_dpp v2, v2 row_ror:2 row_mask:0xf bank_mask:0xf bound_ctrl:1
	v_mov_b32_e32 v150, v15
	v_mov_b32_dpp v0, v0 row_ror:1 row_mask:0xf bank_mask:0xf bound_ctrl:1
	v_fmac_f32_e32 v151, v159, v0
	v_fmac_f32_e32 v151, v155, v2
	v_mul_f32_e32 v0, 0xbfb8aa3b, v151
	v_exp_f32_e32 v0, v0
	v_pk_mul_f32 v[2:3], v[28:29], v[20:21]
	v_mul_f32_e32 v16, v22, v23
	v_mul_f32_e32 v14, v2, v3
	v_add_f32_e32 v0, 1.0, v0
	v_rcp_f32_e32 v21, v0
	v_mul_f32_e32 v0, v12, v13
	v_pk_mul_f32 v[2:3], v[8:9], v[20:21] op_sel_hi:[1,0]
	s_nop 0
	v_cndmask_b32_e64 v8, v2, v24, s[6:7]
	v_cndmask_b32_e32 v9, v24, v2, vcc
	v_pk_mul_f32 v[10:11], v[10:11], v[20:21] op_sel_hi:[1,0]
	v_mov_b32_dpp v8, v8 row_ror:1 row_mask:0xf bank_mask:0xf bound_ctrl:1
	v_mov_b32_dpp v12, v9 row_ror:2 row_mask:0xf bank_mask:0xf bound_ctrl:1
	v_fma_f32 v9, v144, v2, v132
	v_fmac_f32_e32 v9, v140, v8
	v_fmac_f32_e32 v9, v136, v12
	v_mul_f32_e32 v2, 0xbfb8aa3b, v9
	v_exp_f32_e32 v2, v2
	v_pk_mul_f32 v[12:13], v[150:151], v[20:21]
	v_cndmask_b32_e32 v8, v25, v3, vcc
	v_mul_f32_e32 v12, v12, v13
	v_add_f32_e32 v2, 1.0, v2
	v_rcp_f32_e32 v21, v2
	v_cndmask_b32_e64 v2, v3, v25, s[6:7]
	v_fma_f32 v13, v145, v3, v133
	v_mov_b32_dpp v8, v8 row_ror:2 row_mask:0xf bank_mask:0xf bound_ctrl:1
	v_mov_b32_dpp v2, v2 row_ror:1 row_mask:0xf bank_mask:0xf bound_ctrl:1
	v_fmac_f32_e32 v13, v141, v2
	v_fmac_f32_e32 v13, v137, v8
	v_mul_f32_e32 v2, 0xbfb8aa3b, v13
	v_exp_f32_e32 v3, v2
	v_cvt_pk_bf16_f32 v2, v16, v0
	v_mov_b32_e32 v8, v4
	v_pk_mul_f32 v[8:9], v[8:9], v[20:21]
	v_add_f32_e32 v0, 1.0, v3
	v_rcp_f32_e32 v21, v0
	v_cndmask_b32_e64 v0, v10, v26, s[6:7]
	v_cndmask_b32_e32 v3, v26, v10, vcc
	v_fma_f32 v15, v146, v10, v134
	v_mov_b32_dpp v0, v0 row_ror:1 row_mask:0xf bank_mask:0xf bound_ctrl:1
	v_mov_b32_dpp v3, v3 row_ror:2 row_mask:0xf bank_mask:0xf bound_ctrl:1
	v_fmac_f32_e32 v15, v142, v0
	v_fmac_f32_e32 v15, v138, v3
	v_mul_f32_e32 v0, 0xbfb8aa3b, v15
	v_exp_f32_e32 v0, v0
	v_cvt_pk_bf16_f32 v3, v14, v12
	v_mov_b32_e32 v12, v5
	v_pk_mul_f32 v[4:5], v[12:13], v[20:21]
	v_add_f32_e32 v0, 1.0, v0
	v_rcp_f32_e32 v21, v0
	v_cndmask_b32_e64 v0, v11, v27, s[6:7]
	v_cndmask_b32_e32 v10, v27, v11, vcc
	v_fmac_f32_e32 v135, v147, v11
	v_mov_b32_dpp v0, v0 row_ror:1 row_mask:0xf bank_mask:0xf bound_ctrl:1
	v_mov_b32_dpp v10, v10 row_ror:2 row_mask:0xf bank_mask:0xf bound_ctrl:1
	v_fmac_f32_e32 v135, v143, v0
	v_fmac_f32_e32 v135, v139, v10
	v_mul_f32_e32 v0, 0xbfb8aa3b, v135
	v_exp_f32_e32 v0, v0
	v_mov_b32_e32 v14, v6
	v_mul_f32_e32 v10, v8, v9
	v_pk_mul_f32 v[8:9], v[14:15], v[20:21]
	v_add_f32_e32 v0, 1.0, v0
	v_rcp_f32_e32 v21, v0
	v_mov_b32_e32 v134, v7
	v_mul_f32_e32 v0, v4, v5
	v_mul_f32_e32 v6, v8, v9
	v_pk_mul_f32 v[4:5], v[134:135], v[20:21]
	s_nop 0
	v_mul_f32_e32 v5, v4, v5
	v_cvt_pk_bf16_f32 v4, v10, v0
	v_add_u32_e32 v0, 0xf2000, v184
	v_cvt_pk_bf16_f32 v5, v6, v5
	global_store_dwordx4 v0, v[2:5], s[0:1] sc1
	s_and_b64 vcc, exec, s[4:5]
	s_mov_b64 s[0:1], -1
	s_cbranch_vccnz .LBB0_1168
